# loop-edge: GEMM loop counter/pointer SALU moved in front of the loop-back barrier; EpiResid row-sum reductions via v_permlane16_swap/v_permlane32_swap instead of ds_bpermute
# speedup vs baseline: 1.0035x; 1.0010x over previous
; #define PG8_STAGE(bufoff, gbase, voff) do { _Pragma("unroll") for (int _i = 0; _i < 2; ++_i) { unsigned _keep; \
;         asm volatile("s_mov_b32 %0, m0\n\ts_mov_b32 m0, %1\n\ts_nop 0\n\tglobal_load_lds_dwordx4 %2, %3\n\ts_mov_b32 m0, %0" : "=&s"(_keep) : "s"(ldsb + (unsigned)((bufoff) + _i * 8192)), "v"((voff)[_i]), "s"((const char*)(gbase)) : "memory"); } } while (0)
; #define PG8_LDA(dst, b, h) do { _Pragma("unroll") for (int m = 0; m < 4; ++m) _Pragma("unroll") for (int k = 0; k < 2; ++k) dst[m][k] = *(const LAS bf16x8*)(lds + PG8_SA(b, h) + aoff + m * 2048 + k * 1024); } while (0)
; #define PG8_LDB(dst, b, h) do { _Pragma("unroll") for (int n = 0; n < 2; ++n) _Pragma("unroll") for (int k = 0; k < 2; ++k) dst[n][k] = *(const LAS bf16x8*)(lds + PG8_SB(b, h) + boff + n * 2048 + k * 1024); } while (0)
; #define PG8_MMA(ai, bj, At, Bt) do { __builtin_amdgcn_s_setprio(1); _Pragma("unroll") for (int m = 0; m < 4; ++m) _Pragma("unroll") for (int n = 0; n < 2; ++n) _Pragma("unroll") for (int k = 0; k < 2; ++k) \
;         acc[ai][bj][m][n] = __builtin_amdgcn_mfma_f32_16x16x32_bf16(Bt[n][k], At[m][k], acc[ai][bj][m][n], 0, 0, 0); __builtin_amdgcn_s_setprio(0); } while (0)
; #define PG8_WAIT_V(n) asm volatile("s_waitcnt vmcnt(" #n ")" ::: "memory")
; #define PG8_WAIT_L(n) asm volatile("s_waitcnt lgkmcnt(" #n ")" ::: "memory")
; #define PG8_BAR __builtin_amdgcn_s_barrier()
; template <class Epi>
; __device__ __forceinline__ void gemm_phase(LAS unsigned char* lds, const Gemm g, const StaticOrder& S, const Epi& E) {
;     ...
;             const bool last = (t == nt - 2);
;             const char* a1 = cA + (size_t)(t + 1) * kstep;
;             const char* a2 = last ? nA : cA + (size_t)(t + 2) * kstep; const char* b2 = last ? nB : cB + (size_t)(t + 2) * kstep;
;             const char* a3 = a2 + kstep; const char* b3 = b2 + kstep;
;             PG8_LDB(B0, 0, 0); PG8_LDB(B1, 0, 1); PG8_SCHED; PG8_LDA(At, 0, 0); PG8_STAGE(PG8_SA(1, 1), a1 + hstepA, voffA);
;             PG8_WAIT_V(8); PG8_WAIT_L(0); PG8_BAR; PG8_MMA(0, 0, At, B0); PG8_MMA(0, 1, At, B1); PG8_BAR; PG8_SCHED;
;             PG8_LDA(At, 0, 1); PG8_STAGE(PG8_SB(0, 0), b2, voffB); PG8_STAGE(PG8_SB(0, 1), b2 + hstepB, voffB); PG8_STAGE(PG8_SA(0, 0), a2, voffA);
;             PG8_WAIT_V(8); PG8_WAIT_L(0); PG8_BAR; PG8_MMA(1, 0, At, B0); PG8_MMA(1, 1, At, B1); PG8_BAR; PG8_SCHED;
.LBB0_204:
	ds_read_b128 v[136:139], v149
	ds_read_b128 v[140:143], v149 offset:1024
	ds_read_b128 v[160:163], v149 offset:2048
	ds_read_b128 v[164:167], v149 offset:3072
	ds_read_b128 v[168:171], v150
	ds_read_b128 v[172:175], v150 offset:1024
	ds_read_b128 v[176:179], v150 offset:2048
	ds_read_b128 v[180:183], v150 offset:3072
	s_cmp_eq_u32 s83, 12
	s_cselect_b32 s42, s77, s79
	s_cselect_b32 s43, s13, s80
	s_cselect_b32 s40, s78, s81
	s_cselect_b32 s41, s11, s82
	s_add_u32 s26, s42, 0x80
	s_addc_u32 s27, s43, 0
	ds_read_b128 v[184:187], v151
	ds_read_b128 v[188:191], v151 offset:1024
	ds_read_b128 v[192:195], v151 offset:2048
	ds_read_b128 v[196:199], v151 offset:3072
	ds_read_b128 v[200:203], v151 offset:4096
	ds_read_b128 v[204:207], v151 offset:5120
	ds_read_b128 v[208:211], v151 offset:6144
	ds_read_b128 v[212:215], v151 offset:7168
	s_add_u32 s86, s79, 0x3ff80
	s_addc_u32 s87, s80, 0
	s_mov_b32 s90, m0
	s_mov_b32 m0, s72
	s_nop 0
	global_load_lds_dwordx4 v133, s[86:87]
	s_mov_b32 m0, s90
	s_nop 0
	s_mov_b32 s90, m0
	s_mov_b32 m0, s73
	s_nop 0
	global_load_lds_dwordx4 v145, s[86:87]
	s_mov_b32 m0, s90
	s_waitcnt vmcnt(8)
	s_waitcnt lgkmcnt(0)
	s_barrier
	s_setprio 1
	s_waitcnt lgkmcnt(7)
	v_mfma_f32_16x16x32_bf16 v[126:129], v[136:139], v[184:187], v[126:129]
	v_mfma_f32_16x16x32_bf16 v[122:125], v[160:163], v[184:187], v[122:125]
	s_waitcnt lgkmcnt(5)
	v_mfma_f32_16x16x32_bf16 v[110:113], v[136:139], v[192:195], v[110:113]
	v_mfma_f32_16x16x32_bf16 v[106:109], v[160:163], v[192:195], v[106:109]
	s_waitcnt lgkmcnt(3)
	v_mfma_f32_16x16x32_bf16 v[94:97], v[136:139], v[200:203], v[94:97]
	v_mfma_f32_16x16x32_bf16 v[90:93], v[160:163], v[200:203], v[90:93]
	s_waitcnt lgkmcnt(1)
	v_mfma_f32_16x16x32_bf16 v[78:81], v[136:139], v[208:211], v[78:81]
	v_mfma_f32_16x16x32_bf16 v[74:77], v[160:163], v[208:211], v[74:77]
	v_mfma_f32_16x16x32_bf16 v[126:129], v[140:143], v[188:191], v[126:129]
	v_mfma_f32_16x16x32_bf16 v[122:125], v[164:167], v[188:191], v[122:125]
	v_mfma_f32_16x16x32_bf16 v[110:113], v[140:143], v[196:199], v[110:113]
	v_mfma_f32_16x16x32_bf16 v[106:109], v[164:167], v[196:199], v[106:109]
	v_mfma_f32_16x16x32_bf16 v[94:97], v[140:143], v[204:207], v[94:97]
	v_mfma_f32_16x16x32_bf16 v[90:93], v[164:167], v[204:207], v[90:93]
	s_waitcnt lgkmcnt(0)
	v_mfma_f32_16x16x32_bf16 v[78:81], v[140:143], v[212:215], v[78:81]
	v_mfma_f32_16x16x32_bf16 v[74:77], v[164:167], v[212:215], v[74:77]
	s_setprio 0
	s_setprio 1
	v_mfma_f32_16x16x32_bf16 v[118:121], v[168:171], v[184:187], v[118:121]
	v_mfma_f32_16x16x32_bf16 v[114:117], v[176:179], v[184:187], v[114:117]
	v_mfma_f32_16x16x32_bf16 v[102:105], v[168:171], v[192:195], v[102:105]
	v_mfma_f32_16x16x32_bf16 v[98:101], v[176:179], v[192:195], v[98:101]
	v_mfma_f32_16x16x32_bf16 v[86:89], v[168:171], v[200:203], v[86:89]
	v_mfma_f32_16x16x32_bf16 v[82:85], v[176:179], v[200:203], v[82:85]
	v_mfma_f32_16x16x32_bf16 v[70:73], v[168:171], v[208:211], v[70:73]
	v_mfma_f32_16x16x32_bf16 v[66:69], v[176:179], v[208:211], v[66:69]
	v_mfma_f32_16x16x32_bf16 v[118:121], v[172:175], v[188:191], v[118:121]
	v_mfma_f32_16x16x32_bf16 v[114:117], v[180:183], v[188:191], v[114:117]
	v_mfma_f32_16x16x32_bf16 v[102:105], v[172:175], v[196:199], v[102:105]
	v_mfma_f32_16x16x32_bf16 v[98:101], v[180:183], v[196:199], v[98:101]
	v_mfma_f32_16x16x32_bf16 v[86:89], v[172:175], v[204:207], v[86:89]
	v_mfma_f32_16x16x32_bf16 v[82:85], v[180:183], v[204:207], v[82:85]
	v_mfma_f32_16x16x32_bf16 v[70:73], v[172:175], v[212:215], v[70:73]
	v_mfma_f32_16x16x32_bf16 v[66:69], v[180:183], v[212:215], v[66:69]
	s_setprio 0
	s_barrier
	ds_read_b128 v[184:187], v151 offset:16384
	ds_read_b128 v[188:191], v151 offset:17408
	ds_read_b128 v[192:195], v151 offset:18432
	ds_read_b128 v[196:199], v151 offset:19456
	ds_read_b128 v[200:203], v151 offset:20480
	ds_read_b128 v[204:207], v151 offset:21504
	ds_read_b128 v[208:211], v151 offset:22528
	ds_read_b128 v[212:215], v151 offset:23552
	s_mov_b32 s86, m0
	s_mov_b32 m0, s23
	s_nop 0
	global_load_lds_dwordx4 v144, s[40:41]
	s_mov_b32 m0, s86
	s_nop 0
	s_mov_b32 s86, m0
	s_mov_b32 m0, s51
	s_nop 0
	global_load_lds_dwordx4 v146, s[40:41]
	s_mov_b32 m0, s86
	s_add_u32 s86, s40, 0x40000
	s_addc_u32 s87, s41, 0
	s_mov_b32 s90, m0
	s_mov_b32 m0, s52
	s_nop 0
	global_load_lds_dwordx4 v144, s[86:87]
	s_mov_b32 m0, s90
	s_nop 0
	s_mov_b32 s90, m0
	s_mov_b32 m0, s53
	s_nop 0
	global_load_lds_dwordx4 v146, s[86:87]
	s_mov_b32 m0, s90
	s_mov_b32 s86, m0
	s_mov_b32 m0, s50
	s_nop 0
	global_load_lds_dwordx4 v133, s[42:43]
	s_mov_b32 m0, s86
	s_nop 0
	s_mov_b32 s86, m0
	s_mov_b32 m0, s58
	s_nop 0
	global_load_lds_dwordx4 v145, s[42:43]
	s_mov_b32 m0, s86
	s_waitcnt vmcnt(8)
	s_waitcnt lgkmcnt(0)
	s_barrier
; #define PG8_STAGE(bufoff, gbase, voff) do { _Pragma("unroll") for (int _i = 0; _i < 2; ++_i) { unsigned _keep; \
;         asm volatile("s_mov_b32 %0, m0\n\ts_mov_b32 m0, %1\n\ts_nop 0\n\tglobal_load_lds_dwordx4 %2, %3\n\ts_mov_b32 m0, %0" : "=&s"(_keep) : "s"(ldsb + (unsigned)((bufoff) + _i * 8192)), "v"((voff)[_i]), "s"((const char*)(gbase)) : "memory"); } } while (0)
; #define PG8_LDA(dst, b, h) do { _Pragma("unroll") for (int m = 0; m < 4; ++m) _Pragma("unroll") for (int k = 0; k < 2; ++k) dst[m][k] = *(const LAS bf16x8*)(lds + PG8_SA(b, h) + aoff + m * 2048 + k * 1024); } while (0)
; #define PG8_LDB(dst, b, h) do { _Pragma("unroll") for (int n = 0; n < 2; ++n) _Pragma("unroll") for (int k = 0; k < 2; ++k) dst[n][k] = *(const LAS bf16x8*)(lds + PG8_SB(b, h) + boff + n * 2048 + k * 1024); } while (0)
; #define PG8_MMA(ai, bj, At, Bt) do { __builtin_amdgcn_s_setprio(1); _Pragma("unroll") for (int m = 0; m < 4; ++m) _Pragma("unroll") for (int n = 0; n < 2; ++n) _Pragma("unroll") for (int k = 0; k < 2; ++k) \
;         acc[ai][bj][m][n] = __builtin_amdgcn_mfma_f32_16x16x32_bf16(Bt[n][k], At[m][k], acc[ai][bj][m][n], 0, 0, 0); __builtin_amdgcn_s_setprio(0); } while (0)
; #define PG8_WAIT_V(n) asm volatile("s_waitcnt vmcnt(" #n ")" ::: "memory")
; #define PG8_WAIT_L(n) asm volatile("s_waitcnt lgkmcnt(" #n ")" ::: "memory")
; #define PG8_BAR __builtin_amdgcn_s_barrier()
; #define PG8_SCHED __builtin_amdgcn_sched_barrier(0)
; template <class Epi>
; __device__ __forceinline__ void gemm_phase(LAS unsigned char* lds, const Gemm g, const StaticOrder& S, const Epi& E) {
;     ...
;             PG8_WAIT_V(8); PG8_WAIT_L(0); PG8_BAR; PG8_MMA(0, 0, At, B0); PG8_MMA(0, 1, At, B1); PG8_BAR; PG8_SCHED;
;             PG8_LDA(At, 0, 1); PG8_STAGE(PG8_SB(0, 0), b2, voffB); PG8_STAGE(PG8_SB(0, 1), b2 + hstepB, voffB); PG8_STAGE(PG8_SA(0, 0), a2, voffA);
;             PG8_WAIT_V(8); PG8_WAIT_L(0); PG8_BAR; PG8_MMA(1, 0, At, B0); PG8_MMA(1, 1, At, B1); PG8_BAR; PG8_SCHED;
;             PG8_LDB(B0, 1, 0); PG8_LDB(B1, 1, 1); PG8_SCHED; PG8_LDA(At, 1, 0); PG8_STAGE(PG8_SA(0, 1), a2 + hstepA, voffA);
;             PG8_WAIT_V(8); PG8_WAIT_L(0); PG8_BAR; PG8_MMA(0, 0, At, B0); PG8_MMA(0, 1, At, B1); PG8_BAR; PG8_SCHED;
	s_setprio 1
	s_waitcnt lgkmcnt(7)
	v_mfma_f32_16x16x32_bf16 v[62:65], v[136:139], v[184:187], v[62:65]
	v_mfma_f32_16x16x32_bf16 v[58:61], v[160:163], v[184:187], v[58:61]
	s_waitcnt lgkmcnt(5)
	v_mfma_f32_16x16x32_bf16 v[46:49], v[136:139], v[192:195], v[46:49]
	v_mfma_f32_16x16x32_bf16 v[42:45], v[160:163], v[192:195], v[42:45]
	s_waitcnt lgkmcnt(3)
	v_mfma_f32_16x16x32_bf16 v[30:33], v[136:139], v[200:203], v[30:33]
	v_mfma_f32_16x16x32_bf16 v[26:29], v[160:163], v[200:203], v[26:29]
	s_waitcnt lgkmcnt(1)
	v_mfma_f32_16x16x32_bf16 v[14:17], v[136:139], v[208:211], v[14:17]
	v_mfma_f32_16x16x32_bf16 v[10:13], v[160:163], v[208:211], v[10:13]
	v_mfma_f32_16x16x32_bf16 v[62:65], v[140:143], v[188:191], v[62:65]
	v_mfma_f32_16x16x32_bf16 v[58:61], v[164:167], v[188:191], v[58:61]
	v_mfma_f32_16x16x32_bf16 v[46:49], v[140:143], v[196:199], v[46:49]
	v_mfma_f32_16x16x32_bf16 v[42:45], v[164:167], v[196:199], v[42:45]
	v_mfma_f32_16x16x32_bf16 v[30:33], v[140:143], v[204:207], v[30:33]
	v_mfma_f32_16x16x32_bf16 v[26:29], v[164:167], v[204:207], v[26:29]
	s_waitcnt lgkmcnt(0)
	v_mfma_f32_16x16x32_bf16 v[14:17], v[140:143], v[212:215], v[14:17]
	v_mfma_f32_16x16x32_bf16 v[10:13], v[164:167], v[212:215], v[10:13]
	s_setprio 0
	s_setprio 1
	v_mfma_f32_16x16x32_bf16 v[54:57], v[168:171], v[184:187], v[54:57]
	v_mfma_f32_16x16x32_bf16 v[50:53], v[176:179], v[184:187], v[50:53]
	v_mfma_f32_16x16x32_bf16 v[38:41], v[168:171], v[192:195], v[38:41]
	v_mfma_f32_16x16x32_bf16 v[34:37], v[176:179], v[192:195], v[34:37]
	v_mfma_f32_16x16x32_bf16 v[22:25], v[168:171], v[200:203], v[22:25]
	v_mfma_f32_16x16x32_bf16 v[18:21], v[176:179], v[200:203], v[18:21]
	v_mfma_f32_16x16x32_bf16 v[6:9], v[168:171], v[208:211], v[6:9]
	v_mfma_f32_16x16x32_bf16 v[2:5], v[176:179], v[208:211], v[2:5]
	v_mfma_f32_16x16x32_bf16 v[54:57], v[172:175], v[188:191], v[54:57]
	v_mfma_f32_16x16x32_bf16 v[50:53], v[180:183], v[188:191], v[50:53]
	v_mfma_f32_16x16x32_bf16 v[38:41], v[172:175], v[196:199], v[38:41]
	v_mfma_f32_16x16x32_bf16 v[34:37], v[180:183], v[196:199], v[34:37]
	v_mfma_f32_16x16x32_bf16 v[22:25], v[172:175], v[204:207], v[22:25]
	v_mfma_f32_16x16x32_bf16 v[18:21], v[180:183], v[204:207], v[18:21]
	v_mfma_f32_16x16x32_bf16 v[6:9], v[172:175], v[212:215], v[6:9]
	v_mfma_f32_16x16x32_bf16 v[2:5], v[180:183], v[212:215], v[2:5]
	s_setprio 0
	s_barrier
	ds_read_b128 v[136:139], v152
	ds_read_b128 v[140:143], v152 offset:1024
	ds_read_b128 v[160:163], v152 offset:2048
	ds_read_b128 v[164:167], v152 offset:3072
	ds_read_b128 v[168:171], v153
	ds_read_b128 v[172:175], v153 offset:1024
	ds_read_b128 v[176:179], v153 offset:2048
	ds_read_b128 v[180:183], v153 offset:3072
	ds_read_b128 v[184:187], v151 offset:32768
	ds_read_b128 v[188:191], v151 offset:33792
	ds_read_b128 v[192:195], v151 offset:34816
	ds_read_b128 v[196:199], v151 offset:35840
	ds_read_b128 v[200:203], v151 offset:36864
	ds_read_b128 v[204:207], v151 offset:37888
	ds_read_b128 v[208:211], v151 offset:38912
	ds_read_b128 v[212:215], v151 offset:39936
	s_add_u32 s42, s42, 0x40000
	s_addc_u32 s43, s43, 0
	s_mov_b32 s86, m0
	s_mov_b32 m0, s59
	s_nop 0
	global_load_lds_dwordx4 v133, s[42:43]
	s_mov_b32 m0, s86
	s_nop 0
	s_mov_b32 s86, m0
	s_mov_b32 m0, s62
	s_nop 0
	global_load_lds_dwordx4 v145, s[42:43]
	s_mov_b32 m0, s86
	s_waitcnt vmcnt(8)
	s_waitcnt lgkmcnt(0)
	s_barrier
	s_setprio 1
	s_waitcnt lgkmcnt(7)
	v_mfma_f32_16x16x32_bf16 v[126:129], v[136:139], v[184:187], v[126:129]
	v_mfma_f32_16x16x32_bf16 v[122:125], v[160:163], v[184:187], v[122:125]
	s_waitcnt lgkmcnt(5)
	v_mfma_f32_16x16x32_bf16 v[110:113], v[136:139], v[192:195], v[110:113]
	v_mfma_f32_16x16x32_bf16 v[106:109], v[160:163], v[192:195], v[106:109]
	s_waitcnt lgkmcnt(3)
	v_mfma_f32_16x16x32_bf16 v[94:97], v[136:139], v[200:203], v[94:97]
	v_mfma_f32_16x16x32_bf16 v[90:93], v[160:163], v[200:203], v[90:93]
	s_waitcnt lgkmcnt(1)
	v_mfma_f32_16x16x32_bf16 v[78:81], v[136:139], v[208:211], v[78:81]
	v_mfma_f32_16x16x32_bf16 v[74:77], v[160:163], v[208:211], v[74:77]
	v_mfma_f32_16x16x32_bf16 v[126:129], v[140:143], v[188:191], v[126:129]
	v_mfma_f32_16x16x32_bf16 v[122:125], v[164:167], v[188:191], v[122:125]
	v_mfma_f32_16x16x32_bf16 v[110:113], v[140:143], v[196:199], v[110:113]
	v_mfma_f32_16x16x32_bf16 v[106:109], v[164:167], v[196:199], v[106:109]
	v_mfma_f32_16x16x32_bf16 v[94:97], v[140:143], v[204:207], v[94:97]
	v_mfma_f32_16x16x32_bf16 v[90:93], v[164:167], v[204:207], v[90:93]
	s_waitcnt lgkmcnt(0)
	v_mfma_f32_16x16x32_bf16 v[78:81], v[140:143], v[212:215], v[78:81]
	v_mfma_f32_16x16x32_bf16 v[74:77], v[164:167], v[212:215], v[74:77]
	s_setprio 0
	s_setprio 1
	v_mfma_f32_16x16x32_bf16 v[118:121], v[168:171], v[184:187], v[118:121]
	v_mfma_f32_16x16x32_bf16 v[114:117], v[176:179], v[184:187], v[114:117]
	v_mfma_f32_16x16x32_bf16 v[102:105], v[168:171], v[192:195], v[102:105]
	v_mfma_f32_16x16x32_bf16 v[98:101], v[176:179], v[192:195], v[98:101]
	v_mfma_f32_16x16x32_bf16 v[86:89], v[168:171], v[200:203], v[86:89]
	v_mfma_f32_16x16x32_bf16 v[82:85], v[176:179], v[200:203], v[82:85]
	v_mfma_f32_16x16x32_bf16 v[70:73], v[168:171], v[208:211], v[70:73]
	v_mfma_f32_16x16x32_bf16 v[66:69], v[176:179], v[208:211], v[66:69]
	v_mfma_f32_16x16x32_bf16 v[118:121], v[172:175], v[188:191], v[118:121]
	v_mfma_f32_16x16x32_bf16 v[114:117], v[180:183], v[188:191], v[114:117]
	v_mfma_f32_16x16x32_bf16 v[102:105], v[172:175], v[196:199], v[102:105]
	v_mfma_f32_16x16x32_bf16 v[98:101], v[180:183], v[196:199], v[98:101]
	v_mfma_f32_16x16x32_bf16 v[86:89], v[172:175], v[204:207], v[86:89]
	v_mfma_f32_16x16x32_bf16 v[82:85], v[180:183], v[204:207], v[82:85]
	v_mfma_f32_16x16x32_bf16 v[70:73], v[172:175], v[212:215], v[70:73]
	v_mfma_f32_16x16x32_bf16 v[66:69], v[180:183], v[212:215], v[66:69]
	s_setprio 0
	s_barrier
; #define PG8_STAGE(bufoff, gbase, voff) do { _Pragma("unroll") for (int _i = 0; _i < 2; ++_i) { unsigned _keep; \
;         asm volatile("s_mov_b32 %0, m0\n\ts_mov_b32 m0, %1\n\ts_nop 0\n\tglobal_load_lds_dwordx4 %2, %3\n\ts_mov_b32 m0, %0" : "=&s"(_keep) : "s"(ldsb + (unsigned)((bufoff) + _i * 8192)), "v"((voff)[_i]), "s"((const char*)(gbase)) : "memory"); } } while (0)
; #define PG8_LDA(dst, b, h) do { _Pragma("unroll") for (int m = 0; m < 4; ++m) _Pragma("unroll") for (int k = 0; k < 2; ++k) dst[m][k] = *(const LAS bf16x8*)(lds + PG8_SA(b, h) + aoff + m * 2048 + k * 1024); } while (0)
; #define PG8_MMA(ai, bj, At, Bt) do { __builtin_amdgcn_s_setprio(1); _Pragma("unroll") for (int m = 0; m < 4; ++m) _Pragma("unroll") for (int n = 0; n < 2; ++n) _Pragma("unroll") for (int k = 0; k < 2; ++k) \
;         acc[ai][bj][m][n] = __builtin_amdgcn_mfma_f32_16x16x32_bf16(Bt[n][k], At[m][k], acc[ai][bj][m][n], 0, 0, 0); __builtin_amdgcn_s_setprio(0); } while (0)
; #define PG8_WAIT_V(n) asm volatile("s_waitcnt vmcnt(" #n ")" ::: "memory")
; #define PG8_WAIT_L(n) asm volatile("s_waitcnt lgkmcnt(" #n ")" ::: "memory")
; #define PG8_BAR __builtin_amdgcn_s_barrier()
; #define PG8_SCHED __builtin_amdgcn_sched_barrier(0)
; template <class Epi>
; __device__ __forceinline__ void gemm_phase(LAS unsigned char* lds, const Gemm g, const StaticOrder& S, const Epi& E) {
;     ...
;             PG8_LDA(At, 1, 1); PG8_STAGE(PG8_SB(1, 0), b3, voffB); PG8_STAGE(PG8_SB(1, 1), b3 + hstepB, voffB); PG8_STAGE(PG8_SA(1, 0), a3, voffA);
;             PG8_WAIT_V(8); PG8_WAIT_L(0); PG8_BAR; PG8_MMA(1, 0, At, B0); PG8_MMA(1, 1, At, B1); PG8_BAR; PG8_SCHED;
;         }
;         if (wr == 0) PG8_BAR;
	ds_read_b128 v[184:187], v151 offset:49152
	ds_read_b128 v[188:191], v151 offset:50176
	ds_read_b128 v[192:195], v151 offset:51200
	ds_read_b128 v[196:199], v151 offset:52224
	ds_read_b128 v[200:203], v151 offset:53248
	ds_read_b128 v[204:207], v151 offset:54272
	ds_read_b128 v[208:211], v151 offset:55296
	ds_read_b128 v[212:215], v151 offset:56320
	s_add_u32 s42, s40, 0x80
	s_addc_u32 s43, s41, 0
	s_mov_b32 s86, m0
	s_mov_b32 m0, s63
	s_nop 0
	global_load_lds_dwordx4 v144, s[42:43]
	s_mov_b32 m0, s86
	s_add_u32 s40, s40, 0x40080
	s_mov_b32 s86, m0
	s_mov_b32 m0, s67
	s_nop 0
	global_load_lds_dwordx4 v146, s[42:43]
	s_mov_b32 m0, s86
	s_addc_u32 s41, s41, 0
	s_mov_b32 s42, m0
	s_mov_b32 m0, s70
	s_nop 0
	global_load_lds_dwordx4 v144, s[40:41]
	s_mov_b32 m0, s42
	s_nop 0
	s_mov_b32 s42, m0
	s_mov_b32 m0, s71
	s_nop 0
	global_load_lds_dwordx4 v146, s[40:41]
	s_mov_b32 m0, s42
	s_mov_b32 s40, m0
	s_mov_b32 m0, s68
	s_nop 0
	global_load_lds_dwordx4 v133, s[26:27]
	s_mov_b32 m0, s40
	s_nop 0
	s_mov_b32 s40, m0
	s_mov_b32 m0, s69
	s_nop 0
	global_load_lds_dwordx4 v145, s[26:27]
	s_mov_b32 m0, s40
	s_waitcnt vmcnt(8)
	s_waitcnt lgkmcnt(0)
	s_barrier
	s_setprio 1
	s_waitcnt lgkmcnt(7)
	v_mfma_f32_16x16x32_bf16 v[62:65], v[136:139], v[184:187], v[62:65]
	v_mfma_f32_16x16x32_bf16 v[58:61], v[160:163], v[184:187], v[58:61]
	s_waitcnt lgkmcnt(5)
	v_mfma_f32_16x16x32_bf16 v[46:49], v[136:139], v[192:195], v[46:49]
	v_mfma_f32_16x16x32_bf16 v[42:45], v[160:163], v[192:195], v[42:45]
	s_waitcnt lgkmcnt(3)
	v_mfma_f32_16x16x32_bf16 v[30:33], v[136:139], v[200:203], v[30:33]
	v_mfma_f32_16x16x32_bf16 v[26:29], v[160:163], v[200:203], v[26:29]
	s_waitcnt lgkmcnt(1)
	v_mfma_f32_16x16x32_bf16 v[14:17], v[136:139], v[208:211], v[14:17]
	v_mfma_f32_16x16x32_bf16 v[10:13], v[160:163], v[208:211], v[10:13]
	v_mfma_f32_16x16x32_bf16 v[62:65], v[140:143], v[188:191], v[62:65]
	v_mfma_f32_16x16x32_bf16 v[58:61], v[164:167], v[188:191], v[58:61]
	v_mfma_f32_16x16x32_bf16 v[46:49], v[140:143], v[196:199], v[46:49]
	v_mfma_f32_16x16x32_bf16 v[42:45], v[164:167], v[196:199], v[42:45]
	v_mfma_f32_16x16x32_bf16 v[30:33], v[140:143], v[204:207], v[30:33]
	v_mfma_f32_16x16x32_bf16 v[26:29], v[164:167], v[204:207], v[26:29]
	s_waitcnt lgkmcnt(0)
	v_mfma_f32_16x16x32_bf16 v[14:17], v[140:143], v[212:215], v[14:17]
	v_mfma_f32_16x16x32_bf16 v[10:13], v[164:167], v[212:215], v[10:13]
	s_setprio 0
	s_setprio 1
	v_mfma_f32_16x16x32_bf16 v[54:57], v[168:171], v[184:187], v[54:57]
	v_mfma_f32_16x16x32_bf16 v[50:53], v[176:179], v[184:187], v[50:53]
	v_mfma_f32_16x16x32_bf16 v[38:41], v[168:171], v[192:195], v[38:41]
	v_mfma_f32_16x16x32_bf16 v[34:37], v[176:179], v[192:195], v[34:37]
	v_mfma_f32_16x16x32_bf16 v[22:25], v[168:171], v[200:203], v[22:25]
	v_mfma_f32_16x16x32_bf16 v[18:21], v[176:179], v[200:203], v[18:21]
	v_mfma_f32_16x16x32_bf16 v[6:9], v[168:171], v[208:211], v[6:9]
	v_mfma_f32_16x16x32_bf16 v[2:5], v[176:179], v[208:211], v[2:5]
	v_mfma_f32_16x16x32_bf16 v[54:57], v[172:175], v[188:191], v[54:57]
	v_mfma_f32_16x16x32_bf16 v[50:53], v[180:183], v[188:191], v[50:53]
	v_mfma_f32_16x16x32_bf16 v[38:41], v[172:175], v[196:199], v[38:41]
	v_mfma_f32_16x16x32_bf16 v[34:37], v[180:183], v[196:199], v[34:37]
	v_mfma_f32_16x16x32_bf16 v[22:25], v[172:175], v[204:207], v[22:25]
	v_mfma_f32_16x16x32_bf16 v[18:21], v[180:183], v[204:207], v[18:21]
	v_mfma_f32_16x16x32_bf16 v[6:9], v[172:175], v[212:215], v[6:9]
	v_mfma_f32_16x16x32_bf16 v[2:5], v[180:183], v[212:215], v[2:5]
	s_setprio 0
	s_add_i32 s83, s83, 2
	s_add_u32 s79, s79, 0x100
	s_addc_u32 s80, s80, 0
	s_add_u32 s81, s81, 0x100
	s_addc_u32 s82, s82, 0
	s_cmp_gt_u32 s83, 13
	s_barrier
	s_cbranch_scc0 .LBB0_204
	s_and_b64 vcc, exec, s[8:9]
	s_cbranch_vccz .LBB0_207
	s_barrier

; #define PG8_STAGE(bufoff, gbase, voff) do { _Pragma("unroll") for (int _i = 0; _i < 2; ++_i) { unsigned _keep; \
;         asm volatile("s_mov_b32 %0, m0\n\ts_mov_b32 m0, %1\n\ts_nop 0\n\tglobal_load_lds_dwordx4 %2, %3\n\ts_mov_b32 m0, %0" : "=&s"(_keep) : "s"(ldsb + (unsigned)((bufoff) + _i * 8192)), "v"((voff)[_i]), "s"((const char*)(gbase)) : "memory"); } } while (0)
; #define PG8_LDA(dst, b, h) do { _Pragma("unroll") for (int m = 0; m < 4; ++m) _Pragma("unroll") for (int k = 0; k < 2; ++k) dst[m][k] = *(const LAS bf16x8*)(lds + PG8_SA(b, h) + aoff + m * 2048 + k * 1024); } while (0)
; #define PG8_LDB(dst, b, h) do { _Pragma("unroll") for (int n = 0; n < 2; ++n) _Pragma("unroll") for (int k = 0; k < 2; ++k) dst[n][k] = *(const LAS bf16x8*)(lds + PG8_SB(b, h) + boff + n * 2048 + k * 1024); } while (0)
; #define PG8_MMA(ai, bj, At, Bt) do { __builtin_amdgcn_s_setprio(1); _Pragma("unroll") for (int m = 0; m < 4; ++m) _Pragma("unroll") for (int n = 0; n < 2; ++n) _Pragma("unroll") for (int k = 0; k < 2; ++k) \
;         acc[ai][bj][m][n] = __builtin_amdgcn_mfma_f32_16x16x32_bf16(Bt[n][k], At[m][k], acc[ai][bj][m][n], 0, 0, 0); __builtin_amdgcn_s_setprio(0); } while (0)
; #define PG8_WAIT_V(n) asm volatile("s_waitcnt vmcnt(" #n ")" ::: "memory")
; #define PG8_WAIT_L(n) asm volatile("s_waitcnt lgkmcnt(" #n ")" ::: "memory")
; template <class Epi>
; __device__ __forceinline__ void gemm_phase(LAS unsigned char* lds, const Gemm g, const StaticOrder& S, const Epi& E) {
;     ...
;         for (int t = 0; t < nt; t += 2) {
;             const bool last = (t == nt - 2);
;             const char* a1 = cA + (size_t)(t + 1) * kstep;
;             const char* a2 = last ? nA : cA + (size_t)(t + 2) * kstep; const char* b2 = last ? nB : cB + (size_t)(t + 2) * kstep;
;             const char* a3 = a2 + kstep; const char* b3 = b2 + kstep;
;             PG8_LDB(B0, 0, 0); PG8_LDB(B1, 0, 1); PG8_SCHED; PG8_LDA(At, 0, 0); PG8_STAGE(PG8_SA(1, 1), a1 + hstepA, voffA);
;             PG8_WAIT_V(8); PG8_WAIT_L(0); PG8_BAR; PG8_MMA(0, 0, At, B0); PG8_MMA(0, 1, At, B1); PG8_BAR; PG8_SCHED;
;             PG8_LDA(At, 0, 1); PG8_STAGE(PG8_SB(0, 0), b2, voffB); PG8_STAGE(PG8_SB(0, 1), b2 + hstepB, voffB); PG8_STAGE(PG8_SA(0, 0), a2, voffA);
;             PG8_WAIT_V(8); PG8_WAIT_L(0); PG8_BAR; PG8_MMA(1, 0, At, B0); PG8_MMA(1, 1, At, B1); PG8_BAR; PG8_SCHED;
.LBB0_293:
	ds_read_b128 v[144:147], v190
	ds_read_b128 v[196:199], v190 offset:1024
	ds_read_b128 v[200:203], v190 offset:2048
	ds_read_b128 v[204:207], v190 offset:3072
	ds_read_b128 v[208:211], v192
	ds_read_b128 v[212:215], v192 offset:1024
	ds_read_b128 v[216:219], v192 offset:2048
	ds_read_b128 v[220:223], v192 offset:3072
	s_add_i32 vcc_hi, s16, 2
	s_cmp_eq_u32 s21, s16
	s_cselect_b32 s16, s0, s43
	s_cselect_b32 s17, s1, s71
	s_cselect_b32 s68, s58, s97
	s_cselect_b32 s69, s59, vcc_lo
	s_add_u32 s40, s16, 0x80
	s_addc_u32 s41, s17, 0
	ds_read_b128 v[224:227], v191
	ds_read_b128 v[228:231], v191 offset:1024
	ds_read_b128 v[232:235], v191 offset:2048
	ds_read_b128 v[236:239], v191 offset:3072
	ds_read_b128 v[240:243], v191 offset:4096
	ds_read_b128 v[244:247], v191 offset:5120
	ds_read_b128 v[248:251], v191 offset:6144
	ds_read_b128 v[138:141], v191 offset:7168
	s_mov_b32 s74, m0
	s_mov_b32 m0, s82
	s_nop 0
	global_load_lds_dwordx4 v150, s[62:63]
	s_mov_b32 m0, s74
	s_nop 0
	s_mov_b32 s74, m0
	s_mov_b32 m0, s83
	s_nop 0
	global_load_lds_dwordx4 v153, s[62:63]
	s_mov_b32 m0, s74
	s_waitcnt vmcnt(8)
	s_waitcnt lgkmcnt(0)
	s_barrier
	s_setprio 1
	s_waitcnt lgkmcnt(7)
	v_mfma_f32_16x16x32_bf16 v[128:131], v[144:147], v[224:227], v[128:131]
	v_mfma_f32_16x16x32_bf16 v[124:127], v[200:203], v[224:227], v[124:127]
	s_waitcnt lgkmcnt(5)
	v_mfma_f32_16x16x32_bf16 v[112:115], v[144:147], v[232:235], v[112:115]
	v_mfma_f32_16x16x32_bf16 v[108:111], v[200:203], v[232:235], v[108:111]
	s_waitcnt lgkmcnt(3)
	v_mfma_f32_16x16x32_bf16 v[96:99], v[144:147], v[240:243], v[96:99]
	v_mfma_f32_16x16x32_bf16 v[92:95], v[200:203], v[240:243], v[92:95]
	s_waitcnt lgkmcnt(1)
	v_mfma_f32_16x16x32_bf16 v[80:83], v[144:147], v[248:251], v[80:83]
	v_mfma_f32_16x16x32_bf16 v[76:79], v[200:203], v[248:251], v[76:79]
	v_mfma_f32_16x16x32_bf16 v[128:131], v[196:199], v[228:231], v[128:131]
	v_mfma_f32_16x16x32_bf16 v[124:127], v[204:207], v[228:231], v[124:127]
	v_mfma_f32_16x16x32_bf16 v[112:115], v[196:199], v[236:239], v[112:115]
	v_mfma_f32_16x16x32_bf16 v[108:111], v[204:207], v[236:239], v[108:111]
	v_mfma_f32_16x16x32_bf16 v[96:99], v[196:199], v[244:247], v[96:99]
	v_mfma_f32_16x16x32_bf16 v[92:95], v[204:207], v[244:247], v[92:95]
	s_waitcnt lgkmcnt(0)
	v_mfma_f32_16x16x32_bf16 v[80:83], v[196:199], v[138:141], v[80:83]
	v_mfma_f32_16x16x32_bf16 v[76:79], v[204:207], v[138:141], v[76:79]
	s_setprio 0
	s_setprio 1
	v_mfma_f32_16x16x32_bf16 v[120:123], v[208:211], v[224:227], v[120:123]
	v_mfma_f32_16x16x32_bf16 v[116:119], v[216:219], v[224:227], v[116:119]
	v_mfma_f32_16x16x32_bf16 v[104:107], v[208:211], v[232:235], v[104:107]
	v_mfma_f32_16x16x32_bf16 v[100:103], v[216:219], v[232:235], v[100:103]
	v_mfma_f32_16x16x32_bf16 v[88:91], v[208:211], v[240:243], v[88:91]
	v_mfma_f32_16x16x32_bf16 v[84:87], v[216:219], v[240:243], v[84:87]
	v_mfma_f32_16x16x32_bf16 v[72:75], v[208:211], v[248:251], v[72:75]
	v_mfma_f32_16x16x32_bf16 v[68:71], v[216:219], v[248:251], v[68:71]
	v_mfma_f32_16x16x32_bf16 v[120:123], v[212:215], v[228:231], v[120:123]
	v_mfma_f32_16x16x32_bf16 v[116:119], v[220:223], v[228:231], v[116:119]
	v_mfma_f32_16x16x32_bf16 v[104:107], v[212:215], v[236:239], v[104:107]
	v_mfma_f32_16x16x32_bf16 v[100:103], v[220:223], v[236:239], v[100:103]
	v_mfma_f32_16x16x32_bf16 v[88:91], v[212:215], v[244:247], v[88:91]
	v_mfma_f32_16x16x32_bf16 v[84:87], v[220:223], v[244:247], v[84:87]
	v_mfma_f32_16x16x32_bf16 v[72:75], v[212:215], v[138:141], v[72:75]
	v_mfma_f32_16x16x32_bf16 v[68:71], v[220:223], v[138:141], v[68:71]
	s_setprio 0
	s_barrier
	ds_read_b128 v[138:141], v191 offset:16384
	ds_read_b128 v[224:227], v191 offset:17408
	ds_read_b128 v[228:231], v191 offset:18432
	ds_read_b128 v[232:235], v191 offset:19456
	ds_read_b128 v[236:239], v191 offset:20480
	ds_read_b128 v[240:243], v191 offset:21504
	ds_read_b128 v[244:247], v191 offset:22528
	ds_read_b128 v[248:251], v191 offset:23552
	s_mov_b32 s74, m0
	s_mov_b32 m0, s50
	s_nop 0
	global_load_lds_dwordx4 v151, s[68:69]
	s_mov_b32 m0, s74
	s_nop 0
	s_mov_b32 s74, m0
	s_mov_b32 m0, s51
	s_nop 0
	global_load_lds_dwordx4 v154, s[68:69]
	s_mov_b32 m0, s74
	s_add_u32 s74, s68, 0xb0000
	s_addc_u32 s75, s69, 0
	s_mov_b32 s10, m0
	s_mov_b32 m0, s52
	s_nop 0
	global_load_lds_dwordx4 v151, s[74:75]
	s_mov_b32 m0, s10
	s_nop 0
	s_mov_b32 s10, m0
	s_mov_b32 m0, s53
	s_nop 0
	global_load_lds_dwordx4 v154, s[74:75]
	s_mov_b32 m0, s10
	s_nop 0
	s_mov_b32 s10, m0
	s_mov_b32 m0, s35
	s_nop 0
	global_load_lds_dwordx4 v150, s[16:17]
	s_mov_b32 m0, s10
	s_nop 0
	s_mov_b32 s10, m0
	s_mov_b32 m0, s67
	s_nop 0
	global_load_lds_dwordx4 v153, s[16:17]
	s_mov_b32 m0, s10
	s_waitcnt vmcnt(8)
	s_waitcnt lgkmcnt(0)
	s_barrier
; #define PG8_STAGE(bufoff, gbase, voff) do { _Pragma("unroll") for (int _i = 0; _i < 2; ++_i) { unsigned _keep; \
;         asm volatile("s_mov_b32 %0, m0\n\ts_mov_b32 m0, %1\n\ts_nop 0\n\tglobal_load_lds_dwordx4 %2, %3\n\ts_mov_b32 m0, %0" : "=&s"(_keep) : "s"(ldsb + (unsigned)((bufoff) + _i * 8192)), "v"((voff)[_i]), "s"((const char*)(gbase)) : "memory"); } } while (0)
; #define PG8_LDA(dst, b, h) do { _Pragma("unroll") for (int m = 0; m < 4; ++m) _Pragma("unroll") for (int k = 0; k < 2; ++k) dst[m][k] = *(const LAS bf16x8*)(lds + PG8_SA(b, h) + aoff + m * 2048 + k * 1024); } while (0)
; #define PG8_LDB(dst, b, h) do { _Pragma("unroll") for (int n = 0; n < 2; ++n) _Pragma("unroll") for (int k = 0; k < 2; ++k) dst[n][k] = *(const LAS bf16x8*)(lds + PG8_SB(b, h) + boff + n * 2048 + k * 1024); } while (0)
; #define PG8_MMA(ai, bj, At, Bt) do { __builtin_amdgcn_s_setprio(1); _Pragma("unroll") for (int m = 0; m < 4; ++m) _Pragma("unroll") for (int n = 0; n < 2; ++n) _Pragma("unroll") for (int k = 0; k < 2; ++k) \
;         acc[ai][bj][m][n] = __builtin_amdgcn_mfma_f32_16x16x32_bf16(Bt[n][k], At[m][k], acc[ai][bj][m][n], 0, 0, 0); __builtin_amdgcn_s_setprio(0); } while (0)
; #define PG8_WAIT_V(n) asm volatile("s_waitcnt vmcnt(" #n ")" ::: "memory")
; #define PG8_WAIT_L(n) asm volatile("s_waitcnt lgkmcnt(" #n ")" ::: "memory")
; #define PG8_BAR __builtin_amdgcn_s_barrier()
; #define PG8_SCHED __builtin_amdgcn_sched_barrier(0)
; template <class Epi>
; __device__ __forceinline__ void gemm_phase(LAS unsigned char* lds, const Gemm g, const StaticOrder& S, const Epi& E) {
;     ...
;             PG8_WAIT_V(8); PG8_WAIT_L(0); PG8_BAR; PG8_MMA(1, 0, At, B0); PG8_MMA(1, 1, At, B1); PG8_BAR; PG8_SCHED;
;             PG8_LDB(B0, 1, 0); PG8_LDB(B1, 1, 1); PG8_SCHED; PG8_LDA(At, 1, 0); PG8_STAGE(PG8_SA(0, 1), a2 + hstepA, voffA);
;             PG8_WAIT_V(8); PG8_WAIT_L(0); PG8_BAR; PG8_MMA(0, 0, At, B0); PG8_MMA(0, 1, At, B1); PG8_BAR; PG8_SCHED;
;             PG8_LDA(At, 1, 1); PG8_STAGE(PG8_SB(1, 0), b3, voffB); PG8_STAGE(PG8_SB(1, 1), b3 + hstepB, voffB); PG8_STAGE(PG8_SA(1, 0), a3, voffA);
	s_setprio 1
	s_waitcnt lgkmcnt(7)
	v_mfma_f32_16x16x32_bf16 v[64:67], v[144:147], v[138:141], v[64:67]
	v_mfma_f32_16x16x32_bf16 v[60:63], v[200:203], v[138:141], v[60:63]
	s_waitcnt lgkmcnt(5)
	v_mfma_f32_16x16x32_bf16 v[48:51], v[144:147], v[228:231], v[48:51]
	v_mfma_f32_16x16x32_bf16 v[44:47], v[200:203], v[228:231], v[44:47]
	s_waitcnt lgkmcnt(3)
	v_mfma_f32_16x16x32_bf16 v[32:35], v[144:147], v[236:239], v[32:35]
	v_mfma_f32_16x16x32_bf16 v[28:31], v[200:203], v[236:239], v[28:31]
	s_waitcnt lgkmcnt(1)
	v_mfma_f32_16x16x32_bf16 v[16:19], v[144:147], v[244:247], v[16:19]
	v_mfma_f32_16x16x32_bf16 v[12:15], v[200:203], v[244:247], v[12:15]
	v_mfma_f32_16x16x32_bf16 v[64:67], v[196:199], v[224:227], v[64:67]
	v_mfma_f32_16x16x32_bf16 v[60:63], v[204:207], v[224:227], v[60:63]
	v_mfma_f32_16x16x32_bf16 v[48:51], v[196:199], v[232:235], v[48:51]
	v_mfma_f32_16x16x32_bf16 v[44:47], v[204:207], v[232:235], v[44:47]
	v_mfma_f32_16x16x32_bf16 v[32:35], v[196:199], v[240:243], v[32:35]
	v_mfma_f32_16x16x32_bf16 v[28:31], v[204:207], v[240:243], v[28:31]
	s_waitcnt lgkmcnt(0)
	v_mfma_f32_16x16x32_bf16 v[16:19], v[196:199], v[248:251], v[16:19]
	v_mfma_f32_16x16x32_bf16 v[12:15], v[204:207], v[248:251], v[12:15]
	s_setprio 0
	s_setprio 1
	v_mfma_f32_16x16x32_bf16 v[56:59], v[208:211], v[138:141], v[56:59]
	v_mfma_f32_16x16x32_bf16 v[52:55], v[216:219], v[138:141], v[52:55]
	v_mfma_f32_16x16x32_bf16 v[40:43], v[208:211], v[228:231], v[40:43]
	v_mfma_f32_16x16x32_bf16 v[36:39], v[216:219], v[228:231], v[36:39]
	v_mfma_f32_16x16x32_bf16 v[24:27], v[208:211], v[236:239], v[24:27]
	v_mfma_f32_16x16x32_bf16 v[20:23], v[216:219], v[236:239], v[20:23]
	v_mfma_f32_16x16x32_bf16 v[8:11], v[208:211], v[244:247], v[8:11]
	v_mfma_f32_16x16x32_bf16 v[4:7], v[216:219], v[244:247], v[4:7]
	v_mfma_f32_16x16x32_bf16 v[56:59], v[212:215], v[224:227], v[56:59]
	v_mfma_f32_16x16x32_bf16 v[52:55], v[220:223], v[224:227], v[52:55]
	v_mfma_f32_16x16x32_bf16 v[40:43], v[212:215], v[232:235], v[40:43]
	v_mfma_f32_16x16x32_bf16 v[36:39], v[220:223], v[232:235], v[36:39]
	v_mfma_f32_16x16x32_bf16 v[24:27], v[212:215], v[240:243], v[24:27]
	v_mfma_f32_16x16x32_bf16 v[20:23], v[220:223], v[240:243], v[20:23]
	v_mfma_f32_16x16x32_bf16 v[8:11], v[212:215], v[248:251], v[8:11]
	v_mfma_f32_16x16x32_bf16 v[4:7], v[220:223], v[248:251], v[4:7]
	s_setprio 0
	s_barrier
	v_add_u32_e32 v3, 0x18000, v189
	ds_read_b128 v[138:141], v3
	ds_read_b128 v[144:147], v3 offset:1024
	ds_read_b128 v[196:199], v3 offset:2048
	ds_read_b128 v[200:203], v3 offset:3072
	v_add_u32_e32 v3, 0x1c000, v189
	ds_read_b128 v[204:207], v3
	ds_read_b128 v[208:211], v3 offset:1024
	ds_read_b128 v[212:215], v3 offset:2048
	ds_read_b128 v[216:219], v3 offset:3072
	ds_read_b128 v[220:223], v191 offset:32768
	ds_read_b128 v[224:227], v191 offset:33792
	ds_read_b128 v[228:231], v191 offset:34816
	ds_read_b128 v[232:235], v191 offset:35840
	ds_read_b128 v[236:239], v191 offset:36864
	ds_read_b128 v[240:243], v191 offset:37888
	ds_read_b128 v[244:247], v191 offset:38912
	ds_read_b128 v[248:251], v191 offset:39936
	s_add_u32 s16, s16, 0xb0000
	s_addc_u32 s17, s17, 0
	s_mov_b32 s10, m0
	s_mov_b32 m0, s72
	s_nop 0
	global_load_lds_dwordx4 v150, s[16:17]
	s_mov_b32 m0, s10
	s_nop 0
	s_mov_b32 s10, m0
	s_mov_b32 m0, s73
	s_nop 0
	global_load_lds_dwordx4 v153, s[16:17]
	s_mov_b32 m0, s10
	s_waitcnt vmcnt(8)
	s_waitcnt lgkmcnt(0)
	s_barrier
	s_setprio 1
	s_waitcnt lgkmcnt(7)
	v_mfma_f32_16x16x32_bf16 v[128:131], v[138:141], v[220:223], v[128:131]
	v_mfma_f32_16x16x32_bf16 v[124:127], v[196:199], v[220:223], v[124:127]
	s_waitcnt lgkmcnt(5)
	v_mfma_f32_16x16x32_bf16 v[112:115], v[138:141], v[228:231], v[112:115]
	v_mfma_f32_16x16x32_bf16 v[108:111], v[196:199], v[228:231], v[108:111]
	s_waitcnt lgkmcnt(3)
	v_mfma_f32_16x16x32_bf16 v[96:99], v[138:141], v[236:239], v[96:99]
	v_mfma_f32_16x16x32_bf16 v[92:95], v[196:199], v[236:239], v[92:95]
	s_waitcnt lgkmcnt(1)
	v_mfma_f32_16x16x32_bf16 v[80:83], v[138:141], v[244:247], v[80:83]
	v_mfma_f32_16x16x32_bf16 v[76:79], v[196:199], v[244:247], v[76:79]
	v_mfma_f32_16x16x32_bf16 v[128:131], v[144:147], v[224:227], v[128:131]
	v_mfma_f32_16x16x32_bf16 v[124:127], v[200:203], v[224:227], v[124:127]
	v_mfma_f32_16x16x32_bf16 v[112:115], v[144:147], v[232:235], v[112:115]
	v_mfma_f32_16x16x32_bf16 v[108:111], v[200:203], v[232:235], v[108:111]
	v_mfma_f32_16x16x32_bf16 v[96:99], v[144:147], v[240:243], v[96:99]
	v_mfma_f32_16x16x32_bf16 v[92:95], v[200:203], v[240:243], v[92:95]
	s_waitcnt lgkmcnt(0)
	v_mfma_f32_16x16x32_bf16 v[80:83], v[144:147], v[248:251], v[80:83]
	v_mfma_f32_16x16x32_bf16 v[76:79], v[200:203], v[248:251], v[76:79]
	s_setprio 0
	s_setprio 1
	v_mfma_f32_16x16x32_bf16 v[120:123], v[204:207], v[220:223], v[120:123]
	v_mfma_f32_16x16x32_bf16 v[116:119], v[212:215], v[220:223], v[116:119]
	v_mfma_f32_16x16x32_bf16 v[104:107], v[204:207], v[228:231], v[104:107]
	v_mfma_f32_16x16x32_bf16 v[100:103], v[212:215], v[228:231], v[100:103]
	v_mfma_f32_16x16x32_bf16 v[88:91], v[204:207], v[236:239], v[88:91]
	v_mfma_f32_16x16x32_bf16 v[84:87], v[212:215], v[236:239], v[84:87]
	v_mfma_f32_16x16x32_bf16 v[72:75], v[204:207], v[244:247], v[72:75]
	v_mfma_f32_16x16x32_bf16 v[68:71], v[212:215], v[244:247], v[68:71]
	v_mfma_f32_16x16x32_bf16 v[120:123], v[208:211], v[224:227], v[120:123]
	v_mfma_f32_16x16x32_bf16 v[116:119], v[216:219], v[224:227], v[116:119]
	v_mfma_f32_16x16x32_bf16 v[104:107], v[208:211], v[232:235], v[104:107]
	v_mfma_f32_16x16x32_bf16 v[100:103], v[216:219], v[232:235], v[100:103]
	v_mfma_f32_16x16x32_bf16 v[88:91], v[208:211], v[240:243], v[88:91]
	v_mfma_f32_16x16x32_bf16 v[84:87], v[216:219], v[240:243], v[84:87]
	v_mfma_f32_16x16x32_bf16 v[72:75], v[208:211], v[248:251], v[72:75]
	v_mfma_f32_16x16x32_bf16 v[68:71], v[216:219], v[248:251], v[68:71]
	s_setprio 0
	s_barrier
; #define PG8_STAGE(bufoff, gbase, voff) do { _Pragma("unroll") for (int _i = 0; _i < 2; ++_i) { unsigned _keep; \
;         asm volatile("s_mov_b32 %0, m0\n\ts_mov_b32 m0, %1\n\ts_nop 0\n\tglobal_load_lds_dwordx4 %2, %3\n\ts_mov_b32 m0, %0" : "=&s"(_keep) : "s"(ldsb + (unsigned)((bufoff) + _i * 8192)), "v"((voff)[_i]), "s"((const char*)(gbase)) : "memory"); } } while (0)
; #define PG8_LDA(dst, b, h) do { _Pragma("unroll") for (int m = 0; m < 4; ++m) _Pragma("unroll") for (int k = 0; k < 2; ++k) dst[m][k] = *(const LAS bf16x8*)(lds + PG8_SA(b, h) + aoff + m * 2048 + k * 1024); } while (0)
; #define PG8_MMA(ai, bj, At, Bt) do { __builtin_amdgcn_s_setprio(1); _Pragma("unroll") for (int m = 0; m < 4; ++m) _Pragma("unroll") for (int n = 0; n < 2; ++n) _Pragma("unroll") for (int k = 0; k < 2; ++k) \
;         acc[ai][bj][m][n] = __builtin_amdgcn_mfma_f32_16x16x32_bf16(Bt[n][k], At[m][k], acc[ai][bj][m][n], 0, 0, 0); __builtin_amdgcn_s_setprio(0); } while (0)
; #define PG8_WAIT_V(n) asm volatile("s_waitcnt vmcnt(" #n ")" ::: "memory")
; #define PG8_WAIT_L(n) asm volatile("s_waitcnt lgkmcnt(" #n ")" ::: "memory")
; #define PG8_BAR __builtin_amdgcn_s_barrier()
; #define PG8_SCHED __builtin_amdgcn_sched_barrier(0)
; template <class Epi>
; __device__ __forceinline__ void gemm_phase(LAS unsigned char* lds, const Gemm g, const StaticOrder& S, const Epi& E) {
;     ...
;             PG8_LDA(At, 1, 1); PG8_STAGE(PG8_SB(1, 0), b3, voffB); PG8_STAGE(PG8_SB(1, 1), b3 + hstepB, voffB); PG8_STAGE(PG8_SA(1, 0), a3, voffA);
;             PG8_WAIT_V(8); PG8_WAIT_L(0); PG8_BAR; PG8_MMA(1, 0, At, B0); PG8_MMA(1, 1, At, B1); PG8_BAR; PG8_SCHED;
;         }
;         if (wr == 0) PG8_BAR;
;         bool run_epi = true;
	ds_read_b128 v[220:223], v191 offset:49152
	ds_read_b128 v[224:227], v191 offset:50176
	ds_read_b128 v[228:231], v191 offset:51200
	ds_read_b128 v[232:235], v191 offset:52224
	ds_read_b128 v[236:239], v191 offset:53248
	ds_read_b128 v[240:243], v191 offset:54272
	ds_read_b128 v[244:247], v191 offset:55296
	ds_read_b128 v[248:251], v191 offset:56320
	s_add_u32 s16, s68, 0x80
	s_addc_u32 s17, s69, 0
	s_mov_b32 s10, m0
	s_mov_b32 m0, s76
	s_nop 0
	global_load_lds_dwordx4 v151, s[16:17]
	s_mov_b32 m0, s10
	s_nop 0
	s_mov_b32 s10, m0
	s_mov_b32 m0, s77
	s_nop 0
	global_load_lds_dwordx4 v154, s[16:17]
	s_mov_b32 m0, s10
	s_add_u32 s16, s68, 0xb0080
	s_addc_u32 s17, s69, 0
	s_mov_b32 s10, m0
	s_mov_b32 m0, s80
	s_nop 0
	global_load_lds_dwordx4 v151, s[16:17]
	s_mov_b32 m0, s10
	s_nop 0
	s_mov_b32 s10, m0
	s_mov_b32 m0, s81
	s_nop 0
	global_load_lds_dwordx4 v154, s[16:17]
	s_mov_b32 m0, s10
	s_nop 0
	s_mov_b32 s10, m0
	s_mov_b32 m0, s78
	s_nop 0
	global_load_lds_dwordx4 v150, s[40:41]
	s_mov_b32 m0, s10
	s_nop 0
	s_mov_b32 s10, m0
	s_mov_b32 m0, s79
	s_nop 0
	global_load_lds_dwordx4 v153, s[40:41]
	s_mov_b32 m0, s10
	s_waitcnt vmcnt(8)
	s_waitcnt lgkmcnt(0)
	s_barrier
	s_setprio 1
	s_waitcnt lgkmcnt(7)
	v_mfma_f32_16x16x32_bf16 v[64:67], v[138:141], v[220:223], v[64:67]
	v_mfma_f32_16x16x32_bf16 v[60:63], v[196:199], v[220:223], v[60:63]
	s_waitcnt lgkmcnt(5)
	v_mfma_f32_16x16x32_bf16 v[48:51], v[138:141], v[228:231], v[48:51]
	v_mfma_f32_16x16x32_bf16 v[44:47], v[196:199], v[228:231], v[44:47]
	s_waitcnt lgkmcnt(3)
	v_mfma_f32_16x16x32_bf16 v[32:35], v[138:141], v[236:239], v[32:35]
	v_mfma_f32_16x16x32_bf16 v[28:31], v[196:199], v[236:239], v[28:31]
	s_waitcnt lgkmcnt(1)
	v_mfma_f32_16x16x32_bf16 v[16:19], v[138:141], v[244:247], v[16:19]
	v_mfma_f32_16x16x32_bf16 v[12:15], v[196:199], v[244:247], v[12:15]
	v_mfma_f32_16x16x32_bf16 v[64:67], v[144:147], v[224:227], v[64:67]
	v_mfma_f32_16x16x32_bf16 v[60:63], v[200:203], v[224:227], v[60:63]
	v_mfma_f32_16x16x32_bf16 v[48:51], v[144:147], v[232:235], v[48:51]
	v_mfma_f32_16x16x32_bf16 v[44:47], v[200:203], v[232:235], v[44:47]
	v_mfma_f32_16x16x32_bf16 v[32:35], v[144:147], v[240:243], v[32:35]
	v_mfma_f32_16x16x32_bf16 v[28:31], v[200:203], v[240:243], v[28:31]
	s_waitcnt lgkmcnt(0)
	v_mfma_f32_16x16x32_bf16 v[16:19], v[144:147], v[248:251], v[16:19]
	v_mfma_f32_16x16x32_bf16 v[12:15], v[200:203], v[248:251], v[12:15]
	s_setprio 0
	s_setprio 1
	v_mfma_f32_16x16x32_bf16 v[56:59], v[204:207], v[220:223], v[56:59]
	v_mfma_f32_16x16x32_bf16 v[52:55], v[212:215], v[220:223], v[52:55]
	v_mfma_f32_16x16x32_bf16 v[40:43], v[204:207], v[228:231], v[40:43]
	v_mfma_f32_16x16x32_bf16 v[36:39], v[212:215], v[228:231], v[36:39]
	v_mfma_f32_16x16x32_bf16 v[24:27], v[204:207], v[236:239], v[24:27]
	v_mfma_f32_16x16x32_bf16 v[20:23], v[212:215], v[236:239], v[20:23]
	v_mfma_f32_16x16x32_bf16 v[8:11], v[204:207], v[244:247], v[8:11]
	v_mfma_f32_16x16x32_bf16 v[4:7], v[212:215], v[244:247], v[4:7]
	v_mfma_f32_16x16x32_bf16 v[56:59], v[208:211], v[224:227], v[56:59]
	v_mfma_f32_16x16x32_bf16 v[52:55], v[216:219], v[224:227], v[52:55]
	v_mfma_f32_16x16x32_bf16 v[40:43], v[208:211], v[232:235], v[40:43]
	v_mfma_f32_16x16x32_bf16 v[36:39], v[216:219], v[232:235], v[36:39]
	v_mfma_f32_16x16x32_bf16 v[24:27], v[208:211], v[240:243], v[24:27]
	v_mfma_f32_16x16x32_bf16 v[20:23], v[216:219], v[240:243], v[20:23]
	v_mfma_f32_16x16x32_bf16 v[8:11], v[208:211], v[248:251], v[8:11]
	v_mfma_f32_16x16x32_bf16 v[4:7], v[216:219], v[248:251], v[4:7]
	s_setprio 0
	s_add_u32 s43, s43, 0x100
	s_addc_u32 s71, s71, 0
	s_add_u32 s97, s97, 0x100
	s_addc_u32 vcc_lo, vcc_lo, 0
	s_add_u32 s62, s62, 0x100
	s_addc_u32 s63, s63, 0
	s_cmp_ge_i32 vcc_hi, s70
	s_mov_b32 s16, vcc_hi
	s_barrier
	s_cbranch_scc0 .LBB0_293
	s_and_b64 vcc, exec, s[12:13]
	s_cbranch_vccz .LBB0_296

; #define EPI_ROWS(...) _Pragma("unroll") for (int ai = 0; ai < 2; ++ai) _Pragma("unroll") for (int m = 0; m < 4; ++m) { const int row = row0 + ai * 128 + m * 16; __VA_ARGS__ __builtin_amdgcn_sched_barrier(0); }
; __device__ __forceinline__ u32x4 pack8(f32x4 a, f32x4 b) { u32x4 w; w.x = pk2(a[0], a[1]); w.y = pk2(a[2], a[3]); w.z = pk2(b[0], b[1]); w.w = pk2(b[2], b[3]); return w; }
; __device__ __forceinline__ float dot8(f32x4 a, f32x4 b) { return (a[0] * a[0] + a[1] * a[1]) + (a[2] * a[2] + a[3] * a[3]) + (b[0] * b[0] + b[1] * b[1]) + (b[2] * b[2] + b[3] * b[3]); }
; __device__ __forceinline__ float red_fq(float s) { s += __shfl_xor(s, 16); s += __shfl_xor(s, 32); return s; }
;     __device__ __forceinline__ void operator()(AccRef acc, const Unit& u, int wr, int wc, int fr, int fq) const {
;         const int row0 = u.pm * 256 + wr * 64 + fr, col0 = u.pn * 256 + wc * 32 + 8 * fq;
;         EPI_ROWS(
;             const float* rp = (row < MP) ? res0 + (size_t)row * DM : res1 + (size_t)(row - MP) * DM;
;             float s = 0.f;
;             _Pragma("unroll") for (int bj = 0; bj < 2; ++bj) { const int col = col0 + bj * 128;
;                 f32x4 v0 = *(const f32x4*)(rp + col) + acc[ai][bj][m][0] * scale, v1 = *(const f32x4*)(rp + col + 4) + acc[ai][bj][m][1] * scale;
;                 *(f32x4*)(out + (size_t)row * DM + col) = v0; *(f32x4*)(out + (size_t)row * DM + col + 4) = v1;
;                 if (WB) *(u32x4*)(ob + (size_t)row * DM + col) = pack8(v0, v1);
;                 s += dot8(v0, v1); }
;             s = red_fq(s); if (fq == 0) unsafeAtomicAdd(ss + row, s);
;         )
.LBB0_312:
	v_lshl_add_u32 v144, s96, 8, v155
	v_cmp_lt_i32_e32 vcc, s91, v144
	s_and_saveexec_b64 s[16:17], vcc
	s_xor_b64 s[16:17], exec, s[16:17]
	v_add_u32_e32 v138, 0xffff8000, v144
	v_mov_b32_e32 v139, v2
	v_lshlrev_b64 v[138:139], 12, v[138:139]
	v_lshl_add_u64 v[148:149], s[38:39], 0, v[138:139]
	v_mov_b32_e32 v145, v2
	s_andn2_saveexec_b64 s[16:17], s[16:17]
	v_ashrrev_i32_e32 v145, 31, v144
	v_lshlrev_b64 v[138:139], 12, v[144:145]
	v_lshl_add_u64 v[148:149], s[36:37], 0, v[138:139]
	s_or_b64 exec, exec, s[16:17]
	v_and_b32_e32 v138, 64, v193
	v_lshl_or_b32 v142, s95, 8, v188
	v_xor_b32_e32 v3, 16, v193
	v_add_u32_e32 v138, 64, v138
	v_cmp_lt_i32_e32 vcc, v3, v138
	v_ashrrev_i32_e32 v143, 31, v142
	v_lshlrev_b64 v[146:147], 2, v[142:143]
	v_cndmask_b32_e32 v3, v193, v3, vcc
	v_lshlrev_b32_e32 v195, 2, v3
	v_xor_b32_e32 v3, 32, v193
	v_lshl_add_u64 v[148:149], v[148:149], 0, v[146:147]
	v_cmp_lt_i32_e32 vcc, v3, v138
	global_load_dwordx4 v[138:141], v[148:149], off offset:16
	global_load_dwordx4 v[196:199], v[148:149], off
	global_load_dwordx4 v[216:219], v[148:149], off offset:528
	global_load_dwordx4 v[220:223], v[148:149], off offset:512
	v_cndmask_b32_e32 v3, v193, v3, vcc
	v_lshlrev_b32_e32 v3, 2, v3
	s_waitcnt vmcnt(3)
	v_pk_fma_f32 v[140:141], v[126:127], 0.5, v[140:141] op_sel_hi:[1,0,1]
	v_lshlrev_b64 v[126:127], 11, v[144:145]
	s_waitcnt vmcnt(2)
	v_pk_fma_f32 v[130:131], v[130:131], 0.5, v[198:199] op_sel_hi:[1,0,1]
	v_pk_fma_f32 v[128:129], v[128:129], 0.5, v[196:197] op_sel_hi:[1,0,1]
	v_lshl_add_u64 v[126:127], s[18:19], 0, v[126:127]
	v_lshl_add_u64 v[200:201], v[142:143], 1, v[126:127]
	v_mul_f32_e32 v126, v129, v129
	v_mul_f32_e32 v127, v131, v131
	v_pk_fma_f32 v[138:139], v[124:125], 0.5, v[138:139] op_sel_hi:[1,0,1]
	v_fmac_f32_e32 v126, v128, v128
	v_fmac_f32_e32 v127, v130, v130
	v_lshlrev_b64 v[124:125], 12, v[144:145]
	v_add_f32_e32 v126, v126, v127
	v_mul_f32_e32 v127, v139, v139
	v_lshl_add_u64 v[124:125], s[30:31], 0, v[124:125]
	v_fmac_f32_e32 v127, v138, v138
	v_lshl_add_u64 v[124:125], v[124:125], 0, v[146:147]
	v_cvt_pk_bf16_f32 v196, v128, v129
	v_cvt_pk_bf16_f32 v197, v130, v131
	v_cvt_pk_bf16_f32 v198, v138, v139
	v_cvt_pk_bf16_f32 v199, v140, v141
	v_add_f32_e32 v126, v127, v126
	v_mul_f32_e32 v127, v141, v141
	global_store_dwordx4 v[124:125], v[128:131], off
	global_store_dwordx4 v[124:125], v[138:141], off offset:16
	global_store_dwordx4 v[200:201], v[196:199], off
	v_fmac_f32_e32 v127, v140, v140
	v_add_f32_e32 v130, v127, v126
	s_nop 0
	s_nop 0
	s_waitcnt vmcnt(4)
	v_pk_fma_f32 v[118:119], v[118:119], 0.5, v[218:219] op_sel_hi:[1,0,1]
	s_waitcnt vmcnt(3)
	v_pk_fma_f32 v[122:123], v[122:123], 0.5, v[222:223] op_sel_hi:[1,0,1]
	v_pk_fma_f32 v[120:121], v[120:121], 0.5, v[220:221] op_sel_hi:[1,0,1]
	v_pk_fma_f32 v[116:117], v[116:117], 0.5, v[216:217] op_sel_hi:[1,0,1]
	global_store_dwordx4 v[124:125], v[120:123], off offset:512
	global_store_dwordx4 v[124:125], v[116:119], off offset:528
	v_cvt_pk_bf16_f32 v124, v120, v121
	v_mul_f32_e32 v121, v121, v121
	v_fmac_f32_e32 v121, v120, v120
	v_mul_f32_e32 v120, v123, v123
	v_cvt_pk_bf16_f32 v126, v116, v117
	v_fmac_f32_e32 v120, v122, v122
	v_mul_f32_e32 v117, v117, v117
	v_add_f32_e32 v120, v121, v120
	v_fmac_f32_e32 v117, v116, v116
	v_add_f32_e32 v116, v117, v120
	v_mul_f32_e32 v117, v119, v119
	v_fmac_f32_e32 v117, v118, v118
	v_add_f32_e32 v116, v117, v116
	v_add_f32_e32 v116, v130, v116
	v_mov_b32_e32 v117, v116
	v_cvt_pk_bf16_f32 v125, v122, v123
	v_cvt_pk_bf16_f32 v127, v118, v119
	global_store_dwordx4 v[200:201], v[124:127], off offset:256
	v_permlane16_swap_b32_e32 v116, v117
	v_add_f32_e32 v116, v116, v117
	v_mov_b32_e32 v117, v116
	s_nop 1
	v_permlane32_swap_b32_e32 v116, v117
	s_and_saveexec_b64 s[16:17], s[6:7]
	s_cbranch_execz .LBB0_318
	s_waitcnt lgkmcnt(0)
	v_add_f32_e32 v118, v116, v117
	v_lshl_add_u64 v[116:117], v[144:145], 2, s[84:85]
	v_mov_b32_e32 v224, v116
	v_mov_b32_e32 v225, v117
	v_mov_b32_e32 v226, v118
.LBB0_318:
	s_or_b64 exec, exec, s[16:17]
	s_waitcnt lgkmcnt(0)
	v_or_b32_e32 v116, 16, v144
	v_cmp_lt_i32_e32 vcc, s91, v116
	s_and_saveexec_b64 s[16:17], vcc
	s_xor_b64 s[16:17], exec, s[16:17]
	v_add_u32_e32 v118, 0xffff8010, v144
	v_mov_b32_e32 v119, v2
	v_lshlrev_b64 v[118:119], 12, v[118:119]
	v_lshl_add_u64 v[118:119], s[38:39], 0, v[118:119]
	v_mov_b32_e32 v117, v2
	s_andn2_saveexec_b64 s[16:17], s[16:17]
	v_ashrrev_i32_e32 v117, 31, v116
	v_lshlrev_b64 v[118:119], 12, v[116:117]
	v_lshl_add_u64 v[118:119], s[36:37], 0, v[118:119]
	s_or_b64 exec, exec, s[16:17]
	v_lshl_add_u64 v[126:127], v[118:119], 0, v[146:147]
	global_load_dwordx4 v[118:121], v[126:127], off offset:16
	global_load_dwordx4 v[122:125], v[126:127], off
	global_load_dwordx4 v[216:219], v[126:127], off offset:528
	global_load_dwordx4 v[220:223], v[126:127], off offset:512
	s_waitcnt vmcnt(3)
	v_pk_fma_f32 v[108:109], v[108:109], 0.5, v[118:119] op_sel_hi:[1,0,1]
	v_lshlrev_b64 v[118:119], 12, v[116:117]
	v_lshl_add_u64 v[118:119], s[30:31], 0, v[118:119]
	s_waitcnt vmcnt(2)
	v_pk_fma_f32 v[114:115], v[114:115], 0.5, v[124:125] op_sel_hi:[1,0,1]
	v_pk_fma_f32 v[112:113], v[112:113], 0.5, v[122:123] op_sel_hi:[1,0,1]
	v_lshl_add_u64 v[122:123], v[118:119], 0, v[146:147]
	v_pk_fma_f32 v[110:111], v[110:111], 0.5, v[120:121] op_sel_hi:[1,0,1]
	global_store_dwordx4 v[122:123], v[112:115], off
	global_store_dwordx4 v[122:123], v[108:111], off offset:16
	v_cvt_pk_bf16_f32 v118, v112, v113
	v_mul_f32_e32 v113, v113, v113
	v_fmac_f32_e32 v113, v112, v112
	v_mul_f32_e32 v112, v115, v115
	v_cvt_pk_bf16_f32 v120, v108, v109
	v_lshlrev_b64 v[124:125], 11, v[116:117]
	v_fmac_f32_e32 v112, v114, v114
	v_mul_f32_e32 v109, v109, v109
	v_lshl_add_u64 v[124:125], s[18:19], 0, v[124:125]
	v_add_f32_e32 v112, v113, v112
	v_fmac_f32_e32 v109, v108, v108
	v_cvt_pk_bf16_f32 v119, v114, v115
	v_cvt_pk_bf16_f32 v121, v110, v111
	v_lshl_add_u64 v[124:125], v[142:143], 1, v[124:125]
	v_add_f32_e32 v108, v109, v112
	v_mul_f32_e32 v109, v111, v111
	global_store_dwordx4 v[124:125], v[118:121], off
	v_fmac_f32_e32 v109, v110, v110
	s_nop 0
	v_add_f32_e32 v118, v109, v108
	s_nop 0
	s_nop 0
	s_waitcnt vmcnt(4)
; #define EPI_ROWS(...) _Pragma("unroll") for (int ai = 0; ai < 2; ++ai) _Pragma("unroll") for (int m = 0; m < 4; ++m) { const int row = row0 + ai * 128 + m * 16; __VA_ARGS__ __builtin_amdgcn_sched_barrier(0); }
; __device__ __forceinline__ u32x4 pack8(f32x4 a, f32x4 b) { u32x4 w; w.x = pk2(a[0], a[1]); w.y = pk2(a[2], a[3]); w.z = pk2(b[0], b[1]); w.w = pk2(b[2], b[3]); return w; }
; __device__ __forceinline__ float dot8(f32x4 a, f32x4 b) { return (a[0] * a[0] + a[1] * a[1]) + (a[2] * a[2] + a[3] * a[3]) + (b[0] * b[0] + b[1] * b[1]) + (b[2] * b[2] + b[3] * b[3]); }
; __device__ __forceinline__ float red_fq(float s) { s += __shfl_xor(s, 16); s += __shfl_xor(s, 32); return s; }
;     __device__ __forceinline__ void operator()(AccRef acc, const Unit& u, int wr, int wc, int fr, int fq) const {
;         const int row0 = u.pm * 256 + wr * 64 + fr, col0 = u.pn * 256 + wc * 32 + 8 * fq;
;         EPI_ROWS(
;             const float* rp = (row < MP) ? res0 + (size_t)row * DM : res1 + (size_t)(row - MP) * DM;
;             float s = 0.f;
;             _Pragma("unroll") for (int bj = 0; bj < 2; ++bj) { const int col = col0 + bj * 128;
;                 f32x4 v0 = *(const f32x4*)(rp + col) + acc[ai][bj][m][0] * scale, v1 = *(const f32x4*)(rp + col + 4) + acc[ai][bj][m][1] * scale;
;                 *(f32x4*)(out + (size_t)row * DM + col) = v0; *(f32x4*)(out + (size_t)row * DM + col + 4) = v1;
;                 if (WB) *(u32x4*)(ob + (size_t)row * DM + col) = pack8(v0, v1);
;                 s += dot8(v0, v1); }
;             s = red_fq(s); if (fq == 0) unsafeAtomicAdd(ss + row, s);
;         )
	v_pk_fma_f32 v[102:103], v[102:103], 0.5, v[218:219] op_sel_hi:[1,0,1]
	s_waitcnt vmcnt(3)
	v_pk_fma_f32 v[106:107], v[106:107], 0.5, v[222:223] op_sel_hi:[1,0,1]
	v_pk_fma_f32 v[104:105], v[104:105], 0.5, v[220:221] op_sel_hi:[1,0,1]
	v_pk_fma_f32 v[100:101], v[100:101], 0.5, v[216:217] op_sel_hi:[1,0,1]
	global_store_dwordx4 v[122:123], v[104:107], off offset:512
	global_store_dwordx4 v[122:123], v[100:103], off offset:528
	v_cvt_pk_bf16_f32 v108, v104, v105
	v_mul_f32_e32 v105, v105, v105
	v_fmac_f32_e32 v105, v104, v104
	v_mul_f32_e32 v104, v107, v107
	v_cvt_pk_bf16_f32 v110, v100, v101
	v_fmac_f32_e32 v104, v106, v106
	v_mul_f32_e32 v101, v101, v101
	v_add_f32_e32 v104, v105, v104
	v_fmac_f32_e32 v101, v100, v100
	v_add_f32_e32 v100, v101, v104
	v_mul_f32_e32 v101, v103, v103
	v_fmac_f32_e32 v101, v102, v102
	v_add_f32_e32 v100, v101, v100
	v_add_f32_e32 v100, v118, v100
	v_mov_b32_e32 v101, v100
	v_cvt_pk_bf16_f32 v109, v106, v107
	v_cvt_pk_bf16_f32 v111, v102, v103
	global_store_dwordx4 v[124:125], v[108:111], off offset:256
	v_permlane16_swap_b32_e32 v100, v101
	v_add_f32_e32 v100, v100, v101
	v_mov_b32_e32 v101, v100
	s_nop 1
	v_permlane32_swap_b32_e32 v100, v101
	s_and_saveexec_b64 s[16:17], s[6:7]
	s_cbranch_execz .LBB0_324
	s_waitcnt lgkmcnt(0)
	v_add_f32_e32 v102, v100, v101
	v_lshl_add_u64 v[100:101], v[116:117], 2, s[84:85]
	v_mov_b32_e32 v228, v100
	v_mov_b32_e32 v229, v101
	v_mov_b32_e32 v230, v102
.LBB0_324:
	s_or_b64 exec, exec, s[16:17]
	s_waitcnt lgkmcnt(0)
	v_or_b32_e32 v100, 32, v144
	v_cmp_lt_i32_e32 vcc, s91, v100
	s_and_saveexec_b64 s[16:17], vcc
	s_xor_b64 s[16:17], exec, s[16:17]
	v_add_u32_e32 v102, 0xffff8020, v144
	v_mov_b32_e32 v103, v2
	v_lshlrev_b64 v[102:103], 12, v[102:103]
	v_lshl_add_u64 v[102:103], s[38:39], 0, v[102:103]
	v_mov_b32_e32 v101, v2
	s_andn2_saveexec_b64 s[16:17], s[16:17]
	v_ashrrev_i32_e32 v101, 31, v100
	v_lshlrev_b64 v[102:103], 12, v[100:101]
	v_lshl_add_u64 v[102:103], s[36:37], 0, v[102:103]
	s_or_b64 exec, exec, s[16:17]
	v_lshl_add_u64 v[110:111], v[102:103], 0, v[146:147]
	global_load_dwordx4 v[102:105], v[110:111], off offset:16
	global_load_dwordx4 v[106:109], v[110:111], off
	global_load_dwordx4 v[216:219], v[110:111], off offset:528
	global_load_dwordx4 v[220:223], v[110:111], off offset:512
	s_waitcnt vmcnt(3)
	v_pk_fma_f32 v[92:93], v[92:93], 0.5, v[102:103] op_sel_hi:[1,0,1]
	v_lshlrev_b64 v[102:103], 12, v[100:101]
	v_lshl_add_u64 v[102:103], s[30:31], 0, v[102:103]
	s_waitcnt vmcnt(2)
	v_pk_fma_f32 v[98:99], v[98:99], 0.5, v[108:109] op_sel_hi:[1,0,1]
	v_pk_fma_f32 v[96:97], v[96:97], 0.5, v[106:107] op_sel_hi:[1,0,1]
	v_lshl_add_u64 v[106:107], v[102:103], 0, v[146:147]
	v_pk_fma_f32 v[94:95], v[94:95], 0.5, v[104:105] op_sel_hi:[1,0,1]
	global_store_dwordx4 v[106:107], v[96:99], off
	global_store_dwordx4 v[106:107], v[92:95], off offset:16
	v_cvt_pk_bf16_f32 v102, v96, v97
	v_mul_f32_e32 v97, v97, v97
	v_fmac_f32_e32 v97, v96, v96
	v_mul_f32_e32 v96, v99, v99
	v_cvt_pk_bf16_f32 v104, v92, v93
	v_lshlrev_b64 v[108:109], 11, v[100:101]
	v_fmac_f32_e32 v96, v98, v98
	v_mul_f32_e32 v93, v93, v93
	v_lshl_add_u64 v[108:109], s[18:19], 0, v[108:109]
	v_add_f32_e32 v96, v97, v96
	v_fmac_f32_e32 v93, v92, v92
	v_cvt_pk_bf16_f32 v103, v98, v99
	v_cvt_pk_bf16_f32 v105, v94, v95
	v_lshl_add_u64 v[108:109], v[142:143], 1, v[108:109]
	v_add_f32_e32 v92, v93, v96
	v_mul_f32_e32 v93, v95, v95
	global_store_dwordx4 v[108:109], v[102:105], off
	v_fmac_f32_e32 v93, v94, v94
	s_nop 0
	v_add_f32_e32 v102, v93, v92
	s_nop 0
	s_nop 0
	s_waitcnt vmcnt(4)
	v_pk_fma_f32 v[86:87], v[86:87], 0.5, v[218:219] op_sel_hi:[1,0,1]
	s_waitcnt vmcnt(3)
	v_pk_fma_f32 v[90:91], v[90:91], 0.5, v[222:223] op_sel_hi:[1,0,1]
	v_pk_fma_f32 v[88:89], v[88:89], 0.5, v[220:221] op_sel_hi:[1,0,1]
	v_pk_fma_f32 v[84:85], v[84:85], 0.5, v[216:217] op_sel_hi:[1,0,1]
	global_store_dwordx4 v[106:107], v[88:91], off offset:512
	global_store_dwordx4 v[106:107], v[84:87], off offset:528
	v_cvt_pk_bf16_f32 v92, v88, v89
	v_mul_f32_e32 v89, v89, v89
	v_fmac_f32_e32 v89, v88, v88
	v_mul_f32_e32 v88, v91, v91
	v_cvt_pk_bf16_f32 v94, v84, v85
	v_fmac_f32_e32 v88, v90, v90
	v_mul_f32_e32 v85, v85, v85
	v_add_f32_e32 v88, v89, v88
	v_fmac_f32_e32 v85, v84, v84
	v_add_f32_e32 v84, v85, v88
	v_mul_f32_e32 v85, v87, v87
	v_fmac_f32_e32 v85, v86, v86
	v_add_f32_e32 v84, v85, v84
	v_add_f32_e32 v84, v102, v84
	v_mov_b32_e32 v85, v84
	v_cvt_pk_bf16_f32 v93, v90, v91
	v_cvt_pk_bf16_f32 v95, v86, v87
	global_store_dwordx4 v[108:109], v[92:95], off offset:256
	v_permlane16_swap_b32_e32 v84, v85
	v_add_f32_e32 v84, v84, v85
	v_mov_b32_e32 v85, v84
	s_nop 1
	v_permlane32_swap_b32_e32 v84, v85
	s_and_saveexec_b64 s[16:17], s[6:7]
	s_cbranch_execz .LBB0_330
	s_waitcnt lgkmcnt(0)
	v_add_f32_e32 v86, v84, v85
	v_lshl_add_u64 v[84:85], v[100:101], 2, s[84:85]
	v_mov_b32_e32 v232, v84
	v_mov_b32_e32 v233, v85
	v_mov_b32_e32 v234, v86
; #define EPI_ROWS(...) _Pragma("unroll") for (int ai = 0; ai < 2; ++ai) _Pragma("unroll") for (int m = 0; m < 4; ++m) { const int row = row0 + ai * 128 + m * 16; __VA_ARGS__ __builtin_amdgcn_sched_barrier(0); }
; __device__ __forceinline__ u32x4 pack8(f32x4 a, f32x4 b) { u32x4 w; w.x = pk2(a[0], a[1]); w.y = pk2(a[2], a[3]); w.z = pk2(b[0], b[1]); w.w = pk2(b[2], b[3]); return w; }
; __device__ __forceinline__ float dot8(f32x4 a, f32x4 b) { return (a[0] * a[0] + a[1] * a[1]) + (a[2] * a[2] + a[3] * a[3]) + (b[0] * b[0] + b[1] * b[1]) + (b[2] * b[2] + b[3] * b[3]); }
; __device__ __forceinline__ float red_fq(float s) { s += __shfl_xor(s, 16); s += __shfl_xor(s, 32); return s; }
;     __device__ __forceinline__ void operator()(AccRef acc, const Unit& u, int wr, int wc, int fr, int fq) const {
;         const int row0 = u.pm * 256 + wr * 64 + fr, col0 = u.pn * 256 + wc * 32 + 8 * fq;
;         EPI_ROWS(
;             const float* rp = (row < MP) ? res0 + (size_t)row * DM : res1 + (size_t)(row - MP) * DM;
;             float s = 0.f;
;             _Pragma("unroll") for (int bj = 0; bj < 2; ++bj) { const int col = col0 + bj * 128;
;                 f32x4 v0 = *(const f32x4*)(rp + col) + acc[ai][bj][m][0] * scale, v1 = *(const f32x4*)(rp + col + 4) + acc[ai][bj][m][1] * scale;
;                 *(f32x4*)(out + (size_t)row * DM + col) = v0; *(f32x4*)(out + (size_t)row * DM + col + 4) = v1;
;                 if (WB) *(u32x4*)(ob + (size_t)row * DM + col) = pack8(v0, v1);
;                 s += dot8(v0, v1); }
;             s = red_fq(s); if (fq == 0) unsafeAtomicAdd(ss + row, s);
;         )
.LBB0_330:
	s_or_b64 exec, exec, s[16:17]
	s_waitcnt lgkmcnt(0)
	v_or_b32_e32 v84, 48, v144
	v_cmp_lt_i32_e32 vcc, s91, v84
	s_and_saveexec_b64 s[16:17], vcc
	s_xor_b64 s[16:17], exec, s[16:17]
	v_add_u32_e32 v86, 0xffff8030, v144
	v_mov_b32_e32 v87, v2
	v_lshlrev_b64 v[86:87], 12, v[86:87]
	v_lshl_add_u64 v[86:87], s[38:39], 0, v[86:87]
	v_mov_b32_e32 v85, v2
	s_andn2_saveexec_b64 s[16:17], s[16:17]
	v_ashrrev_i32_e32 v85, 31, v84
	v_lshlrev_b64 v[86:87], 12, v[84:85]
	v_lshl_add_u64 v[86:87], s[36:37], 0, v[86:87]
	s_or_b64 exec, exec, s[16:17]
	v_lshl_add_u64 v[94:95], v[86:87], 0, v[146:147]
	global_load_dwordx4 v[86:89], v[94:95], off offset:16
	global_load_dwordx4 v[90:93], v[94:95], off
	global_load_dwordx4 v[216:219], v[94:95], off offset:528
	global_load_dwordx4 v[220:223], v[94:95], off offset:512
	s_waitcnt vmcnt(3)
	v_pk_fma_f32 v[76:77], v[76:77], 0.5, v[86:87] op_sel_hi:[1,0,1]
	v_lshlrev_b64 v[86:87], 12, v[84:85]
	v_lshl_add_u64 v[86:87], s[30:31], 0, v[86:87]
	s_waitcnt vmcnt(2)
	v_pk_fma_f32 v[82:83], v[82:83], 0.5, v[92:93] op_sel_hi:[1,0,1]
	v_pk_fma_f32 v[80:81], v[80:81], 0.5, v[90:91] op_sel_hi:[1,0,1]
	v_lshl_add_u64 v[90:91], v[86:87], 0, v[146:147]
	v_pk_fma_f32 v[78:79], v[78:79], 0.5, v[88:89] op_sel_hi:[1,0,1]
	global_store_dwordx4 v[90:91], v[80:83], off
	global_store_dwordx4 v[90:91], v[76:79], off offset:16
	v_cvt_pk_bf16_f32 v86, v80, v81
	v_mul_f32_e32 v81, v81, v81
	v_fmac_f32_e32 v81, v80, v80
	v_mul_f32_e32 v80, v83, v83
	v_cvt_pk_bf16_f32 v88, v76, v77
	v_lshlrev_b64 v[92:93], 11, v[84:85]
	v_fmac_f32_e32 v80, v82, v82
	v_mul_f32_e32 v77, v77, v77
	v_lshl_add_u64 v[92:93], s[18:19], 0, v[92:93]
	v_add_f32_e32 v80, v81, v80
	v_fmac_f32_e32 v77, v76, v76
	v_cvt_pk_bf16_f32 v87, v82, v83
	v_cvt_pk_bf16_f32 v89, v78, v79
	v_lshl_add_u64 v[92:93], v[142:143], 1, v[92:93]
	v_add_f32_e32 v76, v77, v80
	v_mul_f32_e32 v77, v79, v79
	global_store_dwordx4 v[92:93], v[86:89], off
	v_fmac_f32_e32 v77, v78, v78
	s_nop 0
	v_add_f32_e32 v86, v77, v76
	s_nop 0
	s_nop 0
	s_waitcnt vmcnt(4)
	v_pk_fma_f32 v[70:71], v[70:71], 0.5, v[218:219] op_sel_hi:[1,0,1]
	s_waitcnt vmcnt(3)
	v_pk_fma_f32 v[74:75], v[74:75], 0.5, v[222:223] op_sel_hi:[1,0,1]
	v_pk_fma_f32 v[72:73], v[72:73], 0.5, v[220:221] op_sel_hi:[1,0,1]
	v_pk_fma_f32 v[68:69], v[68:69], 0.5, v[216:217] op_sel_hi:[1,0,1]
	global_store_dwordx4 v[90:91], v[72:75], off offset:512
	global_store_dwordx4 v[90:91], v[68:71], off offset:528
	v_cvt_pk_bf16_f32 v76, v72, v73
	v_mul_f32_e32 v73, v73, v73
	v_fmac_f32_e32 v73, v72, v72
	v_mul_f32_e32 v72, v75, v75
	v_cvt_pk_bf16_f32 v78, v68, v69
	v_fmac_f32_e32 v72, v74, v74
	v_mul_f32_e32 v69, v69, v69
	v_add_f32_e32 v72, v73, v72
	v_fmac_f32_e32 v69, v68, v68
	v_add_f32_e32 v68, v69, v72
	v_mul_f32_e32 v69, v71, v71
	v_fmac_f32_e32 v69, v70, v70
	v_add_f32_e32 v68, v69, v68
	v_add_f32_e32 v68, v86, v68
	v_mov_b32_e32 v69, v68
	v_cvt_pk_bf16_f32 v77, v74, v75
	v_cvt_pk_bf16_f32 v79, v70, v71
	global_store_dwordx4 v[92:93], v[76:79], off offset:256
	v_permlane16_swap_b32_e32 v68, v69
	v_add_f32_e32 v68, v68, v69
	v_mov_b32_e32 v69, v68
	s_nop 1
	v_permlane32_swap_b32_e32 v68, v69
	s_and_saveexec_b64 s[16:17], s[6:7]
	s_cbranch_execz .LBB0_336
	s_waitcnt lgkmcnt(0)
	v_add_f32_e32 v70, v68, v69
	v_lshl_add_u64 v[68:69], v[84:85], 2, s[84:85]
	v_mov_b32_e32 v236, v68
	v_mov_b32_e32 v237, v69
	v_mov_b32_e32 v238, v70
.LBB0_336:
	s_or_b64 exec, exec, s[16:17]
	s_movk_i32 s10, 0x7f7f
	s_waitcnt lgkmcnt(0)
	v_add_u32_e32 v68, 0x80, v144
	v_cmp_lt_i32_e32 vcc, s10, v144
	s_and_saveexec_b64 s[16:17], vcc
	s_xor_b64 s[16:17], exec, s[16:17]
	v_add_u32_e32 v70, 0xffff8080, v144
	v_mov_b32_e32 v71, v2
	v_lshlrev_b64 v[70:71], 12, v[70:71]
	v_lshl_add_u64 v[70:71], s[38:39], 0, v[70:71]
	v_mov_b32_e32 v69, v2
	s_andn2_saveexec_b64 s[16:17], s[16:17]
	v_ashrrev_i32_e32 v69, 31, v68
	v_lshlrev_b64 v[70:71], 12, v[68:69]
	v_lshl_add_u64 v[70:71], s[36:37], 0, v[70:71]
	s_or_b64 exec, exec, s[16:17]
	v_lshl_add_u64 v[78:79], v[70:71], 0, v[146:147]
	global_load_dwordx4 v[70:73], v[78:79], off offset:16
	global_load_dwordx4 v[74:77], v[78:79], off
	global_load_dwordx4 v[216:219], v[78:79], off offset:528
	global_load_dwordx4 v[220:223], v[78:79], off offset:512
	s_waitcnt vmcnt(3)
	v_pk_fma_f32 v[60:61], v[60:61], 0.5, v[70:71] op_sel_hi:[1,0,1]
	v_lshlrev_b64 v[70:71], 12, v[68:69]
	v_lshl_add_u64 v[70:71], s[30:31], 0, v[70:71]
	s_waitcnt vmcnt(2)
	v_pk_fma_f32 v[66:67], v[66:67], 0.5, v[76:77] op_sel_hi:[1,0,1]
	v_pk_fma_f32 v[64:65], v[64:65], 0.5, v[74:75] op_sel_hi:[1,0,1]
	v_lshl_add_u64 v[74:75], v[70:71], 0, v[146:147]
	v_pk_fma_f32 v[62:63], v[62:63], 0.5, v[72:73] op_sel_hi:[1,0,1]
	global_store_dwordx4 v[74:75], v[64:67], off
	global_store_dwordx4 v[74:75], v[60:63], off offset:16
	v_cvt_pk_bf16_f32 v70, v64, v65
	v_mul_f32_e32 v65, v65, v65
	v_fmac_f32_e32 v65, v64, v64
	v_mul_f32_e32 v64, v67, v67
	v_cvt_pk_bf16_f32 v72, v60, v61
	v_lshlrev_b64 v[76:77], 11, v[68:69]
	v_fmac_f32_e32 v64, v66, v66
	v_mul_f32_e32 v61, v61, v61
	v_lshl_add_u64 v[76:77], s[18:19], 0, v[76:77]
	v_add_f32_e32 v64, v65, v64
	v_fmac_f32_e32 v61, v60, v60
	v_cvt_pk_bf16_f32 v71, v66, v67
	v_cvt_pk_bf16_f32 v73, v62, v63
	v_lshl_add_u64 v[76:77], v[142:143], 1, v[76:77]
	v_add_f32_e32 v60, v61, v64
	v_mul_f32_e32 v61, v63, v63
	global_store_dwordx4 v[76:77], v[70:73], off
	v_fmac_f32_e32 v61, v62, v62
	s_nop 0
	v_add_f32_e32 v70, v61, v60
	s_nop 0
	s_nop 0
	s_waitcnt vmcnt(4)
	v_pk_fma_f32 v[54:55], v[54:55], 0.5, v[218:219] op_sel_hi:[1,0,1]
	s_waitcnt vmcnt(3)
	v_pk_fma_f32 v[58:59], v[58:59], 0.5, v[222:223] op_sel_hi:[1,0,1]
	v_pk_fma_f32 v[56:57], v[56:57], 0.5, v[220:221] op_sel_hi:[1,0,1]
	v_pk_fma_f32 v[52:53], v[52:53], 0.5, v[216:217] op_sel_hi:[1,0,1]
	global_store_dwordx4 v[74:75], v[56:59], off offset:512
	global_store_dwordx4 v[74:75], v[52:55], off offset:528
	v_cvt_pk_bf16_f32 v60, v56, v57
	v_mul_f32_e32 v57, v57, v57
	v_fmac_f32_e32 v57, v56, v56
	v_mul_f32_e32 v56, v59, v59
	v_cvt_pk_bf16_f32 v62, v52, v53
	v_fmac_f32_e32 v56, v58, v58
	v_mul_f32_e32 v53, v53, v53
	v_add_f32_e32 v56, v57, v56
	v_fmac_f32_e32 v53, v52, v52
	v_add_f32_e32 v52, v53, v56
	v_mul_f32_e32 v53, v55, v55
	v_fmac_f32_e32 v53, v54, v54
	v_add_f32_e32 v52, v53, v52
	v_add_f32_e32 v52, v70, v52
	v_mov_b32_e32 v53, v52
	v_cvt_pk_bf16_f32 v61, v58, v59
	v_cvt_pk_bf16_f32 v63, v54, v55
	global_store_dwordx4 v[76:77], v[60:63], off offset:256
	v_permlane16_swap_b32_e32 v52, v53
	v_add_f32_e32 v52, v52, v53
	v_mov_b32_e32 v53, v52
	s_nop 1
	v_permlane32_swap_b32_e32 v52, v53
	s_and_saveexec_b64 s[16:17], s[6:7]
	s_cbranch_execz .LBB0_342
	s_waitcnt lgkmcnt(0)
	v_add_f32_e32 v54, v52, v53
	v_lshl_add_u64 v[52:53], v[68:69], 2, s[84:85]
	v_mov_b32_e32 v240, v52
	v_mov_b32_e32 v241, v53
	v_mov_b32_e32 v242, v54
; #define EPI_ROWS(...) _Pragma("unroll") for (int ai = 0; ai < 2; ++ai) _Pragma("unroll") for (int m = 0; m < 4; ++m) { const int row = row0 + ai * 128 + m * 16; __VA_ARGS__ __builtin_amdgcn_sched_barrier(0); }
; __device__ __forceinline__ u32x4 pack8(f32x4 a, f32x4 b) { u32x4 w; w.x = pk2(a[0], a[1]); w.y = pk2(a[2], a[3]); w.z = pk2(b[0], b[1]); w.w = pk2(b[2], b[3]); return w; }
; __device__ __forceinline__ float dot8(f32x4 a, f32x4 b) { return (a[0] * a[0] + a[1] * a[1]) + (a[2] * a[2] + a[3] * a[3]) + (b[0] * b[0] + b[1] * b[1]) + (b[2] * b[2] + b[3] * b[3]); }
; __device__ __forceinline__ float red_fq(float s) { s += __shfl_xor(s, 16); s += __shfl_xor(s, 32); return s; }
;     __device__ __forceinline__ void operator()(AccRef acc, const Unit& u, int wr, int wc, int fr, int fq) const {
;         const int row0 = u.pm * 256 + wr * 64 + fr, col0 = u.pn * 256 + wc * 32 + 8 * fq;
;         EPI_ROWS(
;             const float* rp = (row < MP) ? res0 + (size_t)row * DM : res1 + (size_t)(row - MP) * DM;
;             float s = 0.f;
;             _Pragma("unroll") for (int bj = 0; bj < 2; ++bj) { const int col = col0 + bj * 128;
;                 f32x4 v0 = *(const f32x4*)(rp + col) + acc[ai][bj][m][0] * scale, v1 = *(const f32x4*)(rp + col + 4) + acc[ai][bj][m][1] * scale;
;                 *(f32x4*)(out + (size_t)row * DM + col) = v0; *(f32x4*)(out + (size_t)row * DM + col + 4) = v1;
;                 if (WB) *(u32x4*)(ob + (size_t)row * DM + col) = pack8(v0, v1);
;                 s += dot8(v0, v1); }
;             s = red_fq(s); if (fq == 0) unsafeAtomicAdd(ss + row, s);
;         )
.LBB0_342:
	s_or_b64 exec, exec, s[16:17]
	s_movk_i32 s10, 0x7f6f
	s_waitcnt lgkmcnt(0)
	v_add_u32_e32 v52, 0x90, v144
	v_cmp_lt_i32_e32 vcc, s10, v144
	s_and_saveexec_b64 s[16:17], vcc
	s_xor_b64 s[16:17], exec, s[16:17]
	v_add_u32_e32 v54, 0xffff8090, v144
	v_mov_b32_e32 v55, v2
	v_lshlrev_b64 v[54:55], 12, v[54:55]
	v_lshl_add_u64 v[54:55], s[38:39], 0, v[54:55]
	v_mov_b32_e32 v53, v2
	s_andn2_saveexec_b64 s[16:17], s[16:17]
	v_ashrrev_i32_e32 v53, 31, v52
	v_lshlrev_b64 v[54:55], 12, v[52:53]
	v_lshl_add_u64 v[54:55], s[36:37], 0, v[54:55]
	s_or_b64 exec, exec, s[16:17]
	v_lshl_add_u64 v[62:63], v[54:55], 0, v[146:147]
	global_load_dwordx4 v[54:57], v[62:63], off offset:16
	global_load_dwordx4 v[58:61], v[62:63], off
	global_load_dwordx4 v[216:219], v[62:63], off offset:528
	global_load_dwordx4 v[220:223], v[62:63], off offset:512
	s_waitcnt vmcnt(3)
	v_pk_fma_f32 v[44:45], v[44:45], 0.5, v[54:55] op_sel_hi:[1,0,1]
	v_lshlrev_b64 v[54:55], 12, v[52:53]
	v_lshl_add_u64 v[54:55], s[30:31], 0, v[54:55]
	s_waitcnt vmcnt(2)
	v_pk_fma_f32 v[50:51], v[50:51], 0.5, v[60:61] op_sel_hi:[1,0,1]
	v_pk_fma_f32 v[48:49], v[48:49], 0.5, v[58:59] op_sel_hi:[1,0,1]
	v_lshl_add_u64 v[58:59], v[54:55], 0, v[146:147]
	v_pk_fma_f32 v[46:47], v[46:47], 0.5, v[56:57] op_sel_hi:[1,0,1]
	global_store_dwordx4 v[58:59], v[48:51], off
	global_store_dwordx4 v[58:59], v[44:47], off offset:16
	v_cvt_pk_bf16_f32 v54, v48, v49
	v_mul_f32_e32 v49, v49, v49
	v_fmac_f32_e32 v49, v48, v48
	v_mul_f32_e32 v48, v51, v51
	v_cvt_pk_bf16_f32 v56, v44, v45
	v_lshlrev_b64 v[60:61], 11, v[52:53]
	v_fmac_f32_e32 v48, v50, v50
	v_mul_f32_e32 v45, v45, v45
	v_lshl_add_u64 v[60:61], s[18:19], 0, v[60:61]
	v_add_f32_e32 v48, v49, v48
	v_fmac_f32_e32 v45, v44, v44
	v_cvt_pk_bf16_f32 v55, v50, v51
	v_cvt_pk_bf16_f32 v57, v46, v47
	v_lshl_add_u64 v[60:61], v[142:143], 1, v[60:61]
	v_add_f32_e32 v44, v45, v48
	v_mul_f32_e32 v45, v47, v47
	global_store_dwordx4 v[60:61], v[54:57], off
	v_fmac_f32_e32 v45, v46, v46
	s_nop 0
	v_add_f32_e32 v54, v45, v44
	s_nop 0
	s_nop 0
	s_waitcnt vmcnt(4)
	v_pk_fma_f32 v[38:39], v[38:39], 0.5, v[218:219] op_sel_hi:[1,0,1]
	s_waitcnt vmcnt(3)
	v_pk_fma_f32 v[42:43], v[42:43], 0.5, v[222:223] op_sel_hi:[1,0,1]
	v_pk_fma_f32 v[40:41], v[40:41], 0.5, v[220:221] op_sel_hi:[1,0,1]
	v_pk_fma_f32 v[36:37], v[36:37], 0.5, v[216:217] op_sel_hi:[1,0,1]
	global_store_dwordx4 v[58:59], v[40:43], off offset:512
	global_store_dwordx4 v[58:59], v[36:39], off offset:528
	v_cvt_pk_bf16_f32 v44, v40, v41
	v_mul_f32_e32 v41, v41, v41
	v_fmac_f32_e32 v41, v40, v40
	v_mul_f32_e32 v40, v43, v43
	v_cvt_pk_bf16_f32 v46, v36, v37
	v_fmac_f32_e32 v40, v42, v42
	v_mul_f32_e32 v37, v37, v37
	v_add_f32_e32 v40, v41, v40
	v_fmac_f32_e32 v37, v36, v36
	v_add_f32_e32 v36, v37, v40
	v_mul_f32_e32 v37, v39, v39
	v_fmac_f32_e32 v37, v38, v38
	v_add_f32_e32 v36, v37, v36
	v_add_f32_e32 v36, v54, v36
	v_mov_b32_e32 v37, v36
	v_cvt_pk_bf16_f32 v45, v42, v43
	v_cvt_pk_bf16_f32 v47, v38, v39
	global_store_dwordx4 v[60:61], v[44:47], off offset:256
	v_permlane16_swap_b32_e32 v36, v37
	v_add_f32_e32 v36, v36, v37
	v_mov_b32_e32 v37, v36
	s_nop 1
	v_permlane32_swap_b32_e32 v36, v37
	s_and_saveexec_b64 s[16:17], s[6:7]
	s_cbranch_execz .LBB0_348
	s_waitcnt lgkmcnt(0)
	v_add_f32_e32 v38, v36, v37
	v_lshl_add_u64 v[36:37], v[52:53], 2, s[84:85]
	v_mov_b32_e32 v244, v36
	v_mov_b32_e32 v245, v37
	v_mov_b32_e32 v246, v38
.LBB0_348:
	s_or_b64 exec, exec, s[16:17]
	s_movk_i32 s10, 0x7f5f
	s_waitcnt lgkmcnt(0)
	v_add_u32_e32 v36, 0xa0, v144
	v_cmp_lt_i32_e32 vcc, s10, v144
	s_and_saveexec_b64 s[16:17], vcc
	s_xor_b64 s[16:17], exec, s[16:17]
	v_add_u32_e32 v38, 0xffff80a0, v144
	v_mov_b32_e32 v39, v2
	v_lshlrev_b64 v[38:39], 12, v[38:39]
	v_lshl_add_u64 v[38:39], s[38:39], 0, v[38:39]
	v_mov_b32_e32 v37, v2
	s_andn2_saveexec_b64 s[16:17], s[16:17]
	v_ashrrev_i32_e32 v37, 31, v36
	v_lshlrev_b64 v[38:39], 12, v[36:37]
	v_lshl_add_u64 v[38:39], s[36:37], 0, v[38:39]
	s_or_b64 exec, exec, s[16:17]
	v_lshl_add_u64 v[46:47], v[38:39], 0, v[146:147]
	global_load_dwordx4 v[38:41], v[46:47], off offset:16
	global_load_dwordx4 v[42:45], v[46:47], off
	global_load_dwordx4 v[216:219], v[46:47], off offset:528
	global_load_dwordx4 v[220:223], v[46:47], off offset:512
	s_waitcnt vmcnt(3)
	v_pk_fma_f32 v[28:29], v[28:29], 0.5, v[38:39] op_sel_hi:[1,0,1]
	v_lshlrev_b64 v[38:39], 12, v[36:37]
	v_lshl_add_u64 v[38:39], s[30:31], 0, v[38:39]
	s_waitcnt vmcnt(2)
	v_pk_fma_f32 v[34:35], v[34:35], 0.5, v[44:45] op_sel_hi:[1,0,1]
	v_pk_fma_f32 v[32:33], v[32:33], 0.5, v[42:43] op_sel_hi:[1,0,1]
	v_lshl_add_u64 v[42:43], v[38:39], 0, v[146:147]
	v_pk_fma_f32 v[30:31], v[30:31], 0.5, v[40:41] op_sel_hi:[1,0,1]
	global_store_dwordx4 v[42:43], v[32:35], off
	global_store_dwordx4 v[42:43], v[28:31], off offset:16
	v_cvt_pk_bf16_f32 v38, v32, v33
	v_mul_f32_e32 v33, v33, v33
	v_fmac_f32_e32 v33, v32, v32
	v_mul_f32_e32 v32, v35, v35
	v_cvt_pk_bf16_f32 v40, v28, v29
	v_lshlrev_b64 v[44:45], 11, v[36:37]
	v_fmac_f32_e32 v32, v34, v34
	v_mul_f32_e32 v29, v29, v29
	v_lshl_add_u64 v[44:45], s[18:19], 0, v[44:45]
	v_add_f32_e32 v32, v33, v32
	v_fmac_f32_e32 v29, v28, v28
	v_cvt_pk_bf16_f32 v39, v34, v35
	v_cvt_pk_bf16_f32 v41, v30, v31
	v_lshl_add_u64 v[44:45], v[142:143], 1, v[44:45]
	v_add_f32_e32 v28, v29, v32
	v_mul_f32_e32 v29, v31, v31
	global_store_dwordx4 v[44:45], v[38:41], off
	v_fmac_f32_e32 v29, v30, v30
	s_nop 0
	v_add_f32_e32 v38, v29, v28
	s_nop 0
	s_nop 0
	s_waitcnt vmcnt(4)
	v_pk_fma_f32 v[22:23], v[22:23], 0.5, v[218:219] op_sel_hi:[1,0,1]
	s_waitcnt vmcnt(3)
	v_pk_fma_f32 v[26:27], v[26:27], 0.5, v[222:223] op_sel_hi:[1,0,1]
	v_pk_fma_f32 v[24:25], v[24:25], 0.5, v[220:221] op_sel_hi:[1,0,1]
	v_pk_fma_f32 v[20:21], v[20:21], 0.5, v[216:217] op_sel_hi:[1,0,1]
	global_store_dwordx4 v[42:43], v[24:27], off offset:512
	global_store_dwordx4 v[42:43], v[20:23], off offset:528
	v_cvt_pk_bf16_f32 v28, v24, v25
	v_mul_f32_e32 v25, v25, v25
	v_fmac_f32_e32 v25, v24, v24
	v_mul_f32_e32 v24, v27, v27
	v_cvt_pk_bf16_f32 v30, v20, v21
	v_fmac_f32_e32 v24, v26, v26
	v_mul_f32_e32 v21, v21, v21
	v_add_f32_e32 v24, v25, v24
	v_fmac_f32_e32 v21, v20, v20
	v_add_f32_e32 v20, v21, v24
	v_mul_f32_e32 v21, v23, v23
	v_fmac_f32_e32 v21, v22, v22
	v_add_f32_e32 v20, v21, v20
	v_add_f32_e32 v20, v38, v20
	v_mov_b32_e32 v21, v20
	v_cvt_pk_bf16_f32 v29, v26, v27
	v_cvt_pk_bf16_f32 v31, v22, v23
	global_store_dwordx4 v[44:45], v[28:31], off offset:256
	v_permlane16_swap_b32_e32 v20, v21
	v_add_f32_e32 v20, v20, v21
	v_mov_b32_e32 v21, v20
	s_nop 1
	v_permlane32_swap_b32_e32 v20, v21
	s_and_saveexec_b64 s[16:17], s[6:7]
	s_cbranch_execz .LBB0_354
	s_waitcnt lgkmcnt(0)
	v_add_f32_e32 v22, v20, v21
	v_lshl_add_u64 v[20:21], v[36:37], 2, s[84:85]
	v_mov_b32_e32 v248, v20
	v_mov_b32_e32 v249, v21
	v_mov_b32_e32 v250, v22
; #define EPI_ROWS(...) _Pragma("unroll") for (int ai = 0; ai < 2; ++ai) _Pragma("unroll") for (int m = 0; m < 4; ++m) { const int row = row0 + ai * 128 + m * 16; __VA_ARGS__ __builtin_amdgcn_sched_barrier(0); }
; __device__ __forceinline__ u32x4 pack8(f32x4 a, f32x4 b) { u32x4 w; w.x = pk2(a[0], a[1]); w.y = pk2(a[2], a[3]); w.z = pk2(b[0], b[1]); w.w = pk2(b[2], b[3]); return w; }
; __device__ __forceinline__ float dot8(f32x4 a, f32x4 b) { return (a[0] * a[0] + a[1] * a[1]) + (a[2] * a[2] + a[3] * a[3]) + (b[0] * b[0] + b[1] * b[1]) + (b[2] * b[2] + b[3] * b[3]); }
; __device__ __forceinline__ float red_fq(float s) { s += __shfl_xor(s, 16); s += __shfl_xor(s, 32); return s; }
;     __device__ __forceinline__ void operator()(AccRef acc, const Unit& u, int wr, int wc, int fr, int fq) const {
;         const int row0 = u.pm * 256 + wr * 64 + fr, col0 = u.pn * 256 + wc * 32 + 8 * fq;
;         EPI_ROWS(
;             const float* rp = (row < MP) ? res0 + (size_t)row * DM : res1 + (size_t)(row - MP) * DM;
;             float s = 0.f;
;             _Pragma("unroll") for (int bj = 0; bj < 2; ++bj) { const int col = col0 + bj * 128;
;                 f32x4 v0 = *(const f32x4*)(rp + col) + acc[ai][bj][m][0] * scale, v1 = *(const f32x4*)(rp + col + 4) + acc[ai][bj][m][1] * scale;
;                 *(f32x4*)(out + (size_t)row * DM + col) = v0; *(f32x4*)(out + (size_t)row * DM + col + 4) = v1;
;                 if (WB) *(u32x4*)(ob + (size_t)row * DM + col) = pack8(v0, v1);
;                 s += dot8(v0, v1); }
;             s = red_fq(s); if (fq == 0) unsafeAtomicAdd(ss + row, s);
;         )
.LBB0_354:
	s_or_b64 exec, exec, s[16:17]
	s_movk_i32 s10, 0x7f4f
	s_waitcnt lgkmcnt(0)
	v_add_u32_e32 v20, 0xb0, v144
	v_cmp_lt_i32_e32 vcc, s10, v144
	s_and_saveexec_b64 s[16:17], vcc
	s_xor_b64 s[16:17], exec, s[16:17]
	v_add_u32_e32 v22, 0xffff80b0, v144
	v_mov_b32_e32 v23, v2
	v_lshlrev_b64 v[22:23], 12, v[22:23]
	v_lshl_add_u64 v[22:23], s[38:39], 0, v[22:23]
	v_mov_b32_e32 v21, v2
	s_andn2_saveexec_b64 s[16:17], s[16:17]
	v_ashrrev_i32_e32 v21, 31, v20
	v_lshlrev_b64 v[22:23], 12, v[20:21]
	v_lshl_add_u64 v[22:23], s[36:37], 0, v[22:23]
	s_or_b64 exec, exec, s[16:17]
	v_lshl_add_u64 v[30:31], v[22:23], 0, v[146:147]
	global_load_dwordx4 v[22:25], v[30:31], off offset:16
	global_load_dwordx4 v[26:29], v[30:31], off
	global_load_dwordx4 v[216:219], v[30:31], off offset:528
	global_load_dwordx4 v[220:223], v[30:31], off offset:512
	s_waitcnt vmcnt(3)
	v_pk_fma_f32 v[12:13], v[12:13], 0.5, v[22:23] op_sel_hi:[1,0,1]
	v_lshlrev_b64 v[22:23], 12, v[20:21]
	v_lshl_add_u64 v[22:23], s[30:31], 0, v[22:23]
	s_waitcnt vmcnt(2)
	v_pk_fma_f32 v[18:19], v[18:19], 0.5, v[28:29] op_sel_hi:[1,0,1]
	v_pk_fma_f32 v[16:17], v[16:17], 0.5, v[26:27] op_sel_hi:[1,0,1]
	v_lshl_add_u64 v[26:27], v[22:23], 0, v[146:147]
	v_pk_fma_f32 v[14:15], v[14:15], 0.5, v[24:25] op_sel_hi:[1,0,1]
	global_store_dwordx4 v[26:27], v[16:19], off
	global_store_dwordx4 v[26:27], v[12:15], off offset:16
	v_cvt_pk_bf16_f32 v22, v16, v17
	v_mul_f32_e32 v17, v17, v17
	v_fmac_f32_e32 v17, v16, v16
	v_mul_f32_e32 v16, v19, v19
	v_cvt_pk_bf16_f32 v24, v12, v13
	v_lshlrev_b64 v[28:29], 11, v[20:21]
	v_fmac_f32_e32 v16, v18, v18
	v_mul_f32_e32 v13, v13, v13
	v_lshl_add_u64 v[28:29], s[18:19], 0, v[28:29]
	v_add_f32_e32 v16, v17, v16
	v_fmac_f32_e32 v13, v12, v12
	v_cvt_pk_bf16_f32 v23, v18, v19
	v_cvt_pk_bf16_f32 v25, v14, v15
	v_lshl_add_u64 v[28:29], v[142:143], 1, v[28:29]
	v_add_f32_e32 v12, v13, v16
	v_mul_f32_e32 v13, v15, v15
	global_store_dwordx4 v[28:29], v[22:25], off
	v_fmac_f32_e32 v13, v14, v14
	s_nop 0
	v_add_f32_e32 v22, v13, v12
	s_nop 0
	s_nop 0
	s_waitcnt vmcnt(4)
	v_pk_fma_f32 v[6:7], v[6:7], 0.5, v[218:219] op_sel_hi:[1,0,1]
	s_waitcnt vmcnt(3)
	v_pk_fma_f32 v[10:11], v[10:11], 0.5, v[222:223] op_sel_hi:[1,0,1]
	v_pk_fma_f32 v[8:9], v[8:9], 0.5, v[220:221] op_sel_hi:[1,0,1]
	v_pk_fma_f32 v[4:5], v[4:5], 0.5, v[216:217] op_sel_hi:[1,0,1]
	global_store_dwordx4 v[26:27], v[8:11], off offset:512
	global_store_dwordx4 v[26:27], v[4:7], off offset:528
	v_cvt_pk_bf16_f32 v12, v8, v9
	v_mul_f32_e32 v9, v9, v9
	v_fmac_f32_e32 v9, v8, v8
	v_mul_f32_e32 v8, v11, v11
	v_cvt_pk_bf16_f32 v14, v4, v5
	v_fmac_f32_e32 v8, v10, v10
	v_mul_f32_e32 v5, v5, v5
	v_add_f32_e32 v8, v9, v8
	v_fmac_f32_e32 v5, v4, v4
	v_add_f32_e32 v4, v5, v8
	v_mul_f32_e32 v5, v7, v7
	v_fmac_f32_e32 v5, v6, v6
	v_add_f32_e32 v4, v5, v4
	v_add_f32_e32 v4, v22, v4
	v_mov_b32_e32 v5, v4
	v_cvt_pk_bf16_f32 v13, v10, v11
	v_cvt_pk_bf16_f32 v15, v6, v7
	global_store_dwordx4 v[28:29], v[12:15], off offset:256
	v_permlane16_swap_b32_e32 v4, v5
	v_add_f32_e32 v4, v4, v5
	v_mov_b32_e32 v3, v4
	s_nop 1
	v_permlane32_swap_b32_e32 v4, v3
	s_and_saveexec_b64 s[16:17], s[6:7]
	s_cbranch_execz .LBB0_360
	s_waitcnt lgkmcnt(0)
	v_add_f32_e32 v3, v4, v3
	v_lshl_add_u64 v[4:5], v[20:21], 2, s[84:85]
	global_atomic_add_f32 v[4:5], v3, off
	global_atomic_add_f32 v[224:225], v226, off
	global_atomic_add_f32 v[228:229], v230, off
	global_atomic_add_f32 v[232:233], v234, off
	global_atomic_add_f32 v[236:237], v238, off
	global_atomic_add_f32 v[240:241], v242, off
	global_atomic_add_f32 v[244:245], v246, off
	global_atomic_add_f32 v[248:249], v250, off

; #define PG8_STAGE(bufoff, gbase, voff) do { _Pragma("unroll") for (int _i = 0; _i < 2; ++_i) { unsigned _keep; \
;         asm volatile("s_mov_b32 %0, m0\n\ts_mov_b32 m0, %1\n\ts_nop 0\n\tglobal_load_lds_dwordx4 %2, %3\n\ts_mov_b32 m0, %0" : "=&s"(_keep) : "s"(ldsb + (unsigned)((bufoff) + _i * 8192)), "v"((voff)[_i]), "s"((const char*)(gbase)) : "memory"); } } while (0)
; #define PG8_LDA(dst, b, h) do { _Pragma("unroll") for (int m = 0; m < 4; ++m) _Pragma("unroll") for (int k = 0; k < 2; ++k) dst[m][k] = *(const LAS bf16x8*)(lds + PG8_SA(b, h) + aoff + m * 2048 + k * 1024); } while (0)
; #define PG8_LDB(dst, b, h) do { _Pragma("unroll") for (int n = 0; n < 2; ++n) _Pragma("unroll") for (int k = 0; k < 2; ++k) dst[n][k] = *(const LAS bf16x8*)(lds + PG8_SB(b, h) + boff + n * 2048 + k * 1024); } while (0)
; #define PG8_MMA(ai, bj, At, Bt) do { __builtin_amdgcn_s_setprio(1); _Pragma("unroll") for (int m = 0; m < 4; ++m) _Pragma("unroll") for (int n = 0; n < 2; ++n) _Pragma("unroll") for (int k = 0; k < 2; ++k) \
;         acc[ai][bj][m][n] = __builtin_amdgcn_mfma_f32_16x16x32_bf16(Bt[n][k], At[m][k], acc[ai][bj][m][n], 0, 0, 0); __builtin_amdgcn_s_setprio(0); } while (0)
; #define PG8_WAIT_V(n) asm volatile("s_waitcnt vmcnt(" #n ")" ::: "memory")
; #define PG8_WAIT_L(n) asm volatile("s_waitcnt lgkmcnt(" #n ")" ::: "memory")
; template <class Epi>
; __device__ __forceinline__ void gemm_phase(LAS unsigned char* lds, const Gemm g, const StaticOrder& S, const Epi& E) {
;     ...
;         for (int t = 0; t < nt; t += 2) {
;             const bool last = (t == nt - 2);
;             const char* a1 = cA + (size_t)(t + 1) * kstep;
;             const char* a2 = last ? nA : cA + (size_t)(t + 2) * kstep; const char* b2 = last ? nB : cB + (size_t)(t + 2) * kstep;
;             const char* a3 = a2 + kstep; const char* b3 = b2 + kstep;
;             PG8_LDB(B0, 0, 0); PG8_LDB(B1, 0, 1); PG8_SCHED; PG8_LDA(At, 0, 0); PG8_STAGE(PG8_SA(1, 1), a1 + hstepA, voffA);
;             PG8_WAIT_V(8); PG8_WAIT_L(0); PG8_BAR; PG8_MMA(0, 0, At, B0); PG8_MMA(0, 1, At, B1); PG8_BAR; PG8_SCHED;
;             PG8_LDA(At, 0, 1); PG8_STAGE(PG8_SB(0, 0), b2, voffB); PG8_STAGE(PG8_SB(0, 1), b2 + hstepB, voffB); PG8_STAGE(PG8_SA(0, 0), a2, voffA);
;             PG8_WAIT_V(8); PG8_WAIT_L(0); PG8_BAR; PG8_MMA(1, 0, At, B0); PG8_MMA(1, 1, At, B1); PG8_BAR; PG8_SCHED;
.LBB0_435:
	ds_read_b128 v[140:143], v150
	ds_read_b128 v[158:161], v150 offset:1024
	ds_read_b128 v[162:165], v150 offset:2048
	ds_read_b128 v[166:169], v150 offset:3072
	ds_read_b128 v[170:173], v151
	ds_read_b128 v[174:177], v151 offset:1024
	ds_read_b128 v[178:181], v151 offset:2048
	ds_read_b128 v[182:185], v151 offset:3072
	s_cmp_eq_u32 s77, 12
	s_cselect_b32 s16, s9, s69
	s_cselect_b32 s17, s0, s74
	s_cselect_b32 s40, s63, s75
	s_cselect_b32 s41, s11, s76
	s_add_u32 s12, s16, 0x80
	s_addc_u32 s13, s17, 0
	ds_read_b128 v[186:189], v152
	ds_read_b128 v[190:193], v152 offset:1024
	ds_read_b128 v[194:197], v152 offset:2048
	ds_read_b128 v[198:201], v152 offset:3072
	ds_read_b128 v[202:205], v152 offset:4096
	ds_read_b128 v[206:209], v152 offset:5120
	ds_read_b128 v[210:213], v152 offset:6144
	ds_read_b128 v[214:217], v152 offset:7168
	s_add_u32 s78, s69, 0x3ff80
	s_addc_u32 s79, s74, 0
	s_mov_b32 s82, m0
	s_mov_b32 m0, s92
	s_nop 0
	global_load_lds_dwordx4 v133, s[78:79]
	s_mov_b32 m0, s82
	s_nop 0
	s_mov_b32 s82, m0
	s_mov_b32 m0, s93
	s_nop 0
	global_load_lds_dwordx4 v147, s[78:79]
	s_mov_b32 m0, s82
	s_waitcnt vmcnt(8)
	s_waitcnt lgkmcnt(0)
	s_barrier
	s_setprio 1
	s_waitcnt lgkmcnt(7)
	v_mfma_f32_16x16x32_bf16 v[126:129], v[140:143], v[186:189], v[126:129]
	v_mfma_f32_16x16x32_bf16 v[122:125], v[162:165], v[186:189], v[122:125]
	s_waitcnt lgkmcnt(5)
	v_mfma_f32_16x16x32_bf16 v[110:113], v[140:143], v[194:197], v[110:113]
	v_mfma_f32_16x16x32_bf16 v[106:109], v[162:165], v[194:197], v[106:109]
	s_waitcnt lgkmcnt(3)
	v_mfma_f32_16x16x32_bf16 v[94:97], v[140:143], v[202:205], v[94:97]
	v_mfma_f32_16x16x32_bf16 v[90:93], v[162:165], v[202:205], v[90:93]
	s_waitcnt lgkmcnt(1)
	v_mfma_f32_16x16x32_bf16 v[78:81], v[140:143], v[210:213], v[78:81]
	v_mfma_f32_16x16x32_bf16 v[74:77], v[162:165], v[210:213], v[74:77]
	v_mfma_f32_16x16x32_bf16 v[126:129], v[158:161], v[190:193], v[126:129]
	v_mfma_f32_16x16x32_bf16 v[122:125], v[166:169], v[190:193], v[122:125]
	v_mfma_f32_16x16x32_bf16 v[110:113], v[158:161], v[198:201], v[110:113]
	v_mfma_f32_16x16x32_bf16 v[106:109], v[166:169], v[198:201], v[106:109]
	v_mfma_f32_16x16x32_bf16 v[94:97], v[158:161], v[206:209], v[94:97]
	v_mfma_f32_16x16x32_bf16 v[90:93], v[166:169], v[206:209], v[90:93]
	s_waitcnt lgkmcnt(0)
	v_mfma_f32_16x16x32_bf16 v[78:81], v[158:161], v[214:217], v[78:81]
	v_mfma_f32_16x16x32_bf16 v[74:77], v[166:169], v[214:217], v[74:77]
	s_setprio 0
	s_setprio 1
	v_mfma_f32_16x16x32_bf16 v[118:121], v[170:173], v[186:189], v[118:121]
	v_mfma_f32_16x16x32_bf16 v[114:117], v[178:181], v[186:189], v[114:117]
	v_mfma_f32_16x16x32_bf16 v[102:105], v[170:173], v[194:197], v[102:105]
	v_mfma_f32_16x16x32_bf16 v[98:101], v[178:181], v[194:197], v[98:101]
	v_mfma_f32_16x16x32_bf16 v[86:89], v[170:173], v[202:205], v[86:89]
	v_mfma_f32_16x16x32_bf16 v[82:85], v[178:181], v[202:205], v[82:85]
	v_mfma_f32_16x16x32_bf16 v[70:73], v[170:173], v[210:213], v[70:73]
	v_mfma_f32_16x16x32_bf16 v[66:69], v[178:181], v[210:213], v[66:69]
	v_mfma_f32_16x16x32_bf16 v[118:121], v[174:177], v[190:193], v[118:121]
	v_mfma_f32_16x16x32_bf16 v[114:117], v[182:185], v[190:193], v[114:117]
	v_mfma_f32_16x16x32_bf16 v[102:105], v[174:177], v[198:201], v[102:105]
	v_mfma_f32_16x16x32_bf16 v[98:101], v[182:185], v[198:201], v[98:101]
	v_mfma_f32_16x16x32_bf16 v[86:89], v[174:177], v[206:209], v[86:89]
	v_mfma_f32_16x16x32_bf16 v[82:85], v[182:185], v[206:209], v[82:85]
	v_mfma_f32_16x16x32_bf16 v[70:73], v[174:177], v[214:217], v[70:73]
	v_mfma_f32_16x16x32_bf16 v[66:69], v[182:185], v[214:217], v[66:69]
	s_setprio 0
	s_barrier
	ds_read_b128 v[186:189], v152 offset:16384
	ds_read_b128 v[190:193], v152 offset:17408
	ds_read_b128 v[194:197], v152 offset:18432
	ds_read_b128 v[198:201], v152 offset:19456
	ds_read_b128 v[202:205], v152 offset:20480
	ds_read_b128 v[206:209], v152 offset:21504
	ds_read_b128 v[210:213], v152 offset:22528
	ds_read_b128 v[214:217], v152 offset:23552
	s_mov_b32 s78, m0
	s_mov_b32 m0, s91
	s_nop 0
	global_load_lds_dwordx4 v146, s[40:41]
	s_mov_b32 m0, s78
	s_nop 0
	s_mov_b32 s78, m0
	s_mov_b32 m0, s96
	s_nop 0
	global_load_lds_dwordx4 v148, s[40:41]
	s_mov_b32 m0, s78
	s_add_u32 s78, s40, 0x40000
	s_addc_u32 s79, s41, 0
	s_mov_b32 s82, m0
	s_mov_b32 m0, s97
	s_nop 0
	global_load_lds_dwordx4 v146, s[78:79]
	s_mov_b32 m0, s82
	s_nop 0
	s_mov_b32 s82, m0
	s_mov_b32 m0, s35
	s_nop 0
	global_load_lds_dwordx4 v148, s[78:79]
	s_mov_b32 m0, s82
	s_mov_b32 s78, m0
	s_mov_b32 m0, s67
	s_nop 0
	global_load_lds_dwordx4 v133, s[16:17]
	s_mov_b32 m0, s78
	s_nop 0
	s_mov_b32 s78, m0
	s_mov_b32 m0, s52
	s_nop 0
	global_load_lds_dwordx4 v147, s[16:17]
	s_mov_b32 m0, s78
	s_waitcnt vmcnt(8)
	s_waitcnt lgkmcnt(0)
	s_barrier
; #define PG8_STAGE(bufoff, gbase, voff) do { _Pragma("unroll") for (int _i = 0; _i < 2; ++_i) { unsigned _keep; \
;         asm volatile("s_mov_b32 %0, m0\n\ts_mov_b32 m0, %1\n\ts_nop 0\n\tglobal_load_lds_dwordx4 %2, %3\n\ts_mov_b32 m0, %0" : "=&s"(_keep) : "s"(ldsb + (unsigned)((bufoff) + _i * 8192)), "v"((voff)[_i]), "s"((const char*)(gbase)) : "memory"); } } while (0)
; #define PG8_LDA(dst, b, h) do { _Pragma("unroll") for (int m = 0; m < 4; ++m) _Pragma("unroll") for (int k = 0; k < 2; ++k) dst[m][k] = *(const LAS bf16x8*)(lds + PG8_SA(b, h) + aoff + m * 2048 + k * 1024); } while (0)
; #define PG8_LDB(dst, b, h) do { _Pragma("unroll") for (int n = 0; n < 2; ++n) _Pragma("unroll") for (int k = 0; k < 2; ++k) dst[n][k] = *(const LAS bf16x8*)(lds + PG8_SB(b, h) + boff + n * 2048 + k * 1024); } while (0)
; #define PG8_MMA(ai, bj, At, Bt) do { __builtin_amdgcn_s_setprio(1); _Pragma("unroll") for (int m = 0; m < 4; ++m) _Pragma("unroll") for (int n = 0; n < 2; ++n) _Pragma("unroll") for (int k = 0; k < 2; ++k) \
;         acc[ai][bj][m][n] = __builtin_amdgcn_mfma_f32_16x16x32_bf16(Bt[n][k], At[m][k], acc[ai][bj][m][n], 0, 0, 0); __builtin_amdgcn_s_setprio(0); } while (0)
; #define PG8_WAIT_V(n) asm volatile("s_waitcnt vmcnt(" #n ")" ::: "memory")
; #define PG8_WAIT_L(n) asm volatile("s_waitcnt lgkmcnt(" #n ")" ::: "memory")
; #define PG8_BAR __builtin_amdgcn_s_barrier()
; #define PG8_SCHED __builtin_amdgcn_sched_barrier(0)
; template <class Epi>
; __device__ __forceinline__ void gemm_phase(LAS unsigned char* lds, const Gemm g, const StaticOrder& S, const Epi& E) {
;     ...
;             PG8_WAIT_V(8); PG8_WAIT_L(0); PG8_BAR; PG8_MMA(1, 0, At, B0); PG8_MMA(1, 1, At, B1); PG8_BAR; PG8_SCHED;
;             PG8_LDB(B0, 1, 0); PG8_LDB(B1, 1, 1); PG8_SCHED; PG8_LDA(At, 1, 0); PG8_STAGE(PG8_SA(0, 1), a2 + hstepA, voffA);
;             PG8_WAIT_V(8); PG8_WAIT_L(0); PG8_BAR; PG8_MMA(0, 0, At, B0); PG8_MMA(0, 1, At, B1); PG8_BAR; PG8_SCHED;
;             PG8_LDA(At, 1, 1); PG8_STAGE(PG8_SB(1, 0), b3, voffB); PG8_STAGE(PG8_SB(1, 1), b3 + hstepB, voffB); PG8_STAGE(PG8_SA(1, 0), a3, voffA);
	s_setprio 1
	s_waitcnt lgkmcnt(7)
	v_mfma_f32_16x16x32_bf16 v[62:65], v[140:143], v[186:189], v[62:65]
	v_mfma_f32_16x16x32_bf16 v[58:61], v[162:165], v[186:189], v[58:61]
	s_waitcnt lgkmcnt(5)
	v_mfma_f32_16x16x32_bf16 v[46:49], v[140:143], v[194:197], v[46:49]
	v_mfma_f32_16x16x32_bf16 v[42:45], v[162:165], v[194:197], v[42:45]
	s_waitcnt lgkmcnt(3)
	v_mfma_f32_16x16x32_bf16 v[30:33], v[140:143], v[202:205], v[30:33]
	v_mfma_f32_16x16x32_bf16 v[26:29], v[162:165], v[202:205], v[26:29]
	s_waitcnt lgkmcnt(1)
	v_mfma_f32_16x16x32_bf16 v[14:17], v[140:143], v[210:213], v[14:17]
	v_mfma_f32_16x16x32_bf16 v[10:13], v[162:165], v[210:213], v[10:13]
	v_mfma_f32_16x16x32_bf16 v[62:65], v[158:161], v[190:193], v[62:65]
	v_mfma_f32_16x16x32_bf16 v[58:61], v[166:169], v[190:193], v[58:61]
	v_mfma_f32_16x16x32_bf16 v[46:49], v[158:161], v[198:201], v[46:49]
	v_mfma_f32_16x16x32_bf16 v[42:45], v[166:169], v[198:201], v[42:45]
	v_mfma_f32_16x16x32_bf16 v[30:33], v[158:161], v[206:209], v[30:33]
	v_mfma_f32_16x16x32_bf16 v[26:29], v[166:169], v[206:209], v[26:29]
	s_waitcnt lgkmcnt(0)
	v_mfma_f32_16x16x32_bf16 v[14:17], v[158:161], v[214:217], v[14:17]
	v_mfma_f32_16x16x32_bf16 v[10:13], v[166:169], v[214:217], v[10:13]
	s_setprio 0
	s_setprio 1
	v_mfma_f32_16x16x32_bf16 v[54:57], v[170:173], v[186:189], v[54:57]
	v_mfma_f32_16x16x32_bf16 v[50:53], v[178:181], v[186:189], v[50:53]
	v_mfma_f32_16x16x32_bf16 v[38:41], v[170:173], v[194:197], v[38:41]
	v_mfma_f32_16x16x32_bf16 v[34:37], v[178:181], v[194:197], v[34:37]
	v_mfma_f32_16x16x32_bf16 v[22:25], v[170:173], v[202:205], v[22:25]
	v_mfma_f32_16x16x32_bf16 v[18:21], v[178:181], v[202:205], v[18:21]
	v_mfma_f32_16x16x32_bf16 v[6:9], v[170:173], v[210:213], v[6:9]
	v_mfma_f32_16x16x32_bf16 v[2:5], v[178:181], v[210:213], v[2:5]
	v_mfma_f32_16x16x32_bf16 v[54:57], v[174:177], v[190:193], v[54:57]
	v_mfma_f32_16x16x32_bf16 v[50:53], v[182:185], v[190:193], v[50:53]
	v_mfma_f32_16x16x32_bf16 v[38:41], v[174:177], v[198:201], v[38:41]
	v_mfma_f32_16x16x32_bf16 v[34:37], v[182:185], v[198:201], v[34:37]
	v_mfma_f32_16x16x32_bf16 v[22:25], v[174:177], v[206:209], v[22:25]
	v_mfma_f32_16x16x32_bf16 v[18:21], v[182:185], v[206:209], v[18:21]
	v_mfma_f32_16x16x32_bf16 v[6:9], v[174:177], v[214:217], v[6:9]
	v_mfma_f32_16x16x32_bf16 v[2:5], v[182:185], v[214:217], v[2:5]
	s_setprio 0
	s_barrier
	ds_read_b128 v[140:143], v153
	ds_read_b128 v[158:161], v153 offset:1024
	ds_read_b128 v[162:165], v153 offset:2048
	ds_read_b128 v[166:169], v153 offset:3072
	ds_read_b128 v[170:173], v154
	ds_read_b128 v[174:177], v154 offset:1024
	ds_read_b128 v[178:181], v154 offset:2048
	ds_read_b128 v[182:185], v154 offset:3072
	ds_read_b128 v[186:189], v152 offset:32768
	ds_read_b128 v[190:193], v152 offset:33792
	ds_read_b128 v[194:197], v152 offset:34816
	ds_read_b128 v[198:201], v152 offset:35840
	ds_read_b128 v[202:205], v152 offset:36864
	ds_read_b128 v[206:209], v152 offset:37888
	ds_read_b128 v[210:213], v152 offset:38912
	ds_read_b128 v[214:217], v152 offset:39936
	s_add_u32 s16, s16, 0x40000
	s_addc_u32 s17, s17, 0
	s_mov_b32 s78, m0
	s_mov_b32 m0, s53
	s_nop 0
	global_load_lds_dwordx4 v133, s[16:17]
	s_mov_b32 m0, s78
	s_nop 0
	s_mov_b32 s78, m0
	s_mov_b32 m0, s14
	s_nop 0
	global_load_lds_dwordx4 v147, s[16:17]
	s_mov_b32 m0, s78
	s_waitcnt vmcnt(8)
	s_waitcnt lgkmcnt(0)
	s_barrier
	s_setprio 1
	s_waitcnt lgkmcnt(7)
	v_mfma_f32_16x16x32_bf16 v[126:129], v[140:143], v[186:189], v[126:129]
	v_mfma_f32_16x16x32_bf16 v[122:125], v[162:165], v[186:189], v[122:125]
	s_waitcnt lgkmcnt(5)
	v_mfma_f32_16x16x32_bf16 v[110:113], v[140:143], v[194:197], v[110:113]
	v_mfma_f32_16x16x32_bf16 v[106:109], v[162:165], v[194:197], v[106:109]
	s_waitcnt lgkmcnt(3)
	v_mfma_f32_16x16x32_bf16 v[94:97], v[140:143], v[202:205], v[94:97]
	v_mfma_f32_16x16x32_bf16 v[90:93], v[162:165], v[202:205], v[90:93]
	s_waitcnt lgkmcnt(1)
	v_mfma_f32_16x16x32_bf16 v[78:81], v[140:143], v[210:213], v[78:81]
	v_mfma_f32_16x16x32_bf16 v[74:77], v[162:165], v[210:213], v[74:77]
	v_mfma_f32_16x16x32_bf16 v[126:129], v[158:161], v[190:193], v[126:129]
	v_mfma_f32_16x16x32_bf16 v[122:125], v[166:169], v[190:193], v[122:125]
	v_mfma_f32_16x16x32_bf16 v[110:113], v[158:161], v[198:201], v[110:113]
	v_mfma_f32_16x16x32_bf16 v[106:109], v[166:169], v[198:201], v[106:109]
	v_mfma_f32_16x16x32_bf16 v[94:97], v[158:161], v[206:209], v[94:97]
	v_mfma_f32_16x16x32_bf16 v[90:93], v[166:169], v[206:209], v[90:93]
	s_waitcnt lgkmcnt(0)
	v_mfma_f32_16x16x32_bf16 v[78:81], v[158:161], v[214:217], v[78:81]
	v_mfma_f32_16x16x32_bf16 v[74:77], v[166:169], v[214:217], v[74:77]
	s_setprio 0
	s_setprio 1
	v_mfma_f32_16x16x32_bf16 v[118:121], v[170:173], v[186:189], v[118:121]
	v_mfma_f32_16x16x32_bf16 v[114:117], v[178:181], v[186:189], v[114:117]
	v_mfma_f32_16x16x32_bf16 v[102:105], v[170:173], v[194:197], v[102:105]
	v_mfma_f32_16x16x32_bf16 v[98:101], v[178:181], v[194:197], v[98:101]
	v_mfma_f32_16x16x32_bf16 v[86:89], v[170:173], v[202:205], v[86:89]
	v_mfma_f32_16x16x32_bf16 v[82:85], v[178:181], v[202:205], v[82:85]
	v_mfma_f32_16x16x32_bf16 v[70:73], v[170:173], v[210:213], v[70:73]
	v_mfma_f32_16x16x32_bf16 v[66:69], v[178:181], v[210:213], v[66:69]
	v_mfma_f32_16x16x32_bf16 v[118:121], v[174:177], v[190:193], v[118:121]
	v_mfma_f32_16x16x32_bf16 v[114:117], v[182:185], v[190:193], v[114:117]
	v_mfma_f32_16x16x32_bf16 v[102:105], v[174:177], v[198:201], v[102:105]
	v_mfma_f32_16x16x32_bf16 v[98:101], v[182:185], v[198:201], v[98:101]
	v_mfma_f32_16x16x32_bf16 v[86:89], v[174:177], v[206:209], v[86:89]
	v_mfma_f32_16x16x32_bf16 v[82:85], v[182:185], v[206:209], v[82:85]
	v_mfma_f32_16x16x32_bf16 v[70:73], v[174:177], v[214:217], v[70:73]
	v_mfma_f32_16x16x32_bf16 v[66:69], v[182:185], v[214:217], v[66:69]
	s_setprio 0
	s_barrier
; #define PG8_STAGE(bufoff, gbase, voff) do { _Pragma("unroll") for (int _i = 0; _i < 2; ++_i) { unsigned _keep; \
;         asm volatile("s_mov_b32 %0, m0\n\ts_mov_b32 m0, %1\n\ts_nop 0\n\tglobal_load_lds_dwordx4 %2, %3\n\ts_mov_b32 m0, %0" : "=&s"(_keep) : "s"(ldsb + (unsigned)((bufoff) + _i * 8192)), "v"((voff)[_i]), "s"((const char*)(gbase)) : "memory"); } } while (0)
; #define PG8_LDA(dst, b, h) do { _Pragma("unroll") for (int m = 0; m < 4; ++m) _Pragma("unroll") for (int k = 0; k < 2; ++k) dst[m][k] = *(const LAS bf16x8*)(lds + PG8_SA(b, h) + aoff + m * 2048 + k * 1024); } while (0)
; #define PG8_MMA(ai, bj, At, Bt) do { __builtin_amdgcn_s_setprio(1); _Pragma("unroll") for (int m = 0; m < 4; ++m) _Pragma("unroll") for (int n = 0; n < 2; ++n) _Pragma("unroll") for (int k = 0; k < 2; ++k) \
;         acc[ai][bj][m][n] = __builtin_amdgcn_mfma_f32_16x16x32_bf16(Bt[n][k], At[m][k], acc[ai][bj][m][n], 0, 0, 0); __builtin_amdgcn_s_setprio(0); } while (0)
; #define PG8_WAIT_V(n) asm volatile("s_waitcnt vmcnt(" #n ")" ::: "memory")
; #define PG8_WAIT_L(n) asm volatile("s_waitcnt lgkmcnt(" #n ")" ::: "memory")
; #define PG8_BAR __builtin_amdgcn_s_barrier()
; #define PG8_SCHED __builtin_amdgcn_sched_barrier(0)
; template <class Epi>
; __device__ __forceinline__ void gemm_phase(LAS unsigned char* lds, const Gemm g, const StaticOrder& S, const Epi& E) {
;     ...
;             PG8_LDA(At, 1, 1); PG8_STAGE(PG8_SB(1, 0), b3, voffB); PG8_STAGE(PG8_SB(1, 1), b3 + hstepB, voffB); PG8_STAGE(PG8_SA(1, 0), a3, voffA);
;             PG8_WAIT_V(8); PG8_WAIT_L(0); PG8_BAR; PG8_MMA(1, 0, At, B0); PG8_MMA(1, 1, At, B1); PG8_BAR; PG8_SCHED;
;         }
;         if (wr == 0) PG8_BAR;
;         bool run_epi = true;
	ds_read_b128 v[186:189], v152 offset:49152
	ds_read_b128 v[190:193], v152 offset:50176
	ds_read_b128 v[194:197], v152 offset:51200
	ds_read_b128 v[198:201], v152 offset:52224
	ds_read_b128 v[202:205], v152 offset:53248
	ds_read_b128 v[206:209], v152 offset:54272
	ds_read_b128 v[210:213], v152 offset:55296
	ds_read_b128 v[214:217], v152 offset:56320
	s_add_u32 s16, s40, 0x80
	s_addc_u32 s17, s41, 0
	s_mov_b32 s78, m0
	s_mov_b32 m0, s87
	s_nop 0
	global_load_lds_dwordx4 v146, s[16:17]
	s_mov_b32 m0, s78
	s_nop 0
	s_mov_b32 s78, m0
	s_mov_b32 m0, s80
	s_nop 0
	global_load_lds_dwordx4 v148, s[16:17]
	s_mov_b32 m0, s78
	s_add_u32 s16, s40, 0x40080
	s_addc_u32 s17, s41, 0
	s_mov_b32 s40, m0
	s_mov_b32 m0, s42
	s_nop 0
	global_load_lds_dwordx4 v146, s[16:17]
	s_mov_b32 m0, s40
	s_nop 0
	s_mov_b32 s40, m0
	s_mov_b32 m0, s43
	s_nop 0
	global_load_lds_dwordx4 v148, s[16:17]
	s_mov_b32 m0, s40
	s_mov_b32 s16, m0
	s_mov_b32 m0, s81
	s_nop 0
	global_load_lds_dwordx4 v133, s[12:13]
	s_mov_b32 m0, s16
	s_nop 0
	s_mov_b32 s16, m0
	s_mov_b32 m0, s33
	s_nop 0
	global_load_lds_dwordx4 v147, s[12:13]
	s_mov_b32 m0, s16
	s_waitcnt vmcnt(8)
	s_waitcnt lgkmcnt(0)
	s_barrier
	s_setprio 1
	s_waitcnt lgkmcnt(7)
	v_mfma_f32_16x16x32_bf16 v[62:65], v[140:143], v[186:189], v[62:65]
	v_mfma_f32_16x16x32_bf16 v[58:61], v[162:165], v[186:189], v[58:61]
	s_waitcnt lgkmcnt(5)
	v_mfma_f32_16x16x32_bf16 v[46:49], v[140:143], v[194:197], v[46:49]
	v_mfma_f32_16x16x32_bf16 v[42:45], v[162:165], v[194:197], v[42:45]
	s_waitcnt lgkmcnt(3)
	v_mfma_f32_16x16x32_bf16 v[30:33], v[140:143], v[202:205], v[30:33]
	v_mfma_f32_16x16x32_bf16 v[26:29], v[162:165], v[202:205], v[26:29]
	s_waitcnt lgkmcnt(1)
	v_mfma_f32_16x16x32_bf16 v[14:17], v[140:143], v[210:213], v[14:17]
	v_mfma_f32_16x16x32_bf16 v[10:13], v[162:165], v[210:213], v[10:13]
	v_mfma_f32_16x16x32_bf16 v[62:65], v[158:161], v[190:193], v[62:65]
	v_mfma_f32_16x16x32_bf16 v[58:61], v[166:169], v[190:193], v[58:61]
	v_mfma_f32_16x16x32_bf16 v[46:49], v[158:161], v[198:201], v[46:49]
	v_mfma_f32_16x16x32_bf16 v[42:45], v[166:169], v[198:201], v[42:45]
	v_mfma_f32_16x16x32_bf16 v[30:33], v[158:161], v[206:209], v[30:33]
	v_mfma_f32_16x16x32_bf16 v[26:29], v[166:169], v[206:209], v[26:29]
	s_waitcnt lgkmcnt(0)
	v_mfma_f32_16x16x32_bf16 v[14:17], v[158:161], v[214:217], v[14:17]
	v_mfma_f32_16x16x32_bf16 v[10:13], v[166:169], v[214:217], v[10:13]
	s_setprio 0
	s_setprio 1
	v_mfma_f32_16x16x32_bf16 v[54:57], v[170:173], v[186:189], v[54:57]
	v_mfma_f32_16x16x32_bf16 v[50:53], v[178:181], v[186:189], v[50:53]
	v_mfma_f32_16x16x32_bf16 v[38:41], v[170:173], v[194:197], v[38:41]
	v_mfma_f32_16x16x32_bf16 v[34:37], v[178:181], v[194:197], v[34:37]
	v_mfma_f32_16x16x32_bf16 v[22:25], v[170:173], v[202:205], v[22:25]
	v_mfma_f32_16x16x32_bf16 v[18:21], v[178:181], v[202:205], v[18:21]
	v_mfma_f32_16x16x32_bf16 v[6:9], v[170:173], v[210:213], v[6:9]
	v_mfma_f32_16x16x32_bf16 v[2:5], v[178:181], v[210:213], v[2:5]
	v_mfma_f32_16x16x32_bf16 v[54:57], v[174:177], v[190:193], v[54:57]
	v_mfma_f32_16x16x32_bf16 v[50:53], v[182:185], v[190:193], v[50:53]
	v_mfma_f32_16x16x32_bf16 v[38:41], v[174:177], v[198:201], v[38:41]
	v_mfma_f32_16x16x32_bf16 v[34:37], v[182:185], v[198:201], v[34:37]
	v_mfma_f32_16x16x32_bf16 v[22:25], v[174:177], v[206:209], v[22:25]
	v_mfma_f32_16x16x32_bf16 v[18:21], v[182:185], v[206:209], v[18:21]
	v_mfma_f32_16x16x32_bf16 v[6:9], v[174:177], v[214:217], v[6:9]
	v_mfma_f32_16x16x32_bf16 v[2:5], v[182:185], v[214:217], v[2:5]
	s_setprio 0
	s_add_i32 s77, s77, 2
	s_add_u32 s69, s69, 0x100
	s_addc_u32 s74, s74, 0
	s_add_u32 s75, s75, 0x100
	s_addc_u32 s76, s76, 0
	s_cmp_gt_u32 s77, 13
	s_barrier
	s_cbranch_scc0 .LBB0_435
	v_readlane_b32 s12, v255, 38
	v_readlane_b32 s13, v255, 39
	s_and_b64 vcc, exec, s[12:13]
	s_cbranch_vccz .LBB0_438
	s_barrier

; #define PG8_STAGE(bufoff, gbase, voff) do { _Pragma("unroll") for (int _i = 0; _i < 2; ++_i) { unsigned _keep; \
;         asm volatile("s_mov_b32 %0, m0\n\ts_mov_b32 m0, %1\n\ts_nop 0\n\tglobal_load_lds_dwordx4 %2, %3\n\ts_mov_b32 m0, %0" : "=&s"(_keep) : "s"(ldsb + (unsigned)((bufoff) + _i * 8192)), "v"((voff)[_i]), "s"((const char*)(gbase)) : "memory"); } } while (0)
; #define PG8_LDA(dst, b, h) do { _Pragma("unroll") for (int m = 0; m < 4; ++m) _Pragma("unroll") for (int k = 0; k < 2; ++k) dst[m][k] = *(const LAS bf16x8*)(lds + PG8_SA(b, h) + aoff + m * 2048 + k * 1024); } while (0)
; #define PG8_LDB(dst, b, h) do { _Pragma("unroll") for (int n = 0; n < 2; ++n) _Pragma("unroll") for (int k = 0; k < 2; ++k) dst[n][k] = *(const LAS bf16x8*)(lds + PG8_SB(b, h) + boff + n * 2048 + k * 1024); } while (0)
; #define PG8_MMA(ai, bj, At, Bt) do { __builtin_amdgcn_s_setprio(1); _Pragma("unroll") for (int m = 0; m < 4; ++m) _Pragma("unroll") for (int n = 0; n < 2; ++n) _Pragma("unroll") for (int k = 0; k < 2; ++k) \
;         acc[ai][bj][m][n] = __builtin_amdgcn_mfma_f32_16x16x32_bf16(Bt[n][k], At[m][k], acc[ai][bj][m][n], 0, 0, 0); __builtin_amdgcn_s_setprio(0); } while (0)
; #define PG8_WAIT_V(n) asm volatile("s_waitcnt vmcnt(" #n ")" ::: "memory")
; #define PG8_WAIT_L(n) asm volatile("s_waitcnt lgkmcnt(" #n ")" ::: "memory")
; template <class Epi>
; __device__ __forceinline__ void gemm_phase(LAS unsigned char* lds, const Gemm g, const StaticOrder& S, const Epi& E) {
;     ...
;         for (int t = 0; t < nt; t += 2) {
;             const bool last = (t == nt - 2);
;             const char* a1 = cA + (size_t)(t + 1) * kstep;
;             const char* a2 = last ? nA : cA + (size_t)(t + 2) * kstep; const char* b2 = last ? nB : cB + (size_t)(t + 2) * kstep;
;             const char* a3 = a2 + kstep; const char* b3 = b2 + kstep;
;             PG8_LDB(B0, 0, 0); PG8_LDB(B1, 0, 1); PG8_SCHED; PG8_LDA(At, 0, 0); PG8_STAGE(PG8_SA(1, 1), a1 + hstepA, voffA);
;             PG8_WAIT_V(8); PG8_WAIT_L(0); PG8_BAR; PG8_MMA(0, 0, At, B0); PG8_MMA(0, 1, At, B1); PG8_BAR; PG8_SCHED;
;             PG8_LDA(At, 0, 1); PG8_STAGE(PG8_SB(0, 0), b2, voffB); PG8_STAGE(PG8_SB(0, 1), b2 + hstepB, voffB); PG8_STAGE(PG8_SA(0, 0), a2, voffA);
;             PG8_WAIT_V(8); PG8_WAIT_L(0); PG8_BAR; PG8_MMA(1, 0, At, B0); PG8_MMA(1, 1, At, B1); PG8_BAR; PG8_SCHED;
.LBB0_930:
	ds_read_b128 v[144:147], v166
	ds_read_b128 v[148:151], v166 offset:1024
	ds_read_b128 v[152:155], v166 offset:2048
	ds_read_b128 v[156:159], v166 offset:3072
	ds_read_b128 v[172:175], v167
	ds_read_b128 v[176:179], v167 offset:1024
	ds_read_b128 v[180:183], v167 offset:2048
	ds_read_b128 v[184:187], v167 offset:3072
	s_cmp_eq_u32 s52, 2
	s_cselect_b32 s8, s42, s40
	s_cselect_b32 s9, s43, s41
	s_cselect_b32 s6, s44, s46
	s_cselect_b32 s7, s45, s47
	s_add_u32 s0, s8, 0x80
	s_addc_u32 s1, s9, 0
	ds_read_b128 v[188:191], v168
	ds_read_b128 v[192:195], v168 offset:1024
	ds_read_b128 v[196:199], v168 offset:2048
	ds_read_b128 v[200:203], v168 offset:3072
	ds_read_b128 v[204:207], v168 offset:4096
	ds_read_b128 v[208:211], v168 offset:5120
	ds_read_b128 v[212:215], v168 offset:6144
	ds_read_b128 v[216:219], v168 offset:7168
	s_add_u32 s82, s40, 0x2ff80
	s_addc_u32 s83, s41, 0
	s_mov_b32 s53, m0
	s_mov_b32 m0, s67
	s_nop 0
	global_load_lds_dwordx4 v131, s[82:83]
	s_mov_b32 m0, s53
	s_nop 0
	s_mov_b32 s53, m0
	s_mov_b32 m0, s68
	s_nop 0
	global_load_lds_dwordx4 v141, s[82:83]
	s_mov_b32 m0, s53
	s_waitcnt vmcnt(8)
	s_waitcnt lgkmcnt(0)
	s_barrier
	s_setprio 1
	s_waitcnt lgkmcnt(7)
	v_mfma_f32_16x16x32_bf16 v[126:129], v[144:147], v[188:191], v[126:129]
	v_mfma_f32_16x16x32_bf16 v[122:125], v[152:155], v[188:191], v[122:125]
	s_waitcnt lgkmcnt(5)
	v_mfma_f32_16x16x32_bf16 v[110:113], v[144:147], v[196:199], v[110:113]
	v_mfma_f32_16x16x32_bf16 v[106:109], v[152:155], v[196:199], v[106:109]
	s_waitcnt lgkmcnt(3)
	v_mfma_f32_16x16x32_bf16 v[94:97], v[144:147], v[204:207], v[94:97]
	v_mfma_f32_16x16x32_bf16 v[90:93], v[152:155], v[204:207], v[90:93]
	s_waitcnt lgkmcnt(1)
	v_mfma_f32_16x16x32_bf16 v[78:81], v[144:147], v[212:215], v[78:81]
	v_mfma_f32_16x16x32_bf16 v[74:77], v[152:155], v[212:215], v[74:77]
	v_mfma_f32_16x16x32_bf16 v[126:129], v[148:151], v[192:195], v[126:129]
	v_mfma_f32_16x16x32_bf16 v[122:125], v[156:159], v[192:195], v[122:125]
	v_mfma_f32_16x16x32_bf16 v[110:113], v[148:151], v[200:203], v[110:113]
	v_mfma_f32_16x16x32_bf16 v[106:109], v[156:159], v[200:203], v[106:109]
	v_mfma_f32_16x16x32_bf16 v[94:97], v[148:151], v[208:211], v[94:97]
	v_mfma_f32_16x16x32_bf16 v[90:93], v[156:159], v[208:211], v[90:93]
	s_waitcnt lgkmcnt(0)
	v_mfma_f32_16x16x32_bf16 v[78:81], v[148:151], v[216:219], v[78:81]
	v_mfma_f32_16x16x32_bf16 v[74:77], v[156:159], v[216:219], v[74:77]
	s_setprio 0
	s_setprio 1
	v_mfma_f32_16x16x32_bf16 v[118:121], v[172:175], v[188:191], v[118:121]
	v_mfma_f32_16x16x32_bf16 v[114:117], v[180:183], v[188:191], v[114:117]
	v_mfma_f32_16x16x32_bf16 v[102:105], v[172:175], v[196:199], v[102:105]
	v_mfma_f32_16x16x32_bf16 v[98:101], v[180:183], v[196:199], v[98:101]
	v_mfma_f32_16x16x32_bf16 v[86:89], v[172:175], v[204:207], v[86:89]
	v_mfma_f32_16x16x32_bf16 v[82:85], v[180:183], v[204:207], v[82:85]
	v_mfma_f32_16x16x32_bf16 v[70:73], v[172:175], v[212:215], v[70:73]
	v_mfma_f32_16x16x32_bf16 v[66:69], v[180:183], v[212:215], v[66:69]
	v_mfma_f32_16x16x32_bf16 v[118:121], v[176:179], v[192:195], v[118:121]
	v_mfma_f32_16x16x32_bf16 v[114:117], v[184:187], v[192:195], v[114:117]
	v_mfma_f32_16x16x32_bf16 v[102:105], v[176:179], v[200:203], v[102:105]
	v_mfma_f32_16x16x32_bf16 v[98:101], v[184:187], v[200:203], v[98:101]
	v_mfma_f32_16x16x32_bf16 v[86:89], v[176:179], v[208:211], v[86:89]
	v_mfma_f32_16x16x32_bf16 v[82:85], v[184:187], v[208:211], v[82:85]
	v_mfma_f32_16x16x32_bf16 v[70:73], v[176:179], v[216:219], v[70:73]
	v_mfma_f32_16x16x32_bf16 v[66:69], v[184:187], v[216:219], v[66:69]
	s_setprio 0
	s_barrier
	ds_read_b128 v[188:191], v168 offset:16384
	ds_read_b128 v[192:195], v168 offset:17408
	ds_read_b128 v[196:199], v168 offset:18432
	ds_read_b128 v[200:203], v168 offset:19456
	ds_read_b128 v[204:207], v168 offset:20480
	ds_read_b128 v[208:211], v168 offset:21504
	ds_read_b128 v[212:215], v168 offset:22528
	ds_read_b128 v[216:219], v168 offset:23552
	s_mov_b32 s53, m0
	s_mov_b32 m0, s50
	s_nop 0
	global_load_lds_dwordx4 v133, s[6:7]
	s_mov_b32 m0, s53
	s_add_u32 s82, s6, 0x18000
	s_mov_b32 s53, m0
	s_mov_b32 m0, s51
	s_nop 0
	global_load_lds_dwordx4 v160, s[6:7]
	s_mov_b32 m0, s53
	s_addc_u32 s83, s7, 0
	s_mov_b32 s53, m0
	s_mov_b32 m0, s54
	s_nop 0
	global_load_lds_dwordx4 v133, s[82:83]
	s_mov_b32 m0, s53
	s_nop 0
	s_mov_b32 s53, m0
	s_mov_b32 m0, s55
	s_nop 0
	global_load_lds_dwordx4 v160, s[82:83]
	s_mov_b32 m0, s53
	s_nop 0
	s_mov_b32 s53, m0
	s_mov_b32 m0, s35
	s_nop 0
	global_load_lds_dwordx4 v131, s[8:9]
	s_mov_b32 m0, s53
	s_nop 0
	s_mov_b32 s53, m0
	s_mov_b32 m0, s56
	s_nop 0
	global_load_lds_dwordx4 v141, s[8:9]
	s_mov_b32 m0, s53
	s_waitcnt vmcnt(8)
	s_waitcnt lgkmcnt(0)
	s_barrier
; #define PG8_STAGE(bufoff, gbase, voff) do { _Pragma("unroll") for (int _i = 0; _i < 2; ++_i) { unsigned _keep; \
;         asm volatile("s_mov_b32 %0, m0\n\ts_mov_b32 m0, %1\n\ts_nop 0\n\tglobal_load_lds_dwordx4 %2, %3\n\ts_mov_b32 m0, %0" : "=&s"(_keep) : "s"(ldsb + (unsigned)((bufoff) + _i * 8192)), "v"((voff)[_i]), "s"((const char*)(gbase)) : "memory"); } } while (0)
; #define PG8_LDA(dst, b, h) do { _Pragma("unroll") for (int m = 0; m < 4; ++m) _Pragma("unroll") for (int k = 0; k < 2; ++k) dst[m][k] = *(const LAS bf16x8*)(lds + PG8_SA(b, h) + aoff + m * 2048 + k * 1024); } while (0)
; #define PG8_LDB(dst, b, h) do { _Pragma("unroll") for (int n = 0; n < 2; ++n) _Pragma("unroll") for (int k = 0; k < 2; ++k) dst[n][k] = *(const LAS bf16x8*)(lds + PG8_SB(b, h) + boff + n * 2048 + k * 1024); } while (0)
; #define PG8_MMA(ai, bj, At, Bt) do { __builtin_amdgcn_s_setprio(1); _Pragma("unroll") for (int m = 0; m < 4; ++m) _Pragma("unroll") for (int n = 0; n < 2; ++n) _Pragma("unroll") for (int k = 0; k < 2; ++k) \
;         acc[ai][bj][m][n] = __builtin_amdgcn_mfma_f32_16x16x32_bf16(Bt[n][k], At[m][k], acc[ai][bj][m][n], 0, 0, 0); __builtin_amdgcn_s_setprio(0); } while (0)
; #define PG8_WAIT_V(n) asm volatile("s_waitcnt vmcnt(" #n ")" ::: "memory")
; #define PG8_WAIT_L(n) asm volatile("s_waitcnt lgkmcnt(" #n ")" ::: "memory")
; #define PG8_BAR __builtin_amdgcn_s_barrier()
; #define PG8_SCHED __builtin_amdgcn_sched_barrier(0)
; template <class Epi>
; __device__ __forceinline__ void gemm_phase(LAS unsigned char* lds, const Gemm g, const StaticOrder& S, const Epi& E) {
;     ...
;             PG8_WAIT_V(8); PG8_WAIT_L(0); PG8_BAR; PG8_MMA(1, 0, At, B0); PG8_MMA(1, 1, At, B1); PG8_BAR; PG8_SCHED;
;             PG8_LDB(B0, 1, 0); PG8_LDB(B1, 1, 1); PG8_SCHED; PG8_LDA(At, 1, 0); PG8_STAGE(PG8_SA(0, 1), a2 + hstepA, voffA);
;             PG8_WAIT_V(8); PG8_WAIT_L(0); PG8_BAR; PG8_MMA(0, 0, At, B0); PG8_MMA(0, 1, At, B1); PG8_BAR; PG8_SCHED;
;             PG8_LDA(At, 1, 1); PG8_STAGE(PG8_SB(1, 0), b3, voffB); PG8_STAGE(PG8_SB(1, 1), b3 + hstepB, voffB); PG8_STAGE(PG8_SA(1, 0), a3, voffA);
	s_setprio 1
	s_waitcnt lgkmcnt(7)
	v_mfma_f32_16x16x32_bf16 v[62:65], v[144:147], v[188:191], v[62:65]
	v_mfma_f32_16x16x32_bf16 v[58:61], v[152:155], v[188:191], v[58:61]
	s_waitcnt lgkmcnt(5)
	v_mfma_f32_16x16x32_bf16 v[46:49], v[144:147], v[196:199], v[46:49]
	v_mfma_f32_16x16x32_bf16 v[42:45], v[152:155], v[196:199], v[42:45]
	s_waitcnt lgkmcnt(3)
	v_mfma_f32_16x16x32_bf16 v[30:33], v[144:147], v[204:207], v[30:33]
	v_mfma_f32_16x16x32_bf16 v[26:29], v[152:155], v[204:207], v[26:29]
	s_waitcnt lgkmcnt(1)
	v_mfma_f32_16x16x32_bf16 v[14:17], v[144:147], v[212:215], v[14:17]
	v_mfma_f32_16x16x32_bf16 v[10:13], v[152:155], v[212:215], v[10:13]
	v_mfma_f32_16x16x32_bf16 v[62:65], v[148:151], v[192:195], v[62:65]
	v_mfma_f32_16x16x32_bf16 v[58:61], v[156:159], v[192:195], v[58:61]
	v_mfma_f32_16x16x32_bf16 v[46:49], v[148:151], v[200:203], v[46:49]
	v_mfma_f32_16x16x32_bf16 v[42:45], v[156:159], v[200:203], v[42:45]
	v_mfma_f32_16x16x32_bf16 v[30:33], v[148:151], v[208:211], v[30:33]
	v_mfma_f32_16x16x32_bf16 v[26:29], v[156:159], v[208:211], v[26:29]
	s_waitcnt lgkmcnt(0)
	v_mfma_f32_16x16x32_bf16 v[14:17], v[148:151], v[216:219], v[14:17]
	v_mfma_f32_16x16x32_bf16 v[10:13], v[156:159], v[216:219], v[10:13]
	s_setprio 0
	s_setprio 1
	v_mfma_f32_16x16x32_bf16 v[54:57], v[172:175], v[188:191], v[54:57]
	v_mfma_f32_16x16x32_bf16 v[50:53], v[180:183], v[188:191], v[50:53]
	v_mfma_f32_16x16x32_bf16 v[38:41], v[172:175], v[196:199], v[38:41]
	v_mfma_f32_16x16x32_bf16 v[34:37], v[180:183], v[196:199], v[34:37]
	v_mfma_f32_16x16x32_bf16 v[22:25], v[172:175], v[204:207], v[22:25]
	v_mfma_f32_16x16x32_bf16 v[18:21], v[180:183], v[204:207], v[18:21]
	v_mfma_f32_16x16x32_bf16 v[6:9], v[172:175], v[212:215], v[6:9]
	v_mfma_f32_16x16x32_bf16 v[2:5], v[180:183], v[212:215], v[2:5]
	v_mfma_f32_16x16x32_bf16 v[54:57], v[176:179], v[192:195], v[54:57]
	v_mfma_f32_16x16x32_bf16 v[50:53], v[184:187], v[192:195], v[50:53]
	v_mfma_f32_16x16x32_bf16 v[38:41], v[176:179], v[200:203], v[38:41]
	v_mfma_f32_16x16x32_bf16 v[34:37], v[184:187], v[200:203], v[34:37]
	v_mfma_f32_16x16x32_bf16 v[22:25], v[176:179], v[208:211], v[22:25]
	v_mfma_f32_16x16x32_bf16 v[18:21], v[184:187], v[208:211], v[18:21]
	v_mfma_f32_16x16x32_bf16 v[6:9], v[176:179], v[216:219], v[6:9]
	v_mfma_f32_16x16x32_bf16 v[2:5], v[184:187], v[216:219], v[2:5]
	s_setprio 0
	s_barrier
	ds_read_b128 v[144:147], v169
	ds_read_b128 v[148:151], v169 offset:1024
	ds_read_b128 v[152:155], v169 offset:2048
	ds_read_b128 v[156:159], v169 offset:3072
	ds_read_b128 v[172:175], v170
	ds_read_b128 v[176:179], v170 offset:1024
	ds_read_b128 v[180:183], v170 offset:2048
	ds_read_b128 v[184:187], v170 offset:3072
	ds_read_b128 v[188:191], v168 offset:32768
	ds_read_b128 v[192:195], v168 offset:33792
	ds_read_b128 v[196:199], v168 offset:34816
	ds_read_b128 v[200:203], v168 offset:35840
	ds_read_b128 v[204:207], v168 offset:36864
	ds_read_b128 v[208:211], v168 offset:37888
	ds_read_b128 v[212:215], v168 offset:38912
	ds_read_b128 v[216:219], v168 offset:39936
	s_add_u32 s8, s8, 0x30000
	s_addc_u32 s9, s9, 0
	s_mov_b32 s53, m0
	s_mov_b32 m0, s57
	s_nop 0
	global_load_lds_dwordx4 v131, s[8:9]
	s_mov_b32 m0, s53
	s_nop 0
	s_mov_b32 s53, m0
	s_mov_b32 m0, s58
	s_nop 0
	global_load_lds_dwordx4 v141, s[8:9]
	s_mov_b32 m0, s53
	s_waitcnt vmcnt(8)
	s_waitcnt lgkmcnt(0)
	s_barrier
	s_setprio 1
	s_waitcnt lgkmcnt(7)
	v_mfma_f32_16x16x32_bf16 v[126:129], v[144:147], v[188:191], v[126:129]
	v_mfma_f32_16x16x32_bf16 v[122:125], v[152:155], v[188:191], v[122:125]
	s_waitcnt lgkmcnt(5)
	v_mfma_f32_16x16x32_bf16 v[110:113], v[144:147], v[196:199], v[110:113]
	v_mfma_f32_16x16x32_bf16 v[106:109], v[152:155], v[196:199], v[106:109]
	s_waitcnt lgkmcnt(3)
	v_mfma_f32_16x16x32_bf16 v[94:97], v[144:147], v[204:207], v[94:97]
	v_mfma_f32_16x16x32_bf16 v[90:93], v[152:155], v[204:207], v[90:93]
	s_waitcnt lgkmcnt(1)
	v_mfma_f32_16x16x32_bf16 v[78:81], v[144:147], v[212:215], v[78:81]
	v_mfma_f32_16x16x32_bf16 v[74:77], v[152:155], v[212:215], v[74:77]
	v_mfma_f32_16x16x32_bf16 v[126:129], v[148:151], v[192:195], v[126:129]
	v_mfma_f32_16x16x32_bf16 v[122:125], v[156:159], v[192:195], v[122:125]
	v_mfma_f32_16x16x32_bf16 v[110:113], v[148:151], v[200:203], v[110:113]
	v_mfma_f32_16x16x32_bf16 v[106:109], v[156:159], v[200:203], v[106:109]
	v_mfma_f32_16x16x32_bf16 v[94:97], v[148:151], v[208:211], v[94:97]
	v_mfma_f32_16x16x32_bf16 v[90:93], v[156:159], v[208:211], v[90:93]
	s_waitcnt lgkmcnt(0)
	v_mfma_f32_16x16x32_bf16 v[78:81], v[148:151], v[216:219], v[78:81]
	v_mfma_f32_16x16x32_bf16 v[74:77], v[156:159], v[216:219], v[74:77]
	s_setprio 0
	s_setprio 1
	v_mfma_f32_16x16x32_bf16 v[118:121], v[172:175], v[188:191], v[118:121]
	v_mfma_f32_16x16x32_bf16 v[114:117], v[180:183], v[188:191], v[114:117]
	v_mfma_f32_16x16x32_bf16 v[102:105], v[172:175], v[196:199], v[102:105]
	v_mfma_f32_16x16x32_bf16 v[98:101], v[180:183], v[196:199], v[98:101]
	v_mfma_f32_16x16x32_bf16 v[86:89], v[172:175], v[204:207], v[86:89]
	v_mfma_f32_16x16x32_bf16 v[82:85], v[180:183], v[204:207], v[82:85]
	v_mfma_f32_16x16x32_bf16 v[70:73], v[172:175], v[212:215], v[70:73]
	v_mfma_f32_16x16x32_bf16 v[66:69], v[180:183], v[212:215], v[66:69]
	v_mfma_f32_16x16x32_bf16 v[118:121], v[176:179], v[192:195], v[118:121]
	v_mfma_f32_16x16x32_bf16 v[114:117], v[184:187], v[192:195], v[114:117]
	v_mfma_f32_16x16x32_bf16 v[102:105], v[176:179], v[200:203], v[102:105]
	v_mfma_f32_16x16x32_bf16 v[98:101], v[184:187], v[200:203], v[98:101]
	v_mfma_f32_16x16x32_bf16 v[86:89], v[176:179], v[208:211], v[86:89]
	v_mfma_f32_16x16x32_bf16 v[82:85], v[184:187], v[208:211], v[82:85]
	v_mfma_f32_16x16x32_bf16 v[70:73], v[176:179], v[216:219], v[70:73]
	v_mfma_f32_16x16x32_bf16 v[66:69], v[184:187], v[216:219], v[66:69]
	s_setprio 0
	s_barrier
; #define PG8_STAGE(bufoff, gbase, voff) do { _Pragma("unroll") for (int _i = 0; _i < 2; ++_i) { unsigned _keep; \
;         asm volatile("s_mov_b32 %0, m0\n\ts_mov_b32 m0, %1\n\ts_nop 0\n\tglobal_load_lds_dwordx4 %2, %3\n\ts_mov_b32 m0, %0" : "=&s"(_keep) : "s"(ldsb + (unsigned)((bufoff) + _i * 8192)), "v"((voff)[_i]), "s"((const char*)(gbase)) : "memory"); } } while (0)
; #define PG8_LDA(dst, b, h) do { _Pragma("unroll") for (int m = 0; m < 4; ++m) _Pragma("unroll") for (int k = 0; k < 2; ++k) dst[m][k] = *(const LAS bf16x8*)(lds + PG8_SA(b, h) + aoff + m * 2048 + k * 1024); } while (0)
; #define PG8_MMA(ai, bj, At, Bt) do { __builtin_amdgcn_s_setprio(1); _Pragma("unroll") for (int m = 0; m < 4; ++m) _Pragma("unroll") for (int n = 0; n < 2; ++n) _Pragma("unroll") for (int k = 0; k < 2; ++k) \
;         acc[ai][bj][m][n] = __builtin_amdgcn_mfma_f32_16x16x32_bf16(Bt[n][k], At[m][k], acc[ai][bj][m][n], 0, 0, 0); __builtin_amdgcn_s_setprio(0); } while (0)
; #define PG8_WAIT_V(n) asm volatile("s_waitcnt vmcnt(" #n ")" ::: "memory")
; #define PG8_WAIT_L(n) asm volatile("s_waitcnt lgkmcnt(" #n ")" ::: "memory")
; #define PG8_BAR __builtin_amdgcn_s_barrier()
; #define PG8_SCHED __builtin_amdgcn_sched_barrier(0)
; template <class Epi>
; __device__ __forceinline__ void gemm_phase(LAS unsigned char* lds, const Gemm g, const StaticOrder& S, const Epi& E) {
;     ...
;             PG8_LDA(At, 1, 1); PG8_STAGE(PG8_SB(1, 0), b3, voffB); PG8_STAGE(PG8_SB(1, 1), b3 + hstepB, voffB); PG8_STAGE(PG8_SA(1, 0), a3, voffA);
;             PG8_WAIT_V(8); PG8_WAIT_L(0); PG8_BAR; PG8_MMA(1, 0, At, B0); PG8_MMA(1, 1, At, B1); PG8_BAR; PG8_SCHED;
;         }
;         if (wr == 0) PG8_BAR;
;         bool run_epi = true;
	ds_read_b128 v[188:191], v168 offset:49152
	ds_read_b128 v[192:195], v168 offset:50176
	ds_read_b128 v[196:199], v168 offset:51200
	ds_read_b128 v[200:203], v168 offset:52224
	ds_read_b128 v[204:207], v168 offset:53248
	ds_read_b128 v[208:211], v168 offset:54272
	ds_read_b128 v[212:215], v168 offset:55296
	ds_read_b128 v[216:219], v168 offset:56320
	s_add_u32 s8, s6, 0x80
	s_addc_u32 s9, s7, 0
	s_mov_b32 s53, m0
	s_mov_b32 m0, s60
	s_nop 0
	global_load_lds_dwordx4 v133, s[8:9]
	s_mov_b32 m0, s53
	s_add_u32 s6, s6, 0x18080
	s_mov_b32 s53, m0
	s_mov_b32 m0, s61
	s_nop 0
	global_load_lds_dwordx4 v160, s[8:9]
	s_mov_b32 m0, s53
	s_addc_u32 s7, s7, 0
	s_mov_b32 s8, m0
	s_mov_b32 m0, s65
	s_nop 0
	global_load_lds_dwordx4 v133, s[6:7]
	s_mov_b32 m0, s8
	s_nop 0
	s_mov_b32 s8, m0
	s_mov_b32 m0, s66
	s_nop 0
	global_load_lds_dwordx4 v160, s[6:7]
	s_mov_b32 m0, s8
	s_mov_b32 s6, m0
	s_mov_b32 m0, s63
	s_nop 0
	global_load_lds_dwordx4 v131, s[0:1]
	s_mov_b32 m0, s6
	s_nop 0
	s_mov_b32 s6, m0
	s_mov_b32 m0, s64
	s_nop 0
	global_load_lds_dwordx4 v141, s[0:1]
	s_mov_b32 m0, s6
	s_waitcnt vmcnt(8)
	s_waitcnt lgkmcnt(0)
	s_barrier
	s_setprio 1
	s_waitcnt lgkmcnt(7)
	v_mfma_f32_16x16x32_bf16 v[62:65], v[144:147], v[188:191], v[62:65]
	v_mfma_f32_16x16x32_bf16 v[58:61], v[152:155], v[188:191], v[58:61]
	s_waitcnt lgkmcnt(5)
	v_mfma_f32_16x16x32_bf16 v[46:49], v[144:147], v[196:199], v[46:49]
	v_mfma_f32_16x16x32_bf16 v[42:45], v[152:155], v[196:199], v[42:45]
	s_waitcnt lgkmcnt(3)
	v_mfma_f32_16x16x32_bf16 v[30:33], v[144:147], v[204:207], v[30:33]
	v_mfma_f32_16x16x32_bf16 v[26:29], v[152:155], v[204:207], v[26:29]
	s_waitcnt lgkmcnt(1)
	v_mfma_f32_16x16x32_bf16 v[14:17], v[144:147], v[212:215], v[14:17]
	v_mfma_f32_16x16x32_bf16 v[10:13], v[152:155], v[212:215], v[10:13]
	v_mfma_f32_16x16x32_bf16 v[62:65], v[148:151], v[192:195], v[62:65]
	v_mfma_f32_16x16x32_bf16 v[58:61], v[156:159], v[192:195], v[58:61]
	v_mfma_f32_16x16x32_bf16 v[46:49], v[148:151], v[200:203], v[46:49]
	v_mfma_f32_16x16x32_bf16 v[42:45], v[156:159], v[200:203], v[42:45]
	v_mfma_f32_16x16x32_bf16 v[30:33], v[148:151], v[208:211], v[30:33]
	v_mfma_f32_16x16x32_bf16 v[26:29], v[156:159], v[208:211], v[26:29]
	s_waitcnt lgkmcnt(0)
	v_mfma_f32_16x16x32_bf16 v[14:17], v[148:151], v[216:219], v[14:17]
	v_mfma_f32_16x16x32_bf16 v[10:13], v[156:159], v[216:219], v[10:13]
	s_setprio 0
	s_setprio 1
	v_mfma_f32_16x16x32_bf16 v[54:57], v[172:175], v[188:191], v[54:57]
	v_mfma_f32_16x16x32_bf16 v[50:53], v[180:183], v[188:191], v[50:53]
	v_mfma_f32_16x16x32_bf16 v[38:41], v[172:175], v[196:199], v[38:41]
	v_mfma_f32_16x16x32_bf16 v[34:37], v[180:183], v[196:199], v[34:37]
	v_mfma_f32_16x16x32_bf16 v[22:25], v[172:175], v[204:207], v[22:25]
	v_mfma_f32_16x16x32_bf16 v[18:21], v[180:183], v[204:207], v[18:21]
	v_mfma_f32_16x16x32_bf16 v[6:9], v[172:175], v[212:215], v[6:9]
	v_mfma_f32_16x16x32_bf16 v[2:5], v[180:183], v[212:215], v[2:5]
	v_mfma_f32_16x16x32_bf16 v[54:57], v[176:179], v[192:195], v[54:57]
	v_mfma_f32_16x16x32_bf16 v[50:53], v[184:187], v[192:195], v[50:53]
	v_mfma_f32_16x16x32_bf16 v[38:41], v[176:179], v[200:203], v[38:41]
	v_mfma_f32_16x16x32_bf16 v[34:37], v[184:187], v[200:203], v[34:37]
	v_mfma_f32_16x16x32_bf16 v[22:25], v[176:179], v[208:211], v[22:25]
	v_mfma_f32_16x16x32_bf16 v[18:21], v[184:187], v[208:211], v[18:21]
	v_mfma_f32_16x16x32_bf16 v[6:9], v[176:179], v[216:219], v[6:9]
	v_mfma_f32_16x16x32_bf16 v[2:5], v[184:187], v[216:219], v[2:5]
	s_setprio 0
	s_add_i32 s52, s52, 2
	s_add_u32 s40, s40, 0x100
	s_addc_u32 s41, s41, 0
	s_add_u32 s46, s46, 0x100
	s_addc_u32 s47, s47, 0
	s_cmp_gt_u32 s52, 3
	s_barrier
	s_cbranch_scc0 .LBB0_930
	s_and_b64 vcc, exec, s[12:13]
	s_cbranch_vccz .LBB0_933
	s_barrier

; #define PG8_STAGE(bufoff, gbase, voff) do { _Pragma("unroll") for (int _i = 0; _i < 2; ++_i) { unsigned _keep; \
;         asm volatile("s_mov_b32 %0, m0\n\ts_mov_b32 m0, %1\n\ts_nop 0\n\tglobal_load_lds_dwordx4 %2, %3\n\ts_mov_b32 m0, %0" : "=&s"(_keep) : "s"(ldsb + (unsigned)((bufoff) + _i * 8192)), "v"((voff)[_i]), "s"((const char*)(gbase)) : "memory"); } } while (0)
; #define PG8_LDA(dst, b, h) do { _Pragma("unroll") for (int m = 0; m < 4; ++m) _Pragma("unroll") for (int k = 0; k < 2; ++k) dst[m][k] = *(const LAS bf16x8*)(lds + PG8_SA(b, h) + aoff + m * 2048 + k * 1024); } while (0)
; #define PG8_LDB(dst, b, h) do { _Pragma("unroll") for (int n = 0; n < 2; ++n) _Pragma("unroll") for (int k = 0; k < 2; ++k) dst[n][k] = *(const LAS bf16x8*)(lds + PG8_SB(b, h) + boff + n * 2048 + k * 1024); } while (0)
; #define PG8_MMA(ai, bj, At, Bt) do { __builtin_amdgcn_s_setprio(1); _Pragma("unroll") for (int m = 0; m < 4; ++m) _Pragma("unroll") for (int n = 0; n < 2; ++n) _Pragma("unroll") for (int k = 0; k < 2; ++k) \
;         acc[ai][bj][m][n] = __builtin_amdgcn_mfma_f32_16x16x32_bf16(Bt[n][k], At[m][k], acc[ai][bj][m][n], 0, 0, 0); __builtin_amdgcn_s_setprio(0); } while (0)
; #define PG8_WAIT_V(n) asm volatile("s_waitcnt vmcnt(" #n ")" ::: "memory")
; #define PG8_WAIT_L(n) asm volatile("s_waitcnt lgkmcnt(" #n ")" ::: "memory")
; template <class Epi>
; __device__ __forceinline__ void gemm_phase(LAS unsigned char* lds, const Gemm g, const StaticOrder& S, const Epi& E) {
;     ...
;         for (int t = 0; t < nt; t += 2) {
;             const bool last = (t == nt - 2);
;             const char* a1 = cA + (size_t)(t + 1) * kstep;
;             const char* a2 = last ? nA : cA + (size_t)(t + 2) * kstep; const char* b2 = last ? nB : cB + (size_t)(t + 2) * kstep;
;             const char* a3 = a2 + kstep; const char* b3 = b2 + kstep;
;             PG8_LDB(B0, 0, 0); PG8_LDB(B1, 0, 1); PG8_SCHED; PG8_LDA(At, 0, 0); PG8_STAGE(PG8_SA(1, 1), a1 + hstepA, voffA);
;             PG8_WAIT_V(8); PG8_WAIT_L(0); PG8_BAR; PG8_MMA(0, 0, At, B0); PG8_MMA(0, 1, At, B1); PG8_BAR; PG8_SCHED;
;             PG8_LDA(At, 0, 1); PG8_STAGE(PG8_SB(0, 0), b2, voffB); PG8_STAGE(PG8_SB(0, 1), b2 + hstepB, voffB); PG8_STAGE(PG8_SA(0, 0), a2, voffA);
;             PG8_WAIT_V(8); PG8_WAIT_L(0); PG8_BAR; PG8_MMA(1, 0, At, B0); PG8_MMA(1, 1, At, B1); PG8_BAR; PG8_SCHED;
.LBB0_1275:
	ds_read_b128 v[134:137], v149
	ds_read_b128 v[154:157], v149 offset:1024
	ds_read_b128 v[158:161], v149 offset:2048
	ds_read_b128 v[162:165], v149 offset:3072
	ds_read_b128 v[166:169], v150
	ds_read_b128 v[170:173], v150 offset:1024
	ds_read_b128 v[174:177], v150 offset:2048
	ds_read_b128 v[178:181], v150 offset:3072
	s_cmp_eq_u32 s80, 4
	s_cselect_b32 s16, s74, s76
	s_cselect_b32 s17, s49, s77
	s_cselect_b32 s58, s75, s78
	s_cselect_b32 s59, s47, s79
	s_add_u32 s40, s16, 0x80
	s_addc_u32 s41, s17, 0
	ds_read_b128 v[182:185], v151
	ds_read_b128 v[186:189], v151 offset:1024
	ds_read_b128 v[190:193], v151 offset:2048
	ds_read_b128 v[194:197], v151 offset:3072
	ds_read_b128 v[198:201], v151 offset:4096
	ds_read_b128 v[202:205], v151 offset:5120
	ds_read_b128 v[206:209], v151 offset:6144
	ds_read_b128 v[210:213], v151 offset:7168
	s_add_u32 s82, s76, 0x1ff80
	s_addc_u32 s83, s77, 0
	s_mov_b32 s81, m0
	s_mov_b32 m0, s71
	s_nop 0
	global_load_lds_dwordx4 v141, s[82:83]
	s_mov_b32 m0, s81
	s_nop 0
	s_mov_b32 s81, m0
	s_mov_b32 m0, s72
	s_nop 0
	global_load_lds_dwordx4 v145, s[82:83]
	s_mov_b32 m0, s81
	s_waitcnt vmcnt(8)
	s_waitcnt lgkmcnt(0)
	s_barrier
	s_setprio 1
	s_waitcnt lgkmcnt(7)
	v_mfma_f32_16x16x32_bf16 v[126:129], v[134:137], v[182:185], v[126:129]
	v_mfma_f32_16x16x32_bf16 v[122:125], v[158:161], v[182:185], v[122:125]
	s_waitcnt lgkmcnt(5)
	v_mfma_f32_16x16x32_bf16 v[110:113], v[134:137], v[190:193], v[110:113]
	v_mfma_f32_16x16x32_bf16 v[106:109], v[158:161], v[190:193], v[106:109]
	s_waitcnt lgkmcnt(3)
	v_mfma_f32_16x16x32_bf16 v[94:97], v[134:137], v[198:201], v[94:97]
	v_mfma_f32_16x16x32_bf16 v[90:93], v[158:161], v[198:201], v[90:93]
	s_waitcnt lgkmcnt(1)
	v_mfma_f32_16x16x32_bf16 v[78:81], v[134:137], v[206:209], v[78:81]
	v_mfma_f32_16x16x32_bf16 v[74:77], v[158:161], v[206:209], v[74:77]
	v_mfma_f32_16x16x32_bf16 v[126:129], v[154:157], v[186:189], v[126:129]
	v_mfma_f32_16x16x32_bf16 v[122:125], v[162:165], v[186:189], v[122:125]
	v_mfma_f32_16x16x32_bf16 v[110:113], v[154:157], v[194:197], v[110:113]
	v_mfma_f32_16x16x32_bf16 v[106:109], v[162:165], v[194:197], v[106:109]
	v_mfma_f32_16x16x32_bf16 v[94:97], v[154:157], v[202:205], v[94:97]
	v_mfma_f32_16x16x32_bf16 v[90:93], v[162:165], v[202:205], v[90:93]
	s_waitcnt lgkmcnt(0)
	v_mfma_f32_16x16x32_bf16 v[78:81], v[154:157], v[210:213], v[78:81]
	v_mfma_f32_16x16x32_bf16 v[74:77], v[162:165], v[210:213], v[74:77]
	s_setprio 0
	s_setprio 1
	v_mfma_f32_16x16x32_bf16 v[118:121], v[166:169], v[182:185], v[118:121]
	v_mfma_f32_16x16x32_bf16 v[114:117], v[174:177], v[182:185], v[114:117]
	v_mfma_f32_16x16x32_bf16 v[102:105], v[166:169], v[190:193], v[102:105]
	v_mfma_f32_16x16x32_bf16 v[98:101], v[174:177], v[190:193], v[98:101]
	v_mfma_f32_16x16x32_bf16 v[86:89], v[166:169], v[198:201], v[86:89]
	v_mfma_f32_16x16x32_bf16 v[82:85], v[174:177], v[198:201], v[82:85]
	v_mfma_f32_16x16x32_bf16 v[70:73], v[166:169], v[206:209], v[70:73]
	v_mfma_f32_16x16x32_bf16 v[66:69], v[174:177], v[206:209], v[66:69]
	v_mfma_f32_16x16x32_bf16 v[118:121], v[170:173], v[186:189], v[118:121]
	v_mfma_f32_16x16x32_bf16 v[114:117], v[178:181], v[186:189], v[114:117]
	v_mfma_f32_16x16x32_bf16 v[102:105], v[170:173], v[194:197], v[102:105]
	v_mfma_f32_16x16x32_bf16 v[98:101], v[178:181], v[194:197], v[98:101]
	v_mfma_f32_16x16x32_bf16 v[86:89], v[170:173], v[202:205], v[86:89]
	v_mfma_f32_16x16x32_bf16 v[82:85], v[178:181], v[202:205], v[82:85]
	v_mfma_f32_16x16x32_bf16 v[70:73], v[170:173], v[210:213], v[70:73]
	v_mfma_f32_16x16x32_bf16 v[66:69], v[178:181], v[210:213], v[66:69]
	s_setprio 0
	s_barrier
	ds_read_b128 v[182:185], v151 offset:16384
	ds_read_b128 v[186:189], v151 offset:17408
	ds_read_b128 v[190:193], v151 offset:18432
	ds_read_b128 v[194:197], v151 offset:19456
	ds_read_b128 v[198:201], v151 offset:20480
	ds_read_b128 v[202:205], v151 offset:21504
	ds_read_b128 v[206:209], v151 offset:22528
	ds_read_b128 v[210:213], v151 offset:23552
	s_mov_b32 s81, m0
	s_mov_b32 m0, s55
	s_nop 0
	global_load_lds_dwordx4 v144, s[58:59]
	s_mov_b32 m0, s81
	s_add_u32 s82, s58, 0x20000
	s_mov_b32 s81, m0
	s_mov_b32 m0, s57
	s_nop 0
	global_load_lds_dwordx4 v146, s[58:59]
	s_mov_b32 m0, s81
	s_addc_u32 s83, s59, 0
	s_mov_b32 s81, m0
	s_mov_b32 m0, s60
	s_nop 0
	global_load_lds_dwordx4 v144, s[82:83]
	s_mov_b32 m0, s81
	s_nop 0
	s_mov_b32 s81, m0
	s_mov_b32 m0, s61
	s_nop 0
	global_load_lds_dwordx4 v146, s[82:83]
	s_mov_b32 m0, s81
	s_nop 0
	s_mov_b32 s81, m0
	s_mov_b32 m0, s14
	s_nop 0
	global_load_lds_dwordx4 v141, s[16:17]
	s_mov_b32 m0, s81
	s_nop 0
	s_mov_b32 s81, m0
	s_mov_b32 m0, s62
	s_nop 0
	global_load_lds_dwordx4 v145, s[16:17]
	s_mov_b32 m0, s81
	s_waitcnt vmcnt(8)
	s_waitcnt lgkmcnt(0)
	s_barrier
; #define PG8_STAGE(bufoff, gbase, voff) do { _Pragma("unroll") for (int _i = 0; _i < 2; ++_i) { unsigned _keep; \
;         asm volatile("s_mov_b32 %0, m0\n\ts_mov_b32 m0, %1\n\ts_nop 0\n\tglobal_load_lds_dwordx4 %2, %3\n\ts_mov_b32 m0, %0" : "=&s"(_keep) : "s"(ldsb + (unsigned)((bufoff) + _i * 8192)), "v"((voff)[_i]), "s"((const char*)(gbase)) : "memory"); } } while (0)
; #define PG8_LDA(dst, b, h) do { _Pragma("unroll") for (int m = 0; m < 4; ++m) _Pragma("unroll") for (int k = 0; k < 2; ++k) dst[m][k] = *(const LAS bf16x8*)(lds + PG8_SA(b, h) + aoff + m * 2048 + k * 1024); } while (0)
; #define PG8_LDB(dst, b, h) do { _Pragma("unroll") for (int n = 0; n < 2; ++n) _Pragma("unroll") for (int k = 0; k < 2; ++k) dst[n][k] = *(const LAS bf16x8*)(lds + PG8_SB(b, h) + boff + n * 2048 + k * 1024); } while (0)
; #define PG8_MMA(ai, bj, At, Bt) do { __builtin_amdgcn_s_setprio(1); _Pragma("unroll") for (int m = 0; m < 4; ++m) _Pragma("unroll") for (int n = 0; n < 2; ++n) _Pragma("unroll") for (int k = 0; k < 2; ++k) \
;         acc[ai][bj][m][n] = __builtin_amdgcn_mfma_f32_16x16x32_bf16(Bt[n][k], At[m][k], acc[ai][bj][m][n], 0, 0, 0); __builtin_amdgcn_s_setprio(0); } while (0)
; #define PG8_WAIT_V(n) asm volatile("s_waitcnt vmcnt(" #n ")" ::: "memory")
; #define PG8_WAIT_L(n) asm volatile("s_waitcnt lgkmcnt(" #n ")" ::: "memory")
; #define PG8_BAR __builtin_amdgcn_s_barrier()
; #define PG8_SCHED __builtin_amdgcn_sched_barrier(0)
; template <class Epi>
; __device__ __forceinline__ void gemm_phase(LAS unsigned char* lds, const Gemm g, const StaticOrder& S, const Epi& E) {
;     ...
;             PG8_WAIT_V(8); PG8_WAIT_L(0); PG8_BAR; PG8_MMA(1, 0, At, B0); PG8_MMA(1, 1, At, B1); PG8_BAR; PG8_SCHED;
;             PG8_LDB(B0, 1, 0); PG8_LDB(B1, 1, 1); PG8_SCHED; PG8_LDA(At, 1, 0); PG8_STAGE(PG8_SA(0, 1), a2 + hstepA, voffA);
;             PG8_WAIT_V(8); PG8_WAIT_L(0); PG8_BAR; PG8_MMA(0, 0, At, B0); PG8_MMA(0, 1, At, B1); PG8_BAR; PG8_SCHED;
;             PG8_LDA(At, 1, 1); PG8_STAGE(PG8_SB(1, 0), b3, voffB); PG8_STAGE(PG8_SB(1, 1), b3 + hstepB, voffB); PG8_STAGE(PG8_SA(1, 0), a3, voffA);
	s_setprio 1
	s_waitcnt lgkmcnt(7)
	v_mfma_f32_16x16x32_bf16 v[62:65], v[134:137], v[182:185], v[62:65]
	v_mfma_f32_16x16x32_bf16 v[58:61], v[158:161], v[182:185], v[58:61]
	s_waitcnt lgkmcnt(5)
	v_mfma_f32_16x16x32_bf16 v[46:49], v[134:137], v[190:193], v[46:49]
	v_mfma_f32_16x16x32_bf16 v[42:45], v[158:161], v[190:193], v[42:45]
	s_waitcnt lgkmcnt(3)
	v_mfma_f32_16x16x32_bf16 v[30:33], v[134:137], v[198:201], v[30:33]
	v_mfma_f32_16x16x32_bf16 v[26:29], v[158:161], v[198:201], v[26:29]
	s_waitcnt lgkmcnt(1)
	v_mfma_f32_16x16x32_bf16 v[14:17], v[134:137], v[206:209], v[14:17]
	v_mfma_f32_16x16x32_bf16 v[10:13], v[158:161], v[206:209], v[10:13]
	v_mfma_f32_16x16x32_bf16 v[62:65], v[154:157], v[186:189], v[62:65]
	v_mfma_f32_16x16x32_bf16 v[58:61], v[162:165], v[186:189], v[58:61]
	v_mfma_f32_16x16x32_bf16 v[46:49], v[154:157], v[194:197], v[46:49]
	v_mfma_f32_16x16x32_bf16 v[42:45], v[162:165], v[194:197], v[42:45]
	v_mfma_f32_16x16x32_bf16 v[30:33], v[154:157], v[202:205], v[30:33]
	v_mfma_f32_16x16x32_bf16 v[26:29], v[162:165], v[202:205], v[26:29]
	s_waitcnt lgkmcnt(0)
	v_mfma_f32_16x16x32_bf16 v[14:17], v[154:157], v[210:213], v[14:17]
	v_mfma_f32_16x16x32_bf16 v[10:13], v[162:165], v[210:213], v[10:13]
	s_setprio 0
	s_setprio 1
	v_mfma_f32_16x16x32_bf16 v[54:57], v[166:169], v[182:185], v[54:57]
	v_mfma_f32_16x16x32_bf16 v[50:53], v[174:177], v[182:185], v[50:53]
	v_mfma_f32_16x16x32_bf16 v[38:41], v[166:169], v[190:193], v[38:41]
	v_mfma_f32_16x16x32_bf16 v[34:37], v[174:177], v[190:193], v[34:37]
	v_mfma_f32_16x16x32_bf16 v[22:25], v[166:169], v[198:201], v[22:25]
	v_mfma_f32_16x16x32_bf16 v[18:21], v[174:177], v[198:201], v[18:21]
	v_mfma_f32_16x16x32_bf16 v[6:9], v[166:169], v[206:209], v[6:9]
	v_mfma_f32_16x16x32_bf16 v[2:5], v[174:177], v[206:209], v[2:5]
	v_mfma_f32_16x16x32_bf16 v[54:57], v[170:173], v[186:189], v[54:57]
	v_mfma_f32_16x16x32_bf16 v[50:53], v[178:181], v[186:189], v[50:53]
	v_mfma_f32_16x16x32_bf16 v[38:41], v[170:173], v[194:197], v[38:41]
	v_mfma_f32_16x16x32_bf16 v[34:37], v[178:181], v[194:197], v[34:37]
	v_mfma_f32_16x16x32_bf16 v[22:25], v[170:173], v[202:205], v[22:25]
	v_mfma_f32_16x16x32_bf16 v[18:21], v[178:181], v[202:205], v[18:21]
	v_mfma_f32_16x16x32_bf16 v[6:9], v[170:173], v[210:213], v[6:9]
	v_mfma_f32_16x16x32_bf16 v[2:5], v[178:181], v[210:213], v[2:5]
	s_setprio 0
	s_barrier
	ds_read_b128 v[134:137], v152
	ds_read_b128 v[154:157], v152 offset:1024
	ds_read_b128 v[158:161], v152 offset:2048
	ds_read_b128 v[162:165], v152 offset:3072
	ds_read_b128 v[166:169], v153
	ds_read_b128 v[170:173], v153 offset:1024
	ds_read_b128 v[174:177], v153 offset:2048
	ds_read_b128 v[178:181], v153 offset:3072
	ds_read_b128 v[182:185], v151 offset:32768
	ds_read_b128 v[186:189], v151 offset:33792
	ds_read_b128 v[190:193], v151 offset:34816
	ds_read_b128 v[194:197], v151 offset:35840
	ds_read_b128 v[198:201], v151 offset:36864
	ds_read_b128 v[202:205], v151 offset:37888
	ds_read_b128 v[206:209], v151 offset:38912
	ds_read_b128 v[210:213], v151 offset:39936
	s_add_u32 s16, s16, 0x20000
	s_addc_u32 s17, s17, 0
	s_mov_b32 s81, m0
	s_mov_b32 m0, s63
	s_nop 0
	global_load_lds_dwordx4 v141, s[16:17]
	s_mov_b32 m0, s81
	s_nop 0
	s_mov_b32 s81, m0
	s_mov_b32 m0, s64
	s_nop 0
	global_load_lds_dwordx4 v145, s[16:17]
	s_mov_b32 m0, s81
	s_waitcnt vmcnt(8)
	s_waitcnt lgkmcnt(0)
	s_barrier
	s_setprio 1
	s_waitcnt lgkmcnt(7)
	v_mfma_f32_16x16x32_bf16 v[126:129], v[134:137], v[182:185], v[126:129]
	v_mfma_f32_16x16x32_bf16 v[122:125], v[158:161], v[182:185], v[122:125]
	s_waitcnt lgkmcnt(5)
	v_mfma_f32_16x16x32_bf16 v[110:113], v[134:137], v[190:193], v[110:113]
	v_mfma_f32_16x16x32_bf16 v[106:109], v[158:161], v[190:193], v[106:109]
	s_waitcnt lgkmcnt(3)
	v_mfma_f32_16x16x32_bf16 v[94:97], v[134:137], v[198:201], v[94:97]
	v_mfma_f32_16x16x32_bf16 v[90:93], v[158:161], v[198:201], v[90:93]
	s_waitcnt lgkmcnt(1)
	v_mfma_f32_16x16x32_bf16 v[78:81], v[134:137], v[206:209], v[78:81]
	v_mfma_f32_16x16x32_bf16 v[74:77], v[158:161], v[206:209], v[74:77]
	v_mfma_f32_16x16x32_bf16 v[126:129], v[154:157], v[186:189], v[126:129]
	v_mfma_f32_16x16x32_bf16 v[122:125], v[162:165], v[186:189], v[122:125]
	v_mfma_f32_16x16x32_bf16 v[110:113], v[154:157], v[194:197], v[110:113]
	v_mfma_f32_16x16x32_bf16 v[106:109], v[162:165], v[194:197], v[106:109]
	v_mfma_f32_16x16x32_bf16 v[94:97], v[154:157], v[202:205], v[94:97]
	v_mfma_f32_16x16x32_bf16 v[90:93], v[162:165], v[202:205], v[90:93]
	s_waitcnt lgkmcnt(0)
	v_mfma_f32_16x16x32_bf16 v[78:81], v[154:157], v[210:213], v[78:81]
	v_mfma_f32_16x16x32_bf16 v[74:77], v[162:165], v[210:213], v[74:77]
	s_setprio 0
	s_setprio 1
	v_mfma_f32_16x16x32_bf16 v[118:121], v[166:169], v[182:185], v[118:121]
	v_mfma_f32_16x16x32_bf16 v[114:117], v[174:177], v[182:185], v[114:117]
	v_mfma_f32_16x16x32_bf16 v[102:105], v[166:169], v[190:193], v[102:105]
	v_mfma_f32_16x16x32_bf16 v[98:101], v[174:177], v[190:193], v[98:101]
	v_mfma_f32_16x16x32_bf16 v[86:89], v[166:169], v[198:201], v[86:89]
	v_mfma_f32_16x16x32_bf16 v[82:85], v[174:177], v[198:201], v[82:85]
	v_mfma_f32_16x16x32_bf16 v[70:73], v[166:169], v[206:209], v[70:73]
	v_mfma_f32_16x16x32_bf16 v[66:69], v[174:177], v[206:209], v[66:69]
	v_mfma_f32_16x16x32_bf16 v[118:121], v[170:173], v[186:189], v[118:121]
	v_mfma_f32_16x16x32_bf16 v[114:117], v[178:181], v[186:189], v[114:117]
	v_mfma_f32_16x16x32_bf16 v[102:105], v[170:173], v[194:197], v[102:105]
	v_mfma_f32_16x16x32_bf16 v[98:101], v[178:181], v[194:197], v[98:101]
	v_mfma_f32_16x16x32_bf16 v[86:89], v[170:173], v[202:205], v[86:89]
	v_mfma_f32_16x16x32_bf16 v[82:85], v[178:181], v[202:205], v[82:85]
	v_mfma_f32_16x16x32_bf16 v[70:73], v[170:173], v[210:213], v[70:73]
	v_mfma_f32_16x16x32_bf16 v[66:69], v[178:181], v[210:213], v[66:69]
	s_setprio 0
	s_barrier
; #define PG8_STAGE(bufoff, gbase, voff) do { _Pragma("unroll") for (int _i = 0; _i < 2; ++_i) { unsigned _keep; \
;         asm volatile("s_mov_b32 %0, m0\n\ts_mov_b32 m0, %1\n\ts_nop 0\n\tglobal_load_lds_dwordx4 %2, %3\n\ts_mov_b32 m0, %0" : "=&s"(_keep) : "s"(ldsb + (unsigned)((bufoff) + _i * 8192)), "v"((voff)[_i]), "s"((const char*)(gbase)) : "memory"); } } while (0)
; #define PG8_LDA(dst, b, h) do { _Pragma("unroll") for (int m = 0; m < 4; ++m) _Pragma("unroll") for (int k = 0; k < 2; ++k) dst[m][k] = *(const LAS bf16x8*)(lds + PG8_SA(b, h) + aoff + m * 2048 + k * 1024); } while (0)
; #define PG8_MMA(ai, bj, At, Bt) do { __builtin_amdgcn_s_setprio(1); _Pragma("unroll") for (int m = 0; m < 4; ++m) _Pragma("unroll") for (int n = 0; n < 2; ++n) _Pragma("unroll") for (int k = 0; k < 2; ++k) \
;         acc[ai][bj][m][n] = __builtin_amdgcn_mfma_f32_16x16x32_bf16(Bt[n][k], At[m][k], acc[ai][bj][m][n], 0, 0, 0); __builtin_amdgcn_s_setprio(0); } while (0)
; #define PG8_WAIT_V(n) asm volatile("s_waitcnt vmcnt(" #n ")" ::: "memory")
; #define PG8_WAIT_L(n) asm volatile("s_waitcnt lgkmcnt(" #n ")" ::: "memory")
; #define PG8_BAR __builtin_amdgcn_s_barrier()
; #define PG8_SCHED __builtin_amdgcn_sched_barrier(0)
; template <class Epi>
; __device__ __forceinline__ void gemm_phase(LAS unsigned char* lds, const Gemm g, const StaticOrder& S, const Epi& E) {
;     ...
;             PG8_LDA(At, 1, 1); PG8_STAGE(PG8_SB(1, 0), b3, voffB); PG8_STAGE(PG8_SB(1, 1), b3 + hstepB, voffB); PG8_STAGE(PG8_SA(1, 0), a3, voffA);
;             PG8_WAIT_V(8); PG8_WAIT_L(0); PG8_BAR; PG8_MMA(1, 0, At, B0); PG8_MMA(1, 1, At, B1); PG8_BAR; PG8_SCHED;
;         }
;         if (wr == 0) PG8_BAR;
;         bool run_epi = true;
	ds_read_b128 v[182:185], v151 offset:49152
	ds_read_b128 v[186:189], v151 offset:50176
	ds_read_b128 v[190:193], v151 offset:51200
	ds_read_b128 v[194:197], v151 offset:52224
	ds_read_b128 v[198:201], v151 offset:53248
	ds_read_b128 v[202:205], v151 offset:54272
	ds_read_b128 v[206:209], v151 offset:55296
	ds_read_b128 v[210:213], v151 offset:56320
	s_add_u32 s16, s58, 0x80
	s_addc_u32 s17, s59, 0
	s_mov_b32 s81, m0
	s_mov_b32 m0, s65
	s_nop 0
	global_load_lds_dwordx4 v144, s[16:17]
	s_mov_b32 m0, s81
	s_nop 0
	s_mov_b32 s81, m0
	s_mov_b32 m0, s66
	s_nop 0
	global_load_lds_dwordx4 v146, s[16:17]
	s_mov_b32 m0, s81
	s_add_u32 s16, s58, 0x20080
	s_addc_u32 s17, s59, 0
	s_mov_b32 s58, m0
	s_mov_b32 m0, s69
	s_nop 0
	global_load_lds_dwordx4 v144, s[16:17]
	s_mov_b32 m0, s58
	s_nop 0
	s_mov_b32 s58, m0
	s_mov_b32 m0, s70
	s_nop 0
	global_load_lds_dwordx4 v146, s[16:17]
	s_mov_b32 m0, s58
	s_mov_b32 s16, m0
	s_mov_b32 m0, s67
	s_nop 0
	global_load_lds_dwordx4 v141, s[40:41]
	s_mov_b32 m0, s16
	s_nop 0
	s_mov_b32 s16, m0
	s_mov_b32 m0, s68
	s_nop 0
	global_load_lds_dwordx4 v145, s[40:41]
	s_mov_b32 m0, s16
	s_waitcnt vmcnt(8)
	s_waitcnt lgkmcnt(0)
	s_barrier
	s_setprio 1
	s_waitcnt lgkmcnt(7)
	v_mfma_f32_16x16x32_bf16 v[62:65], v[134:137], v[182:185], v[62:65]
	v_mfma_f32_16x16x32_bf16 v[58:61], v[158:161], v[182:185], v[58:61]
	s_waitcnt lgkmcnt(5)
	v_mfma_f32_16x16x32_bf16 v[46:49], v[134:137], v[190:193], v[46:49]
	v_mfma_f32_16x16x32_bf16 v[42:45], v[158:161], v[190:193], v[42:45]
	s_waitcnt lgkmcnt(3)
	v_mfma_f32_16x16x32_bf16 v[30:33], v[134:137], v[198:201], v[30:33]
	v_mfma_f32_16x16x32_bf16 v[26:29], v[158:161], v[198:201], v[26:29]
	s_waitcnt lgkmcnt(1)
	v_mfma_f32_16x16x32_bf16 v[14:17], v[134:137], v[206:209], v[14:17]
	v_mfma_f32_16x16x32_bf16 v[10:13], v[158:161], v[206:209], v[10:13]
	v_mfma_f32_16x16x32_bf16 v[62:65], v[154:157], v[186:189], v[62:65]
	v_mfma_f32_16x16x32_bf16 v[58:61], v[162:165], v[186:189], v[58:61]
	v_mfma_f32_16x16x32_bf16 v[46:49], v[154:157], v[194:197], v[46:49]
	v_mfma_f32_16x16x32_bf16 v[42:45], v[162:165], v[194:197], v[42:45]
	v_mfma_f32_16x16x32_bf16 v[30:33], v[154:157], v[202:205], v[30:33]
	v_mfma_f32_16x16x32_bf16 v[26:29], v[162:165], v[202:205], v[26:29]
	s_waitcnt lgkmcnt(0)
	v_mfma_f32_16x16x32_bf16 v[14:17], v[154:157], v[210:213], v[14:17]
	v_mfma_f32_16x16x32_bf16 v[10:13], v[162:165], v[210:213], v[10:13]
	s_setprio 0
	s_setprio 1
	v_mfma_f32_16x16x32_bf16 v[54:57], v[166:169], v[182:185], v[54:57]
	v_mfma_f32_16x16x32_bf16 v[50:53], v[174:177], v[182:185], v[50:53]
	v_mfma_f32_16x16x32_bf16 v[38:41], v[166:169], v[190:193], v[38:41]
	v_mfma_f32_16x16x32_bf16 v[34:37], v[174:177], v[190:193], v[34:37]
	v_mfma_f32_16x16x32_bf16 v[22:25], v[166:169], v[198:201], v[22:25]
	v_mfma_f32_16x16x32_bf16 v[18:21], v[174:177], v[198:201], v[18:21]
	v_mfma_f32_16x16x32_bf16 v[6:9], v[166:169], v[206:209], v[6:9]
	v_mfma_f32_16x16x32_bf16 v[2:5], v[174:177], v[206:209], v[2:5]
	v_mfma_f32_16x16x32_bf16 v[54:57], v[170:173], v[186:189], v[54:57]
	v_mfma_f32_16x16x32_bf16 v[50:53], v[178:181], v[186:189], v[50:53]
	v_mfma_f32_16x16x32_bf16 v[38:41], v[170:173], v[194:197], v[38:41]
	v_mfma_f32_16x16x32_bf16 v[34:37], v[178:181], v[194:197], v[34:37]
	v_mfma_f32_16x16x32_bf16 v[22:25], v[170:173], v[202:205], v[22:25]
	v_mfma_f32_16x16x32_bf16 v[18:21], v[178:181], v[202:205], v[18:21]
	v_mfma_f32_16x16x32_bf16 v[6:9], v[170:173], v[210:213], v[6:9]
	v_mfma_f32_16x16x32_bf16 v[2:5], v[178:181], v[210:213], v[2:5]
	s_setprio 0
	s_add_i32 s80, s80, 2
	s_add_u32 s76, s76, 0x100
	s_addc_u32 s77, s77, 0
	s_add_u32 s78, s78, 0x100
	s_addc_u32 s79, s79, 0
	s_cmp_gt_u32 s80, 5
	s_barrier
	s_cbranch_scc0 .LBB0_1275
	s_and_b64 vcc, exec, s[8:9]
	s_cbranch_vccz .LBB0_1278
	s_barrier

; #define PG8_STAGE(bufoff, gbase, voff) do { _Pragma("unroll") for (int _i = 0; _i < 2; ++_i) { unsigned _keep; \
;         asm volatile("s_mov_b32 %0, m0\n\ts_mov_b32 m0, %1\n\ts_nop 0\n\tglobal_load_lds_dwordx4 %2, %3\n\ts_mov_b32 m0, %0" : "=&s"(_keep) : "s"(ldsb + (unsigned)((bufoff) + _i * 8192)), "v"((voff)[_i]), "s"((const char*)(gbase)) : "memory"); } } while (0)
; #define PG8_LDA(dst, b, h) do { _Pragma("unroll") for (int m = 0; m < 4; ++m) _Pragma("unroll") for (int k = 0; k < 2; ++k) dst[m][k] = *(const LAS bf16x8*)(lds + PG8_SA(b, h) + aoff + m * 2048 + k * 1024); } while (0)
; #define PG8_LDB(dst, b, h) do { _Pragma("unroll") for (int n = 0; n < 2; ++n) _Pragma("unroll") for (int k = 0; k < 2; ++k) dst[n][k] = *(const LAS bf16x8*)(lds + PG8_SB(b, h) + boff + n * 2048 + k * 1024); } while (0)
; #define PG8_MMA(ai, bj, At, Bt) do { __builtin_amdgcn_s_setprio(1); _Pragma("unroll") for (int m = 0; m < 4; ++m) _Pragma("unroll") for (int n = 0; n < 2; ++n) _Pragma("unroll") for (int k = 0; k < 2; ++k) \
;         acc[ai][bj][m][n] = __builtin_amdgcn_mfma_f32_16x16x32_bf16(Bt[n][k], At[m][k], acc[ai][bj][m][n], 0, 0, 0); __builtin_amdgcn_s_setprio(0); } while (0)
; #define PG8_WAIT_V(n) asm volatile("s_waitcnt vmcnt(" #n ")" ::: "memory")
; #define PG8_WAIT_L(n) asm volatile("s_waitcnt lgkmcnt(" #n ")" ::: "memory")
; template <class Epi>
; __device__ __forceinline__ void gemm_phase(LAS unsigned char* lds, const Gemm g, const StaticOrder& S, const Epi& E) {
;     ...
;         for (int t = 0; t < nt; t += 2) {
;             const bool last = (t == nt - 2);
;             const char* a1 = cA + (size_t)(t + 1) * kstep;
;             const char* a2 = last ? nA : cA + (size_t)(t + 2) * kstep; const char* b2 = last ? nB : cB + (size_t)(t + 2) * kstep;
;             const char* a3 = a2 + kstep; const char* b3 = b2 + kstep;
;             PG8_LDB(B0, 0, 0); PG8_LDB(B1, 0, 1); PG8_SCHED; PG8_LDA(At, 0, 0); PG8_STAGE(PG8_SA(1, 1), a1 + hstepA, voffA);
;             PG8_WAIT_V(8); PG8_WAIT_L(0); PG8_BAR; PG8_MMA(0, 0, At, B0); PG8_MMA(0, 1, At, B1); PG8_BAR; PG8_SCHED;
;             PG8_LDA(At, 0, 1); PG8_STAGE(PG8_SB(0, 0), b2, voffB); PG8_STAGE(PG8_SB(0, 1), b2 + hstepB, voffB); PG8_STAGE(PG8_SA(0, 0), a2, voffA);
;             PG8_WAIT_V(8); PG8_WAIT_L(0); PG8_BAR; PG8_MMA(1, 0, At, B0); PG8_MMA(1, 1, At, B1); PG8_BAR; PG8_SCHED;
.LBB0_1291:
	ds_read_b128 v[134:137], v149
	ds_read_b128 v[154:157], v149 offset:1024
	ds_read_b128 v[158:161], v149 offset:2048
	ds_read_b128 v[162:165], v149 offset:3072
	ds_read_b128 v[166:169], v150
	ds_read_b128 v[170:173], v150 offset:1024
	ds_read_b128 v[174:177], v150 offset:2048
	ds_read_b128 v[178:181], v150 offset:3072
	s_cmp_eq_u32 s78, 12
	s_cselect_b32 s16, s72, s74
	s_cselect_b32 s17, s47, s75
	s_cselect_b32 s56, s73, s76
	s_cselect_b32 s57, s45, s77
	s_add_u32 s40, s16, 0x80
	s_addc_u32 s41, s17, 0
	ds_read_b128 v[182:185], v151
	ds_read_b128 v[186:189], v151 offset:1024
	ds_read_b128 v[190:193], v151 offset:2048
	ds_read_b128 v[194:197], v151 offset:3072
	ds_read_b128 v[198:201], v151 offset:4096
	ds_read_b128 v[202:205], v151 offset:5120
	ds_read_b128 v[206:209], v151 offset:6144
	ds_read_b128 v[210:213], v151 offset:7168
	s_add_u32 s80, s74, 0x3ff80
	s_addc_u32 s81, s75, 0
	s_mov_b32 s79, m0
	s_mov_b32 m0, s69
	s_nop 0
	global_load_lds_dwordx4 v141, s[80:81]
	s_mov_b32 m0, s79
	s_nop 0
	s_mov_b32 s79, m0
	s_mov_b32 m0, s70
	s_nop 0
	global_load_lds_dwordx4 v145, s[80:81]
	s_mov_b32 m0, s79
	s_waitcnt vmcnt(8)
	s_waitcnt lgkmcnt(0)
	s_barrier
	s_setprio 1
	s_waitcnt lgkmcnt(7)
	v_mfma_f32_16x16x32_bf16 v[126:129], v[134:137], v[182:185], v[126:129]
	v_mfma_f32_16x16x32_bf16 v[122:125], v[158:161], v[182:185], v[122:125]
	s_waitcnt lgkmcnt(5)
	v_mfma_f32_16x16x32_bf16 v[110:113], v[134:137], v[190:193], v[110:113]
	v_mfma_f32_16x16x32_bf16 v[106:109], v[158:161], v[190:193], v[106:109]
	s_waitcnt lgkmcnt(3)
	v_mfma_f32_16x16x32_bf16 v[94:97], v[134:137], v[198:201], v[94:97]
	v_mfma_f32_16x16x32_bf16 v[90:93], v[158:161], v[198:201], v[90:93]
	s_waitcnt lgkmcnt(1)
	v_mfma_f32_16x16x32_bf16 v[78:81], v[134:137], v[206:209], v[78:81]
	v_mfma_f32_16x16x32_bf16 v[74:77], v[158:161], v[206:209], v[74:77]
	v_mfma_f32_16x16x32_bf16 v[126:129], v[154:157], v[186:189], v[126:129]
	v_mfma_f32_16x16x32_bf16 v[122:125], v[162:165], v[186:189], v[122:125]
	v_mfma_f32_16x16x32_bf16 v[110:113], v[154:157], v[194:197], v[110:113]
	v_mfma_f32_16x16x32_bf16 v[106:109], v[162:165], v[194:197], v[106:109]
	v_mfma_f32_16x16x32_bf16 v[94:97], v[154:157], v[202:205], v[94:97]
	v_mfma_f32_16x16x32_bf16 v[90:93], v[162:165], v[202:205], v[90:93]
	s_waitcnt lgkmcnt(0)
	v_mfma_f32_16x16x32_bf16 v[78:81], v[154:157], v[210:213], v[78:81]
	v_mfma_f32_16x16x32_bf16 v[74:77], v[162:165], v[210:213], v[74:77]
	s_setprio 0
	s_setprio 1
	v_mfma_f32_16x16x32_bf16 v[118:121], v[166:169], v[182:185], v[118:121]
	v_mfma_f32_16x16x32_bf16 v[114:117], v[174:177], v[182:185], v[114:117]
	v_mfma_f32_16x16x32_bf16 v[102:105], v[166:169], v[190:193], v[102:105]
	v_mfma_f32_16x16x32_bf16 v[98:101], v[174:177], v[190:193], v[98:101]
	v_mfma_f32_16x16x32_bf16 v[86:89], v[166:169], v[198:201], v[86:89]
	v_mfma_f32_16x16x32_bf16 v[82:85], v[174:177], v[198:201], v[82:85]
	v_mfma_f32_16x16x32_bf16 v[70:73], v[166:169], v[206:209], v[70:73]
	v_mfma_f32_16x16x32_bf16 v[66:69], v[174:177], v[206:209], v[66:69]
	v_mfma_f32_16x16x32_bf16 v[118:121], v[170:173], v[186:189], v[118:121]
	v_mfma_f32_16x16x32_bf16 v[114:117], v[178:181], v[186:189], v[114:117]
	v_mfma_f32_16x16x32_bf16 v[102:105], v[170:173], v[194:197], v[102:105]
	v_mfma_f32_16x16x32_bf16 v[98:101], v[178:181], v[194:197], v[98:101]
	v_mfma_f32_16x16x32_bf16 v[86:89], v[170:173], v[202:205], v[86:89]
	v_mfma_f32_16x16x32_bf16 v[82:85], v[178:181], v[202:205], v[82:85]
	v_mfma_f32_16x16x32_bf16 v[70:73], v[170:173], v[210:213], v[70:73]
	v_mfma_f32_16x16x32_bf16 v[66:69], v[178:181], v[210:213], v[66:69]
	s_setprio 0
	s_barrier
	ds_read_b128 v[182:185], v151 offset:16384
	ds_read_b128 v[186:189], v151 offset:17408
	ds_read_b128 v[190:193], v151 offset:18432
	ds_read_b128 v[194:197], v151 offset:19456
	ds_read_b128 v[198:201], v151 offset:20480
	ds_read_b128 v[202:205], v151 offset:21504
	ds_read_b128 v[206:209], v151 offset:22528
	ds_read_b128 v[210:213], v151 offset:23552
	s_mov_b32 s79, m0
	s_mov_b32 m0, s53
	s_nop 0
	global_load_lds_dwordx4 v144, s[56:57]
	s_mov_b32 m0, s79
	s_add_u32 s80, s56, 0x40000
	s_mov_b32 s79, m0
	s_mov_b32 m0, s55
	s_nop 0
	global_load_lds_dwordx4 v146, s[56:57]
	s_mov_b32 m0, s79
	s_addc_u32 s81, s57, 0
	s_mov_b32 s79, m0
	s_mov_b32 m0, s58
	s_nop 0
	global_load_lds_dwordx4 v144, s[80:81]
	s_mov_b32 m0, s79
	s_nop 0
	s_mov_b32 s79, m0
	s_mov_b32 m0, s59
	s_nop 0
	global_load_lds_dwordx4 v146, s[80:81]
	s_mov_b32 m0, s79
	s_nop 0
	s_mov_b32 s79, m0
	s_mov_b32 m0, s14
	s_nop 0
	global_load_lds_dwordx4 v141, s[16:17]
	s_mov_b32 m0, s79
	s_nop 0
	s_mov_b32 s79, m0
	s_mov_b32 m0, s60
	s_nop 0
	global_load_lds_dwordx4 v145, s[16:17]
	s_mov_b32 m0, s79
	s_waitcnt vmcnt(8)
	s_waitcnt lgkmcnt(0)
	s_barrier
; #define PG8_STAGE(bufoff, gbase, voff) do { _Pragma("unroll") for (int _i = 0; _i < 2; ++_i) { unsigned _keep; \
;         asm volatile("s_mov_b32 %0, m0\n\ts_mov_b32 m0, %1\n\ts_nop 0\n\tglobal_load_lds_dwordx4 %2, %3\n\ts_mov_b32 m0, %0" : "=&s"(_keep) : "s"(ldsb + (unsigned)((bufoff) + _i * 8192)), "v"((voff)[_i]), "s"((const char*)(gbase)) : "memory"); } } while (0)
; #define PG8_LDA(dst, b, h) do { _Pragma("unroll") for (int m = 0; m < 4; ++m) _Pragma("unroll") for (int k = 0; k < 2; ++k) dst[m][k] = *(const LAS bf16x8*)(lds + PG8_SA(b, h) + aoff + m * 2048 + k * 1024); } while (0)
; #define PG8_LDB(dst, b, h) do { _Pragma("unroll") for (int n = 0; n < 2; ++n) _Pragma("unroll") for (int k = 0; k < 2; ++k) dst[n][k] = *(const LAS bf16x8*)(lds + PG8_SB(b, h) + boff + n * 2048 + k * 1024); } while (0)
; #define PG8_MMA(ai, bj, At, Bt) do { __builtin_amdgcn_s_setprio(1); _Pragma("unroll") for (int m = 0; m < 4; ++m) _Pragma("unroll") for (int n = 0; n < 2; ++n) _Pragma("unroll") for (int k = 0; k < 2; ++k) \
;         acc[ai][bj][m][n] = __builtin_amdgcn_mfma_f32_16x16x32_bf16(Bt[n][k], At[m][k], acc[ai][bj][m][n], 0, 0, 0); __builtin_amdgcn_s_setprio(0); } while (0)
; #define PG8_WAIT_V(n) asm volatile("s_waitcnt vmcnt(" #n ")" ::: "memory")
; #define PG8_WAIT_L(n) asm volatile("s_waitcnt lgkmcnt(" #n ")" ::: "memory")
; #define PG8_BAR __builtin_amdgcn_s_barrier()
; #define PG8_SCHED __builtin_amdgcn_sched_barrier(0)
; template <class Epi>
; __device__ __forceinline__ void gemm_phase(LAS unsigned char* lds, const Gemm g, const StaticOrder& S, const Epi& E) {
;     ...
;             PG8_WAIT_V(8); PG8_WAIT_L(0); PG8_BAR; PG8_MMA(1, 0, At, B0); PG8_MMA(1, 1, At, B1); PG8_BAR; PG8_SCHED;
;             PG8_LDB(B0, 1, 0); PG8_LDB(B1, 1, 1); PG8_SCHED; PG8_LDA(At, 1, 0); PG8_STAGE(PG8_SA(0, 1), a2 + hstepA, voffA);
;             PG8_WAIT_V(8); PG8_WAIT_L(0); PG8_BAR; PG8_MMA(0, 0, At, B0); PG8_MMA(0, 1, At, B1); PG8_BAR; PG8_SCHED;
;             PG8_LDA(At, 1, 1); PG8_STAGE(PG8_SB(1, 0), b3, voffB); PG8_STAGE(PG8_SB(1, 1), b3 + hstepB, voffB); PG8_STAGE(PG8_SA(1, 0), a3, voffA);
	s_setprio 1
	s_waitcnt lgkmcnt(7)
	v_mfma_f32_16x16x32_bf16 v[62:65], v[134:137], v[182:185], v[62:65]
	v_mfma_f32_16x16x32_bf16 v[58:61], v[158:161], v[182:185], v[58:61]
	s_waitcnt lgkmcnt(5)
	v_mfma_f32_16x16x32_bf16 v[46:49], v[134:137], v[190:193], v[46:49]
	v_mfma_f32_16x16x32_bf16 v[42:45], v[158:161], v[190:193], v[42:45]
	s_waitcnt lgkmcnt(3)
	v_mfma_f32_16x16x32_bf16 v[30:33], v[134:137], v[198:201], v[30:33]
	v_mfma_f32_16x16x32_bf16 v[26:29], v[158:161], v[198:201], v[26:29]
	s_waitcnt lgkmcnt(1)
	v_mfma_f32_16x16x32_bf16 v[14:17], v[134:137], v[206:209], v[14:17]
	v_mfma_f32_16x16x32_bf16 v[10:13], v[158:161], v[206:209], v[10:13]
	v_mfma_f32_16x16x32_bf16 v[62:65], v[154:157], v[186:189], v[62:65]
	v_mfma_f32_16x16x32_bf16 v[58:61], v[162:165], v[186:189], v[58:61]
	v_mfma_f32_16x16x32_bf16 v[46:49], v[154:157], v[194:197], v[46:49]
	v_mfma_f32_16x16x32_bf16 v[42:45], v[162:165], v[194:197], v[42:45]
	v_mfma_f32_16x16x32_bf16 v[30:33], v[154:157], v[202:205], v[30:33]
	v_mfma_f32_16x16x32_bf16 v[26:29], v[162:165], v[202:205], v[26:29]
	s_waitcnt lgkmcnt(0)
	v_mfma_f32_16x16x32_bf16 v[14:17], v[154:157], v[210:213], v[14:17]
	v_mfma_f32_16x16x32_bf16 v[10:13], v[162:165], v[210:213], v[10:13]
	s_setprio 0
	s_setprio 1
	v_mfma_f32_16x16x32_bf16 v[54:57], v[166:169], v[182:185], v[54:57]
	v_mfma_f32_16x16x32_bf16 v[50:53], v[174:177], v[182:185], v[50:53]
	v_mfma_f32_16x16x32_bf16 v[38:41], v[166:169], v[190:193], v[38:41]
	v_mfma_f32_16x16x32_bf16 v[34:37], v[174:177], v[190:193], v[34:37]
	v_mfma_f32_16x16x32_bf16 v[22:25], v[166:169], v[198:201], v[22:25]
	v_mfma_f32_16x16x32_bf16 v[18:21], v[174:177], v[198:201], v[18:21]
	v_mfma_f32_16x16x32_bf16 v[6:9], v[166:169], v[206:209], v[6:9]
	v_mfma_f32_16x16x32_bf16 v[2:5], v[174:177], v[206:209], v[2:5]
	v_mfma_f32_16x16x32_bf16 v[54:57], v[170:173], v[186:189], v[54:57]
	v_mfma_f32_16x16x32_bf16 v[50:53], v[178:181], v[186:189], v[50:53]
	v_mfma_f32_16x16x32_bf16 v[38:41], v[170:173], v[194:197], v[38:41]
	v_mfma_f32_16x16x32_bf16 v[34:37], v[178:181], v[194:197], v[34:37]
	v_mfma_f32_16x16x32_bf16 v[22:25], v[170:173], v[202:205], v[22:25]
	v_mfma_f32_16x16x32_bf16 v[18:21], v[178:181], v[202:205], v[18:21]
	v_mfma_f32_16x16x32_bf16 v[6:9], v[170:173], v[210:213], v[6:9]
	v_mfma_f32_16x16x32_bf16 v[2:5], v[178:181], v[210:213], v[2:5]
	s_setprio 0
	s_barrier
	ds_read_b128 v[134:137], v152
	ds_read_b128 v[154:157], v152 offset:1024
	ds_read_b128 v[158:161], v152 offset:2048
	ds_read_b128 v[162:165], v152 offset:3072
	ds_read_b128 v[166:169], v153
	ds_read_b128 v[170:173], v153 offset:1024
	ds_read_b128 v[174:177], v153 offset:2048
	ds_read_b128 v[178:181], v153 offset:3072
	ds_read_b128 v[182:185], v151 offset:32768
	ds_read_b128 v[186:189], v151 offset:33792
	ds_read_b128 v[190:193], v151 offset:34816
	ds_read_b128 v[194:197], v151 offset:35840
	ds_read_b128 v[198:201], v151 offset:36864
	ds_read_b128 v[202:205], v151 offset:37888
	ds_read_b128 v[206:209], v151 offset:38912
	ds_read_b128 v[210:213], v151 offset:39936
	s_add_u32 s16, s16, 0x40000
	s_addc_u32 s17, s17, 0
	s_mov_b32 s79, m0
	s_mov_b32 m0, s61
	s_nop 0
	global_load_lds_dwordx4 v141, s[16:17]
	s_mov_b32 m0, s79
	s_nop 0
	s_mov_b32 s79, m0
	s_mov_b32 m0, s62
	s_nop 0
	global_load_lds_dwordx4 v145, s[16:17]
	s_mov_b32 m0, s79
	s_waitcnt vmcnt(8)
	s_waitcnt lgkmcnt(0)
	s_barrier
	s_setprio 1
	s_waitcnt lgkmcnt(7)
	v_mfma_f32_16x16x32_bf16 v[126:129], v[134:137], v[182:185], v[126:129]
	v_mfma_f32_16x16x32_bf16 v[122:125], v[158:161], v[182:185], v[122:125]
	s_waitcnt lgkmcnt(5)
	v_mfma_f32_16x16x32_bf16 v[110:113], v[134:137], v[190:193], v[110:113]
	v_mfma_f32_16x16x32_bf16 v[106:109], v[158:161], v[190:193], v[106:109]
	s_waitcnt lgkmcnt(3)
	v_mfma_f32_16x16x32_bf16 v[94:97], v[134:137], v[198:201], v[94:97]
	v_mfma_f32_16x16x32_bf16 v[90:93], v[158:161], v[198:201], v[90:93]
	s_waitcnt lgkmcnt(1)
	v_mfma_f32_16x16x32_bf16 v[78:81], v[134:137], v[206:209], v[78:81]
	v_mfma_f32_16x16x32_bf16 v[74:77], v[158:161], v[206:209], v[74:77]
	v_mfma_f32_16x16x32_bf16 v[126:129], v[154:157], v[186:189], v[126:129]
	v_mfma_f32_16x16x32_bf16 v[122:125], v[162:165], v[186:189], v[122:125]
	v_mfma_f32_16x16x32_bf16 v[110:113], v[154:157], v[194:197], v[110:113]
	v_mfma_f32_16x16x32_bf16 v[106:109], v[162:165], v[194:197], v[106:109]
	v_mfma_f32_16x16x32_bf16 v[94:97], v[154:157], v[202:205], v[94:97]
	v_mfma_f32_16x16x32_bf16 v[90:93], v[162:165], v[202:205], v[90:93]
	s_waitcnt lgkmcnt(0)
	v_mfma_f32_16x16x32_bf16 v[78:81], v[154:157], v[210:213], v[78:81]
	v_mfma_f32_16x16x32_bf16 v[74:77], v[162:165], v[210:213], v[74:77]
	s_setprio 0
	s_setprio 1
	v_mfma_f32_16x16x32_bf16 v[118:121], v[166:169], v[182:185], v[118:121]
	v_mfma_f32_16x16x32_bf16 v[114:117], v[174:177], v[182:185], v[114:117]
	v_mfma_f32_16x16x32_bf16 v[102:105], v[166:169], v[190:193], v[102:105]
	v_mfma_f32_16x16x32_bf16 v[98:101], v[174:177], v[190:193], v[98:101]
	v_mfma_f32_16x16x32_bf16 v[86:89], v[166:169], v[198:201], v[86:89]
	v_mfma_f32_16x16x32_bf16 v[82:85], v[174:177], v[198:201], v[82:85]
	v_mfma_f32_16x16x32_bf16 v[70:73], v[166:169], v[206:209], v[70:73]
	v_mfma_f32_16x16x32_bf16 v[66:69], v[174:177], v[206:209], v[66:69]
	v_mfma_f32_16x16x32_bf16 v[118:121], v[170:173], v[186:189], v[118:121]
	v_mfma_f32_16x16x32_bf16 v[114:117], v[178:181], v[186:189], v[114:117]
	v_mfma_f32_16x16x32_bf16 v[102:105], v[170:173], v[194:197], v[102:105]
	v_mfma_f32_16x16x32_bf16 v[98:101], v[178:181], v[194:197], v[98:101]
	v_mfma_f32_16x16x32_bf16 v[86:89], v[170:173], v[202:205], v[86:89]
	v_mfma_f32_16x16x32_bf16 v[82:85], v[178:181], v[202:205], v[82:85]
	v_mfma_f32_16x16x32_bf16 v[70:73], v[170:173], v[210:213], v[70:73]
	v_mfma_f32_16x16x32_bf16 v[66:69], v[178:181], v[210:213], v[66:69]
	s_setprio 0
	s_barrier
; #define PG8_STAGE(bufoff, gbase, voff) do { _Pragma("unroll") for (int _i = 0; _i < 2; ++_i) { unsigned _keep; \
;         asm volatile("s_mov_b32 %0, m0\n\ts_mov_b32 m0, %1\n\ts_nop 0\n\tglobal_load_lds_dwordx4 %2, %3\n\ts_mov_b32 m0, %0" : "=&s"(_keep) : "s"(ldsb + (unsigned)((bufoff) + _i * 8192)), "v"((voff)[_i]), "s"((const char*)(gbase)) : "memory"); } } while (0)
; #define PG8_LDA(dst, b, h) do { _Pragma("unroll") for (int m = 0; m < 4; ++m) _Pragma("unroll") for (int k = 0; k < 2; ++k) dst[m][k] = *(const LAS bf16x8*)(lds + PG8_SA(b, h) + aoff + m * 2048 + k * 1024); } while (0)
; #define PG8_MMA(ai, bj, At, Bt) do { __builtin_amdgcn_s_setprio(1); _Pragma("unroll") for (int m = 0; m < 4; ++m) _Pragma("unroll") for (int n = 0; n < 2; ++n) _Pragma("unroll") for (int k = 0; k < 2; ++k) \
;         acc[ai][bj][m][n] = __builtin_amdgcn_mfma_f32_16x16x32_bf16(Bt[n][k], At[m][k], acc[ai][bj][m][n], 0, 0, 0); __builtin_amdgcn_s_setprio(0); } while (0)
; #define PG8_WAIT_V(n) asm volatile("s_waitcnt vmcnt(" #n ")" ::: "memory")
; #define PG8_WAIT_L(n) asm volatile("s_waitcnt lgkmcnt(" #n ")" ::: "memory")
; #define PG8_BAR __builtin_amdgcn_s_barrier()
; #define PG8_SCHED __builtin_amdgcn_sched_barrier(0)
; template <class Epi>
; __device__ __forceinline__ void gemm_phase(LAS unsigned char* lds, const Gemm g, const StaticOrder& S, const Epi& E) {
;     ...
;             PG8_LDA(At, 1, 1); PG8_STAGE(PG8_SB(1, 0), b3, voffB); PG8_STAGE(PG8_SB(1, 1), b3 + hstepB, voffB); PG8_STAGE(PG8_SA(1, 0), a3, voffA);
;             PG8_WAIT_V(8); PG8_WAIT_L(0); PG8_BAR; PG8_MMA(1, 0, At, B0); PG8_MMA(1, 1, At, B1); PG8_BAR; PG8_SCHED;
;         }
;         if (wr == 0) PG8_BAR;
;         bool run_epi = true;
	ds_read_b128 v[182:185], v151 offset:49152
	ds_read_b128 v[186:189], v151 offset:50176
	ds_read_b128 v[190:193], v151 offset:51200
	ds_read_b128 v[194:197], v151 offset:52224
	ds_read_b128 v[198:201], v151 offset:53248
	ds_read_b128 v[202:205], v151 offset:54272
	ds_read_b128 v[206:209], v151 offset:55296
	ds_read_b128 v[210:213], v151 offset:56320
	s_add_u32 s16, s56, 0x80
	s_addc_u32 s17, s57, 0
	s_mov_b32 s79, m0
	s_mov_b32 m0, s63
	s_nop 0
	global_load_lds_dwordx4 v144, s[16:17]
	s_mov_b32 m0, s79
	s_nop 0
	s_mov_b32 s79, m0
	s_mov_b32 m0, s64
	s_nop 0
	global_load_lds_dwordx4 v146, s[16:17]
	s_mov_b32 m0, s79
	s_add_u32 s16, s56, 0x40080
	s_addc_u32 s17, s57, 0
	s_mov_b32 s56, m0
	s_mov_b32 m0, s67
	s_nop 0
	global_load_lds_dwordx4 v144, s[16:17]
	s_mov_b32 m0, s56
	s_nop 0
	s_mov_b32 s56, m0
	s_mov_b32 m0, s68
	s_nop 0
	global_load_lds_dwordx4 v146, s[16:17]
	s_mov_b32 m0, s56
	s_mov_b32 s16, m0
	s_mov_b32 m0, s65
	s_nop 0
	global_load_lds_dwordx4 v141, s[40:41]
	s_mov_b32 m0, s16
	s_nop 0
	s_mov_b32 s16, m0
	s_mov_b32 m0, s66
	s_nop 0
	global_load_lds_dwordx4 v145, s[40:41]
	s_mov_b32 m0, s16
	s_waitcnt vmcnt(8)
	s_waitcnt lgkmcnt(0)
	s_barrier
	s_setprio 1
	s_waitcnt lgkmcnt(7)
	v_mfma_f32_16x16x32_bf16 v[62:65], v[134:137], v[182:185], v[62:65]
	v_mfma_f32_16x16x32_bf16 v[58:61], v[158:161], v[182:185], v[58:61]
	s_waitcnt lgkmcnt(5)
	v_mfma_f32_16x16x32_bf16 v[46:49], v[134:137], v[190:193], v[46:49]
	v_mfma_f32_16x16x32_bf16 v[42:45], v[158:161], v[190:193], v[42:45]
	s_waitcnt lgkmcnt(3)
	v_mfma_f32_16x16x32_bf16 v[30:33], v[134:137], v[198:201], v[30:33]
	v_mfma_f32_16x16x32_bf16 v[26:29], v[158:161], v[198:201], v[26:29]
	s_waitcnt lgkmcnt(1)
	v_mfma_f32_16x16x32_bf16 v[14:17], v[134:137], v[206:209], v[14:17]
	v_mfma_f32_16x16x32_bf16 v[10:13], v[158:161], v[206:209], v[10:13]
	v_mfma_f32_16x16x32_bf16 v[62:65], v[154:157], v[186:189], v[62:65]
	v_mfma_f32_16x16x32_bf16 v[58:61], v[162:165], v[186:189], v[58:61]
	v_mfma_f32_16x16x32_bf16 v[46:49], v[154:157], v[194:197], v[46:49]
	v_mfma_f32_16x16x32_bf16 v[42:45], v[162:165], v[194:197], v[42:45]
	v_mfma_f32_16x16x32_bf16 v[30:33], v[154:157], v[202:205], v[30:33]
	v_mfma_f32_16x16x32_bf16 v[26:29], v[162:165], v[202:205], v[26:29]
	s_waitcnt lgkmcnt(0)
	v_mfma_f32_16x16x32_bf16 v[14:17], v[154:157], v[210:213], v[14:17]
	v_mfma_f32_16x16x32_bf16 v[10:13], v[162:165], v[210:213], v[10:13]
	s_setprio 0
	s_setprio 1
	v_mfma_f32_16x16x32_bf16 v[54:57], v[166:169], v[182:185], v[54:57]
	v_mfma_f32_16x16x32_bf16 v[50:53], v[174:177], v[182:185], v[50:53]
	v_mfma_f32_16x16x32_bf16 v[38:41], v[166:169], v[190:193], v[38:41]
	v_mfma_f32_16x16x32_bf16 v[34:37], v[174:177], v[190:193], v[34:37]
	v_mfma_f32_16x16x32_bf16 v[22:25], v[166:169], v[198:201], v[22:25]
	v_mfma_f32_16x16x32_bf16 v[18:21], v[174:177], v[198:201], v[18:21]
	v_mfma_f32_16x16x32_bf16 v[6:9], v[166:169], v[206:209], v[6:9]
	v_mfma_f32_16x16x32_bf16 v[2:5], v[174:177], v[206:209], v[2:5]
	v_mfma_f32_16x16x32_bf16 v[54:57], v[170:173], v[186:189], v[54:57]
	v_mfma_f32_16x16x32_bf16 v[50:53], v[178:181], v[186:189], v[50:53]
	v_mfma_f32_16x16x32_bf16 v[38:41], v[170:173], v[194:197], v[38:41]
	v_mfma_f32_16x16x32_bf16 v[34:37], v[178:181], v[194:197], v[34:37]
	v_mfma_f32_16x16x32_bf16 v[22:25], v[170:173], v[202:205], v[22:25]
	v_mfma_f32_16x16x32_bf16 v[18:21], v[178:181], v[202:205], v[18:21]
	v_mfma_f32_16x16x32_bf16 v[6:9], v[170:173], v[210:213], v[6:9]
	v_mfma_f32_16x16x32_bf16 v[2:5], v[178:181], v[210:213], v[2:5]
	s_setprio 0
	s_add_i32 s78, s78, 2
	s_add_u32 s74, s74, 0x100
	s_addc_u32 s75, s75, 0
	s_add_u32 s76, s76, 0x100
	s_addc_u32 s77, s77, 0
	s_cmp_gt_u32 s78, 13
	s_barrier
	s_cbranch_scc0 .LBB0_1291
	s_and_b64 vcc, exec, s[8:9]
	s_cbranch_vccz .LBB0_1294
	s_barrier

; #define PG8_STAGE(bufoff, gbase, voff) do { _Pragma("unroll") for (int _i = 0; _i < 2; ++_i) { unsigned _keep; \
;         asm volatile("s_mov_b32 %0, m0\n\ts_mov_b32 m0, %1\n\ts_nop 0\n\tglobal_load_lds_dwordx4 %2, %3\n\ts_mov_b32 m0, %0" : "=&s"(_keep) : "s"(ldsb + (unsigned)((bufoff) + _i * 8192)), "v"((voff)[_i]), "s"((const char*)(gbase)) : "memory"); } } while (0)
; #define PG8_LDA(dst, b, h) do { _Pragma("unroll") for (int m = 0; m < 4; ++m) _Pragma("unroll") for (int k = 0; k < 2; ++k) dst[m][k] = *(const LAS bf16x8*)(lds + PG8_SA(b, h) + aoff + m * 2048 + k * 1024); } while (0)
; #define PG8_LDB(dst, b, h) do { _Pragma("unroll") for (int n = 0; n < 2; ++n) _Pragma("unroll") for (int k = 0; k < 2; ++k) dst[n][k] = *(const LAS bf16x8*)(lds + PG8_SB(b, h) + boff + n * 2048 + k * 1024); } while (0)
; #define PG8_MMA(ai, bj, At, Bt) do { __builtin_amdgcn_s_setprio(1); _Pragma("unroll") for (int m = 0; m < 4; ++m) _Pragma("unroll") for (int n = 0; n < 2; ++n) _Pragma("unroll") for (int k = 0; k < 2; ++k) \
;         acc[ai][bj][m][n] = __builtin_amdgcn_mfma_f32_16x16x32_bf16(Bt[n][k], At[m][k], acc[ai][bj][m][n], 0, 0, 0); __builtin_amdgcn_s_setprio(0); } while (0)
; #define PG8_WAIT_V(n) asm volatile("s_waitcnt vmcnt(" #n ")" ::: "memory")
; #define PG8_WAIT_L(n) asm volatile("s_waitcnt lgkmcnt(" #n ")" ::: "memory")
; template <class Epi>
; __device__ __forceinline__ void gemm_phase(LAS unsigned char* lds, const Gemm g, const StaticOrder& S, const Epi& E) {
;     ...
;         for (int t = 0; t < nt; t += 2) {
;             const bool last = (t == nt - 2);
;             const char* a1 = cA + (size_t)(t + 1) * kstep;
;             const char* a2 = last ? nA : cA + (size_t)(t + 2) * kstep; const char* b2 = last ? nB : cB + (size_t)(t + 2) * kstep;
;             const char* a3 = a2 + kstep; const char* b3 = b2 + kstep;
;             PG8_LDB(B0, 0, 0); PG8_LDB(B1, 0, 1); PG8_SCHED; PG8_LDA(At, 0, 0); PG8_STAGE(PG8_SA(1, 1), a1 + hstepA, voffA);
;             PG8_WAIT_V(8); PG8_WAIT_L(0); PG8_BAR; PG8_MMA(0, 0, At, B0); PG8_MMA(0, 1, At, B1); PG8_BAR; PG8_SCHED;
;             PG8_LDA(At, 0, 1); PG8_STAGE(PG8_SB(0, 0), b2, voffB); PG8_STAGE(PG8_SB(0, 1), b2 + hstepB, voffB); PG8_STAGE(PG8_SA(0, 0), a2, voffA);
;             PG8_WAIT_V(8); PG8_WAIT_L(0); PG8_BAR; PG8_MMA(1, 0, At, B0); PG8_MMA(1, 1, At, B1); PG8_BAR; PG8_SCHED;
.LBB0_1378:
	ds_read_b128 v[144:147], v190
	ds_read_b128 v[196:199], v190 offset:1024
	ds_read_b128 v[200:203], v190 offset:2048
	ds_read_b128 v[204:207], v190 offset:3072
	ds_read_b128 v[208:211], v192
	ds_read_b128 v[212:215], v192 offset:1024
	ds_read_b128 v[216:219], v192 offset:2048
	ds_read_b128 v[220:223], v192 offset:3072
	s_add_i32 s87, s16, 2
	s_cmp_eq_u32 s61, s16
	s_cselect_b32 s16, s45, s81
	s_cselect_b32 s17, s21, s82
	s_cselect_b32 s58, s49, s83
	s_cselect_b32 s59, s47, s86
	s_add_u32 s40, s16, 0x80
	s_addc_u32 s41, s17, 0
	ds_read_b128 v[224:227], v191
	ds_read_b128 v[228:231], v191 offset:1024
	ds_read_b128 v[232:235], v191 offset:2048
	ds_read_b128 v[236:239], v191 offset:3072
	ds_read_b128 v[240:243], v191 offset:4096
	ds_read_b128 v[244:247], v191 offset:5120
	ds_read_b128 v[248:251], v191 offset:6144
	ds_read_b128 v[136:139], v191 offset:7168
	s_mov_b32 s88, m0
	s_mov_b32 m0, s74
	s_nop 0
	global_load_lds_dwordx4 v150, s[56:57]
	s_mov_b32 m0, s88
	s_nop 0
	s_mov_b32 s88, m0
	s_mov_b32 m0, s75
	s_nop 0
	global_load_lds_dwordx4 v153, s[56:57]
	s_mov_b32 m0, s88
	s_waitcnt vmcnt(8)
	s_waitcnt lgkmcnt(0)
	s_barrier
	s_setprio 1
	s_waitcnt lgkmcnt(7)
	v_mfma_f32_16x16x32_bf16 v[128:131], v[144:147], v[224:227], v[128:131]
	v_mfma_f32_16x16x32_bf16 v[124:127], v[200:203], v[224:227], v[124:127]
	s_waitcnt lgkmcnt(5)
	v_mfma_f32_16x16x32_bf16 v[112:115], v[144:147], v[232:235], v[112:115]
	v_mfma_f32_16x16x32_bf16 v[108:111], v[200:203], v[232:235], v[108:111]
	s_waitcnt lgkmcnt(3)
	v_mfma_f32_16x16x32_bf16 v[96:99], v[144:147], v[240:243], v[96:99]
	v_mfma_f32_16x16x32_bf16 v[92:95], v[200:203], v[240:243], v[92:95]
	s_waitcnt lgkmcnt(1)
	v_mfma_f32_16x16x32_bf16 v[80:83], v[144:147], v[248:251], v[80:83]
	v_mfma_f32_16x16x32_bf16 v[76:79], v[200:203], v[248:251], v[76:79]
	v_mfma_f32_16x16x32_bf16 v[128:131], v[196:199], v[228:231], v[128:131]
	v_mfma_f32_16x16x32_bf16 v[124:127], v[204:207], v[228:231], v[124:127]
	v_mfma_f32_16x16x32_bf16 v[112:115], v[196:199], v[236:239], v[112:115]
	v_mfma_f32_16x16x32_bf16 v[108:111], v[204:207], v[236:239], v[108:111]
	v_mfma_f32_16x16x32_bf16 v[96:99], v[196:199], v[244:247], v[96:99]
	v_mfma_f32_16x16x32_bf16 v[92:95], v[204:207], v[244:247], v[92:95]
	s_waitcnt lgkmcnt(0)
	v_mfma_f32_16x16x32_bf16 v[80:83], v[196:199], v[136:139], v[80:83]
	v_mfma_f32_16x16x32_bf16 v[76:79], v[204:207], v[136:139], v[76:79]
	s_setprio 0
	s_setprio 1
	v_mfma_f32_16x16x32_bf16 v[120:123], v[208:211], v[224:227], v[120:123]
	v_mfma_f32_16x16x32_bf16 v[116:119], v[216:219], v[224:227], v[116:119]
	v_mfma_f32_16x16x32_bf16 v[104:107], v[208:211], v[232:235], v[104:107]
	v_mfma_f32_16x16x32_bf16 v[100:103], v[216:219], v[232:235], v[100:103]
	v_mfma_f32_16x16x32_bf16 v[88:91], v[208:211], v[240:243], v[88:91]
	v_mfma_f32_16x16x32_bf16 v[84:87], v[216:219], v[240:243], v[84:87]
	v_mfma_f32_16x16x32_bf16 v[72:75], v[208:211], v[248:251], v[72:75]
	v_mfma_f32_16x16x32_bf16 v[68:71], v[216:219], v[248:251], v[68:71]
	v_mfma_f32_16x16x32_bf16 v[120:123], v[212:215], v[228:231], v[120:123]
	v_mfma_f32_16x16x32_bf16 v[116:119], v[220:223], v[228:231], v[116:119]
	v_mfma_f32_16x16x32_bf16 v[104:107], v[212:215], v[236:239], v[104:107]
	v_mfma_f32_16x16x32_bf16 v[100:103], v[220:223], v[236:239], v[100:103]
	v_mfma_f32_16x16x32_bf16 v[88:91], v[212:215], v[244:247], v[88:91]
	v_mfma_f32_16x16x32_bf16 v[84:87], v[220:223], v[244:247], v[84:87]
	v_mfma_f32_16x16x32_bf16 v[72:75], v[212:215], v[136:139], v[72:75]
	v_mfma_f32_16x16x32_bf16 v[68:71], v[220:223], v[136:139], v[68:71]
	s_setprio 0
	s_barrier
	ds_read_b128 v[136:139], v191 offset:16384
	ds_read_b128 v[224:227], v191 offset:17408
	ds_read_b128 v[228:231], v191 offset:18432
	ds_read_b128 v[232:235], v191 offset:19456
	ds_read_b128 v[236:239], v191 offset:20480
	ds_read_b128 v[240:243], v191 offset:21504
	ds_read_b128 v[244:247], v191 offset:22528
	ds_read_b128 v[248:251], v191 offset:23552
	s_mov_b32 s88, m0
	s_mov_b32 m0, s35
	s_nop 0
	global_load_lds_dwordx4 v151, s[58:59]
	s_mov_b32 m0, s88
	s_nop 0
	s_mov_b32 s88, m0
	s_mov_b32 m0, s53
	s_nop 0
	global_load_lds_dwordx4 v154, s[58:59]
	s_mov_b32 m0, s88
	s_add_u32 s88, s58, 0x40000
	s_addc_u32 s89, s59, 0
	s_mov_b32 s90, m0
	s_mov_b32 m0, s55
	s_nop 0
	global_load_lds_dwordx4 v151, s[88:89]
	s_mov_b32 m0, s90
	s_nop 0
	s_mov_b32 s90, m0
	s_mov_b32 m0, s62
	s_nop 0
	global_load_lds_dwordx4 v154, s[88:89]
	s_mov_b32 m0, s90
	s_mov_b32 s88, m0
	s_mov_b32 m0, s33
	s_nop 0
	global_load_lds_dwordx4 v150, s[16:17]
	s_mov_b32 m0, s88
	s_nop 0
	s_mov_b32 s88, m0
	s_mov_b32 m0, s63
	s_nop 0
	global_load_lds_dwordx4 v153, s[16:17]
	s_mov_b32 m0, s88
	s_waitcnt vmcnt(8)
	s_waitcnt lgkmcnt(0)
	s_barrier
; #define PG8_STAGE(bufoff, gbase, voff) do { _Pragma("unroll") for (int _i = 0; _i < 2; ++_i) { unsigned _keep; \
;         asm volatile("s_mov_b32 %0, m0\n\ts_mov_b32 m0, %1\n\ts_nop 0\n\tglobal_load_lds_dwordx4 %2, %3\n\ts_mov_b32 m0, %0" : "=&s"(_keep) : "s"(ldsb + (unsigned)((bufoff) + _i * 8192)), "v"((voff)[_i]), "s"((const char*)(gbase)) : "memory"); } } while (0)
; #define PG8_LDA(dst, b, h) do { _Pragma("unroll") for (int m = 0; m < 4; ++m) _Pragma("unroll") for (int k = 0; k < 2; ++k) dst[m][k] = *(const LAS bf16x8*)(lds + PG8_SA(b, h) + aoff + m * 2048 + k * 1024); } while (0)
; #define PG8_LDB(dst, b, h) do { _Pragma("unroll") for (int n = 0; n < 2; ++n) _Pragma("unroll") for (int k = 0; k < 2; ++k) dst[n][k] = *(const LAS bf16x8*)(lds + PG8_SB(b, h) + boff + n * 2048 + k * 1024); } while (0)
; #define PG8_MMA(ai, bj, At, Bt) do { __builtin_amdgcn_s_setprio(1); _Pragma("unroll") for (int m = 0; m < 4; ++m) _Pragma("unroll") for (int n = 0; n < 2; ++n) _Pragma("unroll") for (int k = 0; k < 2; ++k) \
;         acc[ai][bj][m][n] = __builtin_amdgcn_mfma_f32_16x16x32_bf16(Bt[n][k], At[m][k], acc[ai][bj][m][n], 0, 0, 0); __builtin_amdgcn_s_setprio(0); } while (0)
; #define PG8_WAIT_V(n) asm volatile("s_waitcnt vmcnt(" #n ")" ::: "memory")
; #define PG8_WAIT_L(n) asm volatile("s_waitcnt lgkmcnt(" #n ")" ::: "memory")
; #define PG8_BAR __builtin_amdgcn_s_barrier()
; #define PG8_SCHED __builtin_amdgcn_sched_barrier(0)
; template <class Epi>
; __device__ __forceinline__ void gemm_phase(LAS unsigned char* lds, const Gemm g, const StaticOrder& S, const Epi& E) {
;     ...
;             PG8_WAIT_V(8); PG8_WAIT_L(0); PG8_BAR; PG8_MMA(1, 0, At, B0); PG8_MMA(1, 1, At, B1); PG8_BAR; PG8_SCHED;
;             PG8_LDB(B0, 1, 0); PG8_LDB(B1, 1, 1); PG8_SCHED; PG8_LDA(At, 1, 0); PG8_STAGE(PG8_SA(0, 1), a2 + hstepA, voffA);
;             PG8_WAIT_V(8); PG8_WAIT_L(0); PG8_BAR; PG8_MMA(0, 0, At, B0); PG8_MMA(0, 1, At, B1); PG8_BAR; PG8_SCHED;
;             PG8_LDA(At, 1, 1); PG8_STAGE(PG8_SB(1, 0), b3, voffB); PG8_STAGE(PG8_SB(1, 1), b3 + hstepB, voffB); PG8_STAGE(PG8_SA(1, 0), a3, voffA);
	s_setprio 1
	s_waitcnt lgkmcnt(7)
	v_mfma_f32_16x16x32_bf16 v[64:67], v[144:147], v[136:139], v[64:67]
	v_mfma_f32_16x16x32_bf16 v[60:63], v[200:203], v[136:139], v[60:63]
	s_waitcnt lgkmcnt(5)
	v_mfma_f32_16x16x32_bf16 v[48:51], v[144:147], v[228:231], v[48:51]
	v_mfma_f32_16x16x32_bf16 v[44:47], v[200:203], v[228:231], v[44:47]
	s_waitcnt lgkmcnt(3)
	v_mfma_f32_16x16x32_bf16 v[32:35], v[144:147], v[236:239], v[32:35]
	v_mfma_f32_16x16x32_bf16 v[28:31], v[200:203], v[236:239], v[28:31]
	s_waitcnt lgkmcnt(1)
	v_mfma_f32_16x16x32_bf16 v[16:19], v[144:147], v[244:247], v[16:19]
	v_mfma_f32_16x16x32_bf16 v[12:15], v[200:203], v[244:247], v[12:15]
	v_mfma_f32_16x16x32_bf16 v[64:67], v[196:199], v[224:227], v[64:67]
	v_mfma_f32_16x16x32_bf16 v[60:63], v[204:207], v[224:227], v[60:63]
	v_mfma_f32_16x16x32_bf16 v[48:51], v[196:199], v[232:235], v[48:51]
	v_mfma_f32_16x16x32_bf16 v[44:47], v[204:207], v[232:235], v[44:47]
	v_mfma_f32_16x16x32_bf16 v[32:35], v[196:199], v[240:243], v[32:35]
	v_mfma_f32_16x16x32_bf16 v[28:31], v[204:207], v[240:243], v[28:31]
	s_waitcnt lgkmcnt(0)
	v_mfma_f32_16x16x32_bf16 v[16:19], v[196:199], v[248:251], v[16:19]
	v_mfma_f32_16x16x32_bf16 v[12:15], v[204:207], v[248:251], v[12:15]
	s_setprio 0
	s_setprio 1
	v_mfma_f32_16x16x32_bf16 v[56:59], v[208:211], v[136:139], v[56:59]
	v_mfma_f32_16x16x32_bf16 v[52:55], v[216:219], v[136:139], v[52:55]
	v_mfma_f32_16x16x32_bf16 v[40:43], v[208:211], v[228:231], v[40:43]
	v_mfma_f32_16x16x32_bf16 v[36:39], v[216:219], v[228:231], v[36:39]
	v_mfma_f32_16x16x32_bf16 v[24:27], v[208:211], v[236:239], v[24:27]
	v_mfma_f32_16x16x32_bf16 v[20:23], v[216:219], v[236:239], v[20:23]
	v_mfma_f32_16x16x32_bf16 v[8:11], v[208:211], v[244:247], v[8:11]
	v_mfma_f32_16x16x32_bf16 v[4:7], v[216:219], v[244:247], v[4:7]
	v_mfma_f32_16x16x32_bf16 v[56:59], v[212:215], v[224:227], v[56:59]
	v_mfma_f32_16x16x32_bf16 v[52:55], v[220:223], v[224:227], v[52:55]
	v_mfma_f32_16x16x32_bf16 v[40:43], v[212:215], v[232:235], v[40:43]
	v_mfma_f32_16x16x32_bf16 v[36:39], v[220:223], v[232:235], v[36:39]
	v_mfma_f32_16x16x32_bf16 v[24:27], v[212:215], v[240:243], v[24:27]
	v_mfma_f32_16x16x32_bf16 v[20:23], v[220:223], v[240:243], v[20:23]
	v_mfma_f32_16x16x32_bf16 v[8:11], v[212:215], v[248:251], v[8:11]
	v_mfma_f32_16x16x32_bf16 v[4:7], v[220:223], v[248:251], v[4:7]
	s_setprio 0
	s_barrier
	v_add_u32_e32 v3, 0x18000, v189
	ds_read_b128 v[136:139], v3
	ds_read_b128 v[144:147], v3 offset:1024
	ds_read_b128 v[196:199], v3 offset:2048
	ds_read_b128 v[200:203], v3 offset:3072
	v_add_u32_e32 v3, 0x1c000, v189
	ds_read_b128 v[204:207], v3
	ds_read_b128 v[208:211], v3 offset:1024
	ds_read_b128 v[212:215], v3 offset:2048
	ds_read_b128 v[216:219], v3 offset:3072
	ds_read_b128 v[220:223], v191 offset:32768
	ds_read_b128 v[224:227], v191 offset:33792
	ds_read_b128 v[228:231], v191 offset:34816
	ds_read_b128 v[232:235], v191 offset:35840
	ds_read_b128 v[236:239], v191 offset:36864
	ds_read_b128 v[240:243], v191 offset:37888
	ds_read_b128 v[244:247], v191 offset:38912
	ds_read_b128 v[248:251], v191 offset:39936
	s_add_u32 s16, s16, 0x40000
	s_addc_u32 s17, s17, 0
	s_mov_b32 s88, m0
	s_mov_b32 m0, s64
	s_nop 0
	global_load_lds_dwordx4 v150, s[16:17]
	s_mov_b32 m0, s88
	s_nop 0
	s_mov_b32 s88, m0
	s_mov_b32 m0, s65
	s_nop 0
	global_load_lds_dwordx4 v153, s[16:17]
	s_mov_b32 m0, s88
	s_waitcnt vmcnt(8)
	s_waitcnt lgkmcnt(0)
	s_barrier
	s_setprio 1
	s_waitcnt lgkmcnt(7)
	v_mfma_f32_16x16x32_bf16 v[128:131], v[136:139], v[220:223], v[128:131]
	v_mfma_f32_16x16x32_bf16 v[124:127], v[196:199], v[220:223], v[124:127]
	s_waitcnt lgkmcnt(5)
	v_mfma_f32_16x16x32_bf16 v[112:115], v[136:139], v[228:231], v[112:115]
	v_mfma_f32_16x16x32_bf16 v[108:111], v[196:199], v[228:231], v[108:111]
	s_waitcnt lgkmcnt(3)
	v_mfma_f32_16x16x32_bf16 v[96:99], v[136:139], v[236:239], v[96:99]
	v_mfma_f32_16x16x32_bf16 v[92:95], v[196:199], v[236:239], v[92:95]
	s_waitcnt lgkmcnt(1)
	v_mfma_f32_16x16x32_bf16 v[80:83], v[136:139], v[244:247], v[80:83]
	v_mfma_f32_16x16x32_bf16 v[76:79], v[196:199], v[244:247], v[76:79]
	v_mfma_f32_16x16x32_bf16 v[128:131], v[144:147], v[224:227], v[128:131]
	v_mfma_f32_16x16x32_bf16 v[124:127], v[200:203], v[224:227], v[124:127]
	v_mfma_f32_16x16x32_bf16 v[112:115], v[144:147], v[232:235], v[112:115]
	v_mfma_f32_16x16x32_bf16 v[108:111], v[200:203], v[232:235], v[108:111]
	v_mfma_f32_16x16x32_bf16 v[96:99], v[144:147], v[240:243], v[96:99]
	v_mfma_f32_16x16x32_bf16 v[92:95], v[200:203], v[240:243], v[92:95]
	s_waitcnt lgkmcnt(0)
	v_mfma_f32_16x16x32_bf16 v[80:83], v[144:147], v[248:251], v[80:83]
	v_mfma_f32_16x16x32_bf16 v[76:79], v[200:203], v[248:251], v[76:79]
	s_setprio 0
	s_setprio 1
	v_mfma_f32_16x16x32_bf16 v[120:123], v[204:207], v[220:223], v[120:123]
	v_mfma_f32_16x16x32_bf16 v[116:119], v[212:215], v[220:223], v[116:119]
	v_mfma_f32_16x16x32_bf16 v[104:107], v[204:207], v[228:231], v[104:107]
	v_mfma_f32_16x16x32_bf16 v[100:103], v[212:215], v[228:231], v[100:103]
	v_mfma_f32_16x16x32_bf16 v[88:91], v[204:207], v[236:239], v[88:91]
	v_mfma_f32_16x16x32_bf16 v[84:87], v[212:215], v[236:239], v[84:87]
	v_mfma_f32_16x16x32_bf16 v[72:75], v[204:207], v[244:247], v[72:75]
	v_mfma_f32_16x16x32_bf16 v[68:71], v[212:215], v[244:247], v[68:71]
	v_mfma_f32_16x16x32_bf16 v[120:123], v[208:211], v[224:227], v[120:123]
	v_mfma_f32_16x16x32_bf16 v[116:119], v[216:219], v[224:227], v[116:119]
	v_mfma_f32_16x16x32_bf16 v[104:107], v[208:211], v[232:235], v[104:107]
	v_mfma_f32_16x16x32_bf16 v[100:103], v[216:219], v[232:235], v[100:103]
	v_mfma_f32_16x16x32_bf16 v[88:91], v[208:211], v[240:243], v[88:91]
	v_mfma_f32_16x16x32_bf16 v[84:87], v[216:219], v[240:243], v[84:87]
	v_mfma_f32_16x16x32_bf16 v[72:75], v[208:211], v[248:251], v[72:75]
	v_mfma_f32_16x16x32_bf16 v[68:71], v[216:219], v[248:251], v[68:71]
	s_setprio 0
	s_barrier
; #define PG8_STAGE(bufoff, gbase, voff) do { _Pragma("unroll") for (int _i = 0; _i < 2; ++_i) { unsigned _keep; \
;         asm volatile("s_mov_b32 %0, m0\n\ts_mov_b32 m0, %1\n\ts_nop 0\n\tglobal_load_lds_dwordx4 %2, %3\n\ts_mov_b32 m0, %0" : "=&s"(_keep) : "s"(ldsb + (unsigned)((bufoff) + _i * 8192)), "v"((voff)[_i]), "s"((const char*)(gbase)) : "memory"); } } while (0)
; #define PG8_LDA(dst, b, h) do { _Pragma("unroll") for (int m = 0; m < 4; ++m) _Pragma("unroll") for (int k = 0; k < 2; ++k) dst[m][k] = *(const LAS bf16x8*)(lds + PG8_SA(b, h) + aoff + m * 2048 + k * 1024); } while (0)
; #define PG8_LDB(dst, b, h) do { _Pragma("unroll") for (int n = 0; n < 2; ++n) _Pragma("unroll") for (int k = 0; k < 2; ++k) dst[n][k] = *(const LAS bf16x8*)(lds + PG8_SB(b, h) + boff + n * 2048 + k * 1024); } while (0)
; template <class Epi>
; __device__ __forceinline__ void gemm_phase(LAS unsigned char* lds, const Gemm g, const StaticOrder& S, const Epi& E) {
;     ...
;         for (int t = 0; t < nt; t += 2) {
;             const bool last = (t == nt - 2);
;             const char* a1 = cA + (size_t)(t + 1) * kstep;
;             const char* a2 = last ? nA : cA + (size_t)(t + 2) * kstep; const char* b2 = last ? nB : cB + (size_t)(t + 2) * kstep;
;             const char* a3 = a2 + kstep; const char* b3 = b2 + kstep;
;             PG8_LDB(B0, 0, 0); PG8_LDB(B1, 0, 1); PG8_SCHED; PG8_LDA(At, 0, 0); PG8_STAGE(PG8_SA(1, 1), a1 + hstepA, voffA);
;             PG8_WAIT_V(8); PG8_WAIT_L(0); PG8_BAR; PG8_MMA(0, 0, At, B0); PG8_MMA(0, 1, At, B1); PG8_BAR; PG8_SCHED;
;             PG8_LDA(At, 0, 1); PG8_STAGE(PG8_SB(0, 0), b2, voffB); PG8_STAGE(PG8_SB(0, 1), b2 + hstepB, voffB); PG8_STAGE(PG8_SA(0, 0), a2, voffA);
;             PG8_WAIT_V(8); PG8_WAIT_L(0); PG8_BAR; PG8_MMA(1, 0, At, B0); PG8_MMA(1, 1, At, B1); PG8_BAR; PG8_SCHED;
;             PG8_LDB(B0, 1, 0); PG8_LDB(B1, 1, 1); PG8_SCHED; PG8_LDA(At, 1, 0); PG8_STAGE(PG8_SA(0, 1), a2 + hstepA, voffA);
;             PG8_WAIT_V(8); PG8_WAIT_L(0); PG8_BAR; PG8_MMA(0, 0, At, B0); PG8_MMA(0, 1, At, B1); PG8_BAR; PG8_SCHED;
;             PG8_LDA(At, 1, 1); PG8_STAGE(PG8_SB(1, 0), b3, voffB); PG8_STAGE(PG8_SB(1, 1), b3 + hstepB, voffB); PG8_STAGE(PG8_SA(1, 0), a3, voffA);
;             PG8_WAIT_V(8); PG8_WAIT_L(0); PG8_BAR; PG8_MMA(1, 0, At, B0); PG8_MMA(1, 1, At, B1); PG8_BAR; PG8_SCHED;
;         }
;         if (wr == 0) PG8_BAR;
	ds_read_b128 v[220:223], v191 offset:49152
	ds_read_b128 v[224:227], v191 offset:50176
	ds_read_b128 v[228:231], v191 offset:51200
	ds_read_b128 v[232:235], v191 offset:52224
	ds_read_b128 v[236:239], v191 offset:53248
	ds_read_b128 v[240:243], v191 offset:54272
	ds_read_b128 v[244:247], v191 offset:55296
	ds_read_b128 v[248:251], v191 offset:56320
	s_add_u32 s16, s58, 0x80
	s_addc_u32 s17, s59, 0
	s_mov_b32 s88, m0
	s_mov_b32 m0, s68
	s_nop 0
	global_load_lds_dwordx4 v151, s[16:17]
	s_mov_b32 m0, s88
	s_nop 0
	s_mov_b32 s88, m0
	s_mov_b32 m0, s69
	s_nop 0
	global_load_lds_dwordx4 v154, s[16:17]
	s_mov_b32 m0, s88
	s_add_u32 s16, s58, 0x40080
	s_addc_u32 s17, s59, 0
	s_mov_b32 s58, m0
	s_mov_b32 m0, s72
	s_nop 0
	global_load_lds_dwordx4 v151, s[16:17]
	s_mov_b32 m0, s58
	s_nop 0
	s_mov_b32 s58, m0
	s_mov_b32 m0, s73
	s_nop 0
	global_load_lds_dwordx4 v154, s[16:17]
	s_mov_b32 m0, s58
	s_mov_b32 s16, m0
	s_mov_b32 m0, s70
	s_nop 0
	global_load_lds_dwordx4 v150, s[40:41]
	s_mov_b32 m0, s16
	s_nop 0
	s_mov_b32 s16, m0
	s_mov_b32 m0, s71
	s_nop 0
	global_load_lds_dwordx4 v153, s[40:41]
	s_mov_b32 m0, s16
	s_waitcnt vmcnt(8)
	s_waitcnt lgkmcnt(0)
	s_barrier
	s_setprio 1
	s_waitcnt lgkmcnt(7)
	v_mfma_f32_16x16x32_bf16 v[64:67], v[136:139], v[220:223], v[64:67]
	v_mfma_f32_16x16x32_bf16 v[60:63], v[196:199], v[220:223], v[60:63]
	s_waitcnt lgkmcnt(5)
	v_mfma_f32_16x16x32_bf16 v[48:51], v[136:139], v[228:231], v[48:51]
	v_mfma_f32_16x16x32_bf16 v[44:47], v[196:199], v[228:231], v[44:47]
	s_waitcnt lgkmcnt(3)
	v_mfma_f32_16x16x32_bf16 v[32:35], v[136:139], v[236:239], v[32:35]
	v_mfma_f32_16x16x32_bf16 v[28:31], v[196:199], v[236:239], v[28:31]
	s_waitcnt lgkmcnt(1)
	v_mfma_f32_16x16x32_bf16 v[16:19], v[136:139], v[244:247], v[16:19]
	v_mfma_f32_16x16x32_bf16 v[12:15], v[196:199], v[244:247], v[12:15]
	v_mfma_f32_16x16x32_bf16 v[64:67], v[144:147], v[224:227], v[64:67]
	v_mfma_f32_16x16x32_bf16 v[60:63], v[200:203], v[224:227], v[60:63]
	v_mfma_f32_16x16x32_bf16 v[48:51], v[144:147], v[232:235], v[48:51]
	v_mfma_f32_16x16x32_bf16 v[44:47], v[200:203], v[232:235], v[44:47]
	v_mfma_f32_16x16x32_bf16 v[32:35], v[144:147], v[240:243], v[32:35]
	v_mfma_f32_16x16x32_bf16 v[28:31], v[200:203], v[240:243], v[28:31]
	s_waitcnt lgkmcnt(0)
	v_mfma_f32_16x16x32_bf16 v[16:19], v[144:147], v[248:251], v[16:19]
	v_mfma_f32_16x16x32_bf16 v[12:15], v[200:203], v[248:251], v[12:15]
	s_setprio 0
	s_setprio 1
	v_mfma_f32_16x16x32_bf16 v[56:59], v[204:207], v[220:223], v[56:59]
	v_mfma_f32_16x16x32_bf16 v[52:55], v[212:215], v[220:223], v[52:55]
	v_mfma_f32_16x16x32_bf16 v[40:43], v[204:207], v[228:231], v[40:43]
	v_mfma_f32_16x16x32_bf16 v[36:39], v[212:215], v[228:231], v[36:39]
	v_mfma_f32_16x16x32_bf16 v[24:27], v[204:207], v[236:239], v[24:27]
	v_mfma_f32_16x16x32_bf16 v[20:23], v[212:215], v[236:239], v[20:23]
	v_mfma_f32_16x16x32_bf16 v[8:11], v[204:207], v[244:247], v[8:11]
	v_mfma_f32_16x16x32_bf16 v[4:7], v[212:215], v[244:247], v[4:7]
	v_mfma_f32_16x16x32_bf16 v[56:59], v[208:211], v[224:227], v[56:59]
	v_mfma_f32_16x16x32_bf16 v[52:55], v[216:219], v[224:227], v[52:55]
	v_mfma_f32_16x16x32_bf16 v[40:43], v[208:211], v[232:235], v[40:43]
	v_mfma_f32_16x16x32_bf16 v[36:39], v[216:219], v[232:235], v[36:39]
	v_mfma_f32_16x16x32_bf16 v[24:27], v[208:211], v[240:243], v[24:27]
	v_mfma_f32_16x16x32_bf16 v[20:23], v[216:219], v[240:243], v[20:23]
	v_mfma_f32_16x16x32_bf16 v[8:11], v[208:211], v[248:251], v[8:11]
	v_mfma_f32_16x16x32_bf16 v[4:7], v[216:219], v[248:251], v[4:7]
	s_setprio 0
	s_add_u32 s81, s81, 0x100
	s_addc_u32 s82, s82, 0
	s_add_u32 s83, s83, 0x100
	s_addc_u32 s86, s86, 0
	s_add_u32 s56, s56, 0x100
	s_addc_u32 s57, s57, 0
	s_cmp_ge_i32 s87, s60
	s_mov_b32 s16, s87
	s_barrier
	s_cbranch_scc0 .LBB0_1378
	s_and_b64 vcc, exec, s[42:43]
	s_cbranch_vccz .LBB0_1381

; #define EPI_ROWS(...) _Pragma("unroll") for (int ai = 0; ai < 2; ++ai) _Pragma("unroll") for (int m = 0; m < 4; ++m) { const int row = row0 + ai * 128 + m * 16; __VA_ARGS__ __builtin_amdgcn_sched_barrier(0); }
; __device__ __forceinline__ u32x4 pack8(f32x4 a, f32x4 b) { u32x4 w; w.x = pk2(a[0], a[1]); w.y = pk2(a[2], a[3]); w.z = pk2(b[0], b[1]); w.w = pk2(b[2], b[3]); return w; }
; __device__ __forceinline__ float dot8(f32x4 a, f32x4 b) { return (a[0] * a[0] + a[1] * a[1]) + (a[2] * a[2] + a[3] * a[3]) + (b[0] * b[0] + b[1] * b[1]) + (b[2] * b[2] + b[3] * b[3]); }
; __device__ __forceinline__ float red_fq(float s) { s += __shfl_xor(s, 16); s += __shfl_xor(s, 32); return s; }
;     __device__ __forceinline__ void operator()(AccRef acc, const Unit& u, int wr, int wc, int fr, int fq) const {
;         const int row0 = u.pm * 256 + wr * 64 + fr, col0 = u.pn * 256 + wc * 32 + 8 * fq;
;         EPI_ROWS(
;             const float* rp = (row < MP) ? res0 + (size_t)row * DM : res1 + (size_t)(row - MP) * DM;
;             float s = 0.f;
;             _Pragma("unroll") for (int bj = 0; bj < 2; ++bj) { const int col = col0 + bj * 128;
;                 f32x4 v0 = *(const f32x4*)(rp + col) + acc[ai][bj][m][0] * scale, v1 = *(const f32x4*)(rp + col + 4) + acc[ai][bj][m][1] * scale;
;                 *(f32x4*)(out + (size_t)row * DM + col) = v0; *(f32x4*)(out + (size_t)row * DM + col + 4) = v1;
;                 if (WB) *(u32x4*)(ob + (size_t)row * DM + col) = pack8(v0, v1);
;                 s += dot8(v0, v1); }
;             s = red_fq(s); if (fq == 0) unsafeAtomicAdd(ss + row, s);
;         )
;     }
.LBB0_1395:
	v_lshl_add_u32 v146, s54, 8, v155
	v_cmp_lt_i32_e32 vcc, s79, v146
	s_and_saveexec_b64 s[16:17], vcc
	s_xor_b64 s[16:17], exec, s[16:17]
	v_add_u32_e32 v136, 0xffff8000, v146
	v_mov_b32_e32 v137, v2
	v_lshlrev_b64 v[136:137], 12, v[136:137]
	v_lshl_add_u64 v[148:149], s[10:11], 0, v[136:137]
	v_mov_b32_e32 v147, v2
	s_andn2_saveexec_b64 s[16:17], s[16:17]
	v_ashrrev_i32_e32 v147, 31, v146
	v_lshlrev_b64 v[136:137], 12, v[146:147]
	v_lshl_add_u64 v[148:149], s[30:31], 0, v[136:137]
	s_or_b64 exec, exec, s[16:17]
	v_lshl_or_b32 v142, s52, 8, v188
	v_ashrrev_i32_e32 v143, 31, v142
	v_lshlrev_b64 v[144:145], 2, v[142:143]
	v_lshl_add_u64 v[148:149], v[148:149], 0, v[144:145]
	global_load_dwordx4 v[136:139], v[148:149], off
	global_load_dwordx4 v[196:199], v[148:149], off offset:16
	global_load_dwordx4 v[216:219], v[148:149], off offset:512
	global_load_dwordx4 v[220:223], v[148:149], off offset:528
	v_lshlrev_b64 v[200:201], 12, v[146:147]
	v_lshlrev_b64 v[202:203], 11, v[146:147]
	v_lshl_add_u64 v[200:201], s[30:31], 0, v[200:201]
	v_lshl_add_u64 v[202:203], s[18:19], 0, v[202:203]
	v_lshl_add_u64 v[202:203], v[142:143], 1, v[202:203]
	v_lshl_add_u64 v[200:201], v[200:201], 0, v[144:145]
	v_xor_b32_e32 v3, 16, v193
	s_waitcnt vmcnt(3)
	v_pk_add_f32 v[130:131], v[138:139], v[130:131]
	v_pk_add_f32 v[128:129], v[136:137], v[128:129]
	s_waitcnt vmcnt(2)
	v_pk_add_f32 v[126:127], v[198:199], v[126:127]
	v_pk_add_f32 v[124:125], v[196:197], v[124:125]
	v_cvt_pk_bf16_f32 v136, v128, v129
	v_cvt_pk_bf16_f32 v137, v130, v131
	v_cvt_pk_bf16_f32 v138, v124, v125
	v_cvt_pk_bf16_f32 v139, v126, v127
	global_store_dwordx4 v[200:201], v[128:131], off
	global_store_dwordx4 v[200:201], v[124:127], off offset:16
	global_store_dwordx4 v[202:203], v[136:139], off
	s_nop 0
	s_nop 0
	s_nop 0
	v_mul_f32_e32 v129, v129, v129
	v_mul_f32_e32 v131, v131, v131
	v_mul_f32_e32 v125, v125, v125
	v_fmac_f32_e32 v129, v128, v128
	v_fmac_f32_e32 v131, v130, v130
	v_mul_f32_e32 v127, v127, v127
	v_fmac_f32_e32 v125, v124, v124
	v_add_f32_e32 v124, v129, v131
	v_fmac_f32_e32 v127, v126, v126
	v_add_f32_e32 v124, v125, v124
	v_add_f32_e32 v130, v127, v124
	v_and_b32_e32 v148, 64, v193
	v_add_u32_e32 v148, 64, v148
	v_cmp_lt_i32_e32 vcc, v3, v148
	v_xor_b32_e32 v149, 32, v193
	s_waitcnt vmcnt(4)
	v_pk_add_f32 v[124:125], v[218:219], v[122:123]
	v_pk_add_f32 v[122:123], v[216:217], v[120:121]
	s_waitcnt vmcnt(3)
	v_pk_add_f32 v[126:127], v[220:221], v[116:117]
	v_mul_f32_e32 v116, v123, v123
	v_mul_f32_e32 v117, v125, v125
	v_pk_add_f32 v[128:129], v[222:223], v[118:119]
	v_mul_f32_e32 v118, v127, v127
	v_fmac_f32_e32 v116, v122, v122
	v_fmac_f32_e32 v117, v124, v124
	v_mul_f32_e32 v119, v129, v129
	v_fmac_f32_e32 v118, v126, v126
	v_add_f32_e32 v116, v116, v117
	v_add_f32_e32 v116, v118, v116
	v_fmac_f32_e32 v119, v128, v128
	v_cndmask_b32_e32 v3, v193, v3, vcc
	v_add_f32_e32 v116, v119, v116
	v_lshlrev_b32_e32 v3, 2, v3
	v_add_f32_e32 v116, v130, v116
	v_mov_b32_e32 v117, v116
	v_cmp_lt_i32_e32 vcc, v149, v148
	global_store_dwordx4 v[200:201], v[122:125], off offset:512
	global_store_dwordx4 v[200:201], v[126:129], off offset:528
	v_cndmask_b32_e32 v148, v193, v149, vcc
	v_lshlrev_b32_e32 v120, 2, v148
	v_permlane16_swap_b32_e32 v116, v117
	v_add_f32_e32 v116, v116, v117
	v_mov_b32_e32 v117, v116
	s_nop 1
	v_permlane32_swap_b32_e32 v116, v117
	v_cvt_pk_bf16_f32 v122, v122, v123
	v_cvt_pk_bf16_f32 v123, v124, v125
	v_cvt_pk_bf16_f32 v124, v126, v127
	v_cvt_pk_bf16_f32 v125, v128, v129
	global_store_dwordx4 v[202:203], v[122:125], off offset:256
	s_and_saveexec_b64 s[16:17], s[6:7]
	s_cbranch_execz .LBB0_1401
	s_waitcnt lgkmcnt(0)
	v_add_f32_e32 v118, v116, v117
	v_lshl_add_u64 v[116:117], v[146:147], 2, s[12:13]
	v_mov_b32_e32 v224, v116
	v_mov_b32_e32 v225, v117
	v_mov_b32_e32 v226, v118
.LBB0_1401:
	s_or_b64 exec, exec, s[16:17]
	s_waitcnt lgkmcnt(0)
	v_or_b32_e32 v116, 16, v146
	v_cmp_lt_i32_e32 vcc, s79, v116
	s_and_saveexec_b64 s[16:17], vcc
	s_xor_b64 s[16:17], exec, s[16:17]
	v_add_u32_e32 v118, 0xffff8010, v146
	v_mov_b32_e32 v119, v2
	v_lshlrev_b64 v[118:119], 12, v[118:119]
	v_lshl_add_u64 v[118:119], s[10:11], 0, v[118:119]
	v_mov_b32_e32 v117, v2
	s_andn2_saveexec_b64 s[16:17], s[16:17]
	v_ashrrev_i32_e32 v117, 31, v116
	v_lshlrev_b64 v[118:119], 12, v[116:117]
	v_lshl_add_u64 v[118:119], s[30:31], 0, v[118:119]
	s_or_b64 exec, exec, s[16:17]
	v_lshl_add_u64 v[118:119], v[118:119], 0, v[144:145]
	global_load_dwordx4 v[122:125], v[118:119], off
	global_load_dwordx4 v[126:129], v[118:119], off offset:16
	global_load_dwordx4 v[216:219], v[118:119], off offset:512
	global_load_dwordx4 v[220:223], v[118:119], off offset:528
	v_lshlrev_b64 v[130:131], 12, v[116:117]
	v_lshlrev_b64 v[136:137], 11, v[116:117]
	v_lshl_add_u64 v[130:131], s[30:31], 0, v[130:131]
	v_lshl_add_u64 v[136:137], s[18:19], 0, v[136:137]
	v_lshl_add_u64 v[130:131], v[130:131], 0, v[144:145]
	v_lshl_add_u64 v[136:137], v[142:143], 1, v[136:137]
	s_waitcnt vmcnt(3)
	v_pk_add_f32 v[114:115], v[124:125], v[114:115]
	v_pk_add_f32 v[112:113], v[122:123], v[112:113]
	s_waitcnt vmcnt(2)
	v_pk_add_f32 v[110:111], v[128:129], v[110:111]
	v_pk_add_f32 v[108:109], v[126:127], v[108:109]
	v_cvt_pk_bf16_f32 v122, v112, v113
	v_cvt_pk_bf16_f32 v123, v114, v115
	v_cvt_pk_bf16_f32 v124, v108, v109
	v_cvt_pk_bf16_f32 v125, v110, v111
	global_store_dwordx4 v[130:131], v[112:115], off
	global_store_dwordx4 v[130:131], v[108:111], off offset:16
	global_store_dwordx4 v[136:137], v[122:125], off
	s_nop 0
	s_nop 0
	s_nop 0
	v_mul_f32_e32 v113, v113, v113
	v_mul_f32_e32 v115, v115, v115
	v_mul_f32_e32 v109, v109, v109
	v_fmac_f32_e32 v113, v112, v112
	v_fmac_f32_e32 v115, v114, v114
	v_mul_f32_e32 v111, v111, v111
	v_fmac_f32_e32 v109, v108, v108
	v_add_f32_e32 v108, v113, v115
	v_fmac_f32_e32 v111, v110, v110
	v_add_f32_e32 v108, v109, v108
	v_add_f32_e32 v112, v111, v108
	s_waitcnt vmcnt(4)
; #define EPI_ROWS(...) _Pragma("unroll") for (int ai = 0; ai < 2; ++ai) _Pragma("unroll") for (int m = 0; m < 4; ++m) { const int row = row0 + ai * 128 + m * 16; __VA_ARGS__ __builtin_amdgcn_sched_barrier(0); }
; __device__ __forceinline__ u32x4 pack8(f32x4 a, f32x4 b) { u32x4 w; w.x = pk2(a[0], a[1]); w.y = pk2(a[2], a[3]); w.z = pk2(b[0], b[1]); w.w = pk2(b[2], b[3]); return w; }
; __device__ __forceinline__ float dot8(f32x4 a, f32x4 b) { return (a[0] * a[0] + a[1] * a[1]) + (a[2] * a[2] + a[3] * a[3]) + (b[0] * b[0] + b[1] * b[1]) + (b[2] * b[2] + b[3] * b[3]); }
; __device__ __forceinline__ float red_fq(float s) { s += __shfl_xor(s, 16); s += __shfl_xor(s, 32); return s; }
;     __device__ __forceinline__ void operator()(AccRef acc, const Unit& u, int wr, int wc, int fr, int fq) const {
;         const int row0 = u.pm * 256 + wr * 64 + fr, col0 = u.pn * 256 + wc * 32 + 8 * fq;
;         EPI_ROWS(
;             const float* rp = (row < MP) ? res0 + (size_t)row * DM : res1 + (size_t)(row - MP) * DM;
;             float s = 0.f;
;             _Pragma("unroll") for (int bj = 0; bj < 2; ++bj) { const int col = col0 + bj * 128;
;                 f32x4 v0 = *(const f32x4*)(rp + col) + acc[ai][bj][m][0] * scale, v1 = *(const f32x4*)(rp + col + 4) + acc[ai][bj][m][1] * scale;
;                 *(f32x4*)(out + (size_t)row * DM + col) = v0; *(f32x4*)(out + (size_t)row * DM + col + 4) = v1;
;                 if (WB) *(u32x4*)(ob + (size_t)row * DM + col) = pack8(v0, v1);
;                 s += dot8(v0, v1); }
;             s = red_fq(s); if (fq == 0) unsafeAtomicAdd(ss + row, s);
;         )
;     }
	v_pk_add_f32 v[106:107], v[218:219], v[106:107]
	v_pk_add_f32 v[104:105], v[216:217], v[104:105]
	s_waitcnt vmcnt(3)
	v_pk_add_f32 v[108:109], v[220:221], v[100:101]
	v_mul_f32_e32 v100, v105, v105
	v_mul_f32_e32 v101, v107, v107
	v_pk_add_f32 v[110:111], v[222:223], v[102:103]
	v_mul_f32_e32 v102, v109, v109
	v_fmac_f32_e32 v100, v104, v104
	v_fmac_f32_e32 v101, v106, v106
	v_mul_f32_e32 v103, v111, v111
	v_fmac_f32_e32 v102, v108, v108
	v_add_f32_e32 v100, v100, v101
	v_add_f32_e32 v100, v102, v100
	v_fmac_f32_e32 v103, v110, v110
	v_add_f32_e32 v100, v103, v100
	v_add_f32_e32 v100, v112, v100
	v_mov_b32_e32 v101, v100
	global_store_dwordx4 v[130:131], v[104:107], off offset:512
	global_store_dwordx4 v[130:131], v[108:111], off offset:528
	v_cvt_pk_bf16_f32 v102, v104, v105
	v_cvt_pk_bf16_f32 v103, v106, v107
	v_cvt_pk_bf16_f32 v104, v108, v109
	v_permlane16_swap_b32_e32 v100, v101
	v_add_f32_e32 v100, v100, v101
	v_mov_b32_e32 v101, v100
	s_nop 1
	v_permlane32_swap_b32_e32 v100, v101
	v_cvt_pk_bf16_f32 v105, v110, v111
	global_store_dwordx4 v[136:137], v[102:105], off offset:256
	s_and_saveexec_b64 s[16:17], s[6:7]
	s_cbranch_execz .LBB0_1407
	s_waitcnt lgkmcnt(0)
	v_add_f32_e32 v102, v100, v101
	v_lshl_add_u64 v[100:101], v[116:117], 2, s[12:13]
	v_mov_b32_e32 v228, v100
	v_mov_b32_e32 v229, v101
	v_mov_b32_e32 v230, v102
.LBB0_1407:
	s_or_b64 exec, exec, s[16:17]
	s_waitcnt lgkmcnt(0)
	v_or_b32_e32 v100, 32, v146
	v_cmp_lt_i32_e32 vcc, s79, v100
	s_and_saveexec_b64 s[16:17], vcc
	s_xor_b64 s[16:17], exec, s[16:17]
	v_add_u32_e32 v102, 0xffff8020, v146
	v_mov_b32_e32 v103, v2
	v_lshlrev_b64 v[102:103], 12, v[102:103]
	v_lshl_add_u64 v[102:103], s[10:11], 0, v[102:103]
	v_mov_b32_e32 v101, v2
	s_andn2_saveexec_b64 s[16:17], s[16:17]
	v_ashrrev_i32_e32 v101, 31, v100
	v_lshlrev_b64 v[102:103], 12, v[100:101]
	v_lshl_add_u64 v[102:103], s[30:31], 0, v[102:103]
	s_or_b64 exec, exec, s[16:17]
	v_lshl_add_u64 v[110:111], v[102:103], 0, v[144:145]
	global_load_dwordx4 v[102:105], v[110:111], off
	global_load_dwordx4 v[106:109], v[110:111], off offset:16
	global_load_dwordx4 v[216:219], v[110:111], off offset:512
	global_load_dwordx4 v[220:223], v[110:111], off offset:528
	v_lshlrev_b64 v[112:113], 12, v[100:101]
	v_lshlrev_b64 v[114:115], 11, v[100:101]
	v_lshl_add_u64 v[112:113], s[30:31], 0, v[112:113]
	v_lshl_add_u64 v[114:115], s[18:19], 0, v[114:115]
	v_lshl_add_u64 v[112:113], v[112:113], 0, v[144:145]
	v_lshl_add_u64 v[114:115], v[142:143], 1, v[114:115]
	s_waitcnt vmcnt(3)
	v_pk_add_f32 v[98:99], v[104:105], v[98:99]
	v_pk_add_f32 v[96:97], v[102:103], v[96:97]
	s_waitcnt vmcnt(2)
	v_pk_add_f32 v[94:95], v[108:109], v[94:95]
	v_pk_add_f32 v[92:93], v[106:107], v[92:93]
	v_cvt_pk_bf16_f32 v102, v96, v97
	v_cvt_pk_bf16_f32 v103, v98, v99
	v_cvt_pk_bf16_f32 v104, v92, v93
	v_cvt_pk_bf16_f32 v105, v94, v95
	global_store_dwordx4 v[112:113], v[96:99], off
	global_store_dwordx4 v[112:113], v[92:95], off offset:16
	global_store_dwordx4 v[114:115], v[102:105], off
	s_nop 0
	s_nop 0
	s_nop 0
	v_mul_f32_e32 v97, v97, v97
	v_mul_f32_e32 v99, v99, v99
	v_mul_f32_e32 v93, v93, v93
	v_fmac_f32_e32 v97, v96, v96
	v_fmac_f32_e32 v99, v98, v98
	v_mul_f32_e32 v95, v95, v95
	v_fmac_f32_e32 v93, v92, v92
	v_add_f32_e32 v92, v97, v99
	v_fmac_f32_e32 v95, v94, v94
	v_add_f32_e32 v92, v93, v92
	v_add_f32_e32 v96, v95, v92
	s_waitcnt vmcnt(4)
	v_pk_add_f32 v[90:91], v[218:219], v[90:91]
	v_pk_add_f32 v[88:89], v[216:217], v[88:89]
	s_waitcnt vmcnt(3)
	v_pk_add_f32 v[92:93], v[220:221], v[84:85]
	v_mul_f32_e32 v84, v89, v89
	v_mul_f32_e32 v85, v91, v91
	v_pk_add_f32 v[94:95], v[222:223], v[86:87]
	v_mul_f32_e32 v86, v93, v93
	v_fmac_f32_e32 v84, v88, v88
	v_fmac_f32_e32 v85, v90, v90
	v_mul_f32_e32 v87, v95, v95
	v_fmac_f32_e32 v86, v92, v92
	v_add_f32_e32 v84, v84, v85
	v_add_f32_e32 v84, v86, v84
	v_fmac_f32_e32 v87, v94, v94
	v_add_f32_e32 v84, v87, v84
	v_add_f32_e32 v84, v96, v84
	v_mov_b32_e32 v85, v84
	global_store_dwordx4 v[112:113], v[88:91], off offset:512
	global_store_dwordx4 v[112:113], v[92:95], off offset:528
	v_cvt_pk_bf16_f32 v86, v88, v89
	v_cvt_pk_bf16_f32 v87, v90, v91
	v_cvt_pk_bf16_f32 v88, v92, v93
	v_permlane16_swap_b32_e32 v84, v85
	v_add_f32_e32 v84, v84, v85
	v_mov_b32_e32 v85, v84
	s_nop 1
	v_permlane32_swap_b32_e32 v84, v85
	v_cvt_pk_bf16_f32 v89, v94, v95
	global_store_dwordx4 v[114:115], v[86:89], off offset:256
	s_and_saveexec_b64 s[16:17], s[6:7]
	s_cbranch_execz .LBB0_1413
	s_waitcnt lgkmcnt(0)
	v_add_f32_e32 v86, v84, v85
	v_lshl_add_u64 v[84:85], v[100:101], 2, s[12:13]
	v_mov_b32_e32 v232, v84
	v_mov_b32_e32 v233, v85
	v_mov_b32_e32 v234, v86
; #define EPI_ROWS(...) _Pragma("unroll") for (int ai = 0; ai < 2; ++ai) _Pragma("unroll") for (int m = 0; m < 4; ++m) { const int row = row0 + ai * 128 + m * 16; __VA_ARGS__ __builtin_amdgcn_sched_barrier(0); }
; __device__ __forceinline__ u32x4 pack8(f32x4 a, f32x4 b) { u32x4 w; w.x = pk2(a[0], a[1]); w.y = pk2(a[2], a[3]); w.z = pk2(b[0], b[1]); w.w = pk2(b[2], b[3]); return w; }
; __device__ __forceinline__ float dot8(f32x4 a, f32x4 b) { return (a[0] * a[0] + a[1] * a[1]) + (a[2] * a[2] + a[3] * a[3]) + (b[0] * b[0] + b[1] * b[1]) + (b[2] * b[2] + b[3] * b[3]); }
; __device__ __forceinline__ float red_fq(float s) { s += __shfl_xor(s, 16); s += __shfl_xor(s, 32); return s; }
;     __device__ __forceinline__ void operator()(AccRef acc, const Unit& u, int wr, int wc, int fr, int fq) const {
;         const int row0 = u.pm * 256 + wr * 64 + fr, col0 = u.pn * 256 + wc * 32 + 8 * fq;
;         EPI_ROWS(
;             const float* rp = (row < MP) ? res0 + (size_t)row * DM : res1 + (size_t)(row - MP) * DM;
;             float s = 0.f;
;             _Pragma("unroll") for (int bj = 0; bj < 2; ++bj) { const int col = col0 + bj * 128;
;                 f32x4 v0 = *(const f32x4*)(rp + col) + acc[ai][bj][m][0] * scale, v1 = *(const f32x4*)(rp + col + 4) + acc[ai][bj][m][1] * scale;
;                 *(f32x4*)(out + (size_t)row * DM + col) = v0; *(f32x4*)(out + (size_t)row * DM + col + 4) = v1;
;                 if (WB) *(u32x4*)(ob + (size_t)row * DM + col) = pack8(v0, v1);
;                 s += dot8(v0, v1); }
;             s = red_fq(s); if (fq == 0) unsafeAtomicAdd(ss + row, s);
;         )
;     }
.LBB0_1413:
	s_or_b64 exec, exec, s[16:17]
	s_waitcnt lgkmcnt(0)
	v_or_b32_e32 v84, 48, v146
	v_cmp_lt_i32_e32 vcc, s79, v84
	s_and_saveexec_b64 s[16:17], vcc
	s_xor_b64 s[16:17], exec, s[16:17]
	v_add_u32_e32 v86, 0xffff8030, v146
	v_mov_b32_e32 v87, v2
	v_lshlrev_b64 v[86:87], 12, v[86:87]
	v_lshl_add_u64 v[86:87], s[10:11], 0, v[86:87]
	v_mov_b32_e32 v85, v2
	s_andn2_saveexec_b64 s[16:17], s[16:17]
	v_ashrrev_i32_e32 v85, 31, v84
	v_lshlrev_b64 v[86:87], 12, v[84:85]
	v_lshl_add_u64 v[86:87], s[30:31], 0, v[86:87]
	s_or_b64 exec, exec, s[16:17]
	v_lshl_add_u64 v[94:95], v[86:87], 0, v[144:145]
	global_load_dwordx4 v[86:89], v[94:95], off
	global_load_dwordx4 v[90:93], v[94:95], off offset:16
	global_load_dwordx4 v[216:219], v[94:95], off offset:512
	global_load_dwordx4 v[220:223], v[94:95], off offset:528
	v_lshlrev_b64 v[96:97], 12, v[84:85]
	v_lshlrev_b64 v[98:99], 11, v[84:85]
	v_lshl_add_u64 v[96:97], s[30:31], 0, v[96:97]
	v_lshl_add_u64 v[98:99], s[18:19], 0, v[98:99]
	v_lshl_add_u64 v[96:97], v[96:97], 0, v[144:145]
	v_lshl_add_u64 v[98:99], v[142:143], 1, v[98:99]
	s_waitcnt vmcnt(3)
	v_pk_add_f32 v[82:83], v[88:89], v[82:83]
	v_pk_add_f32 v[80:81], v[86:87], v[80:81]
	s_waitcnt vmcnt(2)
	v_pk_add_f32 v[78:79], v[92:93], v[78:79]
	v_pk_add_f32 v[76:77], v[90:91], v[76:77]
	v_cvt_pk_bf16_f32 v86, v80, v81
	v_cvt_pk_bf16_f32 v87, v82, v83
	v_cvt_pk_bf16_f32 v88, v76, v77
	v_cvt_pk_bf16_f32 v89, v78, v79
	global_store_dwordx4 v[96:97], v[80:83], off
	global_store_dwordx4 v[96:97], v[76:79], off offset:16
	global_store_dwordx4 v[98:99], v[86:89], off
	s_nop 0
	s_nop 0
	s_nop 0
	v_mul_f32_e32 v81, v81, v81
	v_mul_f32_e32 v83, v83, v83
	v_mul_f32_e32 v77, v77, v77
	v_fmac_f32_e32 v81, v80, v80
	v_fmac_f32_e32 v83, v82, v82
	v_mul_f32_e32 v79, v79, v79
	v_fmac_f32_e32 v77, v76, v76
	v_add_f32_e32 v76, v81, v83
	v_fmac_f32_e32 v79, v78, v78
	v_add_f32_e32 v76, v77, v76
	v_add_f32_e32 v80, v79, v76
	s_waitcnt vmcnt(4)
	v_pk_add_f32 v[74:75], v[218:219], v[74:75]
	v_pk_add_f32 v[72:73], v[216:217], v[72:73]
	s_waitcnt vmcnt(3)
	v_pk_add_f32 v[76:77], v[220:221], v[68:69]
	v_mul_f32_e32 v68, v73, v73
	v_mul_f32_e32 v69, v75, v75
	v_pk_add_f32 v[78:79], v[222:223], v[70:71]
	v_mul_f32_e32 v70, v77, v77
	v_fmac_f32_e32 v68, v72, v72
	v_fmac_f32_e32 v69, v74, v74
	v_mul_f32_e32 v71, v79, v79
	v_fmac_f32_e32 v70, v76, v76
	v_add_f32_e32 v68, v68, v69
	v_add_f32_e32 v68, v70, v68
	v_fmac_f32_e32 v71, v78, v78
	v_add_f32_e32 v68, v71, v68
	v_add_f32_e32 v68, v80, v68
	v_mov_b32_e32 v69, v68
	global_store_dwordx4 v[96:97], v[72:75], off offset:512
	global_store_dwordx4 v[96:97], v[76:79], off offset:528
	v_cvt_pk_bf16_f32 v70, v72, v73
	v_cvt_pk_bf16_f32 v71, v74, v75
	v_cvt_pk_bf16_f32 v72, v76, v77
	v_permlane16_swap_b32_e32 v68, v69
	v_add_f32_e32 v68, v68, v69
	v_mov_b32_e32 v69, v68
	s_nop 1
	v_permlane32_swap_b32_e32 v68, v69
	v_cvt_pk_bf16_f32 v73, v78, v79
	global_store_dwordx4 v[98:99], v[70:73], off offset:256
	s_and_saveexec_b64 s[16:17], s[6:7]
	s_cbranch_execz .LBB0_1419
	s_waitcnt lgkmcnt(0)
	v_add_f32_e32 v70, v68, v69
	v_lshl_add_u64 v[68:69], v[84:85], 2, s[12:13]
	v_mov_b32_e32 v236, v68
	v_mov_b32_e32 v237, v69
	v_mov_b32_e32 v238, v70
.LBB0_1419:
	s_or_b64 exec, exec, s[16:17]
	s_movk_i32 s16, 0x7f7f
	s_waitcnt lgkmcnt(0)
	v_add_u32_e32 v68, 0x80, v146
	v_cmp_lt_i32_e32 vcc, s16, v146
	s_and_saveexec_b64 s[16:17], vcc
	s_xor_b64 s[16:17], exec, s[16:17]
	v_add_u32_e32 v70, 0xffff8080, v146
	v_mov_b32_e32 v71, v2
	v_lshlrev_b64 v[70:71], 12, v[70:71]
	v_lshl_add_u64 v[70:71], s[10:11], 0, v[70:71]
	v_mov_b32_e32 v69, v2
	s_andn2_saveexec_b64 s[16:17], s[16:17]
	v_ashrrev_i32_e32 v69, 31, v68
	v_lshlrev_b64 v[70:71], 12, v[68:69]
	v_lshl_add_u64 v[70:71], s[30:31], 0, v[70:71]
	s_or_b64 exec, exec, s[16:17]
	v_lshl_add_u64 v[78:79], v[70:71], 0, v[144:145]
	global_load_dwordx4 v[70:73], v[78:79], off
	global_load_dwordx4 v[74:77], v[78:79], off offset:16
	global_load_dwordx4 v[216:219], v[78:79], off offset:512
	global_load_dwordx4 v[220:223], v[78:79], off offset:528
	v_lshlrev_b64 v[80:81], 12, v[68:69]
	v_lshlrev_b64 v[82:83], 11, v[68:69]
	v_lshl_add_u64 v[80:81], s[30:31], 0, v[80:81]
	v_lshl_add_u64 v[82:83], s[18:19], 0, v[82:83]
	v_lshl_add_u64 v[80:81], v[80:81], 0, v[144:145]
	v_lshl_add_u64 v[82:83], v[142:143], 1, v[82:83]
	s_waitcnt vmcnt(3)
	v_pk_add_f32 v[66:67], v[72:73], v[66:67]
	v_pk_add_f32 v[64:65], v[70:71], v[64:65]
	s_waitcnt vmcnt(2)
	v_pk_add_f32 v[62:63], v[76:77], v[62:63]
	v_pk_add_f32 v[60:61], v[74:75], v[60:61]
	v_cvt_pk_bf16_f32 v70, v64, v65
	v_cvt_pk_bf16_f32 v71, v66, v67
	v_cvt_pk_bf16_f32 v72, v60, v61
	v_cvt_pk_bf16_f32 v73, v62, v63
	global_store_dwordx4 v[80:81], v[64:67], off
	global_store_dwordx4 v[80:81], v[60:63], off offset:16
	global_store_dwordx4 v[82:83], v[70:73], off
	s_nop 0
	s_nop 0
	s_nop 0
	v_mul_f32_e32 v65, v65, v65
	v_mul_f32_e32 v67, v67, v67
	v_mul_f32_e32 v61, v61, v61
	v_fmac_f32_e32 v65, v64, v64
	v_fmac_f32_e32 v67, v66, v66
	v_mul_f32_e32 v63, v63, v63
	v_fmac_f32_e32 v61, v60, v60
	v_add_f32_e32 v60, v65, v67
	v_fmac_f32_e32 v63, v62, v62
	v_add_f32_e32 v60, v61, v60
	v_add_f32_e32 v64, v63, v60
	s_waitcnt vmcnt(4)
	v_pk_add_f32 v[58:59], v[218:219], v[58:59]
	v_pk_add_f32 v[56:57], v[216:217], v[56:57]
	s_waitcnt vmcnt(3)
	v_pk_add_f32 v[60:61], v[220:221], v[52:53]
	v_mul_f32_e32 v52, v57, v57
	v_mul_f32_e32 v53, v59, v59
	v_pk_add_f32 v[62:63], v[222:223], v[54:55]
	v_mul_f32_e32 v54, v61, v61
	v_fmac_f32_e32 v52, v56, v56
	v_fmac_f32_e32 v53, v58, v58
	v_mul_f32_e32 v55, v63, v63
	v_fmac_f32_e32 v54, v60, v60
	v_add_f32_e32 v52, v52, v53
	v_add_f32_e32 v52, v54, v52
	v_fmac_f32_e32 v55, v62, v62
	v_add_f32_e32 v52, v55, v52
	v_add_f32_e32 v52, v64, v52
	v_mov_b32_e32 v53, v52
	global_store_dwordx4 v[80:81], v[56:59], off offset:512
	global_store_dwordx4 v[80:81], v[60:63], off offset:528
	v_cvt_pk_bf16_f32 v54, v56, v57
	v_cvt_pk_bf16_f32 v55, v58, v59
	v_cvt_pk_bf16_f32 v56, v60, v61
	v_permlane16_swap_b32_e32 v52, v53
	v_add_f32_e32 v52, v52, v53
	v_mov_b32_e32 v53, v52
	s_nop 1
	v_permlane32_swap_b32_e32 v52, v53
	v_cvt_pk_bf16_f32 v57, v62, v63
	global_store_dwordx4 v[82:83], v[54:57], off offset:256
	s_and_saveexec_b64 s[16:17], s[6:7]
	s_cbranch_execz .LBB0_1425
	s_waitcnt lgkmcnt(0)
	v_add_f32_e32 v54, v52, v53
	v_lshl_add_u64 v[52:53], v[68:69], 2, s[12:13]
	v_mov_b32_e32 v240, v52
	v_mov_b32_e32 v241, v53
	v_mov_b32_e32 v242, v54
; #define EPI_ROWS(...) _Pragma("unroll") for (int ai = 0; ai < 2; ++ai) _Pragma("unroll") for (int m = 0; m < 4; ++m) { const int row = row0 + ai * 128 + m * 16; __VA_ARGS__ __builtin_amdgcn_sched_barrier(0); }
; __device__ __forceinline__ u32x4 pack8(f32x4 a, f32x4 b) { u32x4 w; w.x = pk2(a[0], a[1]); w.y = pk2(a[2], a[3]); w.z = pk2(b[0], b[1]); w.w = pk2(b[2], b[3]); return w; }
; __device__ __forceinline__ float dot8(f32x4 a, f32x4 b) { return (a[0] * a[0] + a[1] * a[1]) + (a[2] * a[2] + a[3] * a[3]) + (b[0] * b[0] + b[1] * b[1]) + (b[2] * b[2] + b[3] * b[3]); }
; __device__ __forceinline__ float red_fq(float s) { s += __shfl_xor(s, 16); s += __shfl_xor(s, 32); return s; }
;     __device__ __forceinline__ void operator()(AccRef acc, const Unit& u, int wr, int wc, int fr, int fq) const {
;         const int row0 = u.pm * 256 + wr * 64 + fr, col0 = u.pn * 256 + wc * 32 + 8 * fq;
;         EPI_ROWS(
;             const float* rp = (row < MP) ? res0 + (size_t)row * DM : res1 + (size_t)(row - MP) * DM;
;             float s = 0.f;
;             _Pragma("unroll") for (int bj = 0; bj < 2; ++bj) { const int col = col0 + bj * 128;
;                 f32x4 v0 = *(const f32x4*)(rp + col) + acc[ai][bj][m][0] * scale, v1 = *(const f32x4*)(rp + col + 4) + acc[ai][bj][m][1] * scale;
;                 *(f32x4*)(out + (size_t)row * DM + col) = v0; *(f32x4*)(out + (size_t)row * DM + col + 4) = v1;
;                 if (WB) *(u32x4*)(ob + (size_t)row * DM + col) = pack8(v0, v1);
;                 s += dot8(v0, v1); }
;             s = red_fq(s); if (fq == 0) unsafeAtomicAdd(ss + row, s);
;         )
;     }
.LBB0_1425:
	s_or_b64 exec, exec, s[16:17]
	s_movk_i32 s16, 0x7f6f
	s_waitcnt lgkmcnt(0)
	v_add_u32_e32 v52, 0x90, v146
	v_cmp_lt_i32_e32 vcc, s16, v146
	s_and_saveexec_b64 s[16:17], vcc
	s_xor_b64 s[16:17], exec, s[16:17]
	v_add_u32_e32 v54, 0xffff8090, v146
	v_mov_b32_e32 v55, v2
	v_lshlrev_b64 v[54:55], 12, v[54:55]
	v_lshl_add_u64 v[54:55], s[10:11], 0, v[54:55]
	v_mov_b32_e32 v53, v2
	s_andn2_saveexec_b64 s[16:17], s[16:17]
	v_ashrrev_i32_e32 v53, 31, v52
	v_lshlrev_b64 v[54:55], 12, v[52:53]
	v_lshl_add_u64 v[54:55], s[30:31], 0, v[54:55]
	s_or_b64 exec, exec, s[16:17]
	v_lshl_add_u64 v[62:63], v[54:55], 0, v[144:145]
	global_load_dwordx4 v[54:57], v[62:63], off
	global_load_dwordx4 v[58:61], v[62:63], off offset:16
	global_load_dwordx4 v[216:219], v[62:63], off offset:512
	global_load_dwordx4 v[220:223], v[62:63], off offset:528
	v_lshlrev_b64 v[64:65], 12, v[52:53]
	v_lshlrev_b64 v[66:67], 11, v[52:53]
	v_lshl_add_u64 v[64:65], s[30:31], 0, v[64:65]
	v_lshl_add_u64 v[66:67], s[18:19], 0, v[66:67]
	v_lshl_add_u64 v[64:65], v[64:65], 0, v[144:145]
	v_lshl_add_u64 v[66:67], v[142:143], 1, v[66:67]
	s_waitcnt vmcnt(3)
	v_pk_add_f32 v[50:51], v[56:57], v[50:51]
	v_pk_add_f32 v[48:49], v[54:55], v[48:49]
	s_waitcnt vmcnt(2)
	v_pk_add_f32 v[46:47], v[60:61], v[46:47]
	v_pk_add_f32 v[44:45], v[58:59], v[44:45]
	v_cvt_pk_bf16_f32 v54, v48, v49
	v_cvt_pk_bf16_f32 v55, v50, v51
	v_cvt_pk_bf16_f32 v56, v44, v45
	v_cvt_pk_bf16_f32 v57, v46, v47
	global_store_dwordx4 v[64:65], v[48:51], off
	global_store_dwordx4 v[64:65], v[44:47], off offset:16
	global_store_dwordx4 v[66:67], v[54:57], off
	s_nop 0
	s_nop 0
	s_nop 0
	v_mul_f32_e32 v49, v49, v49
	v_mul_f32_e32 v51, v51, v51
	v_mul_f32_e32 v45, v45, v45
	v_fmac_f32_e32 v49, v48, v48
	v_fmac_f32_e32 v51, v50, v50
	v_mul_f32_e32 v47, v47, v47
	v_fmac_f32_e32 v45, v44, v44
	v_add_f32_e32 v44, v49, v51
	v_fmac_f32_e32 v47, v46, v46
	v_add_f32_e32 v44, v45, v44
	v_add_f32_e32 v48, v47, v44
	s_waitcnt vmcnt(4)
	v_pk_add_f32 v[42:43], v[218:219], v[42:43]
	v_pk_add_f32 v[40:41], v[216:217], v[40:41]
	s_waitcnt vmcnt(3)
	v_pk_add_f32 v[44:45], v[220:221], v[36:37]
	v_mul_f32_e32 v36, v41, v41
	v_mul_f32_e32 v37, v43, v43
	v_pk_add_f32 v[46:47], v[222:223], v[38:39]
	v_mul_f32_e32 v38, v45, v45
	v_fmac_f32_e32 v36, v40, v40
	v_fmac_f32_e32 v37, v42, v42
	v_mul_f32_e32 v39, v47, v47
	v_fmac_f32_e32 v38, v44, v44
	v_add_f32_e32 v36, v36, v37
	v_add_f32_e32 v36, v38, v36
	v_fmac_f32_e32 v39, v46, v46
	v_add_f32_e32 v36, v39, v36
	v_add_f32_e32 v36, v48, v36
	v_mov_b32_e32 v37, v36
	global_store_dwordx4 v[64:65], v[40:43], off offset:512
	global_store_dwordx4 v[64:65], v[44:47], off offset:528
	v_cvt_pk_bf16_f32 v38, v40, v41
	v_cvt_pk_bf16_f32 v39, v42, v43
	v_cvt_pk_bf16_f32 v40, v44, v45
	v_permlane16_swap_b32_e32 v36, v37
	v_add_f32_e32 v36, v36, v37
	v_mov_b32_e32 v37, v36
	s_nop 1
	v_permlane32_swap_b32_e32 v36, v37
	v_cvt_pk_bf16_f32 v41, v46, v47
	global_store_dwordx4 v[66:67], v[38:41], off offset:256
	s_and_saveexec_b64 s[16:17], s[6:7]
	s_cbranch_execz .LBB0_1431
	s_waitcnt lgkmcnt(0)
	v_add_f32_e32 v38, v36, v37
	v_lshl_add_u64 v[36:37], v[52:53], 2, s[12:13]
	v_mov_b32_e32 v244, v36
	v_mov_b32_e32 v245, v37
	v_mov_b32_e32 v246, v38
.LBB0_1431:
	s_or_b64 exec, exec, s[16:17]
	s_movk_i32 s16, 0x7f5f
	s_waitcnt lgkmcnt(0)
	v_add_u32_e32 v36, 0xa0, v146
	v_cmp_lt_i32_e32 vcc, s16, v146
	s_and_saveexec_b64 s[16:17], vcc
	s_xor_b64 s[16:17], exec, s[16:17]
	v_add_u32_e32 v38, 0xffff80a0, v146
	v_mov_b32_e32 v39, v2
	v_lshlrev_b64 v[38:39], 12, v[38:39]
	v_lshl_add_u64 v[38:39], s[10:11], 0, v[38:39]
	v_mov_b32_e32 v37, v2
	s_andn2_saveexec_b64 s[16:17], s[16:17]
	v_ashrrev_i32_e32 v37, 31, v36
	v_lshlrev_b64 v[38:39], 12, v[36:37]
	v_lshl_add_u64 v[38:39], s[30:31], 0, v[38:39]
	s_or_b64 exec, exec, s[16:17]
	v_lshl_add_u64 v[46:47], v[38:39], 0, v[144:145]
	global_load_dwordx4 v[38:41], v[46:47], off
	global_load_dwordx4 v[42:45], v[46:47], off offset:16
	global_load_dwordx4 v[216:219], v[46:47], off offset:512
	global_load_dwordx4 v[220:223], v[46:47], off offset:528
	v_lshlrev_b64 v[48:49], 12, v[36:37]
	v_lshlrev_b64 v[50:51], 11, v[36:37]
	v_lshl_add_u64 v[48:49], s[30:31], 0, v[48:49]
	v_lshl_add_u64 v[50:51], s[18:19], 0, v[50:51]
	v_lshl_add_u64 v[48:49], v[48:49], 0, v[144:145]
	v_lshl_add_u64 v[50:51], v[142:143], 1, v[50:51]
	s_waitcnt vmcnt(3)
	v_pk_add_f32 v[34:35], v[40:41], v[34:35]
	v_pk_add_f32 v[32:33], v[38:39], v[32:33]
	s_waitcnt vmcnt(2)
	v_pk_add_f32 v[30:31], v[44:45], v[30:31]
	v_pk_add_f32 v[28:29], v[42:43], v[28:29]
	v_cvt_pk_bf16_f32 v38, v32, v33
	v_cvt_pk_bf16_f32 v39, v34, v35
	v_cvt_pk_bf16_f32 v40, v28, v29
	v_cvt_pk_bf16_f32 v41, v30, v31
	global_store_dwordx4 v[48:49], v[32:35], off
	global_store_dwordx4 v[48:49], v[28:31], off offset:16
	global_store_dwordx4 v[50:51], v[38:41], off
	s_nop 0
	s_nop 0
	s_nop 0
	v_mul_f32_e32 v33, v33, v33
	v_mul_f32_e32 v35, v35, v35
	v_mul_f32_e32 v29, v29, v29
	v_fmac_f32_e32 v33, v32, v32
	v_fmac_f32_e32 v35, v34, v34
	v_mul_f32_e32 v31, v31, v31
	v_fmac_f32_e32 v29, v28, v28
	v_add_f32_e32 v28, v33, v35
	v_fmac_f32_e32 v31, v30, v30
	v_add_f32_e32 v28, v29, v28
	v_add_f32_e32 v32, v31, v28
	s_waitcnt vmcnt(4)
	v_pk_add_f32 v[26:27], v[218:219], v[26:27]
	v_pk_add_f32 v[24:25], v[216:217], v[24:25]
	s_waitcnt vmcnt(3)
	v_pk_add_f32 v[28:29], v[220:221], v[20:21]
	v_mul_f32_e32 v20, v25, v25
	v_mul_f32_e32 v21, v27, v27
	v_pk_add_f32 v[30:31], v[222:223], v[22:23]
	v_mul_f32_e32 v22, v29, v29
	v_fmac_f32_e32 v20, v24, v24
	v_fmac_f32_e32 v21, v26, v26
	v_mul_f32_e32 v23, v31, v31
	v_fmac_f32_e32 v22, v28, v28
	v_add_f32_e32 v20, v20, v21
	v_add_f32_e32 v20, v22, v20
	v_fmac_f32_e32 v23, v30, v30
	v_add_f32_e32 v20, v23, v20
	v_add_f32_e32 v20, v32, v20
	v_mov_b32_e32 v21, v20
	global_store_dwordx4 v[48:49], v[24:27], off offset:512
	global_store_dwordx4 v[48:49], v[28:31], off offset:528
	v_cvt_pk_bf16_f32 v22, v24, v25
	v_cvt_pk_bf16_f32 v23, v26, v27
	v_cvt_pk_bf16_f32 v24, v28, v29
	v_permlane16_swap_b32_e32 v20, v21
	v_add_f32_e32 v20, v20, v21
	v_mov_b32_e32 v21, v20
	s_nop 1
	v_permlane32_swap_b32_e32 v20, v21
	v_cvt_pk_bf16_f32 v25, v30, v31
	global_store_dwordx4 v[50:51], v[22:25], off offset:256
	s_and_saveexec_b64 s[16:17], s[6:7]
	s_cbranch_execz .LBB0_1437
	s_waitcnt lgkmcnt(0)
	v_add_f32_e32 v22, v20, v21
	v_lshl_add_u64 v[20:21], v[36:37], 2, s[12:13]
	v_mov_b32_e32 v248, v20
	v_mov_b32_e32 v249, v21
	v_mov_b32_e32 v250, v22
; #define EPI_ROWS(...) _Pragma("unroll") for (int ai = 0; ai < 2; ++ai) _Pragma("unroll") for (int m = 0; m < 4; ++m) { const int row = row0 + ai * 128 + m * 16; __VA_ARGS__ __builtin_amdgcn_sched_barrier(0); }
; __device__ __forceinline__ u32x4 pack8(f32x4 a, f32x4 b) { u32x4 w; w.x = pk2(a[0], a[1]); w.y = pk2(a[2], a[3]); w.z = pk2(b[0], b[1]); w.w = pk2(b[2], b[3]); return w; }
; __device__ __forceinline__ float dot8(f32x4 a, f32x4 b) { return (a[0] * a[0] + a[1] * a[1]) + (a[2] * a[2] + a[3] * a[3]) + (b[0] * b[0] + b[1] * b[1]) + (b[2] * b[2] + b[3] * b[3]); }
; __device__ __forceinline__ float red_fq(float s) { s += __shfl_xor(s, 16); s += __shfl_xor(s, 32); return s; }
;     __device__ __forceinline__ void operator()(AccRef acc, const Unit& u, int wr, int wc, int fr, int fq) const {
;         const int row0 = u.pm * 256 + wr * 64 + fr, col0 = u.pn * 256 + wc * 32 + 8 * fq;
;         EPI_ROWS(
;             const float* rp = (row < MP) ? res0 + (size_t)row * DM : res1 + (size_t)(row - MP) * DM;
;             float s = 0.f;
;             _Pragma("unroll") for (int bj = 0; bj < 2; ++bj) { const int col = col0 + bj * 128;
;                 f32x4 v0 = *(const f32x4*)(rp + col) + acc[ai][bj][m][0] * scale, v1 = *(const f32x4*)(rp + col + 4) + acc[ai][bj][m][1] * scale;
;                 *(f32x4*)(out + (size_t)row * DM + col) = v0; *(f32x4*)(out + (size_t)row * DM + col + 4) = v1;
;                 if (WB) *(u32x4*)(ob + (size_t)row * DM + col) = pack8(v0, v1);
;                 s += dot8(v0, v1); }
;             s = red_fq(s); if (fq == 0) unsafeAtomicAdd(ss + row, s);
;         )
;     }
.LBB0_1437:
	s_or_b64 exec, exec, s[16:17]
	s_movk_i32 s16, 0x7f4f
	s_waitcnt lgkmcnt(0)
	v_add_u32_e32 v20, 0xb0, v146
	v_cmp_lt_i32_e32 vcc, s16, v146
	s_and_saveexec_b64 s[16:17], vcc
	s_xor_b64 s[16:17], exec, s[16:17]
	v_add_u32_e32 v22, 0xffff80b0, v146
	v_mov_b32_e32 v23, v2
	v_lshlrev_b64 v[22:23], 12, v[22:23]
	v_lshl_add_u64 v[22:23], s[10:11], 0, v[22:23]
	v_mov_b32_e32 v21, v2
	s_andn2_saveexec_b64 s[16:17], s[16:17]
	v_ashrrev_i32_e32 v21, 31, v20
	v_lshlrev_b64 v[22:23], 12, v[20:21]
	v_lshl_add_u64 v[22:23], s[30:31], 0, v[22:23]
	s_or_b64 exec, exec, s[16:17]
	v_lshl_add_u64 v[30:31], v[22:23], 0, v[144:145]
	global_load_dwordx4 v[22:25], v[30:31], off
	global_load_dwordx4 v[26:29], v[30:31], off offset:16
	global_load_dwordx4 v[216:219], v[30:31], off offset:512
	global_load_dwordx4 v[220:223], v[30:31], off offset:528
	v_lshlrev_b64 v[32:33], 12, v[20:21]
	v_lshlrev_b64 v[34:35], 11, v[20:21]
	v_lshl_add_u64 v[32:33], s[30:31], 0, v[32:33]
	v_lshl_add_u64 v[34:35], s[18:19], 0, v[34:35]
	v_lshl_add_u64 v[32:33], v[32:33], 0, v[144:145]
	v_lshl_add_u64 v[34:35], v[142:143], 1, v[34:35]
	s_waitcnt vmcnt(3)
	v_pk_add_f32 v[18:19], v[24:25], v[18:19]
	v_pk_add_f32 v[16:17], v[22:23], v[16:17]
	s_waitcnt vmcnt(2)
	v_pk_add_f32 v[14:15], v[28:29], v[14:15]
	v_pk_add_f32 v[12:13], v[26:27], v[12:13]
	v_cvt_pk_bf16_f32 v22, v16, v17
	v_cvt_pk_bf16_f32 v23, v18, v19
	v_cvt_pk_bf16_f32 v24, v12, v13
	v_cvt_pk_bf16_f32 v25, v14, v15
	global_store_dwordx4 v[32:33], v[16:19], off
	global_store_dwordx4 v[32:33], v[12:15], off offset:16
	global_store_dwordx4 v[34:35], v[22:25], off
	s_nop 0
	s_nop 0
	s_nop 0
	v_mul_f32_e32 v17, v17, v17
	v_mul_f32_e32 v19, v19, v19
	v_mul_f32_e32 v13, v13, v13
	v_fmac_f32_e32 v17, v16, v16
	v_fmac_f32_e32 v19, v18, v18
	v_mul_f32_e32 v15, v15, v15
	v_fmac_f32_e32 v13, v12, v12
	v_add_f32_e32 v12, v17, v19
	v_fmac_f32_e32 v15, v14, v14
	v_add_f32_e32 v12, v13, v12
	v_add_f32_e32 v16, v15, v12
	s_waitcnt vmcnt(4)
	v_pk_add_f32 v[10:11], v[218:219], v[10:11]
	v_pk_add_f32 v[8:9], v[216:217], v[8:9]
	s_waitcnt vmcnt(3)
	v_pk_add_f32 v[12:13], v[220:221], v[4:5]
	v_mul_f32_e32 v4, v9, v9
	v_mul_f32_e32 v5, v11, v11
	v_pk_add_f32 v[14:15], v[222:223], v[6:7]
	v_mul_f32_e32 v6, v13, v13
	v_fmac_f32_e32 v4, v8, v8
	v_fmac_f32_e32 v5, v10, v10
	v_mul_f32_e32 v7, v15, v15
	v_fmac_f32_e32 v6, v12, v12
	v_add_f32_e32 v4, v4, v5
	v_add_f32_e32 v4, v6, v4
	v_fmac_f32_e32 v7, v14, v14
	v_add_f32_e32 v4, v7, v4
	v_add_f32_e32 v4, v16, v4
	v_mov_b32_e32 v3, v4
	global_store_dwordx4 v[32:33], v[8:11], off offset:512
	global_store_dwordx4 v[32:33], v[12:15], off offset:528
	v_cvt_pk_bf16_f32 v6, v8, v9
	v_cvt_pk_bf16_f32 v7, v10, v11
	v_cvt_pk_bf16_f32 v8, v12, v13
	v_permlane16_swap_b32_e32 v4, v3
	v_add_f32_e32 v3, v4, v3
	v_mov_b32_e32 v4, v3
	s_nop 1
	v_permlane32_swap_b32_e32 v3, v4
	v_cvt_pk_bf16_f32 v9, v14, v15
	global_store_dwordx4 v[34:35], v[6:9], off offset:256
	s_and_saveexec_b64 s[16:17], s[6:7]
	s_cbranch_execz .LBB0_1443
	s_waitcnt lgkmcnt(0)
	v_add_f32_e32 v3, v3, v4
	v_lshl_add_u64 v[4:5], v[20:21], 2, s[12:13]
	global_atomic_add_f32 v[4:5], v3, off
	global_atomic_add_f32 v[224:225], v226, off
	global_atomic_add_f32 v[228:229], v230, off
	global_atomic_add_f32 v[232:233], v234, off
	global_atomic_add_f32 v[236:237], v238, off
	global_atomic_add_f32 v[240:241], v242, off
	global_atomic_add_f32 v[244:245], v246, off
	global_atomic_add_f32 v[248:249], v250, off

; #define PG8_STAGE(bufoff, gbase, voff) do { _Pragma("unroll") for (int _i = 0; _i < 2; ++_i) { unsigned _keep; \
;         asm volatile("s_mov_b32 %0, m0\n\ts_mov_b32 m0, %1\n\ts_nop 0\n\tglobal_load_lds_dwordx4 %2, %3\n\ts_mov_b32 m0, %0" : "=&s"(_keep) : "s"(ldsb + (unsigned)((bufoff) + _i * 8192)), "v"((voff)[_i]), "s"((const char*)(gbase)) : "memory"); } } while (0)
; #define PG8_LDA(dst, b, h) do { _Pragma("unroll") for (int m = 0; m < 4; ++m) _Pragma("unroll") for (int k = 0; k < 2; ++k) dst[m][k] = *(const LAS bf16x8*)(lds + PG8_SA(b, h) + aoff + m * 2048 + k * 1024); } while (0)
; #define PG8_LDB(dst, b, h) do { _Pragma("unroll") for (int n = 0; n < 2; ++n) _Pragma("unroll") for (int k = 0; k < 2; ++k) dst[n][k] = *(const LAS bf16x8*)(lds + PG8_SB(b, h) + boff + n * 2048 + k * 1024); } while (0)
; #define PG8_MMA(ai, bj, At, Bt) do { __builtin_amdgcn_s_setprio(1); _Pragma("unroll") for (int m = 0; m < 4; ++m) _Pragma("unroll") for (int n = 0; n < 2; ++n) _Pragma("unroll") for (int k = 0; k < 2; ++k) \
;         acc[ai][bj][m][n] = __builtin_amdgcn_mfma_f32_16x16x32_bf16(Bt[n][k], At[m][k], acc[ai][bj][m][n], 0, 0, 0); __builtin_amdgcn_s_setprio(0); } while (0)
; #define PG8_WAIT_V(n) asm volatile("s_waitcnt vmcnt(" #n ")" ::: "memory")
; #define PG8_WAIT_L(n) asm volatile("s_waitcnt lgkmcnt(" #n ")" ::: "memory")
; template <class Epi>
; __device__ __forceinline__ void gemm_phase(LAS unsigned char* lds, const Gemm g, const StaticOrder& S, const Epi& E) {
;     ...
;         for (int t = 0; t < nt; t += 2) {
;             const bool last = (t == nt - 2);
;             const char* a1 = cA + (size_t)(t + 1) * kstep;
;             const char* a2 = last ? nA : cA + (size_t)(t + 2) * kstep; const char* b2 = last ? nB : cB + (size_t)(t + 2) * kstep;
;             const char* a3 = a2 + kstep; const char* b3 = b2 + kstep;
;             PG8_LDB(B0, 0, 0); PG8_LDB(B1, 0, 1); PG8_SCHED; PG8_LDA(At, 0, 0); PG8_STAGE(PG8_SA(1, 1), a1 + hstepA, voffA);
;             PG8_WAIT_V(8); PG8_WAIT_L(0); PG8_BAR; PG8_MMA(0, 0, At, B0); PG8_MMA(0, 1, At, B1); PG8_BAR; PG8_SCHED;
;             PG8_LDA(At, 0, 1); PG8_STAGE(PG8_SB(0, 0), b2, voffB); PG8_STAGE(PG8_SB(0, 1), b2 + hstepB, voffB); PG8_STAGE(PG8_SA(0, 0), a2, voffA);
;             PG8_WAIT_V(8); PG8_WAIT_L(0); PG8_BAR; PG8_MMA(1, 0, At, B0); PG8_MMA(1, 1, At, B1); PG8_BAR; PG8_SCHED;
.LBB0_1516:
	ds_read_b128 v[134:137], v149
	ds_read_b128 v[156:159], v149 offset:1024
	ds_read_b128 v[160:163], v149 offset:2048
	ds_read_b128 v[164:167], v149 offset:3072
	ds_read_b128 v[168:171], v150
	ds_read_b128 v[172:175], v150 offset:1024
	ds_read_b128 v[176:179], v150 offset:2048
	ds_read_b128 v[180:183], v150 offset:3072
	s_cmp_eq_u32 s67, 12
	s_cselect_b32 s16, s61, s63
	s_cselect_b32 s17, s21, s64
	s_cselect_b32 s42, s62, s65
	s_cselect_b32 s43, s9, s66
	s_add_u32 s40, s16, 0x80
	s_addc_u32 s41, s17, 0
	ds_read_b128 v[184:187], v151
	ds_read_b128 v[188:191], v151 offset:1024
	ds_read_b128 v[192:195], v151 offset:2048
	ds_read_b128 v[196:199], v151 offset:3072
	ds_read_b128 v[200:203], v151 offset:4096
	ds_read_b128 v[204:207], v151 offset:5120
	ds_read_b128 v[208:211], v151 offset:6144
	ds_read_b128 v[212:215], v151 offset:7168
	s_add_u32 s68, s63, 0x3ff80
	s_addc_u32 s69, s64, 0
	s_mov_b32 s70, m0
	s_mov_b32 m0, s56
	s_nop 0
	global_load_lds_dwordx4 v141, s[68:69]
	s_mov_b32 m0, s70
	s_nop 0
	s_mov_b32 s70, m0
	s_mov_b32 m0, s57
	s_nop 0
	global_load_lds_dwordx4 v145, s[68:69]
	s_mov_b32 m0, s70
	s_waitcnt vmcnt(8)
	s_waitcnt lgkmcnt(0)
	s_barrier
	s_setprio 1
	s_waitcnt lgkmcnt(7)
	v_mfma_f32_16x16x32_bf16 v[126:129], v[134:137], v[184:187], v[126:129]
	v_mfma_f32_16x16x32_bf16 v[122:125], v[160:163], v[184:187], v[122:125]
	s_waitcnt lgkmcnt(5)
	v_mfma_f32_16x16x32_bf16 v[110:113], v[134:137], v[192:195], v[110:113]
	v_mfma_f32_16x16x32_bf16 v[106:109], v[160:163], v[192:195], v[106:109]
	s_waitcnt lgkmcnt(3)
	v_mfma_f32_16x16x32_bf16 v[94:97], v[134:137], v[200:203], v[94:97]
	v_mfma_f32_16x16x32_bf16 v[90:93], v[160:163], v[200:203], v[90:93]
	s_waitcnt lgkmcnt(1)
	v_mfma_f32_16x16x32_bf16 v[78:81], v[134:137], v[208:211], v[78:81]
	v_mfma_f32_16x16x32_bf16 v[74:77], v[160:163], v[208:211], v[74:77]
	v_mfma_f32_16x16x32_bf16 v[126:129], v[156:159], v[188:191], v[126:129]
	v_mfma_f32_16x16x32_bf16 v[122:125], v[164:167], v[188:191], v[122:125]
	v_mfma_f32_16x16x32_bf16 v[110:113], v[156:159], v[196:199], v[110:113]
	v_mfma_f32_16x16x32_bf16 v[106:109], v[164:167], v[196:199], v[106:109]
	v_mfma_f32_16x16x32_bf16 v[94:97], v[156:159], v[204:207], v[94:97]
	v_mfma_f32_16x16x32_bf16 v[90:93], v[164:167], v[204:207], v[90:93]
	s_waitcnt lgkmcnt(0)
	v_mfma_f32_16x16x32_bf16 v[78:81], v[156:159], v[212:215], v[78:81]
	v_mfma_f32_16x16x32_bf16 v[74:77], v[164:167], v[212:215], v[74:77]
	s_setprio 0
	s_setprio 1
	v_mfma_f32_16x16x32_bf16 v[118:121], v[168:171], v[184:187], v[118:121]
	v_mfma_f32_16x16x32_bf16 v[114:117], v[176:179], v[184:187], v[114:117]
	v_mfma_f32_16x16x32_bf16 v[102:105], v[168:171], v[192:195], v[102:105]
	v_mfma_f32_16x16x32_bf16 v[98:101], v[176:179], v[192:195], v[98:101]
	v_mfma_f32_16x16x32_bf16 v[86:89], v[168:171], v[200:203], v[86:89]
	v_mfma_f32_16x16x32_bf16 v[82:85], v[176:179], v[200:203], v[82:85]
	v_mfma_f32_16x16x32_bf16 v[70:73], v[168:171], v[208:211], v[70:73]
	v_mfma_f32_16x16x32_bf16 v[66:69], v[176:179], v[208:211], v[66:69]
	v_mfma_f32_16x16x32_bf16 v[118:121], v[172:175], v[188:191], v[118:121]
	v_mfma_f32_16x16x32_bf16 v[114:117], v[180:183], v[188:191], v[114:117]
	v_mfma_f32_16x16x32_bf16 v[102:105], v[172:175], v[196:199], v[102:105]
	v_mfma_f32_16x16x32_bf16 v[98:101], v[180:183], v[196:199], v[98:101]
	v_mfma_f32_16x16x32_bf16 v[86:89], v[172:175], v[204:207], v[86:89]
	v_mfma_f32_16x16x32_bf16 v[82:85], v[180:183], v[204:207], v[82:85]
	v_mfma_f32_16x16x32_bf16 v[70:73], v[172:175], v[212:215], v[70:73]
	v_mfma_f32_16x16x32_bf16 v[66:69], v[180:183], v[212:215], v[66:69]
	s_setprio 0
	s_barrier
	ds_read_b128 v[184:187], v151 offset:16384
	ds_read_b128 v[188:191], v151 offset:17408
	ds_read_b128 v[192:195], v151 offset:18432
	ds_read_b128 v[196:199], v151 offset:19456
	ds_read_b128 v[200:203], v151 offset:20480
	ds_read_b128 v[204:207], v151 offset:21504
	ds_read_b128 v[208:211], v151 offset:22528
	ds_read_b128 v[212:215], v151 offset:23552
	s_mov_b32 s68, m0
	s_mov_b32 m0, s39
	s_nop 0
	global_load_lds_dwordx4 v144, s[42:43]
	s_mov_b32 m0, s68
	s_nop 0
	s_mov_b32 s68, m0
	s_mov_b32 m0, s44
	s_nop 0
	global_load_lds_dwordx4 v146, s[42:43]
	s_mov_b32 m0, s68
	s_add_u32 s68, s42, 0x40000
	s_addc_u32 s69, s43, 0
	s_mov_b32 s70, m0
	s_mov_b32 m0, s45
	s_nop 0
	global_load_lds_dwordx4 v144, s[68:69]
	s_mov_b32 m0, s70
	s_nop 0
	s_mov_b32 s70, m0
	s_mov_b32 m0, s46
	s_nop 0
	global_load_lds_dwordx4 v146, s[68:69]
	s_mov_b32 m0, s70
	s_mov_b32 s68, m0
	s_mov_b32 m0, s35
	s_nop 0
	global_load_lds_dwordx4 v141, s[16:17]
	s_mov_b32 m0, s68
	s_nop 0
	s_mov_b32 s68, m0
	s_mov_b32 m0, s47
	s_nop 0
	global_load_lds_dwordx4 v145, s[16:17]
	s_mov_b32 m0, s68
	s_waitcnt vmcnt(8)
	s_waitcnt lgkmcnt(0)
	s_barrier
; #define PG8_STAGE(bufoff, gbase, voff) do { _Pragma("unroll") for (int _i = 0; _i < 2; ++_i) { unsigned _keep; \
;         asm volatile("s_mov_b32 %0, m0\n\ts_mov_b32 m0, %1\n\ts_nop 0\n\tglobal_load_lds_dwordx4 %2, %3\n\ts_mov_b32 m0, %0" : "=&s"(_keep) : "s"(ldsb + (unsigned)((bufoff) + _i * 8192)), "v"((voff)[_i]), "s"((const char*)(gbase)) : "memory"); } } while (0)
; #define PG8_LDA(dst, b, h) do { _Pragma("unroll") for (int m = 0; m < 4; ++m) _Pragma("unroll") for (int k = 0; k < 2; ++k) dst[m][k] = *(const LAS bf16x8*)(lds + PG8_SA(b, h) + aoff + m * 2048 + k * 1024); } while (0)
; #define PG8_LDB(dst, b, h) do { _Pragma("unroll") for (int n = 0; n < 2; ++n) _Pragma("unroll") for (int k = 0; k < 2; ++k) dst[n][k] = *(const LAS bf16x8*)(lds + PG8_SB(b, h) + boff + n * 2048 + k * 1024); } while (0)
; #define PG8_MMA(ai, bj, At, Bt) do { __builtin_amdgcn_s_setprio(1); _Pragma("unroll") for (int m = 0; m < 4; ++m) _Pragma("unroll") for (int n = 0; n < 2; ++n) _Pragma("unroll") for (int k = 0; k < 2; ++k) \
;         acc[ai][bj][m][n] = __builtin_amdgcn_mfma_f32_16x16x32_bf16(Bt[n][k], At[m][k], acc[ai][bj][m][n], 0, 0, 0); __builtin_amdgcn_s_setprio(0); } while (0)
; #define PG8_WAIT_V(n) asm volatile("s_waitcnt vmcnt(" #n ")" ::: "memory")
; #define PG8_WAIT_L(n) asm volatile("s_waitcnt lgkmcnt(" #n ")" ::: "memory")
; #define PG8_BAR __builtin_amdgcn_s_barrier()
; #define PG8_SCHED __builtin_amdgcn_sched_barrier(0)
; template <class Epi>
; __device__ __forceinline__ void gemm_phase(LAS unsigned char* lds, const Gemm g, const StaticOrder& S, const Epi& E) {
;     ...
;             PG8_WAIT_V(8); PG8_WAIT_L(0); PG8_BAR; PG8_MMA(1, 0, At, B0); PG8_MMA(1, 1, At, B1); PG8_BAR; PG8_SCHED;
;             PG8_LDB(B0, 1, 0); PG8_LDB(B1, 1, 1); PG8_SCHED; PG8_LDA(At, 1, 0); PG8_STAGE(PG8_SA(0, 1), a2 + hstepA, voffA);
;             PG8_WAIT_V(8); PG8_WAIT_L(0); PG8_BAR; PG8_MMA(0, 0, At, B0); PG8_MMA(0, 1, At, B1); PG8_BAR; PG8_SCHED;
	s_setprio 1
	s_waitcnt lgkmcnt(7)
	v_mfma_f32_16x16x32_bf16 v[62:65], v[134:137], v[184:187], v[62:65]
	v_mfma_f32_16x16x32_bf16 v[58:61], v[160:163], v[184:187], v[58:61]
	s_waitcnt lgkmcnt(5)
	v_mfma_f32_16x16x32_bf16 v[46:49], v[134:137], v[192:195], v[46:49]
	v_mfma_f32_16x16x32_bf16 v[42:45], v[160:163], v[192:195], v[42:45]
	s_waitcnt lgkmcnt(3)
	v_mfma_f32_16x16x32_bf16 v[30:33], v[134:137], v[200:203], v[30:33]
	v_mfma_f32_16x16x32_bf16 v[26:29], v[160:163], v[200:203], v[26:29]
	s_waitcnt lgkmcnt(1)
	v_mfma_f32_16x16x32_bf16 v[14:17], v[134:137], v[208:211], v[14:17]
	v_mfma_f32_16x16x32_bf16 v[10:13], v[160:163], v[208:211], v[10:13]
	v_mfma_f32_16x16x32_bf16 v[62:65], v[156:159], v[188:191], v[62:65]
	v_mfma_f32_16x16x32_bf16 v[58:61], v[164:167], v[188:191], v[58:61]
	v_mfma_f32_16x16x32_bf16 v[46:49], v[156:159], v[196:199], v[46:49]
	v_mfma_f32_16x16x32_bf16 v[42:45], v[164:167], v[196:199], v[42:45]
	v_mfma_f32_16x16x32_bf16 v[30:33], v[156:159], v[204:207], v[30:33]
	v_mfma_f32_16x16x32_bf16 v[26:29], v[164:167], v[204:207], v[26:29]
	s_waitcnt lgkmcnt(0)
	v_mfma_f32_16x16x32_bf16 v[14:17], v[156:159], v[212:215], v[14:17]
	v_mfma_f32_16x16x32_bf16 v[10:13], v[164:167], v[212:215], v[10:13]
	s_setprio 0
	s_setprio 1
	v_mfma_f32_16x16x32_bf16 v[54:57], v[168:171], v[184:187], v[54:57]
	v_mfma_f32_16x16x32_bf16 v[50:53], v[176:179], v[184:187], v[50:53]
	v_mfma_f32_16x16x32_bf16 v[38:41], v[168:171], v[192:195], v[38:41]
	v_mfma_f32_16x16x32_bf16 v[34:37], v[176:179], v[192:195], v[34:37]
	v_mfma_f32_16x16x32_bf16 v[22:25], v[168:171], v[200:203], v[22:25]
	v_mfma_f32_16x16x32_bf16 v[18:21], v[176:179], v[200:203], v[18:21]
	v_mfma_f32_16x16x32_bf16 v[6:9], v[168:171], v[208:211], v[6:9]
	v_mfma_f32_16x16x32_bf16 v[2:5], v[176:179], v[208:211], v[2:5]
	v_mfma_f32_16x16x32_bf16 v[54:57], v[172:175], v[188:191], v[54:57]
	v_mfma_f32_16x16x32_bf16 v[50:53], v[180:183], v[188:191], v[50:53]
	v_mfma_f32_16x16x32_bf16 v[38:41], v[172:175], v[196:199], v[38:41]
	v_mfma_f32_16x16x32_bf16 v[34:37], v[180:183], v[196:199], v[34:37]
	v_mfma_f32_16x16x32_bf16 v[22:25], v[172:175], v[204:207], v[22:25]
	v_mfma_f32_16x16x32_bf16 v[18:21], v[180:183], v[204:207], v[18:21]
	v_mfma_f32_16x16x32_bf16 v[6:9], v[172:175], v[212:215], v[6:9]
	v_mfma_f32_16x16x32_bf16 v[2:5], v[180:183], v[212:215], v[2:5]
	s_setprio 0
	s_barrier
	ds_read_b128 v[134:137], v152
	ds_read_b128 v[156:159], v152 offset:1024
	ds_read_b128 v[160:163], v152 offset:2048
	ds_read_b128 v[164:167], v152 offset:3072
	ds_read_b128 v[168:171], v153
	ds_read_b128 v[172:175], v153 offset:1024
	ds_read_b128 v[176:179], v153 offset:2048
	ds_read_b128 v[180:183], v153 offset:3072
	ds_read_b128 v[184:187], v151 offset:32768
	ds_read_b128 v[188:191], v151 offset:33792
	ds_read_b128 v[192:195], v151 offset:34816
	ds_read_b128 v[196:199], v151 offset:35840
	ds_read_b128 v[200:203], v151 offset:36864
	ds_read_b128 v[204:207], v151 offset:37888
	ds_read_b128 v[208:211], v151 offset:38912
	ds_read_b128 v[212:215], v151 offset:39936
	s_add_u32 s16, s16, 0x40000
	s_addc_u32 s17, s17, 0
	s_mov_b32 s68, m0
	s_mov_b32 m0, s48
	s_nop 0
	global_load_lds_dwordx4 v141, s[16:17]
	s_mov_b32 m0, s68
	s_nop 0
	s_mov_b32 s68, m0
	s_mov_b32 m0, s49
	s_nop 0
	global_load_lds_dwordx4 v145, s[16:17]
	s_mov_b32 m0, s68
	s_waitcnt vmcnt(8)
	s_waitcnt lgkmcnt(0)
	s_barrier
	s_setprio 1
	s_waitcnt lgkmcnt(7)
	v_mfma_f32_16x16x32_bf16 v[126:129], v[134:137], v[184:187], v[126:129]
	v_mfma_f32_16x16x32_bf16 v[122:125], v[160:163], v[184:187], v[122:125]
	s_waitcnt lgkmcnt(5)
	v_mfma_f32_16x16x32_bf16 v[110:113], v[134:137], v[192:195], v[110:113]
	v_mfma_f32_16x16x32_bf16 v[106:109], v[160:163], v[192:195], v[106:109]
	s_waitcnt lgkmcnt(3)
	v_mfma_f32_16x16x32_bf16 v[94:97], v[134:137], v[200:203], v[94:97]
	v_mfma_f32_16x16x32_bf16 v[90:93], v[160:163], v[200:203], v[90:93]
	s_waitcnt lgkmcnt(1)
	v_mfma_f32_16x16x32_bf16 v[78:81], v[134:137], v[208:211], v[78:81]
	v_mfma_f32_16x16x32_bf16 v[74:77], v[160:163], v[208:211], v[74:77]
	v_mfma_f32_16x16x32_bf16 v[126:129], v[156:159], v[188:191], v[126:129]
	v_mfma_f32_16x16x32_bf16 v[122:125], v[164:167], v[188:191], v[122:125]
	v_mfma_f32_16x16x32_bf16 v[110:113], v[156:159], v[196:199], v[110:113]
	v_mfma_f32_16x16x32_bf16 v[106:109], v[164:167], v[196:199], v[106:109]
	v_mfma_f32_16x16x32_bf16 v[94:97], v[156:159], v[204:207], v[94:97]
	v_mfma_f32_16x16x32_bf16 v[90:93], v[164:167], v[204:207], v[90:93]
	s_waitcnt lgkmcnt(0)
	v_mfma_f32_16x16x32_bf16 v[78:81], v[156:159], v[212:215], v[78:81]
	v_mfma_f32_16x16x32_bf16 v[74:77], v[164:167], v[212:215], v[74:77]
	s_setprio 0
	s_setprio 1
	v_mfma_f32_16x16x32_bf16 v[118:121], v[168:171], v[184:187], v[118:121]
	v_mfma_f32_16x16x32_bf16 v[114:117], v[176:179], v[184:187], v[114:117]
	v_mfma_f32_16x16x32_bf16 v[102:105], v[168:171], v[192:195], v[102:105]
	v_mfma_f32_16x16x32_bf16 v[98:101], v[176:179], v[192:195], v[98:101]
	v_mfma_f32_16x16x32_bf16 v[86:89], v[168:171], v[200:203], v[86:89]
	v_mfma_f32_16x16x32_bf16 v[82:85], v[176:179], v[200:203], v[82:85]
	v_mfma_f32_16x16x32_bf16 v[70:73], v[168:171], v[208:211], v[70:73]
	v_mfma_f32_16x16x32_bf16 v[66:69], v[176:179], v[208:211], v[66:69]
	v_mfma_f32_16x16x32_bf16 v[118:121], v[172:175], v[188:191], v[118:121]
	v_mfma_f32_16x16x32_bf16 v[114:117], v[180:183], v[188:191], v[114:117]
	v_mfma_f32_16x16x32_bf16 v[102:105], v[172:175], v[196:199], v[102:105]
	v_mfma_f32_16x16x32_bf16 v[98:101], v[180:183], v[196:199], v[98:101]
	v_mfma_f32_16x16x32_bf16 v[86:89], v[172:175], v[204:207], v[86:89]
	v_mfma_f32_16x16x32_bf16 v[82:85], v[180:183], v[204:207], v[82:85]
	v_mfma_f32_16x16x32_bf16 v[70:73], v[172:175], v[212:215], v[70:73]
	v_mfma_f32_16x16x32_bf16 v[66:69], v[180:183], v[212:215], v[66:69]
	s_setprio 0
	s_barrier
; #define PG8_STAGE(bufoff, gbase, voff) do { _Pragma("unroll") for (int _i = 0; _i < 2; ++_i) { unsigned _keep; \
;         asm volatile("s_mov_b32 %0, m0\n\ts_mov_b32 m0, %1\n\ts_nop 0\n\tglobal_load_lds_dwordx4 %2, %3\n\ts_mov_b32 m0, %0" : "=&s"(_keep) : "s"(ldsb + (unsigned)((bufoff) + _i * 8192)), "v"((voff)[_i]), "s"((const char*)(gbase)) : "memory"); } } while (0)
; #define PG8_LDA(dst, b, h) do { _Pragma("unroll") for (int m = 0; m < 4; ++m) _Pragma("unroll") for (int k = 0; k < 2; ++k) dst[m][k] = *(const LAS bf16x8*)(lds + PG8_SA(b, h) + aoff + m * 2048 + k * 1024); } while (0)
; #define PG8_MMA(ai, bj, At, Bt) do { __builtin_amdgcn_s_setprio(1); _Pragma("unroll") for (int m = 0; m < 4; ++m) _Pragma("unroll") for (int n = 0; n < 2; ++n) _Pragma("unroll") for (int k = 0; k < 2; ++k) \
;         acc[ai][bj][m][n] = __builtin_amdgcn_mfma_f32_16x16x32_bf16(Bt[n][k], At[m][k], acc[ai][bj][m][n], 0, 0, 0); __builtin_amdgcn_s_setprio(0); } while (0)
; #define PG8_WAIT_V(n) asm volatile("s_waitcnt vmcnt(" #n ")" ::: "memory")
; #define PG8_WAIT_L(n) asm volatile("s_waitcnt lgkmcnt(" #n ")" ::: "memory")
; #define PG8_BAR __builtin_amdgcn_s_barrier()
; #define PG8_SCHED __builtin_amdgcn_sched_barrier(0)
; template <class Epi>
; __device__ __forceinline__ void gemm_phase(LAS unsigned char* lds, const Gemm g, const StaticOrder& S, const Epi& E) {
;     ...
;             PG8_LDA(At, 1, 1); PG8_STAGE(PG8_SB(1, 0), b3, voffB); PG8_STAGE(PG8_SB(1, 1), b3 + hstepB, voffB); PG8_STAGE(PG8_SA(1, 0), a3, voffA);
;             PG8_WAIT_V(8); PG8_WAIT_L(0); PG8_BAR; PG8_MMA(1, 0, At, B0); PG8_MMA(1, 1, At, B1); PG8_BAR; PG8_SCHED;
;         }
;         if (wr == 0) PG8_BAR;
	ds_read_b128 v[184:187], v151 offset:49152
	ds_read_b128 v[188:191], v151 offset:50176
	ds_read_b128 v[192:195], v151 offset:51200
	ds_read_b128 v[196:199], v151 offset:52224
	ds_read_b128 v[200:203], v151 offset:53248
	ds_read_b128 v[204:207], v151 offset:54272
	ds_read_b128 v[208:211], v151 offset:55296
	ds_read_b128 v[212:215], v151 offset:56320
	s_add_u32 s16, s42, 0x80
	s_addc_u32 s17, s43, 0
	s_mov_b32 s68, m0
	s_mov_b32 m0, s50
	s_nop 0
	global_load_lds_dwordx4 v144, s[16:17]
	s_mov_b32 m0, s68
	s_nop 0
	s_mov_b32 s68, m0
	s_mov_b32 m0, s51
	s_nop 0
	global_load_lds_dwordx4 v146, s[16:17]
	s_mov_b32 m0, s68
	s_add_u32 s16, s42, 0x40080
	s_addc_u32 s17, s43, 0
	s_mov_b32 s42, m0
	s_mov_b32 m0, s54
	s_nop 0
	global_load_lds_dwordx4 v144, s[16:17]
	s_mov_b32 m0, s42
	s_nop 0
	s_mov_b32 s42, m0
	s_mov_b32 m0, s55
	s_nop 0
	global_load_lds_dwordx4 v146, s[16:17]
	s_mov_b32 m0, s42
	s_mov_b32 s16, m0
	s_mov_b32 m0, s52
	s_nop 0
	global_load_lds_dwordx4 v141, s[40:41]
	s_mov_b32 m0, s16
	s_nop 0
	s_mov_b32 s16, m0
	s_mov_b32 m0, s53
	s_nop 0
	global_load_lds_dwordx4 v145, s[40:41]
	s_mov_b32 m0, s16
	s_waitcnt vmcnt(8)
	s_waitcnt lgkmcnt(0)
	s_barrier
	s_setprio 1
	s_waitcnt lgkmcnt(7)
	v_mfma_f32_16x16x32_bf16 v[62:65], v[134:137], v[184:187], v[62:65]
	v_mfma_f32_16x16x32_bf16 v[58:61], v[160:163], v[184:187], v[58:61]
	s_waitcnt lgkmcnt(5)
	v_mfma_f32_16x16x32_bf16 v[46:49], v[134:137], v[192:195], v[46:49]
	v_mfma_f32_16x16x32_bf16 v[42:45], v[160:163], v[192:195], v[42:45]
	s_waitcnt lgkmcnt(3)
	v_mfma_f32_16x16x32_bf16 v[30:33], v[134:137], v[200:203], v[30:33]
	v_mfma_f32_16x16x32_bf16 v[26:29], v[160:163], v[200:203], v[26:29]
	s_waitcnt lgkmcnt(1)
	v_mfma_f32_16x16x32_bf16 v[14:17], v[134:137], v[208:211], v[14:17]
	v_mfma_f32_16x16x32_bf16 v[10:13], v[160:163], v[208:211], v[10:13]
	v_mfma_f32_16x16x32_bf16 v[62:65], v[156:159], v[188:191], v[62:65]
	v_mfma_f32_16x16x32_bf16 v[58:61], v[164:167], v[188:191], v[58:61]
	v_mfma_f32_16x16x32_bf16 v[46:49], v[156:159], v[196:199], v[46:49]
	v_mfma_f32_16x16x32_bf16 v[42:45], v[164:167], v[196:199], v[42:45]
	v_mfma_f32_16x16x32_bf16 v[30:33], v[156:159], v[204:207], v[30:33]
	v_mfma_f32_16x16x32_bf16 v[26:29], v[164:167], v[204:207], v[26:29]
	s_waitcnt lgkmcnt(0)
	v_mfma_f32_16x16x32_bf16 v[14:17], v[156:159], v[212:215], v[14:17]
	v_mfma_f32_16x16x32_bf16 v[10:13], v[164:167], v[212:215], v[10:13]
	s_setprio 0
	s_setprio 1
	v_mfma_f32_16x16x32_bf16 v[54:57], v[168:171], v[184:187], v[54:57]
	v_mfma_f32_16x16x32_bf16 v[50:53], v[176:179], v[184:187], v[50:53]
	v_mfma_f32_16x16x32_bf16 v[38:41], v[168:171], v[192:195], v[38:41]
	v_mfma_f32_16x16x32_bf16 v[34:37], v[176:179], v[192:195], v[34:37]
	v_mfma_f32_16x16x32_bf16 v[22:25], v[168:171], v[200:203], v[22:25]
	v_mfma_f32_16x16x32_bf16 v[18:21], v[176:179], v[200:203], v[18:21]
	v_mfma_f32_16x16x32_bf16 v[6:9], v[168:171], v[208:211], v[6:9]
	v_mfma_f32_16x16x32_bf16 v[2:5], v[176:179], v[208:211], v[2:5]
	v_mfma_f32_16x16x32_bf16 v[54:57], v[172:175], v[188:191], v[54:57]
	v_mfma_f32_16x16x32_bf16 v[50:53], v[180:183], v[188:191], v[50:53]
	v_mfma_f32_16x16x32_bf16 v[38:41], v[172:175], v[196:199], v[38:41]
	v_mfma_f32_16x16x32_bf16 v[34:37], v[180:183], v[196:199], v[34:37]
	v_mfma_f32_16x16x32_bf16 v[22:25], v[172:175], v[204:207], v[22:25]
	v_mfma_f32_16x16x32_bf16 v[18:21], v[180:183], v[204:207], v[18:21]
	v_mfma_f32_16x16x32_bf16 v[6:9], v[172:175], v[212:215], v[6:9]
	v_mfma_f32_16x16x32_bf16 v[2:5], v[180:183], v[212:215], v[2:5]
	s_setprio 0
	s_add_i32 s67, s67, 2
	s_add_u32 s63, s63, 0x100
	s_addc_u32 s64, s64, 0
	s_add_u32 s65, s65, 0x100
	s_addc_u32 s66, s66, 0
	s_cmp_gt_u32 s67, 13
	s_barrier
	s_cbranch_scc0 .LBB0_1516
	s_and_b64 vcc, exec, s[6:7]
	s_cbranch_vccz .LBB0_1519
	s_barrier

; #define PG8_STAGE(bufoff, gbase, voff) do { _Pragma("unroll") for (int _i = 0; _i < 2; ++_i) { unsigned _keep; \
;         asm volatile("s_mov_b32 %0, m0\n\ts_mov_b32 m0, %1\n\ts_nop 0\n\tglobal_load_lds_dwordx4 %2, %3\n\ts_mov_b32 m0, %0" : "=&s"(_keep) : "s"(ldsb + (unsigned)((bufoff) + _i * 8192)), "v"((voff)[_i]), "s"((const char*)(gbase)) : "memory"); } } while (0)
; #define PG8_LDA(dst, b, h) do { _Pragma("unroll") for (int m = 0; m < 4; ++m) _Pragma("unroll") for (int k = 0; k < 2; ++k) dst[m][k] = *(const LAS bf16x8*)(lds + PG8_SA(b, h) + aoff + m * 2048 + k * 1024); } while (0)
; #define PG8_LDB(dst, b, h) do { _Pragma("unroll") for (int n = 0; n < 2; ++n) _Pragma("unroll") for (int k = 0; k < 2; ++k) dst[n][k] = *(const LAS bf16x8*)(lds + PG8_SB(b, h) + boff + n * 2048 + k * 1024); } while (0)
; #define PG8_MMA(ai, bj, At, Bt) do { __builtin_amdgcn_s_setprio(1); _Pragma("unroll") for (int m = 0; m < 4; ++m) _Pragma("unroll") for (int n = 0; n < 2; ++n) _Pragma("unroll") for (int k = 0; k < 2; ++k) \
;         acc[ai][bj][m][n] = __builtin_amdgcn_mfma_f32_16x16x32_bf16(Bt[n][k], At[m][k], acc[ai][bj][m][n], 0, 0, 0); __builtin_amdgcn_s_setprio(0); } while (0)
; #define PG8_WAIT_V(n) asm volatile("s_waitcnt vmcnt(" #n ")" ::: "memory")
; #define PG8_WAIT_L(n) asm volatile("s_waitcnt lgkmcnt(" #n ")" ::: "memory")
; template <class Epi>
; __device__ __forceinline__ void gemm_phase(LAS unsigned char* lds, const Gemm g, const StaticOrder& S, const Epi& E) {
;     ...
;         for (int t = 0; t < nt; t += 2) {
;             const bool last = (t == nt - 2);
;             const char* a1 = cA + (size_t)(t + 1) * kstep;
;             const char* a2 = last ? nA : cA + (size_t)(t + 2) * kstep; const char* b2 = last ? nB : cB + (size_t)(t + 2) * kstep;
;             const char* a3 = a2 + kstep; const char* b3 = b2 + kstep;
;             PG8_LDB(B0, 0, 0); PG8_LDB(B1, 0, 1); PG8_SCHED; PG8_LDA(At, 0, 0); PG8_STAGE(PG8_SA(1, 1), a1 + hstepA, voffA);
;             PG8_WAIT_V(8); PG8_WAIT_L(0); PG8_BAR; PG8_MMA(0, 0, At, B0); PG8_MMA(0, 1, At, B1); PG8_BAR; PG8_SCHED;
;             PG8_LDA(At, 0, 1); PG8_STAGE(PG8_SB(0, 0), b2, voffB); PG8_STAGE(PG8_SB(0, 1), b2 + hstepB, voffB); PG8_STAGE(PG8_SA(0, 0), a2, voffA);
;             PG8_WAIT_V(8); PG8_WAIT_L(0); PG8_BAR; PG8_MMA(1, 0, At, B0); PG8_MMA(1, 1, At, B1); PG8_BAR; PG8_SCHED;
.LBB0_1605:
	ds_read_b128 v[144:147], v190
	ds_read_b128 v[194:197], v190 offset:1024
	ds_read_b128 v[198:201], v190 offset:2048
	ds_read_b128 v[202:205], v190 offset:3072
	ds_read_b128 v[206:209], v192
	ds_read_b128 v[210:213], v192 offset:1024
	ds_read_b128 v[214:217], v192 offset:2048
	ds_read_b128 v[218:221], v192 offset:3072
	s_add_i32 s79, s16, 2
	s_cmp_eq_u32 s37, s16
	s_cselect_b32 s44, s0, s41
	s_cselect_b32 s45, s1, s47
	s_cselect_b32 s42, s38, s77
	s_cselect_b32 s43, s39, s78
	s_add_u32 s16, s44, 0x80
	s_addc_u32 s17, s45, 0
	ds_read_b128 v[222:225], v191
	ds_read_b128 v[226:229], v191 offset:1024
	ds_read_b128 v[230:233], v191 offset:2048
	ds_read_b128 v[234:237], v191 offset:3072
	ds_read_b128 v[238:241], v191 offset:4096
	ds_read_b128 v[242:245], v191 offset:5120
	ds_read_b128 v[246:249], v191 offset:6144
	ds_read_b128 v[250:253], v191 offset:7168
	s_add_u32 s80, s41, 0xaff80
	s_addc_u32 s81, s47, 0
	s_mov_b32 s82, m0
	s_mov_b32 m0, s62
	s_nop 0
	global_load_lds_dwordx4 v150, s[80:81]
	s_mov_b32 m0, s82
	s_nop 0
	s_mov_b32 s82, m0
	s_mov_b32 m0, s63
	s_nop 0
	global_load_lds_dwordx4 v153, s[80:81]
	s_mov_b32 m0, s82
	s_waitcnt vmcnt(8)
	s_waitcnt lgkmcnt(0)
	s_barrier
	s_setprio 1
	s_waitcnt lgkmcnt(7)
	v_mfma_f32_16x16x32_bf16 v[128:131], v[144:147], v[222:225], v[128:131]
	v_mfma_f32_16x16x32_bf16 v[124:127], v[198:201], v[222:225], v[124:127]
	s_waitcnt lgkmcnt(5)
	v_mfma_f32_16x16x32_bf16 v[112:115], v[144:147], v[230:233], v[112:115]
	v_mfma_f32_16x16x32_bf16 v[108:111], v[198:201], v[230:233], v[108:111]
	s_waitcnt lgkmcnt(3)
	v_mfma_f32_16x16x32_bf16 v[96:99], v[144:147], v[238:241], v[96:99]
	v_mfma_f32_16x16x32_bf16 v[92:95], v[198:201], v[238:241], v[92:95]
	s_waitcnt lgkmcnt(1)
	v_mfma_f32_16x16x32_bf16 v[80:83], v[144:147], v[246:249], v[80:83]
	v_mfma_f32_16x16x32_bf16 v[76:79], v[198:201], v[246:249], v[76:79]
	v_mfma_f32_16x16x32_bf16 v[128:131], v[194:197], v[226:229], v[128:131]
	v_mfma_f32_16x16x32_bf16 v[124:127], v[202:205], v[226:229], v[124:127]
	v_mfma_f32_16x16x32_bf16 v[112:115], v[194:197], v[234:237], v[112:115]
	v_mfma_f32_16x16x32_bf16 v[108:111], v[202:205], v[234:237], v[108:111]
	v_mfma_f32_16x16x32_bf16 v[96:99], v[194:197], v[242:245], v[96:99]
	v_mfma_f32_16x16x32_bf16 v[92:95], v[202:205], v[242:245], v[92:95]
	s_waitcnt lgkmcnt(0)
	v_mfma_f32_16x16x32_bf16 v[80:83], v[194:197], v[250:253], v[80:83]
	v_mfma_f32_16x16x32_bf16 v[76:79], v[202:205], v[250:253], v[76:79]
	s_setprio 0
	s_setprio 1
	v_mfma_f32_16x16x32_bf16 v[120:123], v[206:209], v[222:225], v[120:123]
	v_mfma_f32_16x16x32_bf16 v[116:119], v[214:217], v[222:225], v[116:119]
	v_mfma_f32_16x16x32_bf16 v[104:107], v[206:209], v[230:233], v[104:107]
	v_mfma_f32_16x16x32_bf16 v[100:103], v[214:217], v[230:233], v[100:103]
	v_mfma_f32_16x16x32_bf16 v[88:91], v[206:209], v[238:241], v[88:91]
	v_mfma_f32_16x16x32_bf16 v[84:87], v[214:217], v[238:241], v[84:87]
	v_mfma_f32_16x16x32_bf16 v[72:75], v[206:209], v[246:249], v[72:75]
	v_mfma_f32_16x16x32_bf16 v[68:71], v[214:217], v[246:249], v[68:71]
	v_mfma_f32_16x16x32_bf16 v[120:123], v[210:213], v[226:229], v[120:123]
	v_mfma_f32_16x16x32_bf16 v[116:119], v[218:221], v[226:229], v[116:119]
	v_mfma_f32_16x16x32_bf16 v[104:107], v[210:213], v[234:237], v[104:107]
	v_mfma_f32_16x16x32_bf16 v[100:103], v[218:221], v[234:237], v[100:103]
	v_mfma_f32_16x16x32_bf16 v[88:91], v[210:213], v[242:245], v[88:91]
	v_mfma_f32_16x16x32_bf16 v[84:87], v[218:221], v[242:245], v[84:87]
	v_mfma_f32_16x16x32_bf16 v[72:75], v[210:213], v[250:253], v[72:75]
	v_mfma_f32_16x16x32_bf16 v[68:71], v[218:221], v[250:253], v[68:71]
	s_setprio 0
	s_barrier
	ds_read_b128 v[222:225], v191 offset:16384
	ds_read_b128 v[226:229], v191 offset:17408
	ds_read_b128 v[230:233], v191 offset:18432
	ds_read_b128 v[234:237], v191 offset:19456
	ds_read_b128 v[238:241], v191 offset:20480
	ds_read_b128 v[242:245], v191 offset:21504
	ds_read_b128 v[246:249], v191 offset:22528
	ds_read_b128 v[250:253], v191 offset:23552
	s_mov_b32 s80, m0
	s_mov_b32 m0, s35
	s_nop 0
	global_load_lds_dwordx4 v151, s[42:43]
	s_mov_b32 m0, s80
	s_nop 0
	s_mov_b32 s80, m0
	s_mov_b32 m0, s48
	s_nop 0
	global_load_lds_dwordx4 v154, s[42:43]
	s_mov_b32 m0, s80
	s_add_u32 s80, s42, 0xb0000
	s_addc_u32 s81, s43, 0
	s_mov_b32 s82, m0
	s_mov_b32 m0, s49
	s_nop 0
	global_load_lds_dwordx4 v151, s[80:81]
	s_mov_b32 m0, s82
	s_nop 0
	s_mov_b32 s82, m0
	s_mov_b32 m0, s50
	s_nop 0
	global_load_lds_dwordx4 v154, s[80:81]
	s_mov_b32 m0, s82
	s_mov_b32 s80, m0
	s_mov_b32 m0, s33
	s_nop 0
	global_load_lds_dwordx4 v150, s[44:45]
	s_mov_b32 m0, s80
	s_nop 0
	s_mov_b32 s80, m0
	s_mov_b32 m0, s51
	s_nop 0
	global_load_lds_dwordx4 v153, s[44:45]
	s_mov_b32 m0, s80
	s_waitcnt vmcnt(8)
	s_waitcnt lgkmcnt(0)
	s_barrier
; #define PG8_STAGE(bufoff, gbase, voff) do { _Pragma("unroll") for (int _i = 0; _i < 2; ++_i) { unsigned _keep; \
;         asm volatile("s_mov_b32 %0, m0\n\ts_mov_b32 m0, %1\n\ts_nop 0\n\tglobal_load_lds_dwordx4 %2, %3\n\ts_mov_b32 m0, %0" : "=&s"(_keep) : "s"(ldsb + (unsigned)((bufoff) + _i * 8192)), "v"((voff)[_i]), "s"((const char*)(gbase)) : "memory"); } } while (0)
; #define PG8_LDA(dst, b, h) do { _Pragma("unroll") for (int m = 0; m < 4; ++m) _Pragma("unroll") for (int k = 0; k < 2; ++k) dst[m][k] = *(const LAS bf16x8*)(lds + PG8_SA(b, h) + aoff + m * 2048 + k * 1024); } while (0)
; #define PG8_LDB(dst, b, h) do { _Pragma("unroll") for (int n = 0; n < 2; ++n) _Pragma("unroll") for (int k = 0; k < 2; ++k) dst[n][k] = *(const LAS bf16x8*)(lds + PG8_SB(b, h) + boff + n * 2048 + k * 1024); } while (0)
; #define PG8_MMA(ai, bj, At, Bt) do { __builtin_amdgcn_s_setprio(1); _Pragma("unroll") for (int m = 0; m < 4; ++m) _Pragma("unroll") for (int n = 0; n < 2; ++n) _Pragma("unroll") for (int k = 0; k < 2; ++k) \
;         acc[ai][bj][m][n] = __builtin_amdgcn_mfma_f32_16x16x32_bf16(Bt[n][k], At[m][k], acc[ai][bj][m][n], 0, 0, 0); __builtin_amdgcn_s_setprio(0); } while (0)
; #define PG8_WAIT_V(n) asm volatile("s_waitcnt vmcnt(" #n ")" ::: "memory")
; #define PG8_WAIT_L(n) asm volatile("s_waitcnt lgkmcnt(" #n ")" ::: "memory")
; #define PG8_BAR __builtin_amdgcn_s_barrier()
; #define PG8_SCHED __builtin_amdgcn_sched_barrier(0)
; template <class Epi>
; __device__ __forceinline__ void gemm_phase(LAS unsigned char* lds, const Gemm g, const StaticOrder& S, const Epi& E) {
;     ...
;             PG8_WAIT_V(8); PG8_WAIT_L(0); PG8_BAR; PG8_MMA(1, 0, At, B0); PG8_MMA(1, 1, At, B1); PG8_BAR; PG8_SCHED;
;             PG8_LDB(B0, 1, 0); PG8_LDB(B1, 1, 1); PG8_SCHED; PG8_LDA(At, 1, 0); PG8_STAGE(PG8_SA(0, 1), a2 + hstepA, voffA);
;             PG8_WAIT_V(8); PG8_WAIT_L(0); PG8_BAR; PG8_MMA(0, 0, At, B0); PG8_MMA(0, 1, At, B1); PG8_BAR; PG8_SCHED;
	s_setprio 1
	s_waitcnt lgkmcnt(7)
	v_mfma_f32_16x16x32_bf16 v[64:67], v[144:147], v[222:225], v[64:67]
	v_mfma_f32_16x16x32_bf16 v[60:63], v[198:201], v[222:225], v[60:63]
	s_waitcnt lgkmcnt(5)
	v_mfma_f32_16x16x32_bf16 v[48:51], v[144:147], v[230:233], v[48:51]
	v_mfma_f32_16x16x32_bf16 v[44:47], v[198:201], v[230:233], v[44:47]
	s_waitcnt lgkmcnt(3)
	v_mfma_f32_16x16x32_bf16 v[32:35], v[144:147], v[238:241], v[32:35]
	v_mfma_f32_16x16x32_bf16 v[28:31], v[198:201], v[238:241], v[28:31]
	s_waitcnt lgkmcnt(1)
	v_mfma_f32_16x16x32_bf16 v[16:19], v[144:147], v[246:249], v[16:19]
	v_mfma_f32_16x16x32_bf16 v[12:15], v[198:201], v[246:249], v[12:15]
	v_mfma_f32_16x16x32_bf16 v[64:67], v[194:197], v[226:229], v[64:67]
	v_mfma_f32_16x16x32_bf16 v[60:63], v[202:205], v[226:229], v[60:63]
	v_mfma_f32_16x16x32_bf16 v[48:51], v[194:197], v[234:237], v[48:51]
	v_mfma_f32_16x16x32_bf16 v[44:47], v[202:205], v[234:237], v[44:47]
	v_mfma_f32_16x16x32_bf16 v[32:35], v[194:197], v[242:245], v[32:35]
	v_mfma_f32_16x16x32_bf16 v[28:31], v[202:205], v[242:245], v[28:31]
	s_waitcnt lgkmcnt(0)
	v_mfma_f32_16x16x32_bf16 v[16:19], v[194:197], v[250:253], v[16:19]
	v_mfma_f32_16x16x32_bf16 v[12:15], v[202:205], v[250:253], v[12:15]
	s_setprio 0
	s_setprio 1
	v_mfma_f32_16x16x32_bf16 v[56:59], v[206:209], v[222:225], v[56:59]
	v_mfma_f32_16x16x32_bf16 v[52:55], v[214:217], v[222:225], v[52:55]
	v_mfma_f32_16x16x32_bf16 v[40:43], v[206:209], v[230:233], v[40:43]
	v_mfma_f32_16x16x32_bf16 v[36:39], v[214:217], v[230:233], v[36:39]
	v_mfma_f32_16x16x32_bf16 v[24:27], v[206:209], v[238:241], v[24:27]
	v_mfma_f32_16x16x32_bf16 v[20:23], v[214:217], v[238:241], v[20:23]
	v_mfma_f32_16x16x32_bf16 v[8:11], v[206:209], v[246:249], v[8:11]
	v_mfma_f32_16x16x32_bf16 v[4:7], v[214:217], v[246:249], v[4:7]
	v_mfma_f32_16x16x32_bf16 v[56:59], v[210:213], v[226:229], v[56:59]
	v_mfma_f32_16x16x32_bf16 v[52:55], v[218:221], v[226:229], v[52:55]
	v_mfma_f32_16x16x32_bf16 v[40:43], v[210:213], v[234:237], v[40:43]
	v_mfma_f32_16x16x32_bf16 v[36:39], v[218:221], v[234:237], v[36:39]
	v_mfma_f32_16x16x32_bf16 v[24:27], v[210:213], v[242:245], v[24:27]
	v_mfma_f32_16x16x32_bf16 v[20:23], v[218:221], v[242:245], v[20:23]
	v_mfma_f32_16x16x32_bf16 v[8:11], v[210:213], v[250:253], v[8:11]
	v_mfma_f32_16x16x32_bf16 v[4:7], v[218:221], v[250:253], v[4:7]
	s_setprio 0
	s_barrier
	v_add_u32_e32 v3, 0x18000, v189
	ds_read_b128 v[144:147], v3
	ds_read_b128 v[194:197], v3 offset:1024
	ds_read_b128 v[198:201], v3 offset:2048
	ds_read_b128 v[202:205], v3 offset:3072
	v_add_u32_e32 v3, 0x1c000, v189
	ds_read_b128 v[206:209], v3
	ds_read_b128 v[210:213], v3 offset:1024
	ds_read_b128 v[214:217], v3 offset:2048
	ds_read_b128 v[218:221], v3 offset:3072
	ds_read_b128 v[222:225], v191 offset:32768
	ds_read_b128 v[226:229], v191 offset:33792
	ds_read_b128 v[230:233], v191 offset:34816
	ds_read_b128 v[234:237], v191 offset:35840
	ds_read_b128 v[238:241], v191 offset:36864
	ds_read_b128 v[242:245], v191 offset:37888
	ds_read_b128 v[246:249], v191 offset:38912
	ds_read_b128 v[250:253], v191 offset:39936
	s_add_u32 s44, s44, 0xb0000
	s_addc_u32 s45, s45, 0
	s_mov_b32 s80, m0
	s_mov_b32 m0, s52
	s_nop 0
	global_load_lds_dwordx4 v150, s[44:45]
	s_mov_b32 m0, s80
	s_nop 0
	s_mov_b32 s80, m0
	s_mov_b32 m0, s53
	s_nop 0
	global_load_lds_dwordx4 v153, s[44:45]
	s_mov_b32 m0, s80
	s_waitcnt vmcnt(8)
	s_waitcnt lgkmcnt(0)
	s_barrier
	s_setprio 1
	s_waitcnt lgkmcnt(7)
	v_mfma_f32_16x16x32_bf16 v[128:131], v[144:147], v[222:225], v[128:131]
	v_mfma_f32_16x16x32_bf16 v[124:127], v[198:201], v[222:225], v[124:127]
	s_waitcnt lgkmcnt(5)
	v_mfma_f32_16x16x32_bf16 v[112:115], v[144:147], v[230:233], v[112:115]
	v_mfma_f32_16x16x32_bf16 v[108:111], v[198:201], v[230:233], v[108:111]
	s_waitcnt lgkmcnt(3)
	v_mfma_f32_16x16x32_bf16 v[96:99], v[144:147], v[238:241], v[96:99]
	v_mfma_f32_16x16x32_bf16 v[92:95], v[198:201], v[238:241], v[92:95]
	s_waitcnt lgkmcnt(1)
	v_mfma_f32_16x16x32_bf16 v[80:83], v[144:147], v[246:249], v[80:83]
	v_mfma_f32_16x16x32_bf16 v[76:79], v[198:201], v[246:249], v[76:79]
	v_mfma_f32_16x16x32_bf16 v[128:131], v[194:197], v[226:229], v[128:131]
	v_mfma_f32_16x16x32_bf16 v[124:127], v[202:205], v[226:229], v[124:127]
	v_mfma_f32_16x16x32_bf16 v[112:115], v[194:197], v[234:237], v[112:115]
	v_mfma_f32_16x16x32_bf16 v[108:111], v[202:205], v[234:237], v[108:111]
	v_mfma_f32_16x16x32_bf16 v[96:99], v[194:197], v[242:245], v[96:99]
	v_mfma_f32_16x16x32_bf16 v[92:95], v[202:205], v[242:245], v[92:95]
	s_waitcnt lgkmcnt(0)
	v_mfma_f32_16x16x32_bf16 v[80:83], v[194:197], v[250:253], v[80:83]
	v_mfma_f32_16x16x32_bf16 v[76:79], v[202:205], v[250:253], v[76:79]
	s_setprio 0
	s_setprio 1
	v_mfma_f32_16x16x32_bf16 v[120:123], v[206:209], v[222:225], v[120:123]
	v_mfma_f32_16x16x32_bf16 v[116:119], v[214:217], v[222:225], v[116:119]
	v_mfma_f32_16x16x32_bf16 v[104:107], v[206:209], v[230:233], v[104:107]
	v_mfma_f32_16x16x32_bf16 v[100:103], v[214:217], v[230:233], v[100:103]
	v_mfma_f32_16x16x32_bf16 v[88:91], v[206:209], v[238:241], v[88:91]
	v_mfma_f32_16x16x32_bf16 v[84:87], v[214:217], v[238:241], v[84:87]
	v_mfma_f32_16x16x32_bf16 v[72:75], v[206:209], v[246:249], v[72:75]
	v_mfma_f32_16x16x32_bf16 v[68:71], v[214:217], v[246:249], v[68:71]
	v_mfma_f32_16x16x32_bf16 v[120:123], v[210:213], v[226:229], v[120:123]
	v_mfma_f32_16x16x32_bf16 v[116:119], v[218:221], v[226:229], v[116:119]
	v_mfma_f32_16x16x32_bf16 v[104:107], v[210:213], v[234:237], v[104:107]
	v_mfma_f32_16x16x32_bf16 v[100:103], v[218:221], v[234:237], v[100:103]
	v_mfma_f32_16x16x32_bf16 v[88:91], v[210:213], v[242:245], v[88:91]
	v_mfma_f32_16x16x32_bf16 v[84:87], v[218:221], v[242:245], v[84:87]
	v_mfma_f32_16x16x32_bf16 v[72:75], v[210:213], v[250:253], v[72:75]
	v_mfma_f32_16x16x32_bf16 v[68:71], v[218:221], v[250:253], v[68:71]
	s_setprio 0
	s_barrier
; #define PG8_STAGE(bufoff, gbase, voff) do { _Pragma("unroll") for (int _i = 0; _i < 2; ++_i) { unsigned _keep; \
;         asm volatile("s_mov_b32 %0, m0\n\ts_mov_b32 m0, %1\n\ts_nop 0\n\tglobal_load_lds_dwordx4 %2, %3\n\ts_mov_b32 m0, %0" : "=&s"(_keep) : "s"(ldsb + (unsigned)((bufoff) + _i * 8192)), "v"((voff)[_i]), "s"((const char*)(gbase)) : "memory"); } } while (0)
; #define PG8_LDA(dst, b, h) do { _Pragma("unroll") for (int m = 0; m < 4; ++m) _Pragma("unroll") for (int k = 0; k < 2; ++k) dst[m][k] = *(const LAS bf16x8*)(lds + PG8_SA(b, h) + aoff + m * 2048 + k * 1024); } while (0)
; #define PG8_MMA(ai, bj, At, Bt) do { __builtin_amdgcn_s_setprio(1); _Pragma("unroll") for (int m = 0; m < 4; ++m) _Pragma("unroll") for (int n = 0; n < 2; ++n) _Pragma("unroll") for (int k = 0; k < 2; ++k) \
;         acc[ai][bj][m][n] = __builtin_amdgcn_mfma_f32_16x16x32_bf16(Bt[n][k], At[m][k], acc[ai][bj][m][n], 0, 0, 0); __builtin_amdgcn_s_setprio(0); } while (0)
; #define PG8_WAIT_V(n) asm volatile("s_waitcnt vmcnt(" #n ")" ::: "memory")
; #define PG8_WAIT_L(n) asm volatile("s_waitcnt lgkmcnt(" #n ")" ::: "memory")
; #define PG8_BAR __builtin_amdgcn_s_barrier()
; #define PG8_SCHED __builtin_amdgcn_sched_barrier(0)
; template <class Epi>
; __device__ __forceinline__ void gemm_phase(LAS unsigned char* lds, const Gemm g, const StaticOrder& S, const Epi& E) {
;     ...
;             PG8_LDA(At, 1, 1); PG8_STAGE(PG8_SB(1, 0), b3, voffB); PG8_STAGE(PG8_SB(1, 1), b3 + hstepB, voffB); PG8_STAGE(PG8_SA(1, 0), a3, voffA);
;             PG8_WAIT_V(8); PG8_WAIT_L(0); PG8_BAR; PG8_MMA(1, 0, At, B0); PG8_MMA(1, 1, At, B1); PG8_BAR; PG8_SCHED;
;         }
;         if (wr == 0) PG8_BAR;
	ds_read_b128 v[222:225], v191 offset:49152
	ds_read_b128 v[226:229], v191 offset:50176
	ds_read_b128 v[230:233], v191 offset:51200
	ds_read_b128 v[234:237], v191 offset:52224
	ds_read_b128 v[238:241], v191 offset:53248
	ds_read_b128 v[242:245], v191 offset:54272
	ds_read_b128 v[246:249], v191 offset:55296
	ds_read_b128 v[250:253], v191 offset:56320
	s_add_u32 s44, s42, 0x80
	s_addc_u32 s45, s43, 0
	s_mov_b32 s80, m0
	s_mov_b32 m0, s56
	s_nop 0
	global_load_lds_dwordx4 v151, s[44:45]
	s_mov_b32 m0, s80
	s_add_u32 s42, s42, 0xb0080
	s_mov_b32 s80, m0
	s_mov_b32 m0, s57
	s_nop 0
	global_load_lds_dwordx4 v154, s[44:45]
	s_mov_b32 m0, s80
	s_addc_u32 s43, s43, 0
	s_mov_b32 s44, m0
	s_mov_b32 m0, s60
	s_nop 0
	global_load_lds_dwordx4 v151, s[42:43]
	s_mov_b32 m0, s44
	s_nop 0
	s_mov_b32 s44, m0
	s_mov_b32 m0, s61
	s_nop 0
	global_load_lds_dwordx4 v154, s[42:43]
	s_mov_b32 m0, s44
	s_mov_b32 s42, m0
	s_mov_b32 m0, s58
	s_nop 0
	global_load_lds_dwordx4 v150, s[16:17]
	s_mov_b32 m0, s42
	s_nop 0
	s_mov_b32 s42, m0
	s_mov_b32 m0, s59
	s_nop 0
	global_load_lds_dwordx4 v153, s[16:17]
	s_mov_b32 m0, s42
	s_waitcnt vmcnt(8)
	s_waitcnt lgkmcnt(0)
	s_barrier
	s_setprio 1
	s_waitcnt lgkmcnt(7)
	v_mfma_f32_16x16x32_bf16 v[64:67], v[144:147], v[222:225], v[64:67]
	v_mfma_f32_16x16x32_bf16 v[60:63], v[198:201], v[222:225], v[60:63]
	s_waitcnt lgkmcnt(5)
	v_mfma_f32_16x16x32_bf16 v[48:51], v[144:147], v[230:233], v[48:51]
	v_mfma_f32_16x16x32_bf16 v[44:47], v[198:201], v[230:233], v[44:47]
	s_waitcnt lgkmcnt(3)
	v_mfma_f32_16x16x32_bf16 v[32:35], v[144:147], v[238:241], v[32:35]
	v_mfma_f32_16x16x32_bf16 v[28:31], v[198:201], v[238:241], v[28:31]
	s_waitcnt lgkmcnt(1)
	v_mfma_f32_16x16x32_bf16 v[16:19], v[144:147], v[246:249], v[16:19]
	v_mfma_f32_16x16x32_bf16 v[12:15], v[198:201], v[246:249], v[12:15]
	v_mfma_f32_16x16x32_bf16 v[64:67], v[194:197], v[226:229], v[64:67]
	v_mfma_f32_16x16x32_bf16 v[60:63], v[202:205], v[226:229], v[60:63]
	v_mfma_f32_16x16x32_bf16 v[48:51], v[194:197], v[234:237], v[48:51]
	v_mfma_f32_16x16x32_bf16 v[44:47], v[202:205], v[234:237], v[44:47]
	v_mfma_f32_16x16x32_bf16 v[32:35], v[194:197], v[242:245], v[32:35]
	v_mfma_f32_16x16x32_bf16 v[28:31], v[202:205], v[242:245], v[28:31]
	s_waitcnt lgkmcnt(0)
	v_mfma_f32_16x16x32_bf16 v[16:19], v[194:197], v[250:253], v[16:19]
	v_mfma_f32_16x16x32_bf16 v[12:15], v[202:205], v[250:253], v[12:15]
	s_setprio 0
	s_setprio 1
	v_mfma_f32_16x16x32_bf16 v[56:59], v[206:209], v[222:225], v[56:59]
	v_mfma_f32_16x16x32_bf16 v[52:55], v[214:217], v[222:225], v[52:55]
	v_mfma_f32_16x16x32_bf16 v[40:43], v[206:209], v[230:233], v[40:43]
	v_mfma_f32_16x16x32_bf16 v[36:39], v[214:217], v[230:233], v[36:39]
	v_mfma_f32_16x16x32_bf16 v[24:27], v[206:209], v[238:241], v[24:27]
	v_mfma_f32_16x16x32_bf16 v[20:23], v[214:217], v[238:241], v[20:23]
	v_mfma_f32_16x16x32_bf16 v[8:11], v[206:209], v[246:249], v[8:11]
	v_mfma_f32_16x16x32_bf16 v[4:7], v[214:217], v[246:249], v[4:7]
	v_mfma_f32_16x16x32_bf16 v[56:59], v[210:213], v[226:229], v[56:59]
	v_mfma_f32_16x16x32_bf16 v[52:55], v[218:221], v[226:229], v[52:55]
	v_mfma_f32_16x16x32_bf16 v[40:43], v[210:213], v[234:237], v[40:43]
	v_mfma_f32_16x16x32_bf16 v[36:39], v[218:221], v[234:237], v[36:39]
	v_mfma_f32_16x16x32_bf16 v[24:27], v[210:213], v[242:245], v[24:27]
	v_mfma_f32_16x16x32_bf16 v[20:23], v[218:221], v[242:245], v[20:23]
	v_mfma_f32_16x16x32_bf16 v[8:11], v[210:213], v[250:253], v[8:11]
	v_mfma_f32_16x16x32_bf16 v[4:7], v[218:221], v[250:253], v[4:7]
	s_setprio 0
	s_add_u32 s41, s41, 0x100
	s_addc_u32 s47, s47, 0
	s_add_u32 s77, s77, 0x100
	s_addc_u32 s78, s78, 0
	s_cmp_ge_i32 s79, s46
	s_mov_b32 s16, s79
	s_barrier
	s_cbranch_scc0 .LBB0_1605
	s_and_b64 vcc, exec, s[22:23]
	s_cbranch_vccz .LBB0_1608

; #define EPI_ROWS(...) _Pragma("unroll") for (int ai = 0; ai < 2; ++ai) _Pragma("unroll") for (int m = 0; m < 4; ++m) { const int row = row0 + ai * 128 + m * 16; __VA_ARGS__ __builtin_amdgcn_sched_barrier(0); }
; __device__ __forceinline__ u32x4 pack8(f32x4 a, f32x4 b) { u32x4 w; w.x = pk2(a[0], a[1]); w.y = pk2(a[2], a[3]); w.z = pk2(b[0], b[1]); w.w = pk2(b[2], b[3]); return w; }
; __device__ __forceinline__ float dot8(f32x4 a, f32x4 b) { return (a[0] * a[0] + a[1] * a[1]) + (a[2] * a[2] + a[3] * a[3]) + (b[0] * b[0] + b[1] * b[1]) + (b[2] * b[2] + b[3] * b[3]); }
; __device__ __forceinline__ float red_fq(float s) { s += __shfl_xor(s, 16); s += __shfl_xor(s, 32); return s; }
;     __device__ __forceinline__ void operator()(AccRef acc, const Unit& u, int wr, int wc, int fr, int fq) const {
;         const int row0 = u.pm * 256 + wr * 64 + fr, col0 = u.pn * 256 + wc * 32 + 8 * fq;
;         EPI_ROWS(
;             const float* rp = (row < MP) ? res0 + (size_t)row * DM : res1 + (size_t)(row - MP) * DM;
;             float s = 0.f;
;             _Pragma("unroll") for (int bj = 0; bj < 2; ++bj) { const int col = col0 + bj * 128;
;                 f32x4 v0 = *(const f32x4*)(rp + col) + acc[ai][bj][m][0] * scale, v1 = *(const f32x4*)(rp + col + 4) + acc[ai][bj][m][1] * scale;
;                 *(f32x4*)(out + (size_t)row * DM + col) = v0; *(f32x4*)(out + (size_t)row * DM + col + 4) = v1;
;                 if (WB) *(u32x4*)(ob + (size_t)row * DM + col) = pack8(v0, v1);
;                 s += dot8(v0, v1); }
;             s = red_fq(s); if (fq == 0) unsafeAtomicAdd(ss + row, s);
;         )
;     }
.LBB0_1624:
	v_lshl_add_u32 v142, s76, 8, v155
	v_cmp_lt_i32_e32 vcc, s67, v142
	s_and_saveexec_b64 s[16:17], vcc
	s_xor_b64 s[16:17], exec, s[16:17]
	v_add_u32_e32 v144, 0xffff8000, v142
	v_mov_b32_e32 v145, v2
	v_lshlrev_b64 v[144:145], 12, v[144:145]
	v_mov_b32_e32 v143, v2
	v_lshl_add_u64 v[148:149], s[10:11], 0, v[144:145]
	v_lshlrev_b64 v[146:147], 12, v[142:143]
	s_andn2_saveexec_b64 s[16:17], s[16:17]
	v_ashrrev_i32_e32 v143, 31, v142
	v_lshlrev_b64 v[146:147], 12, v[142:143]
	v_lshl_add_u64 v[148:149], s[30:31], 0, v[146:147]
	s_or_b64 exec, exec, s[16:17]
	v_lshl_or_b32 v144, s75, 8, v188
	v_ashrrev_i32_e32 v145, 31, v144
	v_lshlrev_b64 v[144:145], 2, v[144:145]
	v_lshl_add_u64 v[202:203], v[148:149], 0, v[144:145]
	global_load_dwordx4 v[194:197], v[202:203], off
	global_load_dwordx4 v[198:201], v[202:203], off offset:16
	global_load_dwordx4 v[216:219], v[202:203], off offset:512
	global_load_dwordx4 v[220:223], v[202:203], off offset:528
	v_lshl_add_u64 v[146:147], s[30:31], 0, v[146:147]
	v_lshl_add_u64 v[204:205], v[146:147], 0, v[144:145]
	v_and_b32_e32 v158, 64, v159
	v_xor_b32_e32 v3, 16, v159
	v_add_u32_e32 v158, 64, v158
	v_cmp_lt_i32_e32 vcc, v3, v158
	s_waitcnt vmcnt(3)
	v_pk_fma_f32 v[130:131], v[130:131], 0.5, v[196:197] op_sel_hi:[1,0,1]
	v_pk_fma_f32 v[128:129], v[128:129], 0.5, v[194:195] op_sel_hi:[1,0,1]
	s_waitcnt vmcnt(2)
	v_pk_fma_f32 v[126:127], v[126:127], 0.5, v[200:201] op_sel_hi:[1,0,1]
	v_pk_fma_f32 v[124:125], v[124:125], 0.5, v[198:199] op_sel_hi:[1,0,1]
	global_store_dwordx4 v[204:205], v[128:131], off
	global_store_dwordx4 v[204:205], v[124:127], off offset:16
	s_nop 0
	s_nop 0
	v_mul_f32_e32 v129, v129, v129
	v_mul_f32_e32 v131, v131, v131
	v_mul_f32_e32 v125, v125, v125
	v_fmac_f32_e32 v129, v128, v128
	v_fmac_f32_e32 v131, v130, v130
	v_mul_f32_e32 v127, v127, v127
	v_fmac_f32_e32 v125, v124, v124
	v_add_f32_e32 v124, v129, v131
	v_fmac_f32_e32 v127, v126, v126
	v_add_f32_e32 v124, v125, v124
	v_add_f32_e32 v128, v127, v124
	v_cndmask_b32_e32 v3, v159, v3, vcc
	v_lshlrev_b32_e32 v3, 2, v3
	s_waitcnt vmcnt(3)
	v_pk_fma_f32 v[126:127], v[122:123], 0.5, v[218:219] op_sel_hi:[1,0,1]
	v_pk_fma_f32 v[124:125], v[120:121], 0.5, v[216:217] op_sel_hi:[1,0,1]
	s_waitcnt vmcnt(2)
	v_pk_fma_f32 v[120:121], v[118:119], 0.5, v[222:223] op_sel_hi:[1,0,1]
	v_pk_fma_f32 v[118:119], v[116:117], 0.5, v[220:221] op_sel_hi:[1,0,1]
	v_mul_f32_e32 v116, v125, v125
	v_mul_f32_e32 v117, v127, v127
	v_mul_f32_e32 v122, v119, v119
	v_fmac_f32_e32 v116, v124, v124
	v_fmac_f32_e32 v117, v126, v126
	v_mul_f32_e32 v123, v121, v121
	v_fmac_f32_e32 v122, v118, v118
	v_add_f32_e32 v116, v116, v117
	v_add_f32_e32 v116, v122, v116
	v_fmac_f32_e32 v123, v120, v120
	v_add_f32_e32 v116, v123, v116
	v_add_f32_e32 v116, v128, v116
	v_mov_b32_e32 v117, v116
	v_xor_b32_e32 v122, 32, v159
	v_cmp_lt_i32_e32 vcc, v122, v158
	global_store_dwordx4 v[204:205], v[124:127], off offset:512
	global_store_dwordx4 v[204:205], v[118:121], off offset:528
	v_cndmask_b32_e32 v122, v159, v122, vcc
	v_lshlrev_b32_e32 v122, 2, v122
	v_permlane16_swap_b32_e32 v116, v117
	v_add_f32_e32 v116, v116, v117
	v_mov_b32_e32 v117, v116
	s_nop 1
	v_permlane32_swap_b32_e32 v116, v117
	s_and_saveexec_b64 s[16:17], s[4:5]
	s_cbranch_execz .LBB0_1630
	s_waitcnt lgkmcnt(0)
	v_add_f32_e32 v118, v116, v117
	v_lshl_add_u64 v[116:117], v[142:143], 2, s[20:21]
	v_mov_b32_e32 v224, v116
	v_mov_b32_e32 v225, v117
	v_mov_b32_e32 v226, v118
.LBB0_1630:
	s_or_b64 exec, exec, s[16:17]
	s_waitcnt lgkmcnt(0)
	v_or_b32_e32 v116, 16, v142
	v_cmp_lt_i32_e32 vcc, s67, v116
	s_and_saveexec_b64 s[16:17], vcc
	s_xor_b64 s[16:17], exec, s[16:17]
	v_add_u32_e32 v118, 0xffff8010, v142
	v_mov_b32_e32 v119, v2
	v_lshlrev_b64 v[118:119], 12, v[118:119]
	v_mov_b32_e32 v117, v2
	v_lshl_add_u64 v[120:121], s[10:11], 0, v[118:119]
	v_lshlrev_b64 v[118:119], 12, v[116:117]
	s_andn2_saveexec_b64 s[16:17], s[16:17]
	v_ashrrev_i32_e32 v117, 31, v116
	v_lshlrev_b64 v[118:119], 12, v[116:117]
	v_lshl_add_u64 v[120:121], s[30:31], 0, v[118:119]
	s_or_b64 exec, exec, s[16:17]
	v_lshl_add_u64 v[146:147], v[120:121], 0, v[144:145]
	global_load_dwordx4 v[124:127], v[146:147], off
	global_load_dwordx4 v[128:131], v[146:147], off offset:16
	global_load_dwordx4 v[216:219], v[146:147], off offset:512
	global_load_dwordx4 v[220:223], v[146:147], off offset:528
	v_lshl_add_u64 v[118:119], s[30:31], 0, v[118:119]
	v_lshl_add_u64 v[148:149], v[118:119], 0, v[144:145]
	s_waitcnt vmcnt(3)
	v_pk_fma_f32 v[114:115], v[114:115], 0.5, v[126:127] op_sel_hi:[1,0,1]
	v_pk_fma_f32 v[112:113], v[112:113], 0.5, v[124:125] op_sel_hi:[1,0,1]
	s_waitcnt vmcnt(2)
	v_pk_fma_f32 v[110:111], v[110:111], 0.5, v[130:131] op_sel_hi:[1,0,1]
	v_pk_fma_f32 v[108:109], v[108:109], 0.5, v[128:129] op_sel_hi:[1,0,1]
	global_store_dwordx4 v[148:149], v[112:115], off
	global_store_dwordx4 v[148:149], v[108:111], off offset:16
	s_nop 0
	s_nop 0
	v_mul_f32_e32 v113, v113, v113
	v_mul_f32_e32 v115, v115, v115
	v_mul_f32_e32 v109, v109, v109
	v_fmac_f32_e32 v113, v112, v112
	v_fmac_f32_e32 v115, v114, v114
	v_mul_f32_e32 v111, v111, v111
	v_fmac_f32_e32 v109, v108, v108
	v_add_f32_e32 v108, v113, v115
	v_fmac_f32_e32 v111, v110, v110
	v_add_f32_e32 v108, v109, v108
	v_add_f32_e32 v112, v111, v108
	s_waitcnt vmcnt(3)
	v_pk_fma_f32 v[106:107], v[106:107], 0.5, v[218:219] op_sel_hi:[1,0,1]
	v_pk_fma_f32 v[104:105], v[104:105], 0.5, v[216:217] op_sel_hi:[1,0,1]
	s_waitcnt vmcnt(2)
	v_pk_fma_f32 v[108:109], v[100:101], 0.5, v[220:221] op_sel_hi:[1,0,1]
	v_mul_f32_e32 v100, v105, v105
	v_mul_f32_e32 v101, v107, v107
	v_pk_fma_f32 v[110:111], v[102:103], 0.5, v[222:223] op_sel_hi:[1,0,1]
	v_mul_f32_e32 v102, v109, v109
	v_fmac_f32_e32 v100, v104, v104
	v_fmac_f32_e32 v101, v106, v106
	v_mul_f32_e32 v103, v111, v111
	v_fmac_f32_e32 v102, v108, v108
	v_add_f32_e32 v100, v100, v101
	v_add_f32_e32 v100, v102, v100
	v_fmac_f32_e32 v103, v110, v110
	v_add_f32_e32 v100, v103, v100
	v_add_f32_e32 v100, v112, v100
	v_mov_b32_e32 v101, v100
	global_store_dwordx4 v[148:149], v[104:107], off offset:512
	global_store_dwordx4 v[148:149], v[108:111], off offset:528
	v_permlane16_swap_b32_e32 v100, v101
	v_add_f32_e32 v100, v100, v101
	v_mov_b32_e32 v101, v100
	s_nop 1
	v_permlane32_swap_b32_e32 v100, v101
	s_and_saveexec_b64 s[16:17], s[4:5]
	s_cbranch_execz .LBB0_1636
	s_waitcnt lgkmcnt(0)
	v_add_f32_e32 v102, v100, v101
	v_lshl_add_u64 v[100:101], v[116:117], 2, s[20:21]
	v_mov_b32_e32 v228, v100
	v_mov_b32_e32 v229, v101
	v_mov_b32_e32 v230, v102
; #define EPI_ROWS(...) _Pragma("unroll") for (int ai = 0; ai < 2; ++ai) _Pragma("unroll") for (int m = 0; m < 4; ++m) { const int row = row0 + ai * 128 + m * 16; __VA_ARGS__ __builtin_amdgcn_sched_barrier(0); }
; __device__ __forceinline__ u32x4 pack8(f32x4 a, f32x4 b) { u32x4 w; w.x = pk2(a[0], a[1]); w.y = pk2(a[2], a[3]); w.z = pk2(b[0], b[1]); w.w = pk2(b[2], b[3]); return w; }
; __device__ __forceinline__ float dot8(f32x4 a, f32x4 b) { return (a[0] * a[0] + a[1] * a[1]) + (a[2] * a[2] + a[3] * a[3]) + (b[0] * b[0] + b[1] * b[1]) + (b[2] * b[2] + b[3] * b[3]); }
; __device__ __forceinline__ float red_fq(float s) { s += __shfl_xor(s, 16); s += __shfl_xor(s, 32); return s; }
;     __device__ __forceinline__ void operator()(AccRef acc, const Unit& u, int wr, int wc, int fr, int fq) const {
;         const int row0 = u.pm * 256 + wr * 64 + fr, col0 = u.pn * 256 + wc * 32 + 8 * fq;
;         EPI_ROWS(
;             const float* rp = (row < MP) ? res0 + (size_t)row * DM : res1 + (size_t)(row - MP) * DM;
;             float s = 0.f;
;             _Pragma("unroll") for (int bj = 0; bj < 2; ++bj) { const int col = col0 + bj * 128;
;                 f32x4 v0 = *(const f32x4*)(rp + col) + acc[ai][bj][m][0] * scale, v1 = *(const f32x4*)(rp + col + 4) + acc[ai][bj][m][1] * scale;
;                 *(f32x4*)(out + (size_t)row * DM + col) = v0; *(f32x4*)(out + (size_t)row * DM + col + 4) = v1;
;                 if (WB) *(u32x4*)(ob + (size_t)row * DM + col) = pack8(v0, v1);
;                 s += dot8(v0, v1); }
;             s = red_fq(s); if (fq == 0) unsafeAtomicAdd(ss + row, s);
;         )
;     }
.LBB0_1636:
	s_or_b64 exec, exec, s[16:17]
	s_waitcnt lgkmcnt(0)
	v_or_b32_e32 v100, 32, v142
	v_cmp_lt_i32_e32 vcc, s67, v100
	s_and_saveexec_b64 s[16:17], vcc
	s_xor_b64 s[16:17], exec, s[16:17]
	v_add_u32_e32 v102, 0xffff8020, v142
	v_mov_b32_e32 v103, v2
	v_lshlrev_b64 v[102:103], 12, v[102:103]
	v_mov_b32_e32 v101, v2
	v_lshl_add_u64 v[104:105], s[10:11], 0, v[102:103]
	v_lshlrev_b64 v[102:103], 12, v[100:101]
	s_andn2_saveexec_b64 s[16:17], s[16:17]
	v_ashrrev_i32_e32 v101, 31, v100
	v_lshlrev_b64 v[102:103], 12, v[100:101]
	v_lshl_add_u64 v[104:105], s[30:31], 0, v[102:103]
	s_or_b64 exec, exec, s[16:17]
	v_lshl_add_u64 v[112:113], v[104:105], 0, v[144:145]
	global_load_dwordx4 v[104:107], v[112:113], off
	global_load_dwordx4 v[108:111], v[112:113], off offset:16
	global_load_dwordx4 v[216:219], v[112:113], off offset:512
	global_load_dwordx4 v[220:223], v[112:113], off offset:528
	v_lshl_add_u64 v[102:103], s[30:31], 0, v[102:103]
	v_lshl_add_u64 v[114:115], v[102:103], 0, v[144:145]
	s_waitcnt vmcnt(3)
	v_pk_fma_f32 v[98:99], v[98:99], 0.5, v[106:107] op_sel_hi:[1,0,1]
	v_pk_fma_f32 v[96:97], v[96:97], 0.5, v[104:105] op_sel_hi:[1,0,1]
	s_waitcnt vmcnt(2)
	v_pk_fma_f32 v[94:95], v[94:95], 0.5, v[110:111] op_sel_hi:[1,0,1]
	v_pk_fma_f32 v[92:93], v[92:93], 0.5, v[108:109] op_sel_hi:[1,0,1]
	global_store_dwordx4 v[114:115], v[96:99], off
	global_store_dwordx4 v[114:115], v[92:95], off offset:16
	s_nop 0
	s_nop 0
	v_mul_f32_e32 v97, v97, v97
	v_mul_f32_e32 v99, v99, v99
	v_mul_f32_e32 v93, v93, v93
	v_fmac_f32_e32 v97, v96, v96
	v_fmac_f32_e32 v99, v98, v98
	v_mul_f32_e32 v95, v95, v95
	v_fmac_f32_e32 v93, v92, v92
	v_add_f32_e32 v92, v97, v99
	v_fmac_f32_e32 v95, v94, v94
	v_add_f32_e32 v92, v93, v92
	v_add_f32_e32 v96, v95, v92
	s_waitcnt vmcnt(3)
	v_pk_fma_f32 v[90:91], v[90:91], 0.5, v[218:219] op_sel_hi:[1,0,1]
	v_pk_fma_f32 v[88:89], v[88:89], 0.5, v[216:217] op_sel_hi:[1,0,1]
	s_waitcnt vmcnt(2)
	v_pk_fma_f32 v[92:93], v[84:85], 0.5, v[220:221] op_sel_hi:[1,0,1]
	v_mul_f32_e32 v84, v89, v89
	v_mul_f32_e32 v85, v91, v91
	v_pk_fma_f32 v[94:95], v[86:87], 0.5, v[222:223] op_sel_hi:[1,0,1]
	v_mul_f32_e32 v86, v93, v93
	v_fmac_f32_e32 v84, v88, v88
	v_fmac_f32_e32 v85, v90, v90
	v_mul_f32_e32 v87, v95, v95
	v_fmac_f32_e32 v86, v92, v92
	v_add_f32_e32 v84, v84, v85
	v_add_f32_e32 v84, v86, v84
	v_fmac_f32_e32 v87, v94, v94
	v_add_f32_e32 v84, v87, v84
	v_add_f32_e32 v84, v96, v84
	v_mov_b32_e32 v85, v84
	global_store_dwordx4 v[114:115], v[88:91], off offset:512
	global_store_dwordx4 v[114:115], v[92:95], off offset:528
	v_permlane16_swap_b32_e32 v84, v85
	v_add_f32_e32 v84, v84, v85
	v_mov_b32_e32 v85, v84
	s_nop 1
	v_permlane32_swap_b32_e32 v84, v85
	s_and_saveexec_b64 s[16:17], s[4:5]
	s_cbranch_execz .LBB0_1642
	s_waitcnt lgkmcnt(0)
	v_add_f32_e32 v86, v84, v85
	v_lshl_add_u64 v[84:85], v[100:101], 2, s[20:21]
	v_mov_b32_e32 v232, v84
	v_mov_b32_e32 v233, v85
	v_mov_b32_e32 v234, v86
.LBB0_1642:
	s_or_b64 exec, exec, s[16:17]
	s_waitcnt lgkmcnt(0)
	v_or_b32_e32 v84, 48, v142
	v_cmp_lt_i32_e32 vcc, s67, v84
	s_and_saveexec_b64 s[16:17], vcc
	s_xor_b64 s[16:17], exec, s[16:17]
	v_add_u32_e32 v86, 0xffff8030, v142
	v_mov_b32_e32 v87, v2
	v_lshlrev_b64 v[86:87], 12, v[86:87]
	v_mov_b32_e32 v85, v2
	v_lshl_add_u64 v[88:89], s[10:11], 0, v[86:87]
	v_lshlrev_b64 v[86:87], 12, v[84:85]
	s_andn2_saveexec_b64 s[16:17], s[16:17]
	v_ashrrev_i32_e32 v85, 31, v84
	v_lshlrev_b64 v[86:87], 12, v[84:85]
	v_lshl_add_u64 v[88:89], s[30:31], 0, v[86:87]
	s_or_b64 exec, exec, s[16:17]
	v_lshl_add_u64 v[96:97], v[88:89], 0, v[144:145]
	global_load_dwordx4 v[88:91], v[96:97], off
	global_load_dwordx4 v[92:95], v[96:97], off offset:16
	global_load_dwordx4 v[216:219], v[96:97], off offset:512
	global_load_dwordx4 v[220:223], v[96:97], off offset:528
	v_lshl_add_u64 v[86:87], s[30:31], 0, v[86:87]
	v_lshl_add_u64 v[98:99], v[86:87], 0, v[144:145]
	s_waitcnt vmcnt(3)
	v_pk_fma_f32 v[82:83], v[82:83], 0.5, v[90:91] op_sel_hi:[1,0,1]
	v_pk_fma_f32 v[80:81], v[80:81], 0.5, v[88:89] op_sel_hi:[1,0,1]
	s_waitcnt vmcnt(2)
	v_pk_fma_f32 v[78:79], v[78:79], 0.5, v[94:95] op_sel_hi:[1,0,1]
	v_pk_fma_f32 v[76:77], v[76:77], 0.5, v[92:93] op_sel_hi:[1,0,1]
	global_store_dwordx4 v[98:99], v[80:83], off
	global_store_dwordx4 v[98:99], v[76:79], off offset:16
	s_nop 0
	s_nop 0
	v_mul_f32_e32 v81, v81, v81
	v_mul_f32_e32 v83, v83, v83
	v_mul_f32_e32 v77, v77, v77
	v_fmac_f32_e32 v81, v80, v80
	v_fmac_f32_e32 v83, v82, v82
	v_mul_f32_e32 v79, v79, v79
	v_fmac_f32_e32 v77, v76, v76
	v_add_f32_e32 v76, v81, v83
	v_fmac_f32_e32 v79, v78, v78
	v_add_f32_e32 v76, v77, v76
	v_add_f32_e32 v80, v79, v76
	s_waitcnt vmcnt(3)
	v_pk_fma_f32 v[74:75], v[74:75], 0.5, v[218:219] op_sel_hi:[1,0,1]
	v_pk_fma_f32 v[72:73], v[72:73], 0.5, v[216:217] op_sel_hi:[1,0,1]
	s_waitcnt vmcnt(2)
	v_pk_fma_f32 v[76:77], v[68:69], 0.5, v[220:221] op_sel_hi:[1,0,1]
	v_mul_f32_e32 v68, v73, v73
	v_mul_f32_e32 v69, v75, v75
	v_pk_fma_f32 v[78:79], v[70:71], 0.5, v[222:223] op_sel_hi:[1,0,1]
	v_mul_f32_e32 v70, v77, v77
	v_fmac_f32_e32 v68, v72, v72
	v_fmac_f32_e32 v69, v74, v74
	v_mul_f32_e32 v71, v79, v79
	v_fmac_f32_e32 v70, v76, v76
	v_add_f32_e32 v68, v68, v69
	v_add_f32_e32 v68, v70, v68
	v_fmac_f32_e32 v71, v78, v78
	v_add_f32_e32 v68, v71, v68
	v_add_f32_e32 v68, v80, v68
	v_mov_b32_e32 v69, v68
	global_store_dwordx4 v[98:99], v[72:75], off offset:512
	global_store_dwordx4 v[98:99], v[76:79], off offset:528
	v_permlane16_swap_b32_e32 v68, v69
	v_add_f32_e32 v68, v68, v69
	v_mov_b32_e32 v69, v68
	s_nop 1
	v_permlane32_swap_b32_e32 v68, v69
	s_and_saveexec_b64 s[16:17], s[4:5]
	s_cbranch_execz .LBB0_1648
	s_waitcnt lgkmcnt(0)
	v_add_f32_e32 v70, v68, v69
	v_lshl_add_u64 v[68:69], v[84:85], 2, s[20:21]
	v_mov_b32_e32 v236, v68
	v_mov_b32_e32 v237, v69
	v_mov_b32_e32 v238, v70
; #define EPI_ROWS(...) _Pragma("unroll") for (int ai = 0; ai < 2; ++ai) _Pragma("unroll") for (int m = 0; m < 4; ++m) { const int row = row0 + ai * 128 + m * 16; __VA_ARGS__ __builtin_amdgcn_sched_barrier(0); }
; __device__ __forceinline__ u32x4 pack8(f32x4 a, f32x4 b) { u32x4 w; w.x = pk2(a[0], a[1]); w.y = pk2(a[2], a[3]); w.z = pk2(b[0], b[1]); w.w = pk2(b[2], b[3]); return w; }
; __device__ __forceinline__ float dot8(f32x4 a, f32x4 b) { return (a[0] * a[0] + a[1] * a[1]) + (a[2] * a[2] + a[3] * a[3]) + (b[0] * b[0] + b[1] * b[1]) + (b[2] * b[2] + b[3] * b[3]); }
; __device__ __forceinline__ float red_fq(float s) { s += __shfl_xor(s, 16); s += __shfl_xor(s, 32); return s; }
;     __device__ __forceinline__ void operator()(AccRef acc, const Unit& u, int wr, int wc, int fr, int fq) const {
;         const int row0 = u.pm * 256 + wr * 64 + fr, col0 = u.pn * 256 + wc * 32 + 8 * fq;
;         EPI_ROWS(
;             const float* rp = (row < MP) ? res0 + (size_t)row * DM : res1 + (size_t)(row - MP) * DM;
;             float s = 0.f;
;             _Pragma("unroll") for (int bj = 0; bj < 2; ++bj) { const int col = col0 + bj * 128;
;                 f32x4 v0 = *(const f32x4*)(rp + col) + acc[ai][bj][m][0] * scale, v1 = *(const f32x4*)(rp + col + 4) + acc[ai][bj][m][1] * scale;
;                 *(f32x4*)(out + (size_t)row * DM + col) = v0; *(f32x4*)(out + (size_t)row * DM + col + 4) = v1;
;                 if (WB) *(u32x4*)(ob + (size_t)row * DM + col) = pack8(v0, v1);
;                 s += dot8(v0, v1); }
;             s = red_fq(s); if (fq == 0) unsafeAtomicAdd(ss + row, s);
;         )
;     }
.LBB0_1648:
	s_or_b64 exec, exec, s[16:17]
	s_waitcnt lgkmcnt(0)
	v_add_u32_e32 v68, 0x80, v142
	v_cmp_lt_i32_e32 vcc, s68, v142
	s_and_saveexec_b64 s[16:17], vcc
	s_xor_b64 s[16:17], exec, s[16:17]
	v_add_u32_e32 v70, 0xffff8080, v142
	v_mov_b32_e32 v71, v2
	v_lshlrev_b64 v[70:71], 12, v[70:71]
	v_mov_b32_e32 v69, v2
	v_lshl_add_u64 v[72:73], s[10:11], 0, v[70:71]
	v_lshlrev_b64 v[70:71], 12, v[68:69]
	s_andn2_saveexec_b64 s[16:17], s[16:17]
	v_ashrrev_i32_e32 v69, 31, v68
	v_lshlrev_b64 v[70:71], 12, v[68:69]
	v_lshl_add_u64 v[72:73], s[30:31], 0, v[70:71]
	s_or_b64 exec, exec, s[16:17]
	v_lshl_add_u64 v[80:81], v[72:73], 0, v[144:145]
	global_load_dwordx4 v[72:75], v[80:81], off
	global_load_dwordx4 v[76:79], v[80:81], off offset:16
	global_load_dwordx4 v[216:219], v[80:81], off offset:512
	global_load_dwordx4 v[220:223], v[80:81], off offset:528
	v_lshl_add_u64 v[70:71], s[30:31], 0, v[70:71]
	v_lshl_add_u64 v[82:83], v[70:71], 0, v[144:145]
	s_waitcnt vmcnt(3)
	v_pk_fma_f32 v[66:67], v[66:67], 0.5, v[74:75] op_sel_hi:[1,0,1]
	v_pk_fma_f32 v[64:65], v[64:65], 0.5, v[72:73] op_sel_hi:[1,0,1]
	s_waitcnt vmcnt(2)
	v_pk_fma_f32 v[62:63], v[62:63], 0.5, v[78:79] op_sel_hi:[1,0,1]
	v_pk_fma_f32 v[60:61], v[60:61], 0.5, v[76:77] op_sel_hi:[1,0,1]
	global_store_dwordx4 v[82:83], v[64:67], off
	global_store_dwordx4 v[82:83], v[60:63], off offset:16
	s_nop 0
	s_nop 0
	v_mul_f32_e32 v65, v65, v65
	v_mul_f32_e32 v67, v67, v67
	v_mul_f32_e32 v61, v61, v61
	v_fmac_f32_e32 v65, v64, v64
	v_fmac_f32_e32 v67, v66, v66
	v_mul_f32_e32 v63, v63, v63
	v_fmac_f32_e32 v61, v60, v60
	v_add_f32_e32 v60, v65, v67
	v_fmac_f32_e32 v63, v62, v62
	v_add_f32_e32 v60, v61, v60
	v_add_f32_e32 v64, v63, v60
	s_waitcnt vmcnt(3)
	v_pk_fma_f32 v[58:59], v[58:59], 0.5, v[218:219] op_sel_hi:[1,0,1]
	v_pk_fma_f32 v[56:57], v[56:57], 0.5, v[216:217] op_sel_hi:[1,0,1]
	s_waitcnt vmcnt(2)
	v_pk_fma_f32 v[60:61], v[52:53], 0.5, v[220:221] op_sel_hi:[1,0,1]
	v_mul_f32_e32 v52, v57, v57
	v_mul_f32_e32 v53, v59, v59
	v_pk_fma_f32 v[62:63], v[54:55], 0.5, v[222:223] op_sel_hi:[1,0,1]
	v_mul_f32_e32 v54, v61, v61
	v_fmac_f32_e32 v52, v56, v56
	v_fmac_f32_e32 v53, v58, v58
	v_mul_f32_e32 v55, v63, v63
	v_fmac_f32_e32 v54, v60, v60
	v_add_f32_e32 v52, v52, v53
	v_add_f32_e32 v52, v54, v52
	v_fmac_f32_e32 v55, v62, v62
	v_add_f32_e32 v52, v55, v52
	v_add_f32_e32 v52, v64, v52
	v_mov_b32_e32 v53, v52
	global_store_dwordx4 v[82:83], v[56:59], off offset:512
	global_store_dwordx4 v[82:83], v[60:63], off offset:528
	v_permlane16_swap_b32_e32 v52, v53
	v_add_f32_e32 v52, v52, v53
	v_mov_b32_e32 v53, v52
	s_nop 1
	v_permlane32_swap_b32_e32 v52, v53
	s_and_saveexec_b64 s[16:17], s[4:5]
	s_cbranch_execz .LBB0_1654
	s_waitcnt lgkmcnt(0)
	v_add_f32_e32 v54, v52, v53
	v_lshl_add_u64 v[52:53], v[68:69], 2, s[20:21]
	v_mov_b32_e32 v240, v52
	v_mov_b32_e32 v241, v53
	v_mov_b32_e32 v242, v54
.LBB0_1654:
	s_or_b64 exec, exec, s[16:17]
	s_waitcnt lgkmcnt(0)
	v_add_u32_e32 v52, 0x90, v142
	v_cmp_lt_i32_e32 vcc, s69, v142
	s_and_saveexec_b64 s[16:17], vcc
	s_xor_b64 s[16:17], exec, s[16:17]
	v_add_u32_e32 v54, 0xffff8090, v142
	v_mov_b32_e32 v55, v2
	v_lshlrev_b64 v[54:55], 12, v[54:55]
	v_mov_b32_e32 v53, v2
	v_lshl_add_u64 v[56:57], s[10:11], 0, v[54:55]
	v_lshlrev_b64 v[54:55], 12, v[52:53]
	s_andn2_saveexec_b64 s[16:17], s[16:17]
	v_ashrrev_i32_e32 v53, 31, v52
	v_lshlrev_b64 v[54:55], 12, v[52:53]
	v_lshl_add_u64 v[56:57], s[30:31], 0, v[54:55]
	s_or_b64 exec, exec, s[16:17]
	v_lshl_add_u64 v[64:65], v[56:57], 0, v[144:145]
	global_load_dwordx4 v[56:59], v[64:65], off
	global_load_dwordx4 v[60:63], v[64:65], off offset:16
	global_load_dwordx4 v[216:219], v[64:65], off offset:512
	global_load_dwordx4 v[220:223], v[64:65], off offset:528
	v_lshl_add_u64 v[54:55], s[30:31], 0, v[54:55]
	v_lshl_add_u64 v[66:67], v[54:55], 0, v[144:145]
	s_waitcnt vmcnt(3)
	v_pk_fma_f32 v[50:51], v[50:51], 0.5, v[58:59] op_sel_hi:[1,0,1]
	v_pk_fma_f32 v[48:49], v[48:49], 0.5, v[56:57] op_sel_hi:[1,0,1]
	s_waitcnt vmcnt(2)
	v_pk_fma_f32 v[46:47], v[46:47], 0.5, v[62:63] op_sel_hi:[1,0,1]
	v_pk_fma_f32 v[44:45], v[44:45], 0.5, v[60:61] op_sel_hi:[1,0,1]
	global_store_dwordx4 v[66:67], v[48:51], off
	global_store_dwordx4 v[66:67], v[44:47], off offset:16
	s_nop 0
	s_nop 0
	v_mul_f32_e32 v49, v49, v49
	v_mul_f32_e32 v51, v51, v51
	v_mul_f32_e32 v45, v45, v45
	v_fmac_f32_e32 v49, v48, v48
	v_fmac_f32_e32 v51, v50, v50
	v_mul_f32_e32 v47, v47, v47
	v_fmac_f32_e32 v45, v44, v44
	v_add_f32_e32 v44, v49, v51
	v_fmac_f32_e32 v47, v46, v46
	v_add_f32_e32 v44, v45, v44
	v_add_f32_e32 v48, v47, v44
	s_waitcnt vmcnt(3)
	v_pk_fma_f32 v[42:43], v[42:43], 0.5, v[218:219] op_sel_hi:[1,0,1]
	v_pk_fma_f32 v[40:41], v[40:41], 0.5, v[216:217] op_sel_hi:[1,0,1]
	s_waitcnt vmcnt(2)
	v_pk_fma_f32 v[44:45], v[36:37], 0.5, v[220:221] op_sel_hi:[1,0,1]
	v_mul_f32_e32 v36, v41, v41
	v_mul_f32_e32 v37, v43, v43
	v_pk_fma_f32 v[46:47], v[38:39], 0.5, v[222:223] op_sel_hi:[1,0,1]
	v_mul_f32_e32 v38, v45, v45
	v_fmac_f32_e32 v36, v40, v40
	v_fmac_f32_e32 v37, v42, v42
	v_mul_f32_e32 v39, v47, v47
	v_fmac_f32_e32 v38, v44, v44
	v_add_f32_e32 v36, v36, v37
	v_add_f32_e32 v36, v38, v36
	v_fmac_f32_e32 v39, v46, v46
	v_add_f32_e32 v36, v39, v36
	v_add_f32_e32 v36, v48, v36
	v_mov_b32_e32 v37, v36
	global_store_dwordx4 v[66:67], v[40:43], off offset:512
	global_store_dwordx4 v[66:67], v[44:47], off offset:528
	v_permlane16_swap_b32_e32 v36, v37
	v_add_f32_e32 v36, v36, v37
	v_mov_b32_e32 v37, v36
	s_nop 1
	v_permlane32_swap_b32_e32 v36, v37
	s_and_saveexec_b64 s[16:17], s[4:5]
	s_cbranch_execz .LBB0_1660
	s_waitcnt lgkmcnt(0)
	v_add_f32_e32 v38, v36, v37
	v_lshl_add_u64 v[36:37], v[52:53], 2, s[20:21]
	v_mov_b32_e32 v244, v36
	v_mov_b32_e32 v245, v37
	v_mov_b32_e32 v246, v38
; #define EPI_ROWS(...) _Pragma("unroll") for (int ai = 0; ai < 2; ++ai) _Pragma("unroll") for (int m = 0; m < 4; ++m) { const int row = row0 + ai * 128 + m * 16; __VA_ARGS__ __builtin_amdgcn_sched_barrier(0); }
; __device__ __forceinline__ u32x4 pack8(f32x4 a, f32x4 b) { u32x4 w; w.x = pk2(a[0], a[1]); w.y = pk2(a[2], a[3]); w.z = pk2(b[0], b[1]); w.w = pk2(b[2], b[3]); return w; }
; __device__ __forceinline__ float dot8(f32x4 a, f32x4 b) { return (a[0] * a[0] + a[1] * a[1]) + (a[2] * a[2] + a[3] * a[3]) + (b[0] * b[0] + b[1] * b[1]) + (b[2] * b[2] + b[3] * b[3]); }
; __device__ __forceinline__ float red_fq(float s) { s += __shfl_xor(s, 16); s += __shfl_xor(s, 32); return s; }
;     __device__ __forceinline__ void operator()(AccRef acc, const Unit& u, int wr, int wc, int fr, int fq) const {
;         const int row0 = u.pm * 256 + wr * 64 + fr, col0 = u.pn * 256 + wc * 32 + 8 * fq;
;         EPI_ROWS(
;             const float* rp = (row < MP) ? res0 + (size_t)row * DM : res1 + (size_t)(row - MP) * DM;
;             float s = 0.f;
;             _Pragma("unroll") for (int bj = 0; bj < 2; ++bj) { const int col = col0 + bj * 128;
;                 f32x4 v0 = *(const f32x4*)(rp + col) + acc[ai][bj][m][0] * scale, v1 = *(const f32x4*)(rp + col + 4) + acc[ai][bj][m][1] * scale;
;                 *(f32x4*)(out + (size_t)row * DM + col) = v0; *(f32x4*)(out + (size_t)row * DM + col + 4) = v1;
;                 if (WB) *(u32x4*)(ob + (size_t)row * DM + col) = pack8(v0, v1);
;                 s += dot8(v0, v1); }
;             s = red_fq(s); if (fq == 0) unsafeAtomicAdd(ss + row, s);
;         )
;     }
.LBB0_1660:
	s_or_b64 exec, exec, s[16:17]
	s_waitcnt lgkmcnt(0)
	v_add_u32_e32 v36, 0xa0, v142
	v_cmp_lt_i32_e32 vcc, s70, v142
	s_and_saveexec_b64 s[16:17], vcc
	s_xor_b64 s[16:17], exec, s[16:17]
	v_add_u32_e32 v38, 0xffff80a0, v142
	v_mov_b32_e32 v39, v2
	v_lshlrev_b64 v[38:39], 12, v[38:39]
	v_mov_b32_e32 v37, v2
	v_lshl_add_u64 v[40:41], s[10:11], 0, v[38:39]
	v_lshlrev_b64 v[38:39], 12, v[36:37]
	s_andn2_saveexec_b64 s[16:17], s[16:17]
	v_ashrrev_i32_e32 v37, 31, v36
	v_lshlrev_b64 v[38:39], 12, v[36:37]
	v_lshl_add_u64 v[40:41], s[30:31], 0, v[38:39]
	s_or_b64 exec, exec, s[16:17]
	v_lshl_add_u64 v[48:49], v[40:41], 0, v[144:145]
	global_load_dwordx4 v[40:43], v[48:49], off
	global_load_dwordx4 v[44:47], v[48:49], off offset:16
	global_load_dwordx4 v[216:219], v[48:49], off offset:512
	global_load_dwordx4 v[220:223], v[48:49], off offset:528
	v_lshl_add_u64 v[38:39], s[30:31], 0, v[38:39]
	v_lshl_add_u64 v[50:51], v[38:39], 0, v[144:145]
	s_waitcnt vmcnt(3)
	v_pk_fma_f32 v[34:35], v[34:35], 0.5, v[42:43] op_sel_hi:[1,0,1]
	v_pk_fma_f32 v[32:33], v[32:33], 0.5, v[40:41] op_sel_hi:[1,0,1]
	s_waitcnt vmcnt(2)
	v_pk_fma_f32 v[30:31], v[30:31], 0.5, v[46:47] op_sel_hi:[1,0,1]
	v_pk_fma_f32 v[28:29], v[28:29], 0.5, v[44:45] op_sel_hi:[1,0,1]
	global_store_dwordx4 v[50:51], v[32:35], off
	global_store_dwordx4 v[50:51], v[28:31], off offset:16
	s_nop 0
	s_nop 0
	v_mul_f32_e32 v33, v33, v33
	v_mul_f32_e32 v35, v35, v35
	v_mul_f32_e32 v29, v29, v29
	v_fmac_f32_e32 v33, v32, v32
	v_fmac_f32_e32 v35, v34, v34
	v_mul_f32_e32 v31, v31, v31
	v_fmac_f32_e32 v29, v28, v28
	v_add_f32_e32 v28, v33, v35
	v_fmac_f32_e32 v31, v30, v30
	v_add_f32_e32 v28, v29, v28
	v_add_f32_e32 v32, v31, v28
	s_waitcnt vmcnt(3)
	v_pk_fma_f32 v[26:27], v[26:27], 0.5, v[218:219] op_sel_hi:[1,0,1]
	v_pk_fma_f32 v[24:25], v[24:25], 0.5, v[216:217] op_sel_hi:[1,0,1]
	s_waitcnt vmcnt(2)
	v_pk_fma_f32 v[28:29], v[20:21], 0.5, v[220:221] op_sel_hi:[1,0,1]
	v_mul_f32_e32 v20, v25, v25
	v_mul_f32_e32 v21, v27, v27
	v_pk_fma_f32 v[30:31], v[22:23], 0.5, v[222:223] op_sel_hi:[1,0,1]
	v_mul_f32_e32 v22, v29, v29
	v_fmac_f32_e32 v20, v24, v24
	v_fmac_f32_e32 v21, v26, v26
	v_mul_f32_e32 v23, v31, v31
	v_fmac_f32_e32 v22, v28, v28
	v_add_f32_e32 v20, v20, v21
	v_add_f32_e32 v20, v22, v20
	v_fmac_f32_e32 v23, v30, v30
	v_add_f32_e32 v20, v23, v20
	v_add_f32_e32 v20, v32, v20
	v_mov_b32_e32 v21, v20
	global_store_dwordx4 v[50:51], v[24:27], off offset:512
	global_store_dwordx4 v[50:51], v[28:31], off offset:528
	v_permlane16_swap_b32_e32 v20, v21
	v_add_f32_e32 v20, v20, v21
	v_mov_b32_e32 v21, v20
	s_nop 1
	v_permlane32_swap_b32_e32 v20, v21
	s_and_saveexec_b64 s[16:17], s[4:5]
	s_cbranch_execz .LBB0_1666
	s_waitcnt lgkmcnt(0)
	v_add_f32_e32 v22, v20, v21
	v_lshl_add_u64 v[20:21], v[36:37], 2, s[20:21]
	v_mov_b32_e32 v248, v20
	v_mov_b32_e32 v249, v21
	v_mov_b32_e32 v250, v22
.LBB0_1666:
	s_or_b64 exec, exec, s[16:17]
	s_waitcnt lgkmcnt(0)
	v_add_u32_e32 v20, 0xb0, v142
	v_cmp_lt_i32_e32 vcc, s71, v142
	s_and_saveexec_b64 s[16:17], vcc
	s_xor_b64 s[16:17], exec, s[16:17]
	v_add_u32_e32 v22, 0xffff80b0, v142
	v_mov_b32_e32 v23, v2
	v_lshlrev_b64 v[22:23], 12, v[22:23]
	v_mov_b32_e32 v21, v2
	v_lshl_add_u64 v[24:25], s[10:11], 0, v[22:23]
	v_lshlrev_b64 v[22:23], 12, v[20:21]
	s_andn2_saveexec_b64 s[16:17], s[16:17]
	v_ashrrev_i32_e32 v21, 31, v20
	v_lshlrev_b64 v[22:23], 12, v[20:21]
	v_lshl_add_u64 v[24:25], s[30:31], 0, v[22:23]
	s_or_b64 exec, exec, s[16:17]
	v_lshl_add_u64 v[32:33], v[24:25], 0, v[144:145]
	global_load_dwordx4 v[24:27], v[32:33], off
	global_load_dwordx4 v[28:31], v[32:33], off offset:16
	global_load_dwordx4 v[216:219], v[32:33], off offset:512
	global_load_dwordx4 v[220:223], v[32:33], off offset:528
	v_lshl_add_u64 v[22:23], s[30:31], 0, v[22:23]
	v_lshl_add_u64 v[34:35], v[22:23], 0, v[144:145]
	s_waitcnt vmcnt(3)
	v_pk_fma_f32 v[18:19], v[18:19], 0.5, v[26:27] op_sel_hi:[1,0,1]
	v_pk_fma_f32 v[16:17], v[16:17], 0.5, v[24:25] op_sel_hi:[1,0,1]
	s_waitcnt vmcnt(2)
	v_pk_fma_f32 v[14:15], v[14:15], 0.5, v[30:31] op_sel_hi:[1,0,1]
	v_pk_fma_f32 v[12:13], v[12:13], 0.5, v[28:29] op_sel_hi:[1,0,1]
	global_store_dwordx4 v[34:35], v[16:19], off
	global_store_dwordx4 v[34:35], v[12:15], off offset:16
	s_nop 0
	s_nop 0
	v_mul_f32_e32 v17, v17, v17
	v_mul_f32_e32 v19, v19, v19
	v_mul_f32_e32 v13, v13, v13
	v_fmac_f32_e32 v17, v16, v16
	v_fmac_f32_e32 v19, v18, v18
	v_mul_f32_e32 v15, v15, v15
	v_fmac_f32_e32 v13, v12, v12
	v_add_f32_e32 v12, v17, v19
	v_fmac_f32_e32 v15, v14, v14
	v_add_f32_e32 v12, v13, v12
	v_add_f32_e32 v16, v15, v12
	s_waitcnt vmcnt(3)
	v_pk_fma_f32 v[10:11], v[10:11], 0.5, v[218:219] op_sel_hi:[1,0,1]
	v_pk_fma_f32 v[8:9], v[8:9], 0.5, v[216:217] op_sel_hi:[1,0,1]
	s_waitcnt vmcnt(2)
	v_pk_fma_f32 v[12:13], v[4:5], 0.5, v[220:221] op_sel_hi:[1,0,1]
	v_mul_f32_e32 v4, v9, v9
	v_mul_f32_e32 v5, v11, v11
	v_pk_fma_f32 v[14:15], v[6:7], 0.5, v[222:223] op_sel_hi:[1,0,1]
	v_mul_f32_e32 v6, v13, v13
	v_fmac_f32_e32 v4, v8, v8
	v_fmac_f32_e32 v5, v10, v10
	v_mul_f32_e32 v7, v15, v15
	v_fmac_f32_e32 v6, v12, v12
	v_add_f32_e32 v4, v4, v5
	v_add_f32_e32 v4, v6, v4
	v_fmac_f32_e32 v7, v14, v14
	v_add_f32_e32 v4, v7, v4
	v_add_f32_e32 v4, v16, v4
	v_mov_b32_e32 v3, v4
	global_store_dwordx4 v[34:35], v[8:11], off offset:512
	global_store_dwordx4 v[34:35], v[12:15], off offset:528
	v_permlane16_swap_b32_e32 v4, v3
	v_add_f32_e32 v3, v4, v3
	v_mov_b32_e32 v4, v3
	s_nop 1
	v_permlane32_swap_b32_e32 v3, v4
	s_and_saveexec_b64 s[16:17], s[4:5]
	s_cbranch_execz .LBB0_1672
	s_waitcnt lgkmcnt(0)
	v_add_f32_e32 v3, v3, v4
	v_lshl_add_u64 v[4:5], v[20:21], 2, s[20:21]
	global_atomic_add_f32 v[4:5], v3, off
	global_atomic_add_f32 v[224:225], v226, off
	global_atomic_add_f32 v[228:229], v230, off
	global_atomic_add_f32 v[232:233], v234, off
	global_atomic_add_f32 v[236:237], v238, off
	global_atomic_add_f32 v[240:241], v242, off
	global_atomic_add_f32 v[244:245], v246, off
	global_atomic_add_f32 v[248:249], v250, off
